# GEMM K-loops: pre-MFMA s_barrier moved below the first 6 MFMAs of each block, all 18 K-loops
# baseline (speedup 1.0000x reference)
.LBB0_408:
	ds_read_b128 v[34:37], v196
	ds_read_b128 v[38:41], v196 offset:1024
	ds_read_b128 v[42:45], v196 offset:2048
	ds_read_b128 v[46:49], v196 offset:3072
	ds_read_b128 v[146:149], v197
	ds_read_b128 v[150:153], v197 offset:1024
	ds_read_b128 v[184:187], v197 offset:2048
	ds_read_b128 v[188:191], v197 offset:3072
	s_add_i32 s11, s6, 2
	s_add_u32 s12, s4, 0x80
	s_addc_u32 s7, s5, 0
	s_cmp_eq_u32 s27, s6
	s_cselect_b32 s6, s54, s12
	s_cselect_b32 s7, s55, s7
	s_cselect_b32 s13, s61, s9
	s_cselect_b32 s12, s60, s8
	v_lshl_add_u64 v[192:193], s[4:5], 0, v[174:175]
	s_add_i32 m0, s88, 0xc000
	ds_read_b128 v[200:203], v198
	ds_read_b128 v[204:207], v198 offset:1024
	ds_read_b128 v[208:211], v198 offset:2048
	ds_read_b128 v[212:215], v198 offset:3072
	ds_read_b128 v[216:219], v198 offset:4096
	ds_read_b128 v[220:223], v198 offset:5120
	ds_read_b128 v[224:227], v198 offset:6144
	ds_read_b128 v[228:231], v198 offset:7168
	global_load_lds_dwordx4 v[192:193], off
	v_lshl_add_u64 v[192:193], s[4:5], 0, v[176:177]
	s_add_i32 m0, s88, 0xe000
	s_nop 0
	global_load_lds_dwordx4 v[192:193], off
	s_waitcnt vmcnt(8)
	s_waitcnt lgkmcnt(0)
	s_setprio 1
	s_waitcnt lgkmcnt(0)
	v_mfma_f32_16x16x32_bf16 v[142:145], v[34:37], v[200:203], v[142:145]
	v_mfma_f32_16x16x32_bf16 v[138:141], v[42:45], v[200:203], v[138:141]
	v_mfma_f32_16x16x32_bf16 v[126:129], v[34:37], v[208:211], v[126:129]
	v_mfma_f32_16x16x32_bf16 v[122:125], v[42:45], v[208:211], v[122:125]
	v_mfma_f32_16x16x32_bf16 v[110:113], v[34:37], v[216:219], v[110:113]
	v_mfma_f32_16x16x32_bf16 v[106:109], v[42:45], v[216:219], v[106:109]
	s_barrier
	v_mfma_f32_16x16x32_bf16 v[94:97], v[34:37], v[224:227], v[94:97]
	v_mfma_f32_16x16x32_bf16 v[90:93], v[42:45], v[224:227], v[90:93]
	v_mfma_f32_16x16x32_bf16 v[142:145], v[38:41], v[204:207], v[142:145]
	v_mfma_f32_16x16x32_bf16 v[138:141], v[46:49], v[204:207], v[138:141]
	v_mfma_f32_16x16x32_bf16 v[126:129], v[38:41], v[212:215], v[126:129]
	v_mfma_f32_16x16x32_bf16 v[122:125], v[46:49], v[212:215], v[122:125]
	v_mfma_f32_16x16x32_bf16 v[110:113], v[38:41], v[220:223], v[110:113]
	v_mfma_f32_16x16x32_bf16 v[106:109], v[46:49], v[220:223], v[106:109]
	v_mfma_f32_16x16x32_bf16 v[94:97], v[38:41], v[228:231], v[94:97]
	v_mfma_f32_16x16x32_bf16 v[90:93], v[46:49], v[228:231], v[90:93]
	s_setprio 0
	s_setprio 1
	v_mfma_f32_16x16x32_bf16 v[134:137], v[146:149], v[200:203], v[134:137]
	v_mfma_f32_16x16x32_bf16 v[130:133], v[184:187], v[200:203], v[130:133]
	v_mfma_f32_16x16x32_bf16 v[118:121], v[146:149], v[208:211], v[118:121]
	v_mfma_f32_16x16x32_bf16 v[114:117], v[184:187], v[208:211], v[114:117]
	v_mfma_f32_16x16x32_bf16 v[102:105], v[146:149], v[216:219], v[102:105]
	v_mfma_f32_16x16x32_bf16 v[98:101], v[184:187], v[216:219], v[98:101]
	v_mfma_f32_16x16x32_bf16 v[86:89], v[146:149], v[224:227], v[86:89]
	v_mfma_f32_16x16x32_bf16 v[82:85], v[184:187], v[224:227], v[82:85]
	v_mfma_f32_16x16x32_bf16 v[134:137], v[150:153], v[204:207], v[134:137]
	v_mfma_f32_16x16x32_bf16 v[130:133], v[188:191], v[204:207], v[130:133]
	v_mfma_f32_16x16x32_bf16 v[118:121], v[150:153], v[212:215], v[118:121]
	v_mfma_f32_16x16x32_bf16 v[114:117], v[188:191], v[212:215], v[114:117]
	v_mfma_f32_16x16x32_bf16 v[102:105], v[150:153], v[220:223], v[102:105]
	v_mfma_f32_16x16x32_bf16 v[98:101], v[188:191], v[220:223], v[98:101]
	v_mfma_f32_16x16x32_bf16 v[86:89], v[150:153], v[228:231], v[86:89]
	v_mfma_f32_16x16x32_bf16 v[82:85], v[188:191], v[228:231], v[82:85]
	s_setprio 0
	s_barrier
	s_add_i32 s24, s84, s81
	v_lshl_add_u64 v[192:193], s[12:13], 0, v[156:157]
	s_mov_b32 m0, s24
	ds_read_b128 v[200:203], v198 offset:16384
	ds_read_b128 v[204:207], v198 offset:17408
	ds_read_b128 v[208:211], v198 offset:18432
	ds_read_b128 v[212:215], v198 offset:19456
	ds_read_b128 v[216:219], v198 offset:20480
	ds_read_b128 v[220:223], v198 offset:21504
	ds_read_b128 v[224:227], v198 offset:22528
	ds_read_b128 v[228:231], v198 offset:23552
	global_load_lds_dwordx4 v[192:193], off
	s_add_i32 m0, s24, 0x2000
	v_lshl_add_u64 v[232:233], s[12:13], 0, v[160:161]
	s_add_u32 s12, s12, s20
	s_addc_u32 s13, s13, s21
	s_add_i32 s24, s85, s81
	global_load_lds_dwordx4 v[232:233], off
	v_lshl_add_u64 v[234:235], s[12:13], 0, v[156:157]
	s_mov_b32 m0, s24
	v_lshl_add_u64 v[236:237], s[12:13], 0, v[160:161]
	global_load_lds_dwordx4 v[234:235], off
	s_add_i32 m0, s24, 0x2000
	v_lshl_add_u64 v[238:239], s[6:7], 0, v[154:155]
	global_load_lds_dwordx4 v[236:237], off
	s_mov_b32 m0, s88
	v_lshl_add_u64 v[240:241], s[6:7], 0, v[158:159]
	global_load_lds_dwordx4 v[238:239], off
	s_mov_b32 m0, s90
	s_nop 0
	global_load_lds_dwordx4 v[240:241], off
	s_waitcnt vmcnt(8)
	s_waitcnt lgkmcnt(0)
	s_setprio 1
	s_waitcnt lgkmcnt(0)
	v_mfma_f32_16x16x32_bf16 v[78:81], v[34:37], v[200:203], v[78:81]
	v_mfma_f32_16x16x32_bf16 v[74:77], v[42:45], v[200:203], v[74:77]
	v_mfma_f32_16x16x32_bf16 v[62:65], v[34:37], v[208:211], v[62:65]
	v_mfma_f32_16x16x32_bf16 v[58:61], v[42:45], v[208:211], v[58:61]
	v_mfma_f32_16x16x32_bf16 v[30:33], v[34:37], v[216:219], v[30:33]
	v_mfma_f32_16x16x32_bf16 v[26:29], v[42:45], v[216:219], v[26:29]
	s_barrier
	v_mfma_f32_16x16x32_bf16 v[14:17], v[34:37], v[224:227], v[14:17]
	v_mfma_f32_16x16x32_bf16 v[10:13], v[42:45], v[224:227], v[10:13]
	v_mfma_f32_16x16x32_bf16 v[78:81], v[38:41], v[204:207], v[78:81]
	v_mfma_f32_16x16x32_bf16 v[74:77], v[46:49], v[204:207], v[74:77]
	v_mfma_f32_16x16x32_bf16 v[62:65], v[38:41], v[212:215], v[62:65]
	v_mfma_f32_16x16x32_bf16 v[58:61], v[46:49], v[212:215], v[58:61]
	v_mfma_f32_16x16x32_bf16 v[30:33], v[38:41], v[220:223], v[30:33]
	v_mfma_f32_16x16x32_bf16 v[26:29], v[46:49], v[220:223], v[26:29]
	v_mfma_f32_16x16x32_bf16 v[14:17], v[38:41], v[228:231], v[14:17]
	v_mfma_f32_16x16x32_bf16 v[10:13], v[46:49], v[228:231], v[10:13]
	s_setprio 0
	s_setprio 1
	v_mfma_f32_16x16x32_bf16 v[22:25], v[146:149], v[216:219], v[22:25]
	v_mfma_f32_16x16x32_bf16 v[18:21], v[184:187], v[216:219], v[18:21]
	v_mfma_f32_16x16x32_bf16 v[6:9], v[146:149], v[224:227], v[6:9]
	v_mfma_f32_16x16x32_bf16 v[2:5], v[184:187], v[224:227], v[2:5]
	v_mfma_f32_16x16x32_bf16 v[34:37], v[146:149], v[200:203], v[70:73]
	v_mfma_f32_16x16x32_bf16 v[38:41], v[184:187], v[200:203], v[66:69]
	v_mfma_f32_16x16x32_bf16 v[42:45], v[146:149], v[208:211], v[54:57]
	v_mfma_f32_16x16x32_bf16 v[46:49], v[184:187], v[208:211], v[50:53]
	v_mfma_f32_16x16x32_bf16 v[22:25], v[150:153], v[220:223], v[22:25]
	v_mfma_f32_16x16x32_bf16 v[18:21], v[188:191], v[220:223], v[18:21]
	v_mfma_f32_16x16x32_bf16 v[6:9], v[150:153], v[228:231], v[6:9]
	v_mfma_f32_16x16x32_bf16 v[2:5], v[188:191], v[228:231], v[2:5]
	v_mfma_f32_16x16x32_bf16 v[34:37], v[150:153], v[204:207], v[34:37]
	v_mfma_f32_16x16x32_bf16 v[38:41], v[188:191], v[204:207], v[38:41]
	v_mfma_f32_16x16x32_bf16 v[42:45], v[150:153], v[212:215], v[42:45]
	v_mfma_f32_16x16x32_bf16 v[46:49], v[188:191], v[212:215], v[46:49]
	s_setprio 0
	s_barrier
	s_add_i32 s12, 0, 0x18000
	s_add_i32 s13, 0, 0x1c000
	v_add_u32_e32 v70, s12, v194
	v_add_u32_e32 v162, s13, v194
	ds_read_b128 v[50:53], v70
	ds_read_b128 v[54:57], v70 offset:1024
	ds_read_b128 v[66:69], v70 offset:2048
	ds_read_b128 v[70:73], v70 offset:3072
	ds_read_b128 v[146:149], v162
	ds_read_b128 v[150:153], v162 offset:1024
	ds_read_b128 v[184:187], v162 offset:2048
	ds_read_b128 v[188:191], v162 offset:3072
	s_add_u32 s6, s6, s20
	s_addc_u32 s7, s7, s21
	s_mov_b32 m0, s91
	v_lshl_add_u64 v[242:243], s[6:7], 0, v[154:155]
	ds_read_b128 v[200:203], v198 offset:32768
	ds_read_b128 v[204:207], v198 offset:33792
	ds_read_b128 v[208:211], v198 offset:34816
	ds_read_b128 v[212:215], v198 offset:35840
	ds_read_b128 v[216:219], v198 offset:36864
	ds_read_b128 v[220:223], v198 offset:37888
	ds_read_b128 v[224:227], v198 offset:38912
	ds_read_b128 v[228:231], v198 offset:39936
	global_load_lds_dwordx4 v[242:243], off
	v_lshl_add_u64 v[242:243], s[6:7], 0, v[158:159]
	s_mov_b32 m0, s95
	s_nop 0
	global_load_lds_dwordx4 v[242:243], off
	s_waitcnt vmcnt(8)
	s_waitcnt lgkmcnt(0)
	s_setprio 1
	s_waitcnt lgkmcnt(0)
	v_mfma_f32_16x16x32_bf16 v[142:145], v[50:53], v[200:203], v[142:145]
	v_mfma_f32_16x16x32_bf16 v[138:141], v[66:69], v[200:203], v[138:141]
	v_mfma_f32_16x16x32_bf16 v[126:129], v[50:53], v[208:211], v[126:129]
	v_mfma_f32_16x16x32_bf16 v[122:125], v[66:69], v[208:211], v[122:125]
	v_mfma_f32_16x16x32_bf16 v[110:113], v[50:53], v[216:219], v[110:113]
	v_mfma_f32_16x16x32_bf16 v[106:109], v[66:69], v[216:219], v[106:109]
	s_barrier
	v_mfma_f32_16x16x32_bf16 v[94:97], v[50:53], v[224:227], v[94:97]
	v_mfma_f32_16x16x32_bf16 v[90:93], v[66:69], v[224:227], v[90:93]
	v_mfma_f32_16x16x32_bf16 v[142:145], v[54:57], v[204:207], v[142:145]
	v_mfma_f32_16x16x32_bf16 v[138:141], v[70:73], v[204:207], v[138:141]
	v_mfma_f32_16x16x32_bf16 v[126:129], v[54:57], v[212:215], v[126:129]
	v_mfma_f32_16x16x32_bf16 v[122:125], v[70:73], v[212:215], v[122:125]
	v_mfma_f32_16x16x32_bf16 v[110:113], v[54:57], v[220:223], v[110:113]
	v_mfma_f32_16x16x32_bf16 v[106:109], v[70:73], v[220:223], v[106:109]
	v_mfma_f32_16x16x32_bf16 v[94:97], v[54:57], v[228:231], v[94:97]
	v_mfma_f32_16x16x32_bf16 v[90:93], v[70:73], v[228:231], v[90:93]
	s_setprio 0
	s_setprio 1
	v_mfma_f32_16x16x32_bf16 v[134:137], v[146:149], v[200:203], v[134:137]
	v_mfma_f32_16x16x32_bf16 v[130:133], v[184:187], v[200:203], v[130:133]
	v_mfma_f32_16x16x32_bf16 v[118:121], v[146:149], v[208:211], v[118:121]
	v_mfma_f32_16x16x32_bf16 v[114:117], v[184:187], v[208:211], v[114:117]
	v_mfma_f32_16x16x32_bf16 v[102:105], v[146:149], v[216:219], v[102:105]
	v_mfma_f32_16x16x32_bf16 v[98:101], v[184:187], v[216:219], v[98:101]
	v_mfma_f32_16x16x32_bf16 v[86:89], v[146:149], v[224:227], v[86:89]
	v_mfma_f32_16x16x32_bf16 v[82:85], v[184:187], v[224:227], v[82:85]
	v_mfma_f32_16x16x32_bf16 v[134:137], v[150:153], v[204:207], v[134:137]
	v_mfma_f32_16x16x32_bf16 v[130:133], v[188:191], v[204:207], v[130:133]
	v_mfma_f32_16x16x32_bf16 v[118:121], v[150:153], v[212:215], v[118:121]
	v_mfma_f32_16x16x32_bf16 v[114:117], v[188:191], v[212:215], v[114:117]
	v_mfma_f32_16x16x32_bf16 v[102:105], v[150:153], v[220:223], v[102:105]
	v_mfma_f32_16x16x32_bf16 v[98:101], v[188:191], v[220:223], v[98:101]
	v_mfma_f32_16x16x32_bf16 v[86:89], v[150:153], v[228:231], v[86:89]
	v_mfma_f32_16x16x32_bf16 v[82:85], v[188:191], v[228:231], v[82:85]
	s_setprio 0
	s_barrier
	s_add_i32 s6, s12, s81
	v_lshl_add_u64 v[192:193], v[192:193], 0, s[44:45]
	s_mov_b32 m0, s6
	ds_read_b128 v[200:203], v198 offset:49152
	ds_read_b128 v[204:207], v198 offset:50176
	ds_read_b128 v[208:211], v198 offset:51200
	ds_read_b128 v[212:215], v198 offset:52224
	ds_read_b128 v[216:219], v198 offset:53248
	ds_read_b128 v[220:223], v198 offset:54272
	ds_read_b128 v[224:227], v198 offset:55296
	ds_read_b128 v[228:231], v198 offset:56320
	global_load_lds_dwordx4 v[192:193], off
	v_lshl_add_u64 v[192:193], v[232:233], 0, s[44:45]
	s_add_i32 m0, s6, 0x2000
	s_add_i32 s6, s13, s81
	global_load_lds_dwordx4 v[192:193], off
	v_lshl_add_u64 v[192:193], v[234:235], 0, s[44:45]
	s_mov_b32 m0, s6
	s_nop 0
	global_load_lds_dwordx4 v[192:193], off
	v_lshl_add_u64 v[192:193], v[236:237], 0, s[44:45]
	s_add_i32 m0, s6, 0x2000
	s_nop 0
	global_load_lds_dwordx4 v[192:193], off
	v_lshl_add_u64 v[192:193], v[238:239], 0, s[44:45]
	s_mov_b32 m0, s17
	s_nop 0
	global_load_lds_dwordx4 v[192:193], off
	v_lshl_add_u64 v[192:193], v[240:241], 0, s[44:45]
	s_mov_b32 m0, s94
	s_nop 0
	global_load_lds_dwordx4 v[192:193], off
	s_waitcnt vmcnt(8)
	s_waitcnt lgkmcnt(0)
	s_setprio 1
	s_waitcnt lgkmcnt(0)
	v_mfma_f32_16x16x32_bf16 v[78:81], v[50:53], v[200:203], v[78:81]
	v_mfma_f32_16x16x32_bf16 v[74:77], v[66:69], v[200:203], v[74:77]
	v_mfma_f32_16x16x32_bf16 v[62:65], v[50:53], v[208:211], v[62:65]
	v_mfma_f32_16x16x32_bf16 v[58:61], v[66:69], v[208:211], v[58:61]
	v_mfma_f32_16x16x32_bf16 v[30:33], v[50:53], v[216:219], v[30:33]
	v_mfma_f32_16x16x32_bf16 v[26:29], v[66:69], v[216:219], v[26:29]
	s_barrier
	v_mfma_f32_16x16x32_bf16 v[14:17], v[50:53], v[224:227], v[14:17]
	v_mfma_f32_16x16x32_bf16 v[10:13], v[66:69], v[224:227], v[10:13]
	v_mfma_f32_16x16x32_bf16 v[78:81], v[54:57], v[204:207], v[78:81]
	v_mfma_f32_16x16x32_bf16 v[74:77], v[70:73], v[204:207], v[74:77]
	v_mfma_f32_16x16x32_bf16 v[62:65], v[54:57], v[212:215], v[62:65]
	v_mfma_f32_16x16x32_bf16 v[58:61], v[70:73], v[212:215], v[58:61]
	v_mfma_f32_16x16x32_bf16 v[30:33], v[54:57], v[220:223], v[30:33]
	v_mfma_f32_16x16x32_bf16 v[26:29], v[70:73], v[220:223], v[26:29]
	v_mfma_f32_16x16x32_bf16 v[14:17], v[54:57], v[228:231], v[14:17]
	v_mfma_f32_16x16x32_bf16 v[10:13], v[70:73], v[228:231], v[10:13]
	s_setprio 0
	s_setprio 1
	v_mfma_f32_16x16x32_bf16 v[34:37], v[146:149], v[200:203], v[34:37]
	v_mfma_f32_16x16x32_bf16 v[70:73], v[150:153], v[204:207], v[34:37]
	v_mfma_f32_16x16x32_bf16 v[34:37], v[184:187], v[200:203], v[38:41]
	v_mfma_f32_16x16x32_bf16 v[66:69], v[188:191], v[204:207], v[34:37]
	v_mfma_f32_16x16x32_bf16 v[34:37], v[146:149], v[208:211], v[42:45]
	v_mfma_f32_16x16x32_bf16 v[54:57], v[150:153], v[212:215], v[34:37]
	v_mfma_f32_16x16x32_bf16 v[34:37], v[184:187], v[208:211], v[46:49]
	v_mfma_f32_16x16x32_bf16 v[22:25], v[146:149], v[216:219], v[22:25]
	v_mfma_f32_16x16x32_bf16 v[18:21], v[184:187], v[216:219], v[18:21]
	v_mfma_f32_16x16x32_bf16 v[6:9], v[146:149], v[224:227], v[6:9]
	v_mfma_f32_16x16x32_bf16 v[2:5], v[184:187], v[224:227], v[2:5]
	v_mfma_f32_16x16x32_bf16 v[50:53], v[188:191], v[212:215], v[34:37]
	v_mfma_f32_16x16x32_bf16 v[22:25], v[150:153], v[220:223], v[22:25]
	v_mfma_f32_16x16x32_bf16 v[18:21], v[188:191], v[220:223], v[18:21]
	v_mfma_f32_16x16x32_bf16 v[6:9], v[150:153], v[228:231], v[6:9]
	v_mfma_f32_16x16x32_bf16 v[2:5], v[188:191], v[228:231], v[2:5]
	s_setprio 0
	s_barrier
	s_add_u32 s4, s4, 0x100
	s_addc_u32 s5, s5, 0
	s_add_u32 s8, s8, 0x100
	s_addc_u32 s9, s9, 0
	s_cmp_ge_i32 s11, s26
	s_mov_b32 s6, s11
	s_cbranch_scc0 .LBB0_408

.LBB0_895:
	v_add_u32_e32 v158, s84, v227
	v_add_u32_e32 v174, s85, v227
	ds_read_b128 v[146:149], v158
	ds_read_b128 v[150:153], v158 offset:1024
	ds_read_b128 v[154:157], v158 offset:2048
	ds_read_b128 v[158:161], v158 offset:3072
	ds_read_b128 v[162:165], v174
	ds_read_b128 v[166:169], v174 offset:1024
	ds_read_b128 v[170:173], v174 offset:2048
	ds_read_b128 v[174:177], v174 offset:3072
	s_add_i32 s16, s50, 2
	s_add_u32 s17, s46, 0x80
	s_addc_u32 s51, s47, 0
	s_cmp_eq_u32 s81, s50
	s_cselect_b32 s50, s4, s17
	s_cselect_b32 s51, s5, s51
	s_cselect_b32 s55, s45, vcc_hi
	s_cselect_b32 s54, s44, vcc_lo
	v_lshl_add_u64 v[210:211], s[46:47], 0, v[138:139]
	s_add_i32 m0, s63, 0xc000
	ds_read_b128 v[178:181], v229
	ds_read_b128 v[182:185], v229 offset:1024
	ds_read_b128 v[186:189], v229 offset:2048
	ds_read_b128 v[190:193], v229 offset:3072
	ds_read_b128 v[194:197], v229 offset:4096
	ds_read_b128 v[198:201], v229 offset:5120
	ds_read_b128 v[202:205], v229 offset:6144
	ds_read_b128 v[206:209], v229 offset:7168
	global_load_lds_dwordx4 v[210:211], off
	v_lshl_add_u64 v[210:211], s[46:47], 0, v[140:141]
	s_add_i32 m0, s63, 0xe000
	s_nop 0
	global_load_lds_dwordx4 v[210:211], off
	s_waitcnt vmcnt(8)
	s_waitcnt lgkmcnt(0)
	s_setprio 1
	s_waitcnt lgkmcnt(0)
	v_mfma_i32_16x16x64_i8 v[126:129], v[146:149], v[178:181], v[126:129]
	v_mfma_i32_16x16x64_i8 v[122:125], v[154:157], v[178:181], v[122:125]
	v_mfma_i32_16x16x64_i8 v[118:121], v[146:149], v[186:189], v[118:121]
	v_mfma_i32_16x16x64_i8 v[114:117], v[154:157], v[186:189], v[114:117]
	v_mfma_i32_16x16x64_i8 v[106:109], v[146:149], v[194:197], v[106:109]
	v_mfma_i32_16x16x64_i8 v[98:101], v[154:157], v[194:197], v[98:101]
	s_barrier
	v_mfma_i32_16x16x64_i8 v[90:93], v[146:149], v[202:205], v[90:93]
	v_mfma_i32_16x16x64_i8 v[82:85], v[154:157], v[202:205], v[82:85]
	v_mfma_i32_16x16x64_i8 v[126:129], v[150:153], v[182:185], v[126:129]
	v_mfma_i32_16x16x64_i8 v[122:125], v[158:161], v[182:185], v[122:125]
	v_mfma_i32_16x16x64_i8 v[118:121], v[150:153], v[190:193], v[118:121]
	v_mfma_i32_16x16x64_i8 v[114:117], v[158:161], v[190:193], v[114:117]
	v_mfma_i32_16x16x64_i8 v[106:109], v[150:153], v[198:201], v[106:109]
	v_mfma_i32_16x16x64_i8 v[98:101], v[158:161], v[198:201], v[98:101]
	v_mfma_i32_16x16x64_i8 v[90:93], v[150:153], v[206:209], v[90:93]
	v_mfma_i32_16x16x64_i8 v[82:85], v[158:161], v[206:209], v[82:85]
	s_setprio 0
	s_setprio 1
	v_mfma_i32_16x16x64_i8 v[110:113], v[162:165], v[178:181], v[110:113]
	v_mfma_i32_16x16x64_i8 v[102:105], v[170:173], v[178:181], v[102:105]
	v_mfma_i32_16x16x64_i8 v[94:97], v[162:165], v[186:189], v[94:97]
	v_mfma_i32_16x16x64_i8 v[86:89], v[170:173], v[186:189], v[86:89]
	v_mfma_i32_16x16x64_i8 v[78:81], v[162:165], v[194:197], v[78:81]
	v_mfma_i32_16x16x64_i8 v[74:77], v[170:173], v[194:197], v[74:77]
	v_mfma_i32_16x16x64_i8 v[70:73], v[162:165], v[202:205], v[70:73]
	v_mfma_i32_16x16x64_i8 v[66:69], v[170:173], v[202:205], v[66:69]
	v_mfma_i32_16x16x64_i8 v[110:113], v[166:169], v[182:185], v[110:113]
	v_mfma_i32_16x16x64_i8 v[102:105], v[174:177], v[182:185], v[102:105]
	v_mfma_i32_16x16x64_i8 v[94:97], v[166:169], v[190:193], v[94:97]
	v_mfma_i32_16x16x64_i8 v[86:89], v[174:177], v[190:193], v[86:89]
	v_mfma_i32_16x16x64_i8 v[78:81], v[166:169], v[198:201], v[78:81]
	v_mfma_i32_16x16x64_i8 v[74:77], v[174:177], v[198:201], v[74:77]
	v_mfma_i32_16x16x64_i8 v[70:73], v[166:169], v[206:209], v[70:73]
	v_mfma_i32_16x16x64_i8 v[66:69], v[174:177], v[206:209], v[66:69]
	s_setprio 0
	s_barrier
	s_add_i32 s17, s84, s62
	v_lshl_add_u64 v[210:211], s[54:55], 0, v[132:133]
	s_mov_b32 m0, s17
	ds_read_b128 v[178:181], v229 offset:16384
	ds_read_b128 v[182:185], v229 offset:17408
	ds_read_b128 v[186:189], v229 offset:18432
	ds_read_b128 v[190:193], v229 offset:19456
	ds_read_b128 v[194:197], v229 offset:20480
	ds_read_b128 v[198:201], v229 offset:21504
	ds_read_b128 v[202:205], v229 offset:22528
	ds_read_b128 v[206:209], v229 offset:23552
	global_load_lds_dwordx4 v[210:211], off
	s_add_i32 m0, s17, 0x2000
	v_lshl_add_u64 v[212:213], s[54:55], 0, v[136:137]
	s_add_u32 s54, s54, s8
	s_addc_u32 s55, s55, s9
	s_add_i32 s17, s85, s62
	global_load_lds_dwordx4 v[212:213], off
	v_lshl_add_u64 v[214:215], s[54:55], 0, v[132:133]
	s_mov_b32 m0, s17
	v_lshl_add_u64 v[216:217], s[54:55], 0, v[136:137]
	global_load_lds_dwordx4 v[214:215], off
	s_add_i32 m0, s17, 0x2000
	v_lshl_add_u64 v[218:219], s[50:51], 0, v[130:131]
	global_load_lds_dwordx4 v[216:217], off
	s_mov_b32 m0, s63
	v_lshl_add_u64 v[220:221], s[50:51], 0, v[134:135]
	global_load_lds_dwordx4 v[218:219], off
	s_mov_b32 m0, s64
	s_nop 0
	global_load_lds_dwordx4 v[220:221], off
	s_waitcnt vmcnt(8)
	s_waitcnt lgkmcnt(0)
	s_setprio 1
	s_waitcnt lgkmcnt(0)
	v_mfma_i32_16x16x64_i8 v[62:65], v[146:149], v[178:181], v[62:65]
	v_mfma_i32_16x16x64_i8 v[58:61], v[154:157], v[178:181], v[58:61]
	v_mfma_i32_16x16x64_i8 v[54:57], v[146:149], v[186:189], v[54:57]
	v_mfma_i32_16x16x64_i8 v[50:53], v[154:157], v[186:189], v[50:53]
	v_mfma_i32_16x16x64_i8 v[42:45], v[146:149], v[194:197], v[42:45]
	v_mfma_i32_16x16x64_i8 v[34:37], v[154:157], v[194:197], v[34:37]
	s_barrier
	v_mfma_i32_16x16x64_i8 v[26:29], v[146:149], v[202:205], v[26:29]
	v_mfma_i32_16x16x64_i8 v[18:21], v[154:157], v[202:205], v[18:21]
	v_mfma_i32_16x16x64_i8 v[62:65], v[150:153], v[182:185], v[62:65]
	v_mfma_i32_16x16x64_i8 v[58:61], v[158:161], v[182:185], v[58:61]
	v_mfma_i32_16x16x64_i8 v[54:57], v[150:153], v[190:193], v[54:57]
	v_mfma_i32_16x16x64_i8 v[50:53], v[158:161], v[190:193], v[50:53]
	v_mfma_i32_16x16x64_i8 v[42:45], v[150:153], v[198:201], v[42:45]
	v_mfma_i32_16x16x64_i8 v[34:37], v[158:161], v[198:201], v[34:37]
	v_mfma_i32_16x16x64_i8 v[26:29], v[150:153], v[206:209], v[26:29]
	v_mfma_i32_16x16x64_i8 v[18:21], v[158:161], v[206:209], v[18:21]
	s_setprio 0
	s_setprio 1
	v_mfma_i32_16x16x64_i8 v[46:49], v[162:165], v[178:181], v[46:49]
	v_mfma_i32_16x16x64_i8 v[38:41], v[170:173], v[178:181], v[38:41]
	v_mfma_i32_16x16x64_i8 v[30:33], v[162:165], v[186:189], v[30:33]
	v_mfma_i32_16x16x64_i8 v[22:25], v[170:173], v[186:189], v[22:25]
	v_mfma_i32_16x16x64_i8 v[14:17], v[162:165], v[194:197], v[14:17]
	v_mfma_i32_16x16x64_i8 v[10:13], v[170:173], v[194:197], v[10:13]
	v_mfma_i32_16x16x64_i8 v[6:9], v[162:165], v[202:205], v[6:9]
	v_mfma_i32_16x16x64_i8 v[2:5], v[170:173], v[202:205], v[2:5]
	v_mfma_i32_16x16x64_i8 v[46:49], v[166:169], v[182:185], v[46:49]
	v_mfma_i32_16x16x64_i8 v[38:41], v[174:177], v[182:185], v[38:41]
	v_mfma_i32_16x16x64_i8 v[30:33], v[166:169], v[190:193], v[30:33]
	v_mfma_i32_16x16x64_i8 v[22:25], v[174:177], v[190:193], v[22:25]
	v_mfma_i32_16x16x64_i8 v[14:17], v[166:169], v[198:201], v[14:17]
	v_mfma_i32_16x16x64_i8 v[10:13], v[174:177], v[198:201], v[10:13]
	v_mfma_i32_16x16x64_i8 v[6:9], v[166:169], v[206:209], v[6:9]
	v_mfma_i32_16x16x64_i8 v[2:5], v[174:177], v[206:209], v[2:5]
	s_setprio 0
	s_barrier
	s_add_i32 s17, 0, 0x18000
	s_add_i32 s54, 0, 0x1c000
	v_add_u32_e32 v158, s17, v227
	v_add_u32_e32 v174, s54, v227
	ds_read_b128 v[146:149], v158
	ds_read_b128 v[150:153], v158 offset:1024
	ds_read_b128 v[154:157], v158 offset:2048
	ds_read_b128 v[158:161], v158 offset:3072
	ds_read_b128 v[162:165], v174
	ds_read_b128 v[166:169], v174 offset:1024
	ds_read_b128 v[170:173], v174 offset:2048
	ds_read_b128 v[174:177], v174 offset:3072
	s_add_u32 s50, s50, s8
	s_addc_u32 s51, s51, s9
	s_mov_b32 m0, s65
	v_lshl_add_u64 v[222:223], s[50:51], 0, v[130:131]
	ds_read_b128 v[178:181], v229 offset:32768
	ds_read_b128 v[182:185], v229 offset:33792
	ds_read_b128 v[186:189], v229 offset:34816
	ds_read_b128 v[190:193], v229 offset:35840
	ds_read_b128 v[194:197], v229 offset:36864
	ds_read_b128 v[198:201], v229 offset:37888
	ds_read_b128 v[202:205], v229 offset:38912
	ds_read_b128 v[206:209], v229 offset:39936
	global_load_lds_dwordx4 v[222:223], off
	v_lshl_add_u64 v[222:223], s[50:51], 0, v[134:135]
	s_mov_b32 m0, s86
	s_nop 0
	global_load_lds_dwordx4 v[222:223], off
	s_waitcnt vmcnt(8)
	s_waitcnt lgkmcnt(0)
	s_setprio 1
	s_waitcnt lgkmcnt(0)
	v_mfma_i32_16x16x64_i8 v[126:129], v[146:149], v[178:181], v[126:129]
	v_mfma_i32_16x16x64_i8 v[122:125], v[154:157], v[178:181], v[122:125]
	v_mfma_i32_16x16x64_i8 v[118:121], v[146:149], v[186:189], v[118:121]
	v_mfma_i32_16x16x64_i8 v[114:117], v[154:157], v[186:189], v[114:117]
	v_mfma_i32_16x16x64_i8 v[106:109], v[146:149], v[194:197], v[106:109]
	v_mfma_i32_16x16x64_i8 v[98:101], v[154:157], v[194:197], v[98:101]
	s_barrier
	v_mfma_i32_16x16x64_i8 v[90:93], v[146:149], v[202:205], v[90:93]
	v_mfma_i32_16x16x64_i8 v[82:85], v[154:157], v[202:205], v[82:85]
	v_mfma_i32_16x16x64_i8 v[126:129], v[150:153], v[182:185], v[126:129]
	v_mfma_i32_16x16x64_i8 v[122:125], v[158:161], v[182:185], v[122:125]
	v_mfma_i32_16x16x64_i8 v[118:121], v[150:153], v[190:193], v[118:121]
	v_mfma_i32_16x16x64_i8 v[114:117], v[158:161], v[190:193], v[114:117]
	v_mfma_i32_16x16x64_i8 v[106:109], v[150:153], v[198:201], v[106:109]
	v_mfma_i32_16x16x64_i8 v[98:101], v[158:161], v[198:201], v[98:101]
	v_mfma_i32_16x16x64_i8 v[90:93], v[150:153], v[206:209], v[90:93]
	v_mfma_i32_16x16x64_i8 v[82:85], v[158:161], v[206:209], v[82:85]
	s_setprio 0
	s_setprio 1
	v_mfma_i32_16x16x64_i8 v[110:113], v[162:165], v[178:181], v[110:113]
	v_mfma_i32_16x16x64_i8 v[102:105], v[170:173], v[178:181], v[102:105]
	v_mfma_i32_16x16x64_i8 v[94:97], v[162:165], v[186:189], v[94:97]
	v_mfma_i32_16x16x64_i8 v[86:89], v[170:173], v[186:189], v[86:89]
	v_mfma_i32_16x16x64_i8 v[78:81], v[162:165], v[194:197], v[78:81]
	v_mfma_i32_16x16x64_i8 v[74:77], v[170:173], v[194:197], v[74:77]
	v_mfma_i32_16x16x64_i8 v[70:73], v[162:165], v[202:205], v[70:73]
	v_mfma_i32_16x16x64_i8 v[66:69], v[170:173], v[202:205], v[66:69]
	v_mfma_i32_16x16x64_i8 v[110:113], v[166:169], v[182:185], v[110:113]
	v_mfma_i32_16x16x64_i8 v[102:105], v[174:177], v[182:185], v[102:105]
	v_mfma_i32_16x16x64_i8 v[94:97], v[166:169], v[190:193], v[94:97]
	v_mfma_i32_16x16x64_i8 v[86:89], v[174:177], v[190:193], v[86:89]
	v_mfma_i32_16x16x64_i8 v[78:81], v[166:169], v[198:201], v[78:81]
	v_mfma_i32_16x16x64_i8 v[74:77], v[174:177], v[198:201], v[74:77]
	v_mfma_i32_16x16x64_i8 v[70:73], v[166:169], v[206:209], v[70:73]
	v_mfma_i32_16x16x64_i8 v[66:69], v[174:177], v[206:209], v[66:69]
	s_setprio 0
	s_barrier
	s_add_i32 s17, s17, s62
	v_lshl_add_u64 v[210:211], v[210:211], 0, s[36:37]
	s_mov_b32 m0, s17
	ds_read_b128 v[178:181], v229 offset:49152
	ds_read_b128 v[182:185], v229 offset:50176
	ds_read_b128 v[186:189], v229 offset:51200
	ds_read_b128 v[190:193], v229 offset:52224
	ds_read_b128 v[194:197], v229 offset:53248
	ds_read_b128 v[198:201], v229 offset:54272
	ds_read_b128 v[202:205], v229 offset:55296
	ds_read_b128 v[206:209], v229 offset:56320
	global_load_lds_dwordx4 v[210:211], off
	v_lshl_add_u64 v[210:211], v[212:213], 0, s[36:37]
	s_add_i32 m0, s17, 0x2000
	s_add_i32 s17, s54, s62
	global_load_lds_dwordx4 v[210:211], off
	v_lshl_add_u64 v[210:211], v[214:215], 0, s[36:37]
	s_mov_b32 m0, s17
	s_nop 0
	global_load_lds_dwordx4 v[210:211], off
	v_lshl_add_u64 v[210:211], v[216:217], 0, s[36:37]
	s_add_i32 m0, s17, 0x2000
	s_nop 0
	global_load_lds_dwordx4 v[210:211], off
	v_lshl_add_u64 v[210:211], v[218:219], 0, s[36:37]
	s_mov_b32 m0, s95
	s_nop 0
	global_load_lds_dwordx4 v[210:211], off
	v_lshl_add_u64 v[210:211], v[220:221], 0, s[36:37]
	s_mov_b32 m0, s80
	s_nop 0
	global_load_lds_dwordx4 v[210:211], off
	s_waitcnt vmcnt(8)
	s_waitcnt lgkmcnt(0)
	s_setprio 1
	s_waitcnt lgkmcnt(0)
	v_mfma_i32_16x16x64_i8 v[62:65], v[146:149], v[178:181], v[62:65]
	v_mfma_i32_16x16x64_i8 v[58:61], v[154:157], v[178:181], v[58:61]
	v_mfma_i32_16x16x64_i8 v[54:57], v[146:149], v[186:189], v[54:57]
	v_mfma_i32_16x16x64_i8 v[50:53], v[154:157], v[186:189], v[50:53]
	v_mfma_i32_16x16x64_i8 v[42:45], v[146:149], v[194:197], v[42:45]
	v_mfma_i32_16x16x64_i8 v[34:37], v[154:157], v[194:197], v[34:37]
	s_barrier
	v_mfma_i32_16x16x64_i8 v[26:29], v[146:149], v[202:205], v[26:29]
	v_mfma_i32_16x16x64_i8 v[18:21], v[154:157], v[202:205], v[18:21]
	v_mfma_i32_16x16x64_i8 v[62:65], v[150:153], v[182:185], v[62:65]
	v_mfma_i32_16x16x64_i8 v[58:61], v[158:161], v[182:185], v[58:61]
	v_mfma_i32_16x16x64_i8 v[54:57], v[150:153], v[190:193], v[54:57]
	v_mfma_i32_16x16x64_i8 v[50:53], v[158:161], v[190:193], v[50:53]
	v_mfma_i32_16x16x64_i8 v[42:45], v[150:153], v[198:201], v[42:45]
	v_mfma_i32_16x16x64_i8 v[34:37], v[158:161], v[198:201], v[34:37]
	v_mfma_i32_16x16x64_i8 v[26:29], v[150:153], v[206:209], v[26:29]
	v_mfma_i32_16x16x64_i8 v[18:21], v[158:161], v[206:209], v[18:21]
	s_setprio 0
	s_setprio 1
	v_mfma_i32_16x16x64_i8 v[46:49], v[162:165], v[178:181], v[46:49]
	v_mfma_i32_16x16x64_i8 v[38:41], v[170:173], v[178:181], v[38:41]
	v_mfma_i32_16x16x64_i8 v[30:33], v[162:165], v[186:189], v[30:33]
	v_mfma_i32_16x16x64_i8 v[22:25], v[170:173], v[186:189], v[22:25]
	v_mfma_i32_16x16x64_i8 v[14:17], v[162:165], v[194:197], v[14:17]
	v_mfma_i32_16x16x64_i8 v[10:13], v[170:173], v[194:197], v[10:13]
	v_mfma_i32_16x16x64_i8 v[6:9], v[162:165], v[202:205], v[6:9]
	v_mfma_i32_16x16x64_i8 v[2:5], v[170:173], v[202:205], v[2:5]
	v_mfma_i32_16x16x64_i8 v[46:49], v[166:169], v[182:185], v[46:49]
	v_mfma_i32_16x16x64_i8 v[38:41], v[174:177], v[182:185], v[38:41]
	v_mfma_i32_16x16x64_i8 v[30:33], v[166:169], v[190:193], v[30:33]
	v_mfma_i32_16x16x64_i8 v[22:25], v[174:177], v[190:193], v[22:25]
	v_mfma_i32_16x16x64_i8 v[14:17], v[166:169], v[198:201], v[14:17]
	v_mfma_i32_16x16x64_i8 v[10:13], v[174:177], v[198:201], v[10:13]
	v_mfma_i32_16x16x64_i8 v[6:9], v[166:169], v[206:209], v[6:9]
	v_mfma_i32_16x16x64_i8 v[2:5], v[174:177], v[206:209], v[2:5]
	s_setprio 0
	s_barrier
	s_add_u32 s46, s46, 0x100
	s_addc_u32 s47, s47, 0
	s_add_u32 vcc_lo, vcc_lo, 0x100
	s_addc_u32 vcc_hi, vcc_hi, 0
	s_cmp_ge_i32 s16, s90
	s_mov_b32 s50, s16
	s_cbranch_scc0 .LBB0_895
	v_cvt_f32_i32_e32 v220, v126
	v_cvt_f32_i32_e32 v221, v127
	v_cvt_f32_i32_e32 v218, v128
	v_cvt_f32_i32_e32 v219, v129
	v_cvt_f32_i32_e32 v224, v122
	v_cvt_f32_i32_e32 v225, v123
	v_cvt_f32_i32_e32 v222, v124
	v_cvt_f32_i32_e32 v223, v125
	v_cvt_f32_i32_e32 v212, v110
	v_cvt_f32_i32_e32 v213, v111
	v_cvt_f32_i32_e32 v210, v112
	v_cvt_f32_i32_e32 v211, v113
	v_cvt_f32_i32_e32 v216, v102
	v_cvt_f32_i32_e32 v217, v103
	v_cvt_f32_i32_e32 v214, v104
	v_cvt_f32_i32_e32 v215, v105
	v_cvt_f32_i32_e32 v204, v118
	v_cvt_f32_i32_e32 v205, v119
	v_cvt_f32_i32_e32 v202, v120
	v_cvt_f32_i32_e32 v203, v121
	v_cvt_f32_i32_e32 v208, v114
	v_cvt_f32_i32_e32 v209, v115
	v_cvt_f32_i32_e32 v206, v116
	v_cvt_f32_i32_e32 v207, v117
	v_cvt_f32_i32_e32 v198, v94
	v_cvt_f32_i32_e32 v199, v95
	v_cvt_f32_i32_e32 v194, v96
	v_cvt_f32_i32_e32 v195, v97
	v_cvt_f32_i32_e32 v200, v86
	v_cvt_f32_i32_e32 v201, v87
	v_cvt_f32_i32_e32 v196, v88
	v_cvt_f32_i32_e32 v197, v89
	v_cvt_f32_i32_e32 v188, v106
	v_cvt_f32_i32_e32 v189, v107
	v_cvt_f32_i32_e32 v186, v108
	v_cvt_f32_i32_e32 v187, v109
	v_cvt_f32_i32_e32 v192, v98
	v_cvt_f32_i32_e32 v193, v99
	v_cvt_f32_i32_e32 v190, v100
	v_cvt_f32_i32_e32 v191, v101
	v_cvt_f32_i32_e32 v182, v78
	v_cvt_f32_i32_e32 v183, v79
	v_cvt_f32_i32_e32 v178, v80
	v_cvt_f32_i32_e32 v179, v81
	v_cvt_f32_i32_e32 v184, v74
	v_cvt_f32_i32_e32 v185, v75
	v_cvt_f32_i32_e32 v180, v76
	v_cvt_f32_i32_e32 v181, v77
	v_cvt_f32_i32_e32 v170, v90
	v_cvt_f32_i32_e32 v171, v91
	v_cvt_f32_i32_e32 v168, v92
	v_cvt_f32_i32_e32 v169, v93
	v_cvt_f32_i32_e32 v174, v82
	v_cvt_f32_i32_e32 v175, v83
	v_cvt_f32_i32_e32 v172, v84
	v_cvt_f32_i32_e32 v173, v85
	v_cvt_f32_i32_e32 v164, v70
	v_cvt_f32_i32_e32 v165, v71
	v_cvt_f32_i32_e32 v160, v72
	v_cvt_f32_i32_e32 v161, v73
	v_cvt_f32_i32_e32 v166, v66
	v_cvt_f32_i32_e32 v167, v67
	v_cvt_f32_i32_e32 v162, v68
	v_cvt_f32_i32_e32 v163, v69
	v_cvt_f32_i32_e32 v154, v62
	v_cvt_f32_i32_e32 v155, v63
	v_cvt_f32_i32_e32 v152, v64
	v_cvt_f32_i32_e32 v153, v65
	v_cvt_f32_i32_e32 v158, v58
	v_cvt_f32_i32_e32 v159, v59
	v_cvt_f32_i32_e32 v156, v60
	v_cvt_f32_i32_e32 v157, v61
	v_cvt_f32_i32_e32 v148, v46
	v_cvt_f32_i32_e32 v149, v47
	v_cvt_f32_i32_e32 v128, v48
	v_cvt_f32_i32_e32 v129, v49
	v_cvt_f32_i32_e32 v150, v38
	v_cvt_f32_i32_e32 v151, v39
	v_cvt_f32_i32_e32 v146, v40
	v_cvt_f32_i32_e32 v147, v41
	v_cvt_f32_i32_e32 v122, v54
	v_cvt_f32_i32_e32 v123, v55
	v_cvt_f32_i32_e32 v120, v56
	v_cvt_f32_i32_e32 v121, v57
	v_cvt_f32_i32_e32 v126, v50
	v_cvt_f32_i32_e32 v127, v51
	v_cvt_f32_i32_e32 v124, v52
	v_cvt_f32_i32_e32 v125, v53
	v_cvt_f32_i32_e32 v114, v30
	v_cvt_f32_i32_e32 v115, v31
	v_cvt_f32_i32_e32 v110, v32
	v_cvt_f32_i32_e32 v111, v33
	v_cvt_f32_i32_e32 v116, v22
	v_cvt_f32_i32_e32 v117, v23
	v_cvt_f32_i32_e32 v112, v24
	v_cvt_f32_i32_e32 v113, v25
	v_cvt_f32_i32_e32 v102, v42
	v_cvt_f32_i32_e32 v103, v43
	v_cvt_f32_i32_e32 v100, v44
	v_cvt_f32_i32_e32 v101, v45
	v_cvt_f32_i32_e32 v106, v34
	v_cvt_f32_i32_e32 v107, v35
	v_cvt_f32_i32_e32 v104, v36
	v_cvt_f32_i32_e32 v105, v37
	v_cvt_f32_i32_e32 v96, v14
	v_cvt_f32_i32_e32 v97, v15
	v_cvt_f32_i32_e32 v92, v16
	v_cvt_f32_i32_e32 v93, v17
	v_cvt_f32_i32_e32 v98, v10
	v_cvt_f32_i32_e32 v99, v11
	v_cvt_f32_i32_e32 v94, v12
	v_cvt_f32_i32_e32 v95, v13
	v_cvt_f32_i32_e32 v52, v26
	v_cvt_f32_i32_e32 v53, v27
	v_cvt_f32_i32_e32 v50, v28
	v_cvt_f32_i32_e32 v51, v29
	v_cvt_f32_i32_e32 v56, v18
	v_cvt_f32_i32_e32 v57, v19
	v_cvt_f32_i32_e32 v54, v20
	v_cvt_f32_i32_e32 v55, v21
	v_cvt_f32_i32_e32 v46, v6
	v_cvt_f32_i32_e32 v47, v7
	v_cvt_f32_i32_e32 v42, v8
	v_cvt_f32_i32_e32 v43, v9
	v_cvt_f32_i32_e32 v48, v2
	v_cvt_f32_i32_e32 v49, v3
	v_cvt_f32_i32_e32 v44, v4
	v_cvt_f32_i32_e32 v45, v5

.LBB0_1087:
	v_add_u32_e32 v138, s80, v188
	ds_read_b128 v[148:151], v138
	ds_read_b128 v[152:155], v138 offset:1024
	ds_read_b128 v[156:159], v138 offset:2048
	ds_read_b128 v[160:163], v138 offset:3072
	v_add_u32_e32 v138, s81, v188
	ds_read_b128 v[164:167], v138
	ds_read_b128 v[168:171], v138 offset:1024
	ds_read_b128 v[172:175], v138 offset:2048
	ds_read_b128 v[176:179], v138 offset:3072
	s_add_i32 s84, s34, 2
	s_add_u32 s85, s30, 0x80
	s_addc_u32 s35, s31, 0
	s_cmp_eq_u32 s64, s34
	s_cselect_b32 s34, s2, s85
	s_cselect_b32 s35, s3, s35
	s_cselect_b32 s87, s29, s39
	s_cselect_b32 s86, s28, s38
	v_lshl_add_u64 v[184:185], s[30:31], 0, v[140:141]
	s_add_i32 m0, s50, 0xc000
	ds_read_b128 v[180:183], v189
	ds_read_b128 v[190:193], v189 offset:1024
	ds_read_b128 v[194:197], v189 offset:2048
	ds_read_b128 v[198:201], v189 offset:3072
	ds_read_b128 v[202:205], v189 offset:4096
	ds_read_b128 v[206:209], v189 offset:5120
	ds_read_b128 v[210:213], v189 offset:6144
	ds_read_b128 v[214:217], v189 offset:7168
	global_load_lds_dwordx4 v[184:185], off
	v_lshl_add_u64 v[184:185], s[30:31], 0, v[142:143]
	s_add_i32 m0, s50, 0xe000
	s_nop 0
	global_load_lds_dwordx4 v[184:185], off
	s_waitcnt vmcnt(8)
	s_waitcnt lgkmcnt(0)
	s_setprio 1
	s_waitcnt lgkmcnt(0)
	v_mfma_i32_16x16x64_i8 v[126:129], v[148:151], v[180:183], v[126:129]
	v_mfma_i32_16x16x64_i8 v[122:125], v[156:159], v[180:183], v[122:125]
	v_mfma_i32_16x16x64_i8 v[118:121], v[148:151], v[194:197], v[118:121]
	v_mfma_i32_16x16x64_i8 v[114:117], v[156:159], v[194:197], v[114:117]
	v_mfma_i32_16x16x64_i8 v[106:109], v[148:151], v[202:205], v[106:109]
	v_mfma_i32_16x16x64_i8 v[98:101], v[156:159], v[202:205], v[98:101]
	s_barrier
	v_mfma_i32_16x16x64_i8 v[90:93], v[148:151], v[210:213], v[90:93]
	v_mfma_i32_16x16x64_i8 v[82:85], v[156:159], v[210:213], v[82:85]
	v_mfma_i32_16x16x64_i8 v[126:129], v[152:155], v[190:193], v[126:129]
	v_mfma_i32_16x16x64_i8 v[122:125], v[160:163], v[190:193], v[122:125]
	v_mfma_i32_16x16x64_i8 v[118:121], v[152:155], v[198:201], v[118:121]
	v_mfma_i32_16x16x64_i8 v[114:117], v[160:163], v[198:201], v[114:117]
	v_mfma_i32_16x16x64_i8 v[106:109], v[152:155], v[206:209], v[106:109]
	v_mfma_i32_16x16x64_i8 v[98:101], v[160:163], v[206:209], v[98:101]
	v_mfma_i32_16x16x64_i8 v[90:93], v[152:155], v[214:217], v[90:93]
	v_mfma_i32_16x16x64_i8 v[82:85], v[160:163], v[214:217], v[82:85]
	s_setprio 0
	s_setprio 1
	v_mfma_i32_16x16x64_i8 v[110:113], v[164:167], v[180:183], v[110:113]
	v_mfma_i32_16x16x64_i8 v[102:105], v[172:175], v[180:183], v[102:105]
	v_mfma_i32_16x16x64_i8 v[94:97], v[164:167], v[194:197], v[94:97]
	v_mfma_i32_16x16x64_i8 v[86:89], v[172:175], v[194:197], v[86:89]
	v_mfma_i32_16x16x64_i8 v[78:81], v[164:167], v[202:205], v[78:81]
	v_mfma_i32_16x16x64_i8 v[74:77], v[172:175], v[202:205], v[74:77]
	v_mfma_i32_16x16x64_i8 v[70:73], v[164:167], v[210:213], v[70:73]
	v_mfma_i32_16x16x64_i8 v[66:69], v[172:175], v[210:213], v[66:69]
	v_mfma_i32_16x16x64_i8 v[110:113], v[168:171], v[190:193], v[110:113]
	v_mfma_i32_16x16x64_i8 v[102:105], v[176:179], v[190:193], v[102:105]
	v_mfma_i32_16x16x64_i8 v[94:97], v[168:171], v[198:201], v[94:97]
	v_mfma_i32_16x16x64_i8 v[86:89], v[176:179], v[198:201], v[86:89]
	v_mfma_i32_16x16x64_i8 v[78:81], v[168:171], v[206:209], v[78:81]
	v_mfma_i32_16x16x64_i8 v[74:77], v[176:179], v[206:209], v[74:77]
	v_mfma_i32_16x16x64_i8 v[70:73], v[168:171], v[214:217], v[70:73]
	v_mfma_i32_16x16x64_i8 v[66:69], v[176:179], v[214:217], v[66:69]
	s_setprio 0
	s_barrier
	s_add_i32 s85, s80, s47
	v_lshl_add_u64 v[184:185], s[86:87], 0, v[132:133]
	s_mov_b32 m0, s85
	ds_read_b128 v[180:183], v189 offset:16384
	ds_read_b128 v[190:193], v189 offset:17408
	ds_read_b128 v[194:197], v189 offset:18432
	ds_read_b128 v[198:201], v189 offset:19456
	ds_read_b128 v[202:205], v189 offset:20480
	ds_read_b128 v[206:209], v189 offset:21504
	ds_read_b128 v[210:213], v189 offset:22528
	ds_read_b128 v[214:217], v189 offset:23552
	global_load_lds_dwordx4 v[184:185], off
	s_add_i32 m0, s85, 0x2000
	v_lshl_add_u64 v[218:219], s[86:87], 0, v[136:137]
	s_add_u32 s86, s86, s6
	s_addc_u32 s87, s87, s7
	s_add_i32 s85, s81, s47
	global_load_lds_dwordx4 v[218:219], off
	v_lshl_add_u64 v[220:221], s[86:87], 0, v[132:133]
	s_mov_b32 m0, s85
	v_lshl_add_u64 v[222:223], s[86:87], 0, v[136:137]
	global_load_lds_dwordx4 v[220:221], off
	s_add_i32 m0, s85, 0x2000
	v_lshl_add_u64 v[224:225], s[34:35], 0, v[130:131]
	global_load_lds_dwordx4 v[222:223], off
	s_mov_b32 m0, s50
	v_lshl_add_u64 v[226:227], s[34:35], 0, v[134:135]
	global_load_lds_dwordx4 v[224:225], off
	s_mov_b32 m0, s51
	s_nop 0
	global_load_lds_dwordx4 v[226:227], off
	s_waitcnt vmcnt(8)
	s_waitcnt lgkmcnt(0)
	s_setprio 1
	s_waitcnt lgkmcnt(0)
	v_mfma_i32_16x16x64_i8 v[62:65], v[148:151], v[180:183], v[62:65]
	v_mfma_i32_16x16x64_i8 v[58:61], v[156:159], v[180:183], v[58:61]
	v_mfma_i32_16x16x64_i8 v[54:57], v[148:151], v[194:197], v[54:57]
	v_mfma_i32_16x16x64_i8 v[50:53], v[156:159], v[194:197], v[50:53]
	v_mfma_i32_16x16x64_i8 v[42:45], v[148:151], v[202:205], v[42:45]
	v_mfma_i32_16x16x64_i8 v[34:37], v[156:159], v[202:205], v[34:37]
	s_barrier
	v_mfma_i32_16x16x64_i8 v[26:29], v[148:151], v[210:213], v[26:29]
	v_mfma_i32_16x16x64_i8 v[18:21], v[156:159], v[210:213], v[18:21]
	v_mfma_i32_16x16x64_i8 v[62:65], v[152:155], v[190:193], v[62:65]
	v_mfma_i32_16x16x64_i8 v[58:61], v[160:163], v[190:193], v[58:61]
	v_mfma_i32_16x16x64_i8 v[54:57], v[152:155], v[198:201], v[54:57]
	v_mfma_i32_16x16x64_i8 v[50:53], v[160:163], v[198:201], v[50:53]
	v_mfma_i32_16x16x64_i8 v[42:45], v[152:155], v[206:209], v[42:45]
	v_mfma_i32_16x16x64_i8 v[34:37], v[160:163], v[206:209], v[34:37]
	v_mfma_i32_16x16x64_i8 v[26:29], v[152:155], v[214:217], v[26:29]
	v_mfma_i32_16x16x64_i8 v[18:21], v[160:163], v[214:217], v[18:21]
	s_setprio 0
	s_setprio 1
	v_mfma_i32_16x16x64_i8 v[46:49], v[164:167], v[180:183], v[46:49]
	v_mfma_i32_16x16x64_i8 v[38:41], v[172:175], v[180:183], v[38:41]
	v_mfma_i32_16x16x64_i8 v[30:33], v[164:167], v[194:197], v[30:33]
	v_mfma_i32_16x16x64_i8 v[22:25], v[172:175], v[194:197], v[22:25]
	v_mfma_i32_16x16x64_i8 v[14:17], v[164:167], v[202:205], v[14:17]
	v_mfma_i32_16x16x64_i8 v[10:13], v[172:175], v[202:205], v[10:13]
	v_mfma_i32_16x16x64_i8 v[6:9], v[164:167], v[210:213], v[6:9]
	v_mfma_i32_16x16x64_i8 v[2:5], v[172:175], v[210:213], v[2:5]
	v_mfma_i32_16x16x64_i8 v[46:49], v[168:171], v[190:193], v[46:49]
	v_mfma_i32_16x16x64_i8 v[38:41], v[176:179], v[190:193], v[38:41]
	v_mfma_i32_16x16x64_i8 v[30:33], v[168:171], v[198:201], v[30:33]
	v_mfma_i32_16x16x64_i8 v[22:25], v[176:179], v[198:201], v[22:25]
	v_mfma_i32_16x16x64_i8 v[14:17], v[168:171], v[206:209], v[14:17]
	v_mfma_i32_16x16x64_i8 v[10:13], v[176:179], v[206:209], v[10:13]
	v_mfma_i32_16x16x64_i8 v[6:9], v[168:171], v[214:217], v[6:9]
	v_mfma_i32_16x16x64_i8 v[2:5], v[176:179], v[214:217], v[2:5]
	s_setprio 0
	s_barrier
	s_add_i32 s85, 0, 0x18000
	v_add_u32_e32 v138, s85, v188
	s_add_i32 s86, 0, 0x1c000
	ds_read_b128 v[148:151], v138
	ds_read_b128 v[152:155], v138 offset:1024
	ds_read_b128 v[156:159], v138 offset:2048
	ds_read_b128 v[160:163], v138 offset:3072
	v_add_u32_e32 v138, s86, v188
	ds_read_b128 v[164:167], v138
	ds_read_b128 v[168:171], v138 offset:1024
	ds_read_b128 v[172:175], v138 offset:2048
	ds_read_b128 v[176:179], v138 offset:3072
	s_add_u32 s34, s34, s6
	s_addc_u32 s35, s35, s7
	s_mov_b32 m0, s54
	v_lshl_add_u64 v[228:229], s[34:35], 0, v[130:131]
	ds_read_b128 v[180:183], v189 offset:32768
	ds_read_b128 v[190:193], v189 offset:33792
	ds_read_b128 v[194:197], v189 offset:34816
	ds_read_b128 v[198:201], v189 offset:35840
	ds_read_b128 v[202:205], v189 offset:36864
	ds_read_b128 v[206:209], v189 offset:37888
	ds_read_b128 v[210:213], v189 offset:38912
	ds_read_b128 v[214:217], v189 offset:39936
	global_load_lds_dwordx4 v[228:229], off
	v_lshl_add_u64 v[228:229], s[34:35], 0, v[134:135]
	s_mov_b32 m0, s55
	s_nop 0
	global_load_lds_dwordx4 v[228:229], off
	s_waitcnt vmcnt(8)
	s_waitcnt lgkmcnt(0)
	s_setprio 1
	s_waitcnt lgkmcnt(0)
	v_mfma_i32_16x16x64_i8 v[126:129], v[148:151], v[180:183], v[126:129]
	v_mfma_i32_16x16x64_i8 v[122:125], v[156:159], v[180:183], v[122:125]
	v_mfma_i32_16x16x64_i8 v[118:121], v[148:151], v[194:197], v[118:121]
	v_mfma_i32_16x16x64_i8 v[114:117], v[156:159], v[194:197], v[114:117]
	v_mfma_i32_16x16x64_i8 v[106:109], v[148:151], v[202:205], v[106:109]
	v_mfma_i32_16x16x64_i8 v[98:101], v[156:159], v[202:205], v[98:101]
	s_barrier
	v_mfma_i32_16x16x64_i8 v[90:93], v[148:151], v[210:213], v[90:93]
	v_mfma_i32_16x16x64_i8 v[82:85], v[156:159], v[210:213], v[82:85]
	v_mfma_i32_16x16x64_i8 v[126:129], v[152:155], v[190:193], v[126:129]
	v_mfma_i32_16x16x64_i8 v[122:125], v[160:163], v[190:193], v[122:125]
	v_mfma_i32_16x16x64_i8 v[118:121], v[152:155], v[198:201], v[118:121]
	v_mfma_i32_16x16x64_i8 v[114:117], v[160:163], v[198:201], v[114:117]
	v_mfma_i32_16x16x64_i8 v[106:109], v[152:155], v[206:209], v[106:109]
	v_mfma_i32_16x16x64_i8 v[98:101], v[160:163], v[206:209], v[98:101]
	v_mfma_i32_16x16x64_i8 v[90:93], v[152:155], v[214:217], v[90:93]
	v_mfma_i32_16x16x64_i8 v[82:85], v[160:163], v[214:217], v[82:85]
	s_setprio 0
	s_setprio 1
	v_mfma_i32_16x16x64_i8 v[110:113], v[164:167], v[180:183], v[110:113]
	v_mfma_i32_16x16x64_i8 v[102:105], v[172:175], v[180:183], v[102:105]
	v_mfma_i32_16x16x64_i8 v[94:97], v[164:167], v[194:197], v[94:97]
	v_mfma_i32_16x16x64_i8 v[86:89], v[172:175], v[194:197], v[86:89]
	v_mfma_i32_16x16x64_i8 v[78:81], v[164:167], v[202:205], v[78:81]
	v_mfma_i32_16x16x64_i8 v[74:77], v[172:175], v[202:205], v[74:77]
	v_mfma_i32_16x16x64_i8 v[70:73], v[164:167], v[210:213], v[70:73]
	v_mfma_i32_16x16x64_i8 v[66:69], v[172:175], v[210:213], v[66:69]
	v_mfma_i32_16x16x64_i8 v[110:113], v[168:171], v[190:193], v[110:113]
	v_mfma_i32_16x16x64_i8 v[102:105], v[176:179], v[190:193], v[102:105]
	v_mfma_i32_16x16x64_i8 v[94:97], v[168:171], v[198:201], v[94:97]
	v_mfma_i32_16x16x64_i8 v[86:89], v[176:179], v[198:201], v[86:89]
	v_mfma_i32_16x16x64_i8 v[78:81], v[168:171], v[206:209], v[78:81]
	v_mfma_i32_16x16x64_i8 v[74:77], v[176:179], v[206:209], v[74:77]
	v_mfma_i32_16x16x64_i8 v[70:73], v[168:171], v[214:217], v[70:73]
	v_mfma_i32_16x16x64_i8 v[66:69], v[176:179], v[214:217], v[66:69]
	s_setprio 0
	s_barrier
	s_add_i32 s34, s85, s47
	v_lshl_add_u64 v[184:185], v[184:185], 0, s[22:23]
	s_mov_b32 m0, s34
	ds_read_b128 v[180:183], v189 offset:49152
	ds_read_b128 v[190:193], v189 offset:50176
	ds_read_b128 v[194:197], v189 offset:51200
	ds_read_b128 v[198:201], v189 offset:52224
	ds_read_b128 v[202:205], v189 offset:53248
	ds_read_b128 v[206:209], v189 offset:54272
	ds_read_b128 v[210:213], v189 offset:55296
	ds_read_b128 v[214:217], v189 offset:56320
	global_load_lds_dwordx4 v[184:185], off
	v_lshl_add_u64 v[184:185], v[218:219], 0, s[22:23]
	s_add_i32 m0, s34, 0x2000
	s_add_i32 s34, s86, s47
	global_load_lds_dwordx4 v[184:185], off
	v_lshl_add_u64 v[184:185], v[220:221], 0, s[22:23]
	s_mov_b32 m0, s34
	s_nop 0
	global_load_lds_dwordx4 v[184:185], off
	v_lshl_add_u64 v[184:185], v[222:223], 0, s[22:23]
	s_add_i32 m0, s34, 0x2000
	s_nop 0
	global_load_lds_dwordx4 v[184:185], off
	v_lshl_add_u64 v[184:185], v[224:225], 0, s[22:23]
	s_mov_b32 m0, s59
	s_nop 0
	global_load_lds_dwordx4 v[184:185], off
	v_lshl_add_u64 v[184:185], v[226:227], 0, s[22:23]
	s_mov_b32 m0, s60
	s_nop 0
	global_load_lds_dwordx4 v[184:185], off
	s_waitcnt vmcnt(8)
	s_waitcnt lgkmcnt(0)
	s_setprio 1
	s_waitcnt lgkmcnt(0)
	v_mfma_i32_16x16x64_i8 v[62:65], v[148:151], v[180:183], v[62:65]
	v_mfma_i32_16x16x64_i8 v[58:61], v[156:159], v[180:183], v[58:61]
	v_mfma_i32_16x16x64_i8 v[54:57], v[148:151], v[194:197], v[54:57]
	v_mfma_i32_16x16x64_i8 v[50:53], v[156:159], v[194:197], v[50:53]
	v_mfma_i32_16x16x64_i8 v[42:45], v[148:151], v[202:205], v[42:45]
	v_mfma_i32_16x16x64_i8 v[34:37], v[156:159], v[202:205], v[34:37]
	s_barrier
	v_mfma_i32_16x16x64_i8 v[26:29], v[148:151], v[210:213], v[26:29]
	v_mfma_i32_16x16x64_i8 v[18:21], v[156:159], v[210:213], v[18:21]
	v_mfma_i32_16x16x64_i8 v[62:65], v[152:155], v[190:193], v[62:65]
	v_mfma_i32_16x16x64_i8 v[58:61], v[160:163], v[190:193], v[58:61]
	v_mfma_i32_16x16x64_i8 v[54:57], v[152:155], v[198:201], v[54:57]
	v_mfma_i32_16x16x64_i8 v[50:53], v[160:163], v[198:201], v[50:53]
	v_mfma_i32_16x16x64_i8 v[42:45], v[152:155], v[206:209], v[42:45]
	v_mfma_i32_16x16x64_i8 v[34:37], v[160:163], v[206:209], v[34:37]
	v_mfma_i32_16x16x64_i8 v[26:29], v[152:155], v[214:217], v[26:29]
	v_mfma_i32_16x16x64_i8 v[18:21], v[160:163], v[214:217], v[18:21]
	s_setprio 0
	s_setprio 1
	v_mfma_i32_16x16x64_i8 v[46:49], v[164:167], v[180:183], v[46:49]
	v_mfma_i32_16x16x64_i8 v[38:41], v[172:175], v[180:183], v[38:41]
	v_mfma_i32_16x16x64_i8 v[30:33], v[164:167], v[194:197], v[30:33]
	v_mfma_i32_16x16x64_i8 v[22:25], v[172:175], v[194:197], v[22:25]
	v_mfma_i32_16x16x64_i8 v[14:17], v[164:167], v[202:205], v[14:17]
	v_mfma_i32_16x16x64_i8 v[10:13], v[172:175], v[202:205], v[10:13]
	v_mfma_i32_16x16x64_i8 v[6:9], v[164:167], v[210:213], v[6:9]
	v_mfma_i32_16x16x64_i8 v[2:5], v[172:175], v[210:213], v[2:5]
	v_mfma_i32_16x16x64_i8 v[46:49], v[168:171], v[190:193], v[46:49]
	v_mfma_i32_16x16x64_i8 v[38:41], v[176:179], v[190:193], v[38:41]
	v_mfma_i32_16x16x64_i8 v[30:33], v[168:171], v[198:201], v[30:33]
	v_mfma_i32_16x16x64_i8 v[22:25], v[176:179], v[198:201], v[22:25]
	v_mfma_i32_16x16x64_i8 v[14:17], v[168:171], v[206:209], v[14:17]
	v_mfma_i32_16x16x64_i8 v[10:13], v[176:179], v[206:209], v[10:13]
	v_mfma_i32_16x16x64_i8 v[6:9], v[168:171], v[214:217], v[6:9]
	v_mfma_i32_16x16x64_i8 v[2:5], v[176:179], v[214:217], v[2:5]
	s_setprio 0
	s_barrier
	s_add_u32 s30, s30, 0x100
	s_addc_u32 s31, s31, 0
	s_add_u32 s38, s38, 0x100
	s_addc_u32 s39, s39, 0
	s_cmp_ge_i32 s84, s61
	s_mov_b32 s34, s84
	s_cbranch_scc0 .LBB0_1087
	v_cvt_f32_i32_e32 v172, v126
	v_cvt_f32_i32_e32 v173, v127
	v_cvt_f32_i32_e32 v170, v128
	v_cvt_f32_i32_e32 v171, v129
	v_cvt_f32_i32_e32 v174, v122
	v_cvt_f32_i32_e32 v175, v123
	v_cvt_f32_i32_e32 v176, v124
	v_cvt_f32_i32_e32 v177, v125
	v_cvt_f32_i32_e32 v180, v110
	v_cvt_f32_i32_e32 v181, v111
	v_cvt_f32_i32_e32 v182, v112
	v_cvt_f32_i32_e32 v183, v113
	v_cvt_f32_i32_e32 v178, v102
	v_cvt_f32_i32_e32 v179, v103
	v_cvt_f32_i32_e32 v184, v104
	v_cvt_f32_i32_e32 v185, v105
	v_cvt_f32_i32_e32 v152, v118
	v_cvt_f32_i32_e32 v153, v119
	v_cvt_f32_i32_e32 v154, v120
	v_cvt_f32_i32_e32 v155, v121
	v_cvt_f32_i32_e32 v156, v114
	v_cvt_f32_i32_e32 v157, v115
	v_cvt_f32_i32_e32 v158, v116
	v_cvt_f32_i32_e32 v159, v117
	v_cvt_f32_i32_e32 v160, v94
	v_cvt_f32_i32_e32 v161, v95
	v_cvt_f32_i32_e32 v162, v96
	v_cvt_f32_i32_e32 v163, v97
	v_cvt_f32_i32_e32 v164, v86
	v_cvt_f32_i32_e32 v165, v87
	v_cvt_f32_i32_e32 v166, v88
	v_cvt_f32_i32_e32 v167, v89
	v_cvt_f32_i32_e32 v118, v106
	v_cvt_f32_i32_e32 v119, v107
	v_cvt_f32_i32_e32 v120, v108
	v_cvt_f32_i32_e32 v121, v109
	v_cvt_f32_i32_e32 v122, v98
	v_cvt_f32_i32_e32 v123, v99
	v_cvt_f32_i32_e32 v124, v100
	v_cvt_f32_i32_e32 v125, v101
	v_cvt_f32_i32_e32 v126, v78
	v_cvt_f32_i32_e32 v127, v79
	v_cvt_f32_i32_e32 v128, v80
	v_cvt_f32_i32_e32 v129, v81
	v_cvt_f32_i32_e32 v148, v74
	v_cvt_f32_i32_e32 v149, v75
	v_cvt_f32_i32_e32 v150, v76
	v_cvt_f32_i32_e32 v151, v77
	v_cvt_f32_i32_e32 v102, v90
	v_cvt_f32_i32_e32 v103, v91
	v_cvt_f32_i32_e32 v104, v92
	v_cvt_f32_i32_e32 v105, v93
	v_cvt_f32_i32_e32 v106, v82
	v_cvt_f32_i32_e32 v107, v83
	v_cvt_f32_i32_e32 v108, v84
	v_cvt_f32_i32_e32 v109, v85
	v_cvt_f32_i32_e32 v110, v70
	v_cvt_f32_i32_e32 v111, v71
	v_cvt_f32_i32_e32 v112, v72
	v_cvt_f32_i32_e32 v113, v73
	v_cvt_f32_i32_e32 v114, v66
	v_cvt_f32_i32_e32 v115, v67
	v_cvt_f32_i32_e32 v116, v68
	v_cvt_f32_i32_e32 v117, v69
	v_cvt_f32_i32_e32 v82, v62
	v_cvt_f32_i32_e32 v83, v63
	v_cvt_f32_i32_e32 v84, v64
	v_cvt_f32_i32_e32 v85, v65
	v_cvt_f32_i32_e32 v86, v58
	v_cvt_f32_i32_e32 v87, v59
	v_cvt_f32_i32_e32 v88, v60
	v_cvt_f32_i32_e32 v89, v61
	v_cvt_f32_i32_e32 v92, v46
	v_cvt_f32_i32_e32 v93, v47
	v_cvt_f32_i32_e32 v94, v48
	v_cvt_f32_i32_e32 v95, v49
	v_cvt_f32_i32_e32 v96, v38
	v_cvt_f32_i32_e32 v97, v39
	v_cvt_f32_i32_e32 v98, v40
	v_cvt_f32_i32_e32 v99, v41
	v_cvt_f32_i32_e32 v66, v54
	v_cvt_f32_i32_e32 v67, v55
	v_cvt_f32_i32_e32 v68, v56
	v_cvt_f32_i32_e32 v69, v57
	v_cvt_f32_i32_e32 v70, v50
	v_cvt_f32_i32_e32 v71, v51
	v_cvt_f32_i32_e32 v72, v52
	v_cvt_f32_i32_e32 v73, v53
	v_cvt_f32_i32_e32 v74, v30
	v_cvt_f32_i32_e32 v75, v31
	v_cvt_f32_i32_e32 v76, v32
	v_cvt_f32_i32_e32 v77, v33
	v_cvt_f32_i32_e32 v78, v22
	v_cvt_f32_i32_e32 v79, v23
	v_cvt_f32_i32_e32 v80, v24
	v_cvt_f32_i32_e32 v81, v25
	v_cvt_f32_i32_e32 v50, v42
	v_cvt_f32_i32_e32 v51, v43
	v_cvt_f32_i32_e32 v52, v44
	v_cvt_f32_i32_e32 v53, v45
	v_cvt_f32_i32_e32 v54, v34
	v_cvt_f32_i32_e32 v55, v35
	v_cvt_f32_i32_e32 v56, v36
	v_cvt_f32_i32_e32 v57, v37
	v_cvt_f32_i32_e32 v58, v14
	v_cvt_f32_i32_e32 v59, v15
	v_cvt_f32_i32_e32 v60, v16
	v_cvt_f32_i32_e32 v61, v17
	v_cvt_f32_i32_e32 v62, v10
	v_cvt_f32_i32_e32 v63, v11
	v_cvt_f32_i32_e32 v64, v12
	v_cvt_f32_i32_e32 v65, v13
	v_cvt_f32_i32_e32 v34, v26
	v_cvt_f32_i32_e32 v35, v27
	v_cvt_f32_i32_e32 v36, v28
	v_cvt_f32_i32_e32 v37, v29
	v_cvt_f32_i32_e32 v38, v18
	v_cvt_f32_i32_e32 v39, v19
	v_cvt_f32_i32_e32 v40, v20
	v_cvt_f32_i32_e32 v41, v21
	v_cvt_f32_i32_e32 v42, v6
	v_cvt_f32_i32_e32 v43, v7
	v_cvt_f32_i32_e32 v44, v8
	v_cvt_f32_i32_e32 v45, v9
	v_cvt_f32_i32_e32 v46, v2
	v_cvt_f32_i32_e32 v47, v3
	v_cvt_f32_i32_e32 v48, v4
	v_cvt_f32_i32_e32 v49, v5

.LBB0_1170:
	s_waitcnt lgkmcnt(0)
	ds_read_b128 v[114:117], v209
	ds_read_b128 v[118:121], v209 offset:1024
	ds_read_b128 v[122:125], v209 offset:2048
	ds_read_b128 v[126:129], v209 offset:3072
	ds_read_b128 v[146:149], v210
	ds_read_b128 v[150:153], v210 offset:1024
	ds_read_b128 v[154:157], v210 offset:2048
	ds_read_b128 v[158:161], v210 offset:3072
	s_add_i32 s92, s42, 2
	s_add_u32 s43, s38, 0x4000
	s_addc_u32 s44, s39, 0
	s_cmp_eq_u32 s81, s42
	s_cselect_b32 s45, s5, s44
	s_cselect_b32 s44, s4, s43
	s_cselect_b32 s94, s36, s90
	s_cselect_b32 s95, s37, s91
	s_add_u32 s42, s44, 0x8000
	s_addc_u32 s43, s45, 0
	v_lshl_add_u64 v[218:219], s[38:39], 0, v[170:171]
	s_add_i32 m0, s55, 0xc000
	ds_read_b128 v[178:181], v211
	ds_read_b128 v[182:185], v211 offset:1024
	ds_read_b128 v[186:189], v211 offset:2048
	ds_read_b128 v[190:193], v211 offset:3072
	ds_read_b128 v[194:197], v211 offset:4096
	ds_read_b128 v[198:201], v211 offset:5120
	ds_read_b128 v[202:205], v211 offset:6144
	ds_read_b128 v[214:217], v211 offset:7168
	global_load_lds_dwordx4 v[218:219], off
	v_lshl_add_u64 v[218:219], s[38:39], 0, v[172:173]
	s_add_i32 m0, s55, 0xe000
	s_nop 0
	global_load_lds_dwordx4 v[218:219], off
	s_waitcnt vmcnt(8)
	s_waitcnt lgkmcnt(0)
	s_setprio 1
	s_waitcnt lgkmcnt(0)
	v_mfma_f32_16x16x32_bf16 v[142:145], v[114:117], v[178:181], v[142:145]
	v_mfma_f32_16x16x32_bf16 v[138:141], v[122:125], v[178:181], v[138:141]
	v_mfma_f32_16x16x32_bf16 v[110:113], v[114:117], v[186:189], v[110:113]
	v_mfma_f32_16x16x32_bf16 v[106:109], v[122:125], v[186:189], v[106:109]
	v_mfma_f32_16x16x32_bf16 v[94:97], v[114:117], v[194:197], v[94:97]
	v_mfma_f32_16x16x32_bf16 v[90:93], v[122:125], v[194:197], v[90:93]
	s_barrier
	v_mfma_f32_16x16x32_bf16 v[78:81], v[114:117], v[202:205], v[78:81]
	v_mfma_f32_16x16x32_bf16 v[74:77], v[122:125], v[202:205], v[74:77]
	v_mfma_f32_16x16x32_bf16 v[142:145], v[118:121], v[182:185], v[142:145]
	v_mfma_f32_16x16x32_bf16 v[138:141], v[126:129], v[182:185], v[138:141]
	v_mfma_f32_16x16x32_bf16 v[110:113], v[118:121], v[190:193], v[110:113]
	v_mfma_f32_16x16x32_bf16 v[106:109], v[126:129], v[190:193], v[106:109]
	v_mfma_f32_16x16x32_bf16 v[94:97], v[118:121], v[198:201], v[94:97]
	v_mfma_f32_16x16x32_bf16 v[90:93], v[126:129], v[198:201], v[90:93]
	v_mfma_f32_16x16x32_bf16 v[78:81], v[118:121], v[214:217], v[78:81]
	v_mfma_f32_16x16x32_bf16 v[74:77], v[126:129], v[214:217], v[74:77]
	s_setprio 0
	s_setprio 1
	v_mfma_f32_16x16x32_bf16 v[134:137], v[146:149], v[178:181], v[134:137]
	v_mfma_f32_16x16x32_bf16 v[130:133], v[154:157], v[178:181], v[130:133]
	v_mfma_f32_16x16x32_bf16 v[102:105], v[146:149], v[186:189], v[102:105]
	v_mfma_f32_16x16x32_bf16 v[98:101], v[154:157], v[186:189], v[98:101]
	v_mfma_f32_16x16x32_bf16 v[86:89], v[146:149], v[194:197], v[86:89]
	v_mfma_f32_16x16x32_bf16 v[82:85], v[154:157], v[194:197], v[82:85]
	v_mfma_f32_16x16x32_bf16 v[70:73], v[146:149], v[202:205], v[70:73]
	v_mfma_f32_16x16x32_bf16 v[66:69], v[154:157], v[202:205], v[66:69]
	v_mfma_f32_16x16x32_bf16 v[134:137], v[150:153], v[182:185], v[134:137]
	v_mfma_f32_16x16x32_bf16 v[130:133], v[158:161], v[182:185], v[130:133]
	v_mfma_f32_16x16x32_bf16 v[102:105], v[150:153], v[190:193], v[102:105]
	v_mfma_f32_16x16x32_bf16 v[98:101], v[158:161], v[190:193], v[98:101]
	v_mfma_f32_16x16x32_bf16 v[86:89], v[150:153], v[198:201], v[86:89]
	v_mfma_f32_16x16x32_bf16 v[82:85], v[158:161], v[198:201], v[82:85]
	v_mfma_f32_16x16x32_bf16 v[70:73], v[150:153], v[214:217], v[70:73]
	v_mfma_f32_16x16x32_bf16 v[66:69], v[158:161], v[214:217], v[66:69]
	s_setprio 0
	s_barrier
	s_add_i32 s93, s84, s54
	v_lshl_add_u64 v[218:219], s[94:95], 0, v[164:165]
	s_mov_b32 m0, s93
	ds_read_b128 v[178:181], v211 offset:16384
	ds_read_b128 v[182:185], v211 offset:17408
	ds_read_b128 v[186:189], v211 offset:18432
	ds_read_b128 v[190:193], v211 offset:19456
	ds_read_b128 v[194:197], v211 offset:20480
	ds_read_b128 v[198:201], v211 offset:21504
	ds_read_b128 v[202:205], v211 offset:22528
	ds_read_b128 v[214:217], v211 offset:23552
	global_load_lds_dwordx4 v[218:219], off
	s_add_i32 m0, s93, 0x2000
	v_lshl_add_u64 v[220:221], s[94:95], 0, v[168:169]
	s_add_u32 s94, s94, s8
	s_addc_u32 s95, s95, s9
	s_add_i32 s93, s85, s54
	global_load_lds_dwordx4 v[220:221], off
	v_lshl_add_u64 v[222:223], s[94:95], 0, v[164:165]
	s_mov_b32 m0, s93
	v_lshl_add_u64 v[224:225], s[94:95], 0, v[168:169]
	global_load_lds_dwordx4 v[222:223], off
	s_add_i32 m0, s93, 0x2000
	v_lshl_add_u64 v[226:227], s[44:45], 0, v[162:163]
	global_load_lds_dwordx4 v[224:225], off
	s_mov_b32 m0, s55
	s_nop 0
	global_load_lds_dwordx4 v[226:227], off
	v_lshl_add_u64 v[226:227], s[44:45], 0, v[166:167]
	s_mov_b32 m0, s56
	s_nop 0
	global_load_lds_dwordx4 v[226:227], off
	s_waitcnt vmcnt(8)
	s_waitcnt lgkmcnt(0)
	s_setprio 1
	s_waitcnt lgkmcnt(0)
	v_mfma_f32_16x16x32_bf16 v[62:65], v[114:117], v[178:181], v[62:65]
	v_mfma_f32_16x16x32_bf16 v[58:61], v[122:125], v[178:181], v[58:61]
	v_mfma_f32_16x16x32_bf16 v[46:49], v[114:117], v[186:189], v[46:49]
	v_mfma_f32_16x16x32_bf16 v[42:45], v[122:125], v[186:189], v[42:45]
	v_mfma_f32_16x16x32_bf16 v[30:33], v[114:117], v[194:197], v[30:33]
	v_mfma_f32_16x16x32_bf16 v[26:29], v[122:125], v[194:197], v[26:29]
	s_barrier
	v_mfma_f32_16x16x32_bf16 v[14:17], v[114:117], v[202:205], v[14:17]
	v_mfma_f32_16x16x32_bf16 v[10:13], v[122:125], v[202:205], v[10:13]
	v_mfma_f32_16x16x32_bf16 v[62:65], v[118:121], v[182:185], v[62:65]
	v_mfma_f32_16x16x32_bf16 v[58:61], v[126:129], v[182:185], v[58:61]
	v_mfma_f32_16x16x32_bf16 v[46:49], v[118:121], v[190:193], v[46:49]
	v_mfma_f32_16x16x32_bf16 v[42:45], v[126:129], v[190:193], v[42:45]
	v_mfma_f32_16x16x32_bf16 v[30:33], v[118:121], v[198:201], v[30:33]
	v_mfma_f32_16x16x32_bf16 v[26:29], v[126:129], v[198:201], v[26:29]
	v_mfma_f32_16x16x32_bf16 v[14:17], v[118:121], v[214:217], v[14:17]
	v_mfma_f32_16x16x32_bf16 v[10:13], v[126:129], v[214:217], v[10:13]
	s_setprio 0
	s_setprio 1
	v_mfma_f32_16x16x32_bf16 v[54:57], v[146:149], v[178:181], v[54:57]
	v_mfma_f32_16x16x32_bf16 v[50:53], v[154:157], v[178:181], v[50:53]
	v_mfma_f32_16x16x32_bf16 v[38:41], v[146:149], v[186:189], v[38:41]
	v_mfma_f32_16x16x32_bf16 v[34:37], v[154:157], v[186:189], v[34:37]
	v_mfma_f32_16x16x32_bf16 v[22:25], v[146:149], v[194:197], v[22:25]
	v_mfma_f32_16x16x32_bf16 v[18:21], v[154:157], v[194:197], v[18:21]
	v_mfma_f32_16x16x32_bf16 v[6:9], v[146:149], v[202:205], v[6:9]
	v_mfma_f32_16x16x32_bf16 v[2:5], v[154:157], v[202:205], v[2:5]
	v_mfma_f32_16x16x32_bf16 v[54:57], v[150:153], v[182:185], v[54:57]
	v_mfma_f32_16x16x32_bf16 v[50:53], v[158:161], v[182:185], v[50:53]
	v_mfma_f32_16x16x32_bf16 v[38:41], v[150:153], v[190:193], v[38:41]
	v_mfma_f32_16x16x32_bf16 v[34:37], v[158:161], v[190:193], v[34:37]
	v_mfma_f32_16x16x32_bf16 v[22:25], v[150:153], v[198:201], v[22:25]
	v_mfma_f32_16x16x32_bf16 v[18:21], v[158:161], v[198:201], v[18:21]
	v_mfma_f32_16x16x32_bf16 v[6:9], v[150:153], v[214:217], v[6:9]
	v_mfma_f32_16x16x32_bf16 v[2:5], v[158:161], v[214:217], v[2:5]
	s_setprio 0
	s_barrier
	s_add_i32 s93, 0, 0x18000
	s_add_i32 s94, 0, 0x1c000
	v_add_u32_e32 v126, s93, v207
	v_add_u32_e32 v158, s94, v207
	ds_read_b128 v[114:117], v126
	ds_read_b128 v[118:121], v126 offset:1024
	ds_read_b128 v[122:125], v126 offset:2048
	ds_read_b128 v[126:129], v126 offset:3072
	ds_read_b128 v[146:149], v158
	ds_read_b128 v[150:153], v158 offset:1024
	ds_read_b128 v[154:157], v158 offset:2048
	ds_read_b128 v[158:161], v158 offset:3072
	s_add_u32 s44, s44, 0x4000
	s_addc_u32 s45, s45, 0
	s_mov_b32 m0, s57
	v_lshl_add_u64 v[226:227], s[44:45], 0, v[162:163]
	ds_read_b128 v[178:181], v211 offset:32768
	ds_read_b128 v[182:185], v211 offset:33792
	ds_read_b128 v[186:189], v211 offset:34816
	ds_read_b128 v[190:193], v211 offset:35840
	ds_read_b128 v[194:197], v211 offset:36864
	ds_read_b128 v[198:201], v211 offset:37888
	ds_read_b128 v[202:205], v211 offset:38912
	ds_read_b128 v[214:217], v211 offset:39936
	global_load_lds_dwordx4 v[226:227], off
	v_lshl_add_u64 v[226:227], s[44:45], 0, v[166:167]
	s_mov_b32 m0, s58
	s_nop 0
	global_load_lds_dwordx4 v[226:227], off
	s_waitcnt vmcnt(8)
	s_waitcnt lgkmcnt(0)
	s_setprio 1
	s_waitcnt lgkmcnt(0)
	v_mfma_f32_16x16x32_bf16 v[142:145], v[114:117], v[178:181], v[142:145]
	v_mfma_f32_16x16x32_bf16 v[138:141], v[122:125], v[178:181], v[138:141]
	v_mfma_f32_16x16x32_bf16 v[110:113], v[114:117], v[186:189], v[110:113]
	v_mfma_f32_16x16x32_bf16 v[106:109], v[122:125], v[186:189], v[106:109]
	v_mfma_f32_16x16x32_bf16 v[94:97], v[114:117], v[194:197], v[94:97]
	v_mfma_f32_16x16x32_bf16 v[90:93], v[122:125], v[194:197], v[90:93]
	s_barrier
	v_mfma_f32_16x16x32_bf16 v[78:81], v[114:117], v[202:205], v[78:81]
	v_mfma_f32_16x16x32_bf16 v[74:77], v[122:125], v[202:205], v[74:77]
	v_mfma_f32_16x16x32_bf16 v[142:145], v[118:121], v[182:185], v[142:145]
	v_mfma_f32_16x16x32_bf16 v[138:141], v[126:129], v[182:185], v[138:141]
	v_mfma_f32_16x16x32_bf16 v[110:113], v[118:121], v[190:193], v[110:113]
	v_mfma_f32_16x16x32_bf16 v[106:109], v[126:129], v[190:193], v[106:109]
	v_mfma_f32_16x16x32_bf16 v[94:97], v[118:121], v[198:201], v[94:97]
	v_mfma_f32_16x16x32_bf16 v[90:93], v[126:129], v[198:201], v[90:93]
	v_mfma_f32_16x16x32_bf16 v[78:81], v[118:121], v[214:217], v[78:81]
	v_mfma_f32_16x16x32_bf16 v[74:77], v[126:129], v[214:217], v[74:77]
	s_setprio 0
	s_setprio 1
	v_mfma_f32_16x16x32_bf16 v[134:137], v[146:149], v[178:181], v[134:137]
	v_mfma_f32_16x16x32_bf16 v[130:133], v[154:157], v[178:181], v[130:133]
	v_mfma_f32_16x16x32_bf16 v[102:105], v[146:149], v[186:189], v[102:105]
	v_mfma_f32_16x16x32_bf16 v[98:101], v[154:157], v[186:189], v[98:101]
	v_mfma_f32_16x16x32_bf16 v[86:89], v[146:149], v[194:197], v[86:89]
	v_mfma_f32_16x16x32_bf16 v[82:85], v[154:157], v[194:197], v[82:85]
	v_mfma_f32_16x16x32_bf16 v[70:73], v[146:149], v[202:205], v[70:73]
	v_mfma_f32_16x16x32_bf16 v[66:69], v[154:157], v[202:205], v[66:69]
	v_mfma_f32_16x16x32_bf16 v[134:137], v[150:153], v[182:185], v[134:137]
	v_mfma_f32_16x16x32_bf16 v[130:133], v[158:161], v[182:185], v[130:133]
	v_mfma_f32_16x16x32_bf16 v[102:105], v[150:153], v[190:193], v[102:105]
	v_mfma_f32_16x16x32_bf16 v[98:101], v[158:161], v[190:193], v[98:101]
	v_mfma_f32_16x16x32_bf16 v[86:89], v[150:153], v[198:201], v[86:89]
	v_mfma_f32_16x16x32_bf16 v[82:85], v[158:161], v[198:201], v[82:85]
	v_mfma_f32_16x16x32_bf16 v[70:73], v[150:153], v[214:217], v[70:73]
	v_mfma_f32_16x16x32_bf16 v[66:69], v[158:161], v[214:217], v[66:69]
	s_setprio 0
	s_barrier
	s_add_i32 s44, s93, s54
	v_lshl_add_u64 v[218:219], v[218:219], 0, s[28:29]
	s_mov_b32 m0, s44
	ds_read_b128 v[178:181], v211 offset:49152
	ds_read_b128 v[182:185], v211 offset:50176
	ds_read_b128 v[186:189], v211 offset:51200
	ds_read_b128 v[190:193], v211 offset:52224
	ds_read_b128 v[194:197], v211 offset:53248
	ds_read_b128 v[198:201], v211 offset:54272
	ds_read_b128 v[202:205], v211 offset:55296
	ds_read_b128 v[214:217], v211 offset:56320
	global_load_lds_dwordx4 v[218:219], off
	v_lshl_add_u64 v[218:219], v[220:221], 0, s[28:29]
	s_add_i32 m0, s44, 0x2000
	s_add_i32 s44, s94, s54
	global_load_lds_dwordx4 v[218:219], off
	v_lshl_add_u64 v[218:219], v[222:223], 0, s[28:29]
	s_mov_b32 m0, s44
	s_nop 0
	global_load_lds_dwordx4 v[218:219], off
	v_lshl_add_u64 v[218:219], v[224:225], 0, s[28:29]
	s_add_i32 m0, s44, 0x2000
	s_nop 0
	global_load_lds_dwordx4 v[218:219], off
	v_lshl_add_u64 v[218:219], s[42:43], 0, v[162:163]
	s_mov_b32 m0, s65
	s_nop 0
	global_load_lds_dwordx4 v[218:219], off
	v_lshl_add_u64 v[218:219], s[42:43], 0, v[166:167]
	s_mov_b32 m0, s80
	s_nop 0
	global_load_lds_dwordx4 v[218:219], off
	s_waitcnt vmcnt(8)
	s_waitcnt lgkmcnt(0)
	s_setprio 1
	s_waitcnt lgkmcnt(0)
	v_mfma_f32_16x16x32_bf16 v[62:65], v[114:117], v[178:181], v[62:65]
	v_mfma_f32_16x16x32_bf16 v[58:61], v[122:125], v[178:181], v[58:61]
	v_mfma_f32_16x16x32_bf16 v[46:49], v[114:117], v[186:189], v[46:49]
	v_mfma_f32_16x16x32_bf16 v[42:45], v[122:125], v[186:189], v[42:45]
	v_mfma_f32_16x16x32_bf16 v[30:33], v[114:117], v[194:197], v[30:33]
	v_mfma_f32_16x16x32_bf16 v[26:29], v[122:125], v[194:197], v[26:29]
	s_barrier
	v_mfma_f32_16x16x32_bf16 v[14:17], v[114:117], v[202:205], v[14:17]
	v_mfma_f32_16x16x32_bf16 v[10:13], v[122:125], v[202:205], v[10:13]
	v_mfma_f32_16x16x32_bf16 v[62:65], v[118:121], v[182:185], v[62:65]
	v_mfma_f32_16x16x32_bf16 v[58:61], v[126:129], v[182:185], v[58:61]
	v_mfma_f32_16x16x32_bf16 v[46:49], v[118:121], v[190:193], v[46:49]
	v_mfma_f32_16x16x32_bf16 v[42:45], v[126:129], v[190:193], v[42:45]
	v_mfma_f32_16x16x32_bf16 v[30:33], v[118:121], v[198:201], v[30:33]
	v_mfma_f32_16x16x32_bf16 v[26:29], v[126:129], v[198:201], v[26:29]
	v_mfma_f32_16x16x32_bf16 v[14:17], v[118:121], v[214:217], v[14:17]
	v_mfma_f32_16x16x32_bf16 v[10:13], v[126:129], v[214:217], v[10:13]
	s_setprio 0
	s_setprio 1
	v_mfma_f32_16x16x32_bf16 v[54:57], v[146:149], v[178:181], v[54:57]
	v_mfma_f32_16x16x32_bf16 v[50:53], v[154:157], v[178:181], v[50:53]
	v_mfma_f32_16x16x32_bf16 v[38:41], v[146:149], v[186:189], v[38:41]
	v_mfma_f32_16x16x32_bf16 v[34:37], v[154:157], v[186:189], v[34:37]
	v_mfma_f32_16x16x32_bf16 v[22:25], v[146:149], v[194:197], v[22:25]
	v_mfma_f32_16x16x32_bf16 v[18:21], v[154:157], v[194:197], v[18:21]
	v_mfma_f32_16x16x32_bf16 v[6:9], v[146:149], v[202:205], v[6:9]
	v_mfma_f32_16x16x32_bf16 v[2:5], v[154:157], v[202:205], v[2:5]
	v_mfma_f32_16x16x32_bf16 v[54:57], v[150:153], v[182:185], v[54:57]
	v_mfma_f32_16x16x32_bf16 v[50:53], v[158:161], v[182:185], v[50:53]
	v_mfma_f32_16x16x32_bf16 v[38:41], v[150:153], v[190:193], v[38:41]
	v_mfma_f32_16x16x32_bf16 v[34:37], v[158:161], v[190:193], v[34:37]
	v_mfma_f32_16x16x32_bf16 v[22:25], v[150:153], v[198:201], v[22:25]
	v_mfma_f32_16x16x32_bf16 v[18:21], v[158:161], v[198:201], v[18:21]
	v_mfma_f32_16x16x32_bf16 v[6:9], v[150:153], v[214:217], v[6:9]
	v_mfma_f32_16x16x32_bf16 v[2:5], v[158:161], v[214:217], v[2:5]
	s_setprio 0
	s_barrier
	s_add_u32 s90, s90, 0x100
	s_addc_u32 s91, s91, 0
	s_add_u32 s38, s38, 0x10000
	s_addc_u32 s39, s39, 0
	s_cmp_ge_i32 s92, s64
	s_mov_b32 s42, s92
	s_cbranch_scc0 .LBB0_1170

.LBB0_1276:
	ds_read_b128 v[114:117], v171
	ds_read_b128 v[118:121], v171 offset:1024
	ds_read_b128 v[122:125], v171 offset:2048
	ds_read_b128 v[130:133], v171 offset:3072
	ds_read_b128 v[162:165], v172
	ds_read_b128 v[176:179], v172 offset:1024
	ds_read_b128 v[180:183], v172 offset:2048
	ds_read_b128 v[184:187], v172 offset:3072
	s_add_i32 s82, s30, 2
	s_add_u32 s83, s2, 0x80
	s_addc_u32 s31, s3, 0
	s_cmp_eq_u32 s58, s30
	s_cselect_b32 s30, s26, s83
	s_cselect_b32 s31, s27, s31
	s_cselect_b32 s85, s29, s35
	s_cselect_b32 s84, s28, s34
	v_lshl_add_u64 v[220:221], s[2:3], 0, v[154:155]
	s_add_i32 m0, s44, 0xc000
	ds_read_b128 v[188:191], v173
	ds_read_b128 v[192:195], v173 offset:1024
	ds_read_b128 v[196:199], v173 offset:2048
	ds_read_b128 v[200:203], v173 offset:3072
	ds_read_b128 v[204:207], v173 offset:4096
	ds_read_b128 v[208:211], v173 offset:5120
	ds_read_b128 v[212:215], v173 offset:6144
	ds_read_b128 v[216:219], v173 offset:7168
	global_load_lds_dwordx4 v[220:221], off
	v_lshl_add_u64 v[220:221], s[2:3], 0, v[156:157]
	s_add_i32 m0, s44, 0xe000
	s_nop 0
	global_load_lds_dwordx4 v[220:221], off
	s_waitcnt vmcnt(8)
	s_waitcnt lgkmcnt(0)
	s_setprio 1
	s_waitcnt lgkmcnt(0)
	v_mfma_f32_16x16x32_bf16 v[142:145], v[114:117], v[188:191], v[142:145]
	v_mfma_f32_16x16x32_bf16 v[138:141], v[122:125], v[188:191], v[138:141]
	v_mfma_f32_16x16x32_bf16 v[110:113], v[114:117], v[196:199], v[110:113]
	v_mfma_f32_16x16x32_bf16 v[106:109], v[122:125], v[196:199], v[106:109]
	v_mfma_f32_16x16x32_bf16 v[94:97], v[114:117], v[204:207], v[94:97]
	v_mfma_f32_16x16x32_bf16 v[90:93], v[122:125], v[204:207], v[90:93]
	s_barrier
	v_mfma_f32_16x16x32_bf16 v[78:81], v[114:117], v[212:215], v[78:81]
	v_mfma_f32_16x16x32_bf16 v[74:77], v[122:125], v[212:215], v[74:77]
	v_mfma_f32_16x16x32_bf16 v[142:145], v[118:121], v[192:195], v[142:145]
	v_mfma_f32_16x16x32_bf16 v[138:141], v[130:133], v[192:195], v[138:141]
	v_mfma_f32_16x16x32_bf16 v[110:113], v[118:121], v[200:203], v[110:113]
	v_mfma_f32_16x16x32_bf16 v[106:109], v[130:133], v[200:203], v[106:109]
	v_mfma_f32_16x16x32_bf16 v[94:97], v[118:121], v[208:211], v[94:97]
	v_mfma_f32_16x16x32_bf16 v[90:93], v[130:133], v[208:211], v[90:93]
	v_mfma_f32_16x16x32_bf16 v[78:81], v[118:121], v[216:219], v[78:81]
	v_mfma_f32_16x16x32_bf16 v[74:77], v[130:133], v[216:219], v[74:77]
	s_setprio 0
	s_setprio 1
	v_mfma_f32_16x16x32_bf16 v[134:137], v[162:165], v[188:191], v[134:137]
	v_mfma_f32_16x16x32_bf16 v[126:129], v[180:183], v[188:191], v[126:129]
	v_mfma_f32_16x16x32_bf16 v[102:105], v[162:165], v[196:199], v[102:105]
	v_mfma_f32_16x16x32_bf16 v[98:101], v[180:183], v[196:199], v[98:101]
	v_mfma_f32_16x16x32_bf16 v[86:89], v[162:165], v[204:207], v[86:89]
	v_mfma_f32_16x16x32_bf16 v[82:85], v[180:183], v[204:207], v[82:85]
	v_mfma_f32_16x16x32_bf16 v[70:73], v[162:165], v[212:215], v[70:73]
	v_mfma_f32_16x16x32_bf16 v[66:69], v[180:183], v[212:215], v[66:69]
	v_mfma_f32_16x16x32_bf16 v[134:137], v[176:179], v[192:195], v[134:137]
	v_mfma_f32_16x16x32_bf16 v[126:129], v[184:187], v[192:195], v[126:129]
	v_mfma_f32_16x16x32_bf16 v[102:105], v[176:179], v[200:203], v[102:105]
	v_mfma_f32_16x16x32_bf16 v[98:101], v[184:187], v[200:203], v[98:101]
	v_mfma_f32_16x16x32_bf16 v[86:89], v[176:179], v[208:211], v[86:89]
	v_mfma_f32_16x16x32_bf16 v[82:85], v[184:187], v[208:211], v[82:85]
	v_mfma_f32_16x16x32_bf16 v[70:73], v[176:179], v[216:219], v[70:73]
	v_mfma_f32_16x16x32_bf16 v[66:69], v[184:187], v[216:219], v[66:69]
	s_setprio 0
	s_barrier
	s_add_i32 s83, s61, s37
	v_lshl_add_u64 v[220:221], s[84:85], 0, v[148:149]
	s_mov_b32 m0, s83
	ds_read_b128 v[188:191], v173 offset:16384
	ds_read_b128 v[192:195], v173 offset:17408
	ds_read_b128 v[196:199], v173 offset:18432
	ds_read_b128 v[200:203], v173 offset:19456
	ds_read_b128 v[204:207], v173 offset:20480
	ds_read_b128 v[208:211], v173 offset:21504
	ds_read_b128 v[212:215], v173 offset:22528
	ds_read_b128 v[216:219], v173 offset:23552
	global_load_lds_dwordx4 v[220:221], off
	s_add_i32 m0, s83, 0x2000
	v_lshl_add_u64 v[222:223], s[84:85], 0, v[152:153]
	s_add_u32 s84, s84, s6
	s_addc_u32 s85, s85, s7
	s_add_i32 s83, s62, s37
	global_load_lds_dwordx4 v[222:223], off
	v_lshl_add_u64 v[224:225], s[84:85], 0, v[148:149]
	s_mov_b32 m0, s83
	v_lshl_add_u64 v[226:227], s[84:85], 0, v[152:153]
	global_load_lds_dwordx4 v[224:225], off
	s_add_i32 m0, s83, 0x2000
	v_lshl_add_u64 v[228:229], s[30:31], 0, v[146:147]
	global_load_lds_dwordx4 v[226:227], off
	s_mov_b32 m0, s44
	v_lshl_add_u64 v[230:231], s[30:31], 0, v[150:151]
	global_load_lds_dwordx4 v[228:229], off
	s_mov_b32 m0, s45
	s_nop 0
	global_load_lds_dwordx4 v[230:231], off
	s_waitcnt vmcnt(8)
	s_waitcnt lgkmcnt(0)
	s_setprio 1
	s_waitcnt lgkmcnt(0)
	v_mfma_f32_16x16x32_bf16 v[62:65], v[114:117], v[188:191], v[62:65]
	v_mfma_f32_16x16x32_bf16 v[58:61], v[122:125], v[188:191], v[58:61]
	v_mfma_f32_16x16x32_bf16 v[46:49], v[114:117], v[196:199], v[46:49]
	v_mfma_f32_16x16x32_bf16 v[42:45], v[122:125], v[196:199], v[42:45]
	v_mfma_f32_16x16x32_bf16 v[30:33], v[114:117], v[204:207], v[30:33]
	v_mfma_f32_16x16x32_bf16 v[26:29], v[122:125], v[204:207], v[26:29]
	s_barrier
	v_mfma_f32_16x16x32_bf16 v[14:17], v[114:117], v[212:215], v[14:17]
	v_mfma_f32_16x16x32_bf16 v[10:13], v[122:125], v[212:215], v[10:13]
	v_mfma_f32_16x16x32_bf16 v[62:65], v[118:121], v[192:195], v[62:65]
	v_mfma_f32_16x16x32_bf16 v[58:61], v[130:133], v[192:195], v[58:61]
	v_mfma_f32_16x16x32_bf16 v[46:49], v[118:121], v[200:203], v[46:49]
	v_mfma_f32_16x16x32_bf16 v[42:45], v[130:133], v[200:203], v[42:45]
	v_mfma_f32_16x16x32_bf16 v[30:33], v[118:121], v[208:211], v[30:33]
	v_mfma_f32_16x16x32_bf16 v[26:29], v[130:133], v[208:211], v[26:29]
	v_mfma_f32_16x16x32_bf16 v[14:17], v[118:121], v[216:219], v[14:17]
	v_mfma_f32_16x16x32_bf16 v[10:13], v[130:133], v[216:219], v[10:13]
	s_setprio 0
	s_setprio 1
	v_mfma_f32_16x16x32_bf16 v[54:57], v[162:165], v[188:191], v[54:57]
	v_mfma_f32_16x16x32_bf16 v[50:53], v[180:183], v[188:191], v[50:53]
	v_mfma_f32_16x16x32_bf16 v[38:41], v[162:165], v[196:199], v[38:41]
	v_mfma_f32_16x16x32_bf16 v[34:37], v[180:183], v[196:199], v[34:37]
	v_mfma_f32_16x16x32_bf16 v[22:25], v[162:165], v[204:207], v[22:25]
	v_mfma_f32_16x16x32_bf16 v[18:21], v[180:183], v[204:207], v[18:21]
	v_mfma_f32_16x16x32_bf16 v[6:9], v[162:165], v[212:215], v[6:9]
	v_mfma_f32_16x16x32_bf16 v[2:5], v[180:183], v[212:215], v[2:5]
	v_mfma_f32_16x16x32_bf16 v[54:57], v[176:179], v[192:195], v[54:57]
	v_mfma_f32_16x16x32_bf16 v[50:53], v[184:187], v[192:195], v[50:53]
	v_mfma_f32_16x16x32_bf16 v[38:41], v[176:179], v[200:203], v[38:41]
	v_mfma_f32_16x16x32_bf16 v[34:37], v[184:187], v[200:203], v[34:37]
	v_mfma_f32_16x16x32_bf16 v[22:25], v[176:179], v[208:211], v[22:25]
	v_mfma_f32_16x16x32_bf16 v[18:21], v[184:187], v[208:211], v[18:21]
	v_mfma_f32_16x16x32_bf16 v[6:9], v[176:179], v[216:219], v[6:9]
	v_mfma_f32_16x16x32_bf16 v[2:5], v[184:187], v[216:219], v[2:5]
	s_setprio 0
	s_barrier
	s_add_i32 s83, 0, 0x18000
	s_add_i32 s84, 0, 0x1c000
	v_add_u32_e32 v130, s83, v168
	v_add_u32_e32 v166, s84, v168
	ds_read_b128 v[114:117], v130
	ds_read_b128 v[118:121], v130 offset:1024
	ds_read_b128 v[122:125], v130 offset:2048
	ds_read_b128 v[130:133], v130 offset:3072
	ds_read_b128 v[162:165], v166
	ds_read_b128 v[176:179], v166 offset:1024
	ds_read_b128 v[180:183], v166 offset:2048
	ds_read_b128 v[184:187], v166 offset:3072
	s_add_u32 s30, s30, s6
	s_addc_u32 s31, s31, s7
	s_mov_b32 m0, s46
	v_lshl_add_u64 v[232:233], s[30:31], 0, v[146:147]
	ds_read_b128 v[188:191], v173 offset:32768
	ds_read_b128 v[192:195], v173 offset:33792
	ds_read_b128 v[196:199], v173 offset:34816
	ds_read_b128 v[200:203], v173 offset:35840
	ds_read_b128 v[204:207], v173 offset:36864
	ds_read_b128 v[208:211], v173 offset:37888
	ds_read_b128 v[212:215], v173 offset:38912
	ds_read_b128 v[216:219], v173 offset:39936
	global_load_lds_dwordx4 v[232:233], off
	v_lshl_add_u64 v[232:233], s[30:31], 0, v[150:151]
	s_mov_b32 m0, s47
	s_nop 0
	global_load_lds_dwordx4 v[232:233], off
	s_waitcnt vmcnt(8)
	s_waitcnt lgkmcnt(0)
	s_setprio 1
	s_waitcnt lgkmcnt(0)
	v_mfma_f32_16x16x32_bf16 v[142:145], v[114:117], v[188:191], v[142:145]
	v_mfma_f32_16x16x32_bf16 v[138:141], v[122:125], v[188:191], v[138:141]
	v_mfma_f32_16x16x32_bf16 v[110:113], v[114:117], v[196:199], v[110:113]
	v_mfma_f32_16x16x32_bf16 v[106:109], v[122:125], v[196:199], v[106:109]
	v_mfma_f32_16x16x32_bf16 v[94:97], v[114:117], v[204:207], v[94:97]
	v_mfma_f32_16x16x32_bf16 v[90:93], v[122:125], v[204:207], v[90:93]
	s_barrier
	v_mfma_f32_16x16x32_bf16 v[78:81], v[114:117], v[212:215], v[78:81]
	v_mfma_f32_16x16x32_bf16 v[74:77], v[122:125], v[212:215], v[74:77]
	v_mfma_f32_16x16x32_bf16 v[142:145], v[118:121], v[192:195], v[142:145]
	v_mfma_f32_16x16x32_bf16 v[138:141], v[130:133], v[192:195], v[138:141]
	v_mfma_f32_16x16x32_bf16 v[110:113], v[118:121], v[200:203], v[110:113]
	v_mfma_f32_16x16x32_bf16 v[106:109], v[130:133], v[200:203], v[106:109]
	v_mfma_f32_16x16x32_bf16 v[94:97], v[118:121], v[208:211], v[94:97]
	v_mfma_f32_16x16x32_bf16 v[90:93], v[130:133], v[208:211], v[90:93]
	v_mfma_f32_16x16x32_bf16 v[78:81], v[118:121], v[216:219], v[78:81]
	v_mfma_f32_16x16x32_bf16 v[74:77], v[130:133], v[216:219], v[74:77]
	s_setprio 0
	s_setprio 1
	v_mfma_f32_16x16x32_bf16 v[134:137], v[162:165], v[188:191], v[134:137]
	v_mfma_f32_16x16x32_bf16 v[126:129], v[180:183], v[188:191], v[126:129]
	v_mfma_f32_16x16x32_bf16 v[102:105], v[162:165], v[196:199], v[102:105]
	v_mfma_f32_16x16x32_bf16 v[98:101], v[180:183], v[196:199], v[98:101]
	v_mfma_f32_16x16x32_bf16 v[86:89], v[162:165], v[204:207], v[86:89]
	v_mfma_f32_16x16x32_bf16 v[82:85], v[180:183], v[204:207], v[82:85]
	v_mfma_f32_16x16x32_bf16 v[70:73], v[162:165], v[212:215], v[70:73]
	v_mfma_f32_16x16x32_bf16 v[66:69], v[180:183], v[212:215], v[66:69]
	v_mfma_f32_16x16x32_bf16 v[134:137], v[176:179], v[192:195], v[134:137]
	v_mfma_f32_16x16x32_bf16 v[126:129], v[184:187], v[192:195], v[126:129]
	v_mfma_f32_16x16x32_bf16 v[102:105], v[176:179], v[200:203], v[102:105]
	v_mfma_f32_16x16x32_bf16 v[98:101], v[184:187], v[200:203], v[98:101]
	v_mfma_f32_16x16x32_bf16 v[86:89], v[176:179], v[208:211], v[86:89]
	v_mfma_f32_16x16x32_bf16 v[82:85], v[184:187], v[208:211], v[82:85]
	v_mfma_f32_16x16x32_bf16 v[70:73], v[176:179], v[216:219], v[70:73]
	v_mfma_f32_16x16x32_bf16 v[66:69], v[184:187], v[216:219], v[66:69]
	s_setprio 0
	s_barrier
	s_add_i32 s30, s83, s37
	v_lshl_add_u64 v[220:221], v[220:221], 0, s[20:21]
	s_mov_b32 m0, s30
	ds_read_b128 v[188:191], v173 offset:49152
	ds_read_b128 v[192:195], v173 offset:50176
	ds_read_b128 v[196:199], v173 offset:51200
	ds_read_b128 v[200:203], v173 offset:52224
	ds_read_b128 v[204:207], v173 offset:53248
	ds_read_b128 v[208:211], v173 offset:54272
	ds_read_b128 v[212:215], v173 offset:55296
	ds_read_b128 v[216:219], v173 offset:56320
	global_load_lds_dwordx4 v[220:221], off
	v_lshl_add_u64 v[220:221], v[222:223], 0, s[20:21]
	s_add_i32 m0, s30, 0x2000
	s_add_i32 s30, s84, s37
	global_load_lds_dwordx4 v[220:221], off
	v_lshl_add_u64 v[220:221], v[224:225], 0, s[20:21]
	s_mov_b32 m0, s30
	s_nop 0
	global_load_lds_dwordx4 v[220:221], off
	v_lshl_add_u64 v[220:221], v[226:227], 0, s[20:21]
	s_add_i32 m0, s30, 0x2000
	s_nop 0
	global_load_lds_dwordx4 v[220:221], off
	v_lshl_add_u64 v[220:221], v[228:229], 0, s[20:21]
	s_mov_b32 m0, s55
	s_nop 0
	global_load_lds_dwordx4 v[220:221], off
	v_lshl_add_u64 v[220:221], v[230:231], 0, s[20:21]
	s_mov_b32 m0, s56
	s_nop 0
	global_load_lds_dwordx4 v[220:221], off
	s_waitcnt vmcnt(8)
	s_waitcnt lgkmcnt(0)
	s_setprio 1
	s_waitcnt lgkmcnt(0)
	v_mfma_f32_16x16x32_bf16 v[62:65], v[114:117], v[188:191], v[62:65]
	v_mfma_f32_16x16x32_bf16 v[58:61], v[122:125], v[188:191], v[58:61]
	v_mfma_f32_16x16x32_bf16 v[46:49], v[114:117], v[196:199], v[46:49]
	v_mfma_f32_16x16x32_bf16 v[42:45], v[122:125], v[196:199], v[42:45]
	v_mfma_f32_16x16x32_bf16 v[30:33], v[114:117], v[204:207], v[30:33]
	v_mfma_f32_16x16x32_bf16 v[26:29], v[122:125], v[204:207], v[26:29]
	s_barrier
	v_mfma_f32_16x16x32_bf16 v[14:17], v[114:117], v[212:215], v[14:17]
	v_mfma_f32_16x16x32_bf16 v[10:13], v[122:125], v[212:215], v[10:13]
	v_mfma_f32_16x16x32_bf16 v[62:65], v[118:121], v[192:195], v[62:65]
	v_mfma_f32_16x16x32_bf16 v[58:61], v[130:133], v[192:195], v[58:61]
	v_mfma_f32_16x16x32_bf16 v[46:49], v[118:121], v[200:203], v[46:49]
	v_mfma_f32_16x16x32_bf16 v[42:45], v[130:133], v[200:203], v[42:45]
	v_mfma_f32_16x16x32_bf16 v[30:33], v[118:121], v[208:211], v[30:33]
	v_mfma_f32_16x16x32_bf16 v[26:29], v[130:133], v[208:211], v[26:29]
	v_mfma_f32_16x16x32_bf16 v[14:17], v[118:121], v[216:219], v[14:17]
	v_mfma_f32_16x16x32_bf16 v[10:13], v[130:133], v[216:219], v[10:13]
	s_setprio 0
	s_setprio 1
	v_mfma_f32_16x16x32_bf16 v[54:57], v[162:165], v[188:191], v[54:57]
	v_mfma_f32_16x16x32_bf16 v[50:53], v[180:183], v[188:191], v[50:53]
	v_mfma_f32_16x16x32_bf16 v[38:41], v[162:165], v[196:199], v[38:41]
	v_mfma_f32_16x16x32_bf16 v[34:37], v[180:183], v[196:199], v[34:37]
	v_mfma_f32_16x16x32_bf16 v[22:25], v[162:165], v[204:207], v[22:25]
	v_mfma_f32_16x16x32_bf16 v[18:21], v[180:183], v[204:207], v[18:21]
	v_mfma_f32_16x16x32_bf16 v[6:9], v[162:165], v[212:215], v[6:9]
	v_mfma_f32_16x16x32_bf16 v[2:5], v[180:183], v[212:215], v[2:5]
	v_mfma_f32_16x16x32_bf16 v[54:57], v[176:179], v[192:195], v[54:57]
	v_mfma_f32_16x16x32_bf16 v[50:53], v[184:187], v[192:195], v[50:53]
	v_mfma_f32_16x16x32_bf16 v[38:41], v[176:179], v[200:203], v[38:41]
	v_mfma_f32_16x16x32_bf16 v[34:37], v[184:187], v[200:203], v[34:37]
	v_mfma_f32_16x16x32_bf16 v[22:25], v[176:179], v[208:211], v[22:25]
	v_mfma_f32_16x16x32_bf16 v[18:21], v[184:187], v[208:211], v[18:21]
	v_mfma_f32_16x16x32_bf16 v[6:9], v[176:179], v[216:219], v[6:9]
	v_mfma_f32_16x16x32_bf16 v[2:5], v[184:187], v[216:219], v[2:5]
	s_setprio 0
	s_barrier
	s_add_u32 s2, s2, 0x100
	s_addc_u32 s3, s3, 0
	s_add_u32 s34, s34, 0x100
	s_addc_u32 s35, s35, 0
	s_cmp_ge_i32 s82, s57
	s_mov_b32 s30, s82
	s_cbranch_scc0 .LBB0_1276

.LBB0_1461:
	ds_read_b128 v[148:151], v168
	ds_read_b128 v[172:175], v168 offset:1024
	ds_read_b128 v[176:179], v168 offset:2048
	ds_read_b128 v[180:183], v168 offset:3072
	ds_read_b128 v[184:187], v169
	ds_read_b128 v[188:191], v169 offset:1024
	ds_read_b128 v[192:195], v169 offset:2048
	ds_read_b128 v[196:199], v169 offset:3072
	s_add_i32 s67, s26, 2
	s_add_u32 s68, s24, 0x80
	s_addc_u32 s27, s25, 0
	s_cmp_eq_u32 s50, s26
	s_cselect_b32 s26, s2, s68
	s_cselect_b32 s27, s3, s27
	s_cselect_b32 s69, s23, s66
	s_cselect_b32 s68, s22, s65
	v_lshl_add_u64 v[232:233], s[24:25], 0, v[140:141]
	s_add_i32 m0, s37, 0xc000
	ds_read_b128 v[200:203], v170
	ds_read_b128 v[204:207], v170 offset:1024
	ds_read_b128 v[208:211], v170 offset:2048
	ds_read_b128 v[212:215], v170 offset:3072
	ds_read_b128 v[216:219], v170 offset:4096
	ds_read_b128 v[220:223], v170 offset:5120
	ds_read_b128 v[224:227], v170 offset:6144
	ds_read_b128 v[228:231], v170 offset:7168
	global_load_lds_dwordx4 v[232:233], off
	v_lshl_add_u64 v[232:233], s[24:25], 0, v[142:143]
	s_add_i32 m0, s37, 0xe000
	s_nop 0
	global_load_lds_dwordx4 v[232:233], off
	s_waitcnt vmcnt(8)
	s_waitcnt lgkmcnt(0)
	s_setprio 1
	s_waitcnt lgkmcnt(0)
	v_mfma_f32_16x16x32_bf16 v[128:131], v[148:151], v[200:203], v[128:131]
	v_mfma_f32_16x16x32_bf16 v[124:127], v[176:179], v[200:203], v[124:127]
	v_mfma_f32_16x16x32_bf16 v[120:123], v[148:151], v[208:211], v[120:123]
	v_mfma_f32_16x16x32_bf16 v[116:119], v[176:179], v[208:211], v[116:119]
	v_mfma_f32_16x16x32_bf16 v[112:115], v[148:151], v[216:219], v[112:115]
	v_mfma_f32_16x16x32_bf16 v[108:111], v[176:179], v[216:219], v[108:111]
	s_barrier
	v_mfma_f32_16x16x32_bf16 v[104:107], v[148:151], v[224:227], v[104:107]
	v_mfma_f32_16x16x32_bf16 v[100:103], v[176:179], v[224:227], v[100:103]
	v_mfma_f32_16x16x32_bf16 v[128:131], v[172:175], v[204:207], v[128:131]
	v_mfma_f32_16x16x32_bf16 v[124:127], v[180:183], v[204:207], v[124:127]
	v_mfma_f32_16x16x32_bf16 v[120:123], v[172:175], v[212:215], v[120:123]
	v_mfma_f32_16x16x32_bf16 v[116:119], v[180:183], v[212:215], v[116:119]
	v_mfma_f32_16x16x32_bf16 v[112:115], v[172:175], v[220:223], v[112:115]
	v_mfma_f32_16x16x32_bf16 v[108:111], v[180:183], v[220:223], v[108:111]
	v_mfma_f32_16x16x32_bf16 v[104:107], v[172:175], v[228:231], v[104:107]
	v_mfma_f32_16x16x32_bf16 v[100:103], v[180:183], v[228:231], v[100:103]
	s_setprio 0
	s_setprio 1
	v_mfma_f32_16x16x32_bf16 v[64:67], v[184:187], v[200:203], v[64:67]
	v_mfma_f32_16x16x32_bf16 v[60:63], v[192:195], v[200:203], v[60:63]
	v_mfma_f32_16x16x32_bf16 v[56:59], v[184:187], v[208:211], v[56:59]
	v_mfma_f32_16x16x32_bf16 v[52:55], v[192:195], v[208:211], v[52:55]
	v_mfma_f32_16x16x32_bf16 v[48:51], v[184:187], v[216:219], v[48:51]
	v_mfma_f32_16x16x32_bf16 v[44:47], v[192:195], v[216:219], v[44:47]
	v_mfma_f32_16x16x32_bf16 v[40:43], v[184:187], v[224:227], v[40:43]
	v_mfma_f32_16x16x32_bf16 v[36:39], v[192:195], v[224:227], v[36:39]
	v_mfma_f32_16x16x32_bf16 v[64:67], v[188:191], v[204:207], v[64:67]
	v_mfma_f32_16x16x32_bf16 v[60:63], v[196:199], v[204:207], v[60:63]
	v_mfma_f32_16x16x32_bf16 v[56:59], v[188:191], v[212:215], v[56:59]
	v_mfma_f32_16x16x32_bf16 v[52:55], v[196:199], v[212:215], v[52:55]
	v_mfma_f32_16x16x32_bf16 v[48:51], v[188:191], v[220:223], v[48:51]
	v_mfma_f32_16x16x32_bf16 v[44:47], v[196:199], v[220:223], v[44:47]
	v_mfma_f32_16x16x32_bf16 v[40:43], v[188:191], v[228:231], v[40:43]
	v_mfma_f32_16x16x32_bf16 v[36:39], v[196:199], v[228:231], v[36:39]
	s_setprio 0
	s_barrier
	s_add_i32 s80, s57, s36
	v_lshl_add_u64 v[232:233], s[68:69], 0, v[134:135]
	s_mov_b32 m0, s80
	ds_read_b128 v[200:203], v170 offset:16384
	ds_read_b128 v[204:207], v170 offset:17408
	ds_read_b128 v[208:211], v170 offset:18432
	ds_read_b128 v[212:215], v170 offset:19456
	ds_read_b128 v[216:219], v170 offset:20480
	ds_read_b128 v[220:223], v170 offset:21504
	ds_read_b128 v[224:227], v170 offset:22528
	ds_read_b128 v[228:231], v170 offset:23552
	global_load_lds_dwordx4 v[232:233], off
	s_add_i32 m0, s80, 0x2000
	v_lshl_add_u64 v[234:235], s[68:69], 0, v[138:139]
	s_add_u32 s68, s68, s6
	s_addc_u32 s69, s69, s7
	s_add_i32 s80, s58, s36
	global_load_lds_dwordx4 v[234:235], off
	v_lshl_add_u64 v[236:237], s[68:69], 0, v[134:135]
	s_mov_b32 m0, s80
	v_lshl_add_u64 v[238:239], s[68:69], 0, v[138:139]
	global_load_lds_dwordx4 v[236:237], off
	s_add_i32 m0, s80, 0x2000
	v_lshl_add_u64 v[240:241], s[26:27], 0, v[132:133]
	global_load_lds_dwordx4 v[238:239], off
	s_mov_b32 m0, s37
	v_lshl_add_u64 v[242:243], s[26:27], 0, v[136:137]
	global_load_lds_dwordx4 v[240:241], off
	s_mov_b32 m0, s38
	s_nop 0
	global_load_lds_dwordx4 v[242:243], off
	s_waitcnt vmcnt(8)
	s_waitcnt lgkmcnt(0)
	s_setprio 1
	s_waitcnt lgkmcnt(0)
	v_mfma_f32_16x16x32_bf16 v[96:99], v[148:151], v[200:203], v[96:99]
	v_mfma_f32_16x16x32_bf16 v[92:95], v[176:179], v[200:203], v[92:95]
	v_mfma_f32_16x16x32_bf16 v[88:91], v[148:151], v[208:211], v[88:91]
	v_mfma_f32_16x16x32_bf16 v[84:87], v[176:179], v[208:211], v[84:87]
	v_mfma_f32_16x16x32_bf16 v[80:83], v[148:151], v[216:219], v[80:83]
	v_mfma_f32_16x16x32_bf16 v[76:79], v[176:179], v[216:219], v[76:79]
	s_barrier
	v_mfma_f32_16x16x32_bf16 v[72:75], v[148:151], v[224:227], v[72:75]
	v_mfma_f32_16x16x32_bf16 v[68:71], v[176:179], v[224:227], v[68:71]
	v_mfma_f32_16x16x32_bf16 v[96:99], v[172:175], v[204:207], v[96:99]
	v_mfma_f32_16x16x32_bf16 v[92:95], v[180:183], v[204:207], v[92:95]
	v_mfma_f32_16x16x32_bf16 v[88:91], v[172:175], v[212:215], v[88:91]
	v_mfma_f32_16x16x32_bf16 v[84:87], v[180:183], v[212:215], v[84:87]
	v_mfma_f32_16x16x32_bf16 v[80:83], v[172:175], v[220:223], v[80:83]
	v_mfma_f32_16x16x32_bf16 v[76:79], v[180:183], v[220:223], v[76:79]
	v_mfma_f32_16x16x32_bf16 v[72:75], v[172:175], v[228:231], v[72:75]
	v_mfma_f32_16x16x32_bf16 v[68:71], v[180:183], v[228:231], v[68:71]
	s_setprio 0
	s_setprio 1
	v_mfma_f32_16x16x32_bf16 v[32:35], v[184:187], v[200:203], v[32:35]
	v_mfma_f32_16x16x32_bf16 v[28:31], v[192:195], v[200:203], v[28:31]
	v_mfma_f32_16x16x32_bf16 v[24:27], v[184:187], v[208:211], v[24:27]
	v_mfma_f32_16x16x32_bf16 v[20:23], v[192:195], v[208:211], v[20:23]
	v_mfma_f32_16x16x32_bf16 v[16:19], v[184:187], v[216:219], v[16:19]
	v_mfma_f32_16x16x32_bf16 v[12:15], v[192:195], v[216:219], v[12:15]
	v_mfma_f32_16x16x32_bf16 v[8:11], v[184:187], v[224:227], v[8:11]
	v_mfma_f32_16x16x32_bf16 v[4:7], v[192:195], v[224:227], v[4:7]
	v_mfma_f32_16x16x32_bf16 v[32:35], v[188:191], v[204:207], v[32:35]
	v_mfma_f32_16x16x32_bf16 v[28:31], v[196:199], v[204:207], v[28:31]
	v_mfma_f32_16x16x32_bf16 v[24:27], v[188:191], v[212:215], v[24:27]
	v_mfma_f32_16x16x32_bf16 v[20:23], v[196:199], v[212:215], v[20:23]
	v_mfma_f32_16x16x32_bf16 v[16:19], v[188:191], v[220:223], v[16:19]
	v_mfma_f32_16x16x32_bf16 v[12:15], v[196:199], v[220:223], v[12:15]
	v_mfma_f32_16x16x32_bf16 v[8:11], v[188:191], v[228:231], v[8:11]
	v_mfma_f32_16x16x32_bf16 v[4:7], v[196:199], v[228:231], v[4:7]
	s_setprio 0
	s_barrier
	s_add_i32 s68, 0, 0x18000
	v_add_u32_e32 v3, s68, v166
	s_add_i32 s69, 0, 0x1c000
	ds_read_b128 v[148:151], v3
	ds_read_b128 v[172:175], v3 offset:1024
	ds_read_b128 v[176:179], v3 offset:2048
	ds_read_b128 v[180:183], v3 offset:3072
	v_add_u32_e32 v3, s69, v166
	ds_read_b128 v[184:187], v3
	ds_read_b128 v[188:191], v3 offset:1024
	ds_read_b128 v[192:195], v3 offset:2048
	ds_read_b128 v[196:199], v3 offset:3072
	s_add_u32 s26, s26, s6
	s_addc_u32 s27, s27, s7
	s_mov_b32 m0, s39
	v_lshl_add_u64 v[244:245], s[26:27], 0, v[132:133]
	ds_read_b128 v[200:203], v170 offset:32768
	ds_read_b128 v[204:207], v170 offset:33792
	ds_read_b128 v[208:211], v170 offset:34816
	ds_read_b128 v[212:215], v170 offset:35840
	ds_read_b128 v[216:219], v170 offset:36864
	ds_read_b128 v[220:223], v170 offset:37888
	ds_read_b128 v[224:227], v170 offset:38912
	ds_read_b128 v[228:231], v170 offset:39936
	global_load_lds_dwordx4 v[244:245], off
	v_lshl_add_u64 v[244:245], s[26:27], 0, v[136:137]
	s_mov_b32 m0, s42
	s_nop 0
	global_load_lds_dwordx4 v[244:245], off
	s_waitcnt vmcnt(8)
	s_waitcnt lgkmcnt(0)
	s_setprio 1
	s_waitcnt lgkmcnt(0)
	v_mfma_f32_16x16x32_bf16 v[128:131], v[148:151], v[200:203], v[128:131]
	v_mfma_f32_16x16x32_bf16 v[124:127], v[176:179], v[200:203], v[124:127]
	v_mfma_f32_16x16x32_bf16 v[120:123], v[148:151], v[208:211], v[120:123]
	v_mfma_f32_16x16x32_bf16 v[116:119], v[176:179], v[208:211], v[116:119]
	v_mfma_f32_16x16x32_bf16 v[112:115], v[148:151], v[216:219], v[112:115]
	v_mfma_f32_16x16x32_bf16 v[108:111], v[176:179], v[216:219], v[108:111]
	s_barrier
	v_mfma_f32_16x16x32_bf16 v[104:107], v[148:151], v[224:227], v[104:107]
	v_mfma_f32_16x16x32_bf16 v[100:103], v[176:179], v[224:227], v[100:103]
	v_mfma_f32_16x16x32_bf16 v[128:131], v[172:175], v[204:207], v[128:131]
	v_mfma_f32_16x16x32_bf16 v[124:127], v[180:183], v[204:207], v[124:127]
	v_mfma_f32_16x16x32_bf16 v[120:123], v[172:175], v[212:215], v[120:123]
	v_mfma_f32_16x16x32_bf16 v[116:119], v[180:183], v[212:215], v[116:119]
	v_mfma_f32_16x16x32_bf16 v[112:115], v[172:175], v[220:223], v[112:115]
	v_mfma_f32_16x16x32_bf16 v[108:111], v[180:183], v[220:223], v[108:111]
	v_mfma_f32_16x16x32_bf16 v[104:107], v[172:175], v[228:231], v[104:107]
	v_mfma_f32_16x16x32_bf16 v[100:103], v[180:183], v[228:231], v[100:103]
	s_setprio 0
	s_setprio 1
	v_mfma_f32_16x16x32_bf16 v[64:67], v[184:187], v[200:203], v[64:67]
	v_mfma_f32_16x16x32_bf16 v[60:63], v[192:195], v[200:203], v[60:63]
	v_mfma_f32_16x16x32_bf16 v[56:59], v[184:187], v[208:211], v[56:59]
	v_mfma_f32_16x16x32_bf16 v[52:55], v[192:195], v[208:211], v[52:55]
	v_mfma_f32_16x16x32_bf16 v[48:51], v[184:187], v[216:219], v[48:51]
	v_mfma_f32_16x16x32_bf16 v[44:47], v[192:195], v[216:219], v[44:47]
	v_mfma_f32_16x16x32_bf16 v[40:43], v[184:187], v[224:227], v[40:43]
	v_mfma_f32_16x16x32_bf16 v[36:39], v[192:195], v[224:227], v[36:39]
	v_mfma_f32_16x16x32_bf16 v[64:67], v[188:191], v[204:207], v[64:67]
	v_mfma_f32_16x16x32_bf16 v[60:63], v[196:199], v[204:207], v[60:63]
	v_mfma_f32_16x16x32_bf16 v[56:59], v[188:191], v[212:215], v[56:59]
	v_mfma_f32_16x16x32_bf16 v[52:55], v[196:199], v[212:215], v[52:55]
	v_mfma_f32_16x16x32_bf16 v[48:51], v[188:191], v[220:223], v[48:51]
	v_mfma_f32_16x16x32_bf16 v[44:47], v[196:199], v[220:223], v[44:47]
	v_mfma_f32_16x16x32_bf16 v[40:43], v[188:191], v[228:231], v[40:43]
	v_mfma_f32_16x16x32_bf16 v[36:39], v[196:199], v[228:231], v[36:39]
	s_setprio 0
	s_barrier
	s_add_i32 s26, s68, s36
	v_lshl_add_u64 v[232:233], v[232:233], 0, s[16:17]
	s_mov_b32 m0, s26
	ds_read_b128 v[200:203], v170 offset:49152
	ds_read_b128 v[204:207], v170 offset:50176
	ds_read_b128 v[208:211], v170 offset:51200
	ds_read_b128 v[212:215], v170 offset:52224
	ds_read_b128 v[216:219], v170 offset:53248
	ds_read_b128 v[220:223], v170 offset:54272
	ds_read_b128 v[224:227], v170 offset:55296
	ds_read_b128 v[228:231], v170 offset:56320
	global_load_lds_dwordx4 v[232:233], off
	v_lshl_add_u64 v[232:233], v[234:235], 0, s[16:17]
	s_add_i32 m0, s26, 0x2000
	s_add_i32 s26, s69, s36
	global_load_lds_dwordx4 v[232:233], off
	v_lshl_add_u64 v[232:233], v[236:237], 0, s[16:17]
	s_mov_b32 m0, s26
	s_nop 0
	global_load_lds_dwordx4 v[232:233], off
	v_lshl_add_u64 v[232:233], v[238:239], 0, s[16:17]
	s_add_i32 m0, s26, 0x2000
	s_nop 0
	global_load_lds_dwordx4 v[232:233], off
	v_lshl_add_u64 v[232:233], v[240:241], 0, s[16:17]
	s_mov_b32 m0, s44
	s_nop 0
	global_load_lds_dwordx4 v[232:233], off
	v_lshl_add_u64 v[232:233], v[242:243], 0, s[16:17]
	s_mov_b32 m0, s45
	s_nop 0
	global_load_lds_dwordx4 v[232:233], off
	s_waitcnt vmcnt(8)
	s_waitcnt lgkmcnt(0)
	s_setprio 1
	s_waitcnt lgkmcnt(0)
	v_mfma_f32_16x16x32_bf16 v[96:99], v[148:151], v[200:203], v[96:99]
	v_mfma_f32_16x16x32_bf16 v[92:95], v[176:179], v[200:203], v[92:95]
	v_mfma_f32_16x16x32_bf16 v[88:91], v[148:151], v[208:211], v[88:91]
	v_mfma_f32_16x16x32_bf16 v[84:87], v[176:179], v[208:211], v[84:87]
	v_mfma_f32_16x16x32_bf16 v[80:83], v[148:151], v[216:219], v[80:83]
	v_mfma_f32_16x16x32_bf16 v[76:79], v[176:179], v[216:219], v[76:79]
	s_barrier
	v_mfma_f32_16x16x32_bf16 v[72:75], v[148:151], v[224:227], v[72:75]
	v_mfma_f32_16x16x32_bf16 v[68:71], v[176:179], v[224:227], v[68:71]
	v_mfma_f32_16x16x32_bf16 v[96:99], v[172:175], v[204:207], v[96:99]
	v_mfma_f32_16x16x32_bf16 v[92:95], v[180:183], v[204:207], v[92:95]
	v_mfma_f32_16x16x32_bf16 v[88:91], v[172:175], v[212:215], v[88:91]
	v_mfma_f32_16x16x32_bf16 v[84:87], v[180:183], v[212:215], v[84:87]
	v_mfma_f32_16x16x32_bf16 v[80:83], v[172:175], v[220:223], v[80:83]
	v_mfma_f32_16x16x32_bf16 v[76:79], v[180:183], v[220:223], v[76:79]
	v_mfma_f32_16x16x32_bf16 v[72:75], v[172:175], v[228:231], v[72:75]
	v_mfma_f32_16x16x32_bf16 v[68:71], v[180:183], v[228:231], v[68:71]
	s_setprio 0
	s_setprio 1
	v_mfma_f32_16x16x32_bf16 v[32:35], v[184:187], v[200:203], v[32:35]
	v_mfma_f32_16x16x32_bf16 v[28:31], v[192:195], v[200:203], v[28:31]
	v_mfma_f32_16x16x32_bf16 v[24:27], v[184:187], v[208:211], v[24:27]
	v_mfma_f32_16x16x32_bf16 v[20:23], v[192:195], v[208:211], v[20:23]
	v_mfma_f32_16x16x32_bf16 v[16:19], v[184:187], v[216:219], v[16:19]
	v_mfma_f32_16x16x32_bf16 v[12:15], v[192:195], v[216:219], v[12:15]
	v_mfma_f32_16x16x32_bf16 v[8:11], v[184:187], v[224:227], v[8:11]
	v_mfma_f32_16x16x32_bf16 v[4:7], v[192:195], v[224:227], v[4:7]
	v_mfma_f32_16x16x32_bf16 v[32:35], v[188:191], v[204:207], v[32:35]
	v_mfma_f32_16x16x32_bf16 v[28:31], v[196:199], v[204:207], v[28:31]
	v_mfma_f32_16x16x32_bf16 v[24:27], v[188:191], v[212:215], v[24:27]
	v_mfma_f32_16x16x32_bf16 v[20:23], v[196:199], v[212:215], v[20:23]
	v_mfma_f32_16x16x32_bf16 v[16:19], v[188:191], v[220:223], v[16:19]
	v_mfma_f32_16x16x32_bf16 v[12:15], v[196:199], v[220:223], v[12:15]
	v_mfma_f32_16x16x32_bf16 v[8:11], v[188:191], v[228:231], v[8:11]
	v_mfma_f32_16x16x32_bf16 v[4:7], v[196:199], v[228:231], v[4:7]
	s_setprio 0
	s_barrier
	s_add_u32 s24, s24, 0x100
	s_addc_u32 s25, s25, 0
	s_add_u32 s65, s65, 0x100
	s_addc_u32 s66, s66, 0
	s_cmp_ge_i32 s67, s46
	s_mov_b32 s26, s67
	s_cbranch_scc0 .LBB0_1461

.LBB0_1514:
	ds_read_b128 v[152:155], v149
	ds_read_b128 v[156:159], v149 offset:1024
	ds_read_b128 v[160:163], v149 offset:2048
	ds_read_b128 v[164:167], v149 offset:3072
	ds_read_b128 v[168:171], v150
	ds_read_b128 v[172:175], v150 offset:1024
	ds_read_b128 v[176:179], v150 offset:2048
	ds_read_b128 v[180:183], v150 offset:3072
	s_add_i32 s69, s36, 2
	s_add_u32 s80, s34, 0x80
	s_addc_u32 s37, s35, 0
	s_cmp_eq_u32 s59, s36
	s_cselect_b32 s36, s2, s80
	s_cselect_b32 s37, s3, s37
	s_cselect_b32 s81, s31, s68
	s_cselect_b32 s80, s30, s67
	v_lshl_add_u64 v[216:217], s[34:35], 0, v[138:139]
	s_add_i32 m0, s47, 0xc000
	ds_read_b128 v[184:187], v151
	ds_read_b128 v[188:191], v151 offset:1024
	ds_read_b128 v[192:195], v151 offset:2048
	ds_read_b128 v[196:199], v151 offset:3072
	ds_read_b128 v[200:203], v151 offset:4096
	ds_read_b128 v[204:207], v151 offset:5120
	ds_read_b128 v[208:211], v151 offset:6144
	ds_read_b128 v[212:215], v151 offset:7168
	global_load_lds_dwordx4 v[216:217], off
	v_lshl_add_u64 v[216:217], s[34:35], 0, v[140:141]
	s_add_i32 m0, s47, 0xe000
	s_nop 0
	global_load_lds_dwordx4 v[216:217], off
	s_waitcnt vmcnt(8)
	s_waitcnt lgkmcnt(0)
	s_setprio 1
	s_waitcnt lgkmcnt(0)
	v_mfma_f32_16x16x32_bf16 v[122:125], v[152:155], v[184:187], v[122:125]
	v_mfma_f32_16x16x32_bf16 v[126:129], v[160:163], v[184:187], v[126:129]
	v_mfma_f32_16x16x32_bf16 v[110:113], v[152:155], v[192:195], v[110:113]
	v_mfma_f32_16x16x32_bf16 v[106:109], v[160:163], v[192:195], v[106:109]
	v_mfma_f32_16x16x32_bf16 v[94:97], v[152:155], v[200:203], v[94:97]
	v_mfma_f32_16x16x32_bf16 v[90:93], v[160:163], v[200:203], v[90:93]
	s_barrier
	v_mfma_f32_16x16x32_bf16 v[78:81], v[152:155], v[208:211], v[78:81]
	v_mfma_f32_16x16x32_bf16 v[74:77], v[160:163], v[208:211], v[74:77]
	v_mfma_f32_16x16x32_bf16 v[122:125], v[156:159], v[188:191], v[122:125]
	v_mfma_f32_16x16x32_bf16 v[126:129], v[164:167], v[188:191], v[126:129]
	v_mfma_f32_16x16x32_bf16 v[110:113], v[156:159], v[196:199], v[110:113]
	v_mfma_f32_16x16x32_bf16 v[106:109], v[164:167], v[196:199], v[106:109]
	v_mfma_f32_16x16x32_bf16 v[94:97], v[156:159], v[204:207], v[94:97]
	v_mfma_f32_16x16x32_bf16 v[90:93], v[164:167], v[204:207], v[90:93]
	v_mfma_f32_16x16x32_bf16 v[78:81], v[156:159], v[212:215], v[78:81]
	v_mfma_f32_16x16x32_bf16 v[74:77], v[164:167], v[212:215], v[74:77]
	s_setprio 0
	s_setprio 1
	v_mfma_f32_16x16x32_bf16 v[118:121], v[168:171], v[184:187], v[118:121]
	v_mfma_f32_16x16x32_bf16 v[114:117], v[176:179], v[184:187], v[114:117]
	v_mfma_f32_16x16x32_bf16 v[102:105], v[168:171], v[192:195], v[102:105]
	v_mfma_f32_16x16x32_bf16 v[98:101], v[176:179], v[192:195], v[98:101]
	v_mfma_f32_16x16x32_bf16 v[86:89], v[168:171], v[200:203], v[86:89]
	v_mfma_f32_16x16x32_bf16 v[82:85], v[176:179], v[200:203], v[82:85]
	v_mfma_f32_16x16x32_bf16 v[70:73], v[168:171], v[208:211], v[70:73]
	v_mfma_f32_16x16x32_bf16 v[66:69], v[176:179], v[208:211], v[66:69]
	v_mfma_f32_16x16x32_bf16 v[118:121], v[172:175], v[188:191], v[118:121]
	v_mfma_f32_16x16x32_bf16 v[114:117], v[180:183], v[188:191], v[114:117]
	v_mfma_f32_16x16x32_bf16 v[102:105], v[172:175], v[196:199], v[102:105]
	v_mfma_f32_16x16x32_bf16 v[98:101], v[180:183], v[196:199], v[98:101]
	v_mfma_f32_16x16x32_bf16 v[86:89], v[172:175], v[204:207], v[86:89]
	v_mfma_f32_16x16x32_bf16 v[82:85], v[180:183], v[204:207], v[82:85]
	v_mfma_f32_16x16x32_bf16 v[70:73], v[172:175], v[212:215], v[70:73]
	v_mfma_f32_16x16x32_bf16 v[66:69], v[180:183], v[212:215], v[66:69]
	s_setprio 0
	s_barrier
	s_add_i32 s82, s61, s44
	v_lshl_add_u64 v[216:217], s[80:81], 0, v[134:135]
	s_mov_b32 m0, s82
	ds_read_b128 v[184:187], v151 offset:16384
	ds_read_b128 v[188:191], v151 offset:17408
	ds_read_b128 v[192:195], v151 offset:18432
	ds_read_b128 v[196:199], v151 offset:19456
	ds_read_b128 v[200:203], v151 offset:20480
	ds_read_b128 v[204:207], v151 offset:21504
	ds_read_b128 v[208:211], v151 offset:22528
	ds_read_b128 v[212:215], v151 offset:23552
	global_load_lds_dwordx4 v[216:217], off
	s_add_i32 m0, s82, 0x2000
	v_lshl_add_u64 v[218:219], s[80:81], 0, v[130:131]
	s_add_u32 s80, s80, s6
	s_addc_u32 s81, s81, s7
	s_add_i32 s82, s62, s44
	global_load_lds_dwordx4 v[218:219], off
	v_lshl_add_u64 v[220:221], s[80:81], 0, v[134:135]
	s_mov_b32 m0, s82
	v_lshl_add_u64 v[222:223], s[80:81], 0, v[130:131]
	global_load_lds_dwordx4 v[220:221], off
	s_add_i32 m0, s82, 0x2000
	v_lshl_add_u64 v[224:225], s[36:37], 0, v[136:137]
	global_load_lds_dwordx4 v[222:223], off
	s_mov_b32 m0, s47
	v_lshl_add_u64 v[226:227], s[36:37], 0, v[132:133]
	global_load_lds_dwordx4 v[224:225], off
	s_mov_b32 m0, s50
	s_nop 0
	global_load_lds_dwordx4 v[226:227], off
	s_waitcnt vmcnt(8)
	s_waitcnt lgkmcnt(0)
	s_setprio 1
	s_waitcnt lgkmcnt(0)
	v_mfma_f32_16x16x32_bf16 v[62:65], v[152:155], v[184:187], v[62:65]
	v_mfma_f32_16x16x32_bf16 v[58:61], v[160:163], v[184:187], v[58:61]
	v_mfma_f32_16x16x32_bf16 v[46:49], v[152:155], v[192:195], v[46:49]
	v_mfma_f32_16x16x32_bf16 v[42:45], v[160:163], v[192:195], v[42:45]
	v_mfma_f32_16x16x32_bf16 v[30:33], v[152:155], v[200:203], v[30:33]
	v_mfma_f32_16x16x32_bf16 v[26:29], v[160:163], v[200:203], v[26:29]
	s_barrier
	v_mfma_f32_16x16x32_bf16 v[14:17], v[152:155], v[208:211], v[14:17]
	v_mfma_f32_16x16x32_bf16 v[10:13], v[160:163], v[208:211], v[10:13]
	v_mfma_f32_16x16x32_bf16 v[62:65], v[156:159], v[188:191], v[62:65]
	v_mfma_f32_16x16x32_bf16 v[58:61], v[164:167], v[188:191], v[58:61]
	v_mfma_f32_16x16x32_bf16 v[46:49], v[156:159], v[196:199], v[46:49]
	v_mfma_f32_16x16x32_bf16 v[42:45], v[164:167], v[196:199], v[42:45]
	v_mfma_f32_16x16x32_bf16 v[30:33], v[156:159], v[204:207], v[30:33]
	v_mfma_f32_16x16x32_bf16 v[26:29], v[164:167], v[204:207], v[26:29]
	v_mfma_f32_16x16x32_bf16 v[14:17], v[156:159], v[212:215], v[14:17]
	v_mfma_f32_16x16x32_bf16 v[10:13], v[164:167], v[212:215], v[10:13]
	s_setprio 0
	s_setprio 1
	v_mfma_f32_16x16x32_bf16 v[54:57], v[168:171], v[184:187], v[54:57]
	v_mfma_f32_16x16x32_bf16 v[50:53], v[176:179], v[184:187], v[50:53]
	v_mfma_f32_16x16x32_bf16 v[38:41], v[168:171], v[192:195], v[38:41]
	v_mfma_f32_16x16x32_bf16 v[34:37], v[176:179], v[192:195], v[34:37]
	v_mfma_f32_16x16x32_bf16 v[22:25], v[168:171], v[200:203], v[22:25]
	v_mfma_f32_16x16x32_bf16 v[18:21], v[176:179], v[200:203], v[18:21]
	v_mfma_f32_16x16x32_bf16 v[6:9], v[168:171], v[208:211], v[6:9]
	v_mfma_f32_16x16x32_bf16 v[2:5], v[176:179], v[208:211], v[2:5]
	v_mfma_f32_16x16x32_bf16 v[54:57], v[172:175], v[188:191], v[54:57]
	v_mfma_f32_16x16x32_bf16 v[50:53], v[180:183], v[188:191], v[50:53]
	v_mfma_f32_16x16x32_bf16 v[38:41], v[172:175], v[196:199], v[38:41]
	v_mfma_f32_16x16x32_bf16 v[34:37], v[180:183], v[196:199], v[34:37]
	v_mfma_f32_16x16x32_bf16 v[22:25], v[172:175], v[204:207], v[22:25]
	v_mfma_f32_16x16x32_bf16 v[18:21], v[180:183], v[204:207], v[18:21]
	v_mfma_f32_16x16x32_bf16 v[6:9], v[172:175], v[212:215], v[6:9]
	v_mfma_f32_16x16x32_bf16 v[2:5], v[180:183], v[212:215], v[2:5]
	s_setprio 0
	s_barrier
	s_add_i32 s80, 0, 0x18000
	s_add_i32 s81, 0, 0x1c000
	v_add_u32_e32 v164, s80, v147
	v_add_u32_e32 v180, s81, v147
	ds_read_b128 v[152:155], v164
	ds_read_b128 v[156:159], v164 offset:1024
	ds_read_b128 v[160:163], v164 offset:2048
	ds_read_b128 v[164:167], v164 offset:3072
	ds_read_b128 v[168:171], v180
	ds_read_b128 v[172:175], v180 offset:1024
	ds_read_b128 v[176:179], v180 offset:2048
	ds_read_b128 v[180:183], v180 offset:3072
	s_add_u32 s36, s36, s6
	s_addc_u32 s37, s37, s7
	s_mov_b32 m0, s51
	v_lshl_add_u64 v[228:229], s[36:37], 0, v[136:137]
	ds_read_b128 v[184:187], v151 offset:32768
	ds_read_b128 v[188:191], v151 offset:33792
	ds_read_b128 v[192:195], v151 offset:34816
	ds_read_b128 v[196:199], v151 offset:35840
	ds_read_b128 v[200:203], v151 offset:36864
	ds_read_b128 v[204:207], v151 offset:37888
	ds_read_b128 v[208:211], v151 offset:38912
	ds_read_b128 v[212:215], v151 offset:39936
	global_load_lds_dwordx4 v[228:229], off
	v_lshl_add_u64 v[228:229], s[36:37], 0, v[132:133]
	s_mov_b32 m0, s54
	s_nop 0
	global_load_lds_dwordx4 v[228:229], off
	s_waitcnt vmcnt(8)
	s_waitcnt lgkmcnt(0)
	s_setprio 1
	s_waitcnt lgkmcnt(0)
	v_mfma_f32_16x16x32_bf16 v[122:125], v[152:155], v[184:187], v[122:125]
	v_mfma_f32_16x16x32_bf16 v[126:129], v[160:163], v[184:187], v[126:129]
	v_mfma_f32_16x16x32_bf16 v[110:113], v[152:155], v[192:195], v[110:113]
	v_mfma_f32_16x16x32_bf16 v[106:109], v[160:163], v[192:195], v[106:109]
	v_mfma_f32_16x16x32_bf16 v[94:97], v[152:155], v[200:203], v[94:97]
	v_mfma_f32_16x16x32_bf16 v[90:93], v[160:163], v[200:203], v[90:93]
	s_barrier
	v_mfma_f32_16x16x32_bf16 v[78:81], v[152:155], v[208:211], v[78:81]
	v_mfma_f32_16x16x32_bf16 v[74:77], v[160:163], v[208:211], v[74:77]
	v_mfma_f32_16x16x32_bf16 v[122:125], v[156:159], v[188:191], v[122:125]
	v_mfma_f32_16x16x32_bf16 v[126:129], v[164:167], v[188:191], v[126:129]
	v_mfma_f32_16x16x32_bf16 v[110:113], v[156:159], v[196:199], v[110:113]
	v_mfma_f32_16x16x32_bf16 v[106:109], v[164:167], v[196:199], v[106:109]
	v_mfma_f32_16x16x32_bf16 v[94:97], v[156:159], v[204:207], v[94:97]
	v_mfma_f32_16x16x32_bf16 v[90:93], v[164:167], v[204:207], v[90:93]
	v_mfma_f32_16x16x32_bf16 v[78:81], v[156:159], v[212:215], v[78:81]
	v_mfma_f32_16x16x32_bf16 v[74:77], v[164:167], v[212:215], v[74:77]
	s_setprio 0
	s_setprio 1
	v_mfma_f32_16x16x32_bf16 v[118:121], v[168:171], v[184:187], v[118:121]
	v_mfma_f32_16x16x32_bf16 v[114:117], v[176:179], v[184:187], v[114:117]
	v_mfma_f32_16x16x32_bf16 v[102:105], v[168:171], v[192:195], v[102:105]
	v_mfma_f32_16x16x32_bf16 v[98:101], v[176:179], v[192:195], v[98:101]
	v_mfma_f32_16x16x32_bf16 v[86:89], v[168:171], v[200:203], v[86:89]
	v_mfma_f32_16x16x32_bf16 v[82:85], v[176:179], v[200:203], v[82:85]
	v_mfma_f32_16x16x32_bf16 v[70:73], v[168:171], v[208:211], v[70:73]
	v_mfma_f32_16x16x32_bf16 v[66:69], v[176:179], v[208:211], v[66:69]
	v_mfma_f32_16x16x32_bf16 v[118:121], v[172:175], v[188:191], v[118:121]
	v_mfma_f32_16x16x32_bf16 v[114:117], v[180:183], v[188:191], v[114:117]
	v_mfma_f32_16x16x32_bf16 v[102:105], v[172:175], v[196:199], v[102:105]
	v_mfma_f32_16x16x32_bf16 v[98:101], v[180:183], v[196:199], v[98:101]
	v_mfma_f32_16x16x32_bf16 v[86:89], v[172:175], v[204:207], v[86:89]
	v_mfma_f32_16x16x32_bf16 v[82:85], v[180:183], v[204:207], v[82:85]
	v_mfma_f32_16x16x32_bf16 v[70:73], v[172:175], v[212:215], v[70:73]
	v_mfma_f32_16x16x32_bf16 v[66:69], v[180:183], v[212:215], v[66:69]
	s_setprio 0
	s_barrier
	s_add_i32 s36, s80, s44
	v_lshl_add_u64 v[216:217], v[216:217], 0, s[16:17]
	s_mov_b32 m0, s36
	ds_read_b128 v[184:187], v151 offset:49152
	ds_read_b128 v[188:191], v151 offset:50176
	ds_read_b128 v[192:195], v151 offset:51200
	ds_read_b128 v[196:199], v151 offset:52224
	ds_read_b128 v[200:203], v151 offset:53248
	ds_read_b128 v[204:207], v151 offset:54272
	ds_read_b128 v[208:211], v151 offset:55296
	ds_read_b128 v[212:215], v151 offset:56320
	global_load_lds_dwordx4 v[216:217], off
	v_lshl_add_u64 v[216:217], v[218:219], 0, s[16:17]
	s_add_i32 m0, s36, 0x2000
	s_add_i32 s36, s81, s44
	global_load_lds_dwordx4 v[216:217], off
	v_lshl_add_u64 v[216:217], v[220:221], 0, s[16:17]
	s_mov_b32 m0, s36
	s_nop 0
	global_load_lds_dwordx4 v[216:217], off
	v_lshl_add_u64 v[216:217], v[222:223], 0, s[16:17]
	s_add_i32 m0, s36, 0x2000
	s_nop 0
	global_load_lds_dwordx4 v[216:217], off
	v_lshl_add_u64 v[216:217], v[224:225], 0, s[16:17]
	s_mov_b32 m0, s56
	s_nop 0
	global_load_lds_dwordx4 v[216:217], off
	v_lshl_add_u64 v[216:217], v[226:227], 0, s[16:17]
	s_mov_b32 m0, s57
	s_nop 0
	global_load_lds_dwordx4 v[216:217], off
	s_waitcnt vmcnt(8)
	s_waitcnt lgkmcnt(0)
	s_setprio 1
	s_waitcnt lgkmcnt(0)
	v_mfma_f32_16x16x32_bf16 v[62:65], v[152:155], v[184:187], v[62:65]
	v_mfma_f32_16x16x32_bf16 v[58:61], v[160:163], v[184:187], v[58:61]
	v_mfma_f32_16x16x32_bf16 v[46:49], v[152:155], v[192:195], v[46:49]
	v_mfma_f32_16x16x32_bf16 v[42:45], v[160:163], v[192:195], v[42:45]
	v_mfma_f32_16x16x32_bf16 v[30:33], v[152:155], v[200:203], v[30:33]
	v_mfma_f32_16x16x32_bf16 v[26:29], v[160:163], v[200:203], v[26:29]
	s_barrier
	v_mfma_f32_16x16x32_bf16 v[14:17], v[152:155], v[208:211], v[14:17]
	v_mfma_f32_16x16x32_bf16 v[10:13], v[160:163], v[208:211], v[10:13]
	v_mfma_f32_16x16x32_bf16 v[62:65], v[156:159], v[188:191], v[62:65]
	v_mfma_f32_16x16x32_bf16 v[58:61], v[164:167], v[188:191], v[58:61]
	v_mfma_f32_16x16x32_bf16 v[46:49], v[156:159], v[196:199], v[46:49]
	v_mfma_f32_16x16x32_bf16 v[42:45], v[164:167], v[196:199], v[42:45]
	v_mfma_f32_16x16x32_bf16 v[30:33], v[156:159], v[204:207], v[30:33]
	v_mfma_f32_16x16x32_bf16 v[26:29], v[164:167], v[204:207], v[26:29]
	v_mfma_f32_16x16x32_bf16 v[14:17], v[156:159], v[212:215], v[14:17]
	v_mfma_f32_16x16x32_bf16 v[10:13], v[164:167], v[212:215], v[10:13]
	s_setprio 0
	s_setprio 1
	v_mfma_f32_16x16x32_bf16 v[54:57], v[168:171], v[184:187], v[54:57]
	v_mfma_f32_16x16x32_bf16 v[50:53], v[176:179], v[184:187], v[50:53]
	v_mfma_f32_16x16x32_bf16 v[38:41], v[168:171], v[192:195], v[38:41]
	v_mfma_f32_16x16x32_bf16 v[34:37], v[176:179], v[192:195], v[34:37]
	v_mfma_f32_16x16x32_bf16 v[22:25], v[168:171], v[200:203], v[22:25]
	v_mfma_f32_16x16x32_bf16 v[18:21], v[176:179], v[200:203], v[18:21]
	v_mfma_f32_16x16x32_bf16 v[6:9], v[168:171], v[208:211], v[6:9]
	v_mfma_f32_16x16x32_bf16 v[2:5], v[176:179], v[208:211], v[2:5]
	v_mfma_f32_16x16x32_bf16 v[54:57], v[172:175], v[188:191], v[54:57]
	v_mfma_f32_16x16x32_bf16 v[50:53], v[180:183], v[188:191], v[50:53]
	v_mfma_f32_16x16x32_bf16 v[38:41], v[172:175], v[196:199], v[38:41]
	v_mfma_f32_16x16x32_bf16 v[34:37], v[180:183], v[196:199], v[34:37]
	v_mfma_f32_16x16x32_bf16 v[22:25], v[172:175], v[204:207], v[22:25]
	v_mfma_f32_16x16x32_bf16 v[18:21], v[180:183], v[204:207], v[18:21]
	v_mfma_f32_16x16x32_bf16 v[6:9], v[172:175], v[212:215], v[6:9]
	v_mfma_f32_16x16x32_bf16 v[2:5], v[180:183], v[212:215], v[2:5]
	s_setprio 0
	s_barrier
	s_add_u32 s34, s34, 0x100
	s_addc_u32 s35, s35, 0
	s_add_u32 s67, s67, 0x100
	s_addc_u32 s68, s68, 0
	s_cmp_ge_i32 s69, s58
	s_mov_b32 s36, s69
	s_cbranch_scc0 .LBB0_1514

.LBB0_1754:
	v_add_u32_e32 v158, s80, v229
	v_add_u32_e32 v174, s81, v229
	ds_read_b128 v[146:149], v158
	ds_read_b128 v[150:153], v158 offset:1024
	ds_read_b128 v[154:157], v158 offset:2048
	ds_read_b128 v[158:161], v158 offset:3072
	ds_read_b128 v[162:165], v174
	ds_read_b128 v[166:169], v174 offset:1024
	ds_read_b128 v[170:173], v174 offset:2048
	ds_read_b128 v[174:177], v174 offset:3072
	s_add_i32 s88, s44, 2
	s_add_u32 s89, s42, 0x80
	s_addc_u32 s45, s43, 0
	s_cmp_eq_u32 s67, s44
	s_cselect_b32 s44, s4, s89
	s_cselect_b32 s45, s5, s45
	s_cselect_b32 s91, s39, s87
	s_cselect_b32 s90, s38, s86
	v_lshl_add_u64 v[210:211], s[42:43], 0, v[138:139]
	s_add_i32 m0, s55, 0xc000
	ds_read_b128 v[178:181], v231
	ds_read_b128 v[182:185], v231 offset:1024
	ds_read_b128 v[186:189], v231 offset:2048
	ds_read_b128 v[190:193], v231 offset:3072
	ds_read_b128 v[194:197], v231 offset:4096
	ds_read_b128 v[198:201], v231 offset:5120
	ds_read_b128 v[202:205], v231 offset:6144
	ds_read_b128 v[206:209], v231 offset:7168
	global_load_lds_dwordx4 v[210:211], off
	v_lshl_add_u64 v[210:211], s[42:43], 0, v[140:141]
	s_add_i32 m0, s55, 0xe000
	s_nop 0
	global_load_lds_dwordx4 v[210:211], off
	s_waitcnt vmcnt(8)
	s_waitcnt lgkmcnt(0)
	s_setprio 1
	s_waitcnt lgkmcnt(0)
	v_mfma_i32_16x16x64_i8 v[126:129], v[146:149], v[178:181], v[126:129]
	v_mfma_i32_16x16x64_i8 v[122:125], v[154:157], v[178:181], v[122:125]
	v_mfma_i32_16x16x64_i8 v[118:121], v[146:149], v[186:189], v[118:121]
	v_mfma_i32_16x16x64_i8 v[114:117], v[154:157], v[186:189], v[114:117]
	v_mfma_i32_16x16x64_i8 v[106:109], v[146:149], v[194:197], v[106:109]
	v_mfma_i32_16x16x64_i8 v[98:101], v[154:157], v[194:197], v[98:101]
	s_barrier
	v_mfma_i32_16x16x64_i8 v[90:93], v[146:149], v[202:205], v[90:93]
	v_mfma_i32_16x16x64_i8 v[82:85], v[154:157], v[202:205], v[82:85]
	v_mfma_i32_16x16x64_i8 v[126:129], v[150:153], v[182:185], v[126:129]
	v_mfma_i32_16x16x64_i8 v[122:125], v[158:161], v[182:185], v[122:125]
	v_mfma_i32_16x16x64_i8 v[118:121], v[150:153], v[190:193], v[118:121]
	v_mfma_i32_16x16x64_i8 v[114:117], v[158:161], v[190:193], v[114:117]
	v_mfma_i32_16x16x64_i8 v[106:109], v[150:153], v[198:201], v[106:109]
	v_mfma_i32_16x16x64_i8 v[98:101], v[158:161], v[198:201], v[98:101]
	v_mfma_i32_16x16x64_i8 v[90:93], v[150:153], v[206:209], v[90:93]
	v_mfma_i32_16x16x64_i8 v[82:85], v[158:161], v[206:209], v[82:85]
	s_setprio 0
	s_setprio 1
	v_mfma_i32_16x16x64_i8 v[110:113], v[162:165], v[178:181], v[110:113]
	v_mfma_i32_16x16x64_i8 v[102:105], v[170:173], v[178:181], v[102:105]
	v_mfma_i32_16x16x64_i8 v[94:97], v[162:165], v[186:189], v[94:97]
	v_mfma_i32_16x16x64_i8 v[86:89], v[170:173], v[186:189], v[86:89]
	v_mfma_i32_16x16x64_i8 v[78:81], v[162:165], v[194:197], v[78:81]
	v_mfma_i32_16x16x64_i8 v[74:77], v[170:173], v[194:197], v[74:77]
	v_mfma_i32_16x16x64_i8 v[70:73], v[162:165], v[202:205], v[70:73]
	v_mfma_i32_16x16x64_i8 v[66:69], v[170:173], v[202:205], v[66:69]
	v_mfma_i32_16x16x64_i8 v[110:113], v[166:169], v[182:185], v[110:113]
	v_mfma_i32_16x16x64_i8 v[102:105], v[174:177], v[182:185], v[102:105]
	v_mfma_i32_16x16x64_i8 v[94:97], v[166:169], v[190:193], v[94:97]
	v_mfma_i32_16x16x64_i8 v[86:89], v[174:177], v[190:193], v[86:89]
	v_mfma_i32_16x16x64_i8 v[78:81], v[166:169], v[198:201], v[78:81]
	v_mfma_i32_16x16x64_i8 v[74:77], v[174:177], v[198:201], v[74:77]
	v_mfma_i32_16x16x64_i8 v[70:73], v[166:169], v[206:209], v[70:73]
	v_mfma_i32_16x16x64_i8 v[66:69], v[174:177], v[206:209], v[66:69]
	s_setprio 0
	s_barrier
	s_add_i32 s89, s80, s54
	v_lshl_add_u64 v[210:211], s[90:91], 0, v[132:133]
	s_mov_b32 m0, s89
	ds_read_b128 v[178:181], v231 offset:16384
	ds_read_b128 v[182:185], v231 offset:17408
	ds_read_b128 v[186:189], v231 offset:18432
	ds_read_b128 v[190:193], v231 offset:19456
	ds_read_b128 v[194:197], v231 offset:20480
	ds_read_b128 v[198:201], v231 offset:21504
	ds_read_b128 v[202:205], v231 offset:22528
	ds_read_b128 v[206:209], v231 offset:23552
	global_load_lds_dwordx4 v[210:211], off
	s_add_i32 m0, s89, 0x2000
	v_lshl_add_u64 v[212:213], s[90:91], 0, v[136:137]
	s_add_u32 s90, s90, s8
	s_addc_u32 s91, s91, s9
	s_add_i32 s89, s81, s54
	global_load_lds_dwordx4 v[212:213], off
	v_lshl_add_u64 v[214:215], s[90:91], 0, v[132:133]
	s_mov_b32 m0, s89
	v_lshl_add_u64 v[216:217], s[90:91], 0, v[136:137]
	global_load_lds_dwordx4 v[214:215], off
	s_add_i32 m0, s89, 0x2000
	v_lshl_add_u64 v[218:219], s[44:45], 0, v[130:131]
	global_load_lds_dwordx4 v[216:217], off
	s_mov_b32 m0, s55
	v_lshl_add_u64 v[220:221], s[44:45], 0, v[134:135]
	global_load_lds_dwordx4 v[218:219], off
	s_mov_b32 m0, s56
	s_nop 0
	global_load_lds_dwordx4 v[220:221], off
	s_waitcnt vmcnt(8)
	s_waitcnt lgkmcnt(0)
	s_setprio 1
	s_waitcnt lgkmcnt(0)
	v_mfma_i32_16x16x64_i8 v[62:65], v[146:149], v[178:181], v[62:65]
	v_mfma_i32_16x16x64_i8 v[58:61], v[154:157], v[178:181], v[58:61]
	v_mfma_i32_16x16x64_i8 v[54:57], v[146:149], v[186:189], v[54:57]
	v_mfma_i32_16x16x64_i8 v[50:53], v[154:157], v[186:189], v[50:53]
	v_mfma_i32_16x16x64_i8 v[42:45], v[146:149], v[194:197], v[42:45]
	v_mfma_i32_16x16x64_i8 v[34:37], v[154:157], v[194:197], v[34:37]
	s_barrier
	v_mfma_i32_16x16x64_i8 v[26:29], v[146:149], v[202:205], v[26:29]
	v_mfma_i32_16x16x64_i8 v[18:21], v[154:157], v[202:205], v[18:21]
	v_mfma_i32_16x16x64_i8 v[62:65], v[150:153], v[182:185], v[62:65]
	v_mfma_i32_16x16x64_i8 v[58:61], v[158:161], v[182:185], v[58:61]
	v_mfma_i32_16x16x64_i8 v[54:57], v[150:153], v[190:193], v[54:57]
	v_mfma_i32_16x16x64_i8 v[50:53], v[158:161], v[190:193], v[50:53]
	v_mfma_i32_16x16x64_i8 v[42:45], v[150:153], v[198:201], v[42:45]
	v_mfma_i32_16x16x64_i8 v[34:37], v[158:161], v[198:201], v[34:37]
	v_mfma_i32_16x16x64_i8 v[26:29], v[150:153], v[206:209], v[26:29]
	v_mfma_i32_16x16x64_i8 v[18:21], v[158:161], v[206:209], v[18:21]
	s_setprio 0
	s_setprio 1
	v_mfma_i32_16x16x64_i8 v[46:49], v[162:165], v[178:181], v[46:49]
	v_mfma_i32_16x16x64_i8 v[38:41], v[170:173], v[178:181], v[38:41]
	v_mfma_i32_16x16x64_i8 v[30:33], v[162:165], v[186:189], v[30:33]
	v_mfma_i32_16x16x64_i8 v[22:25], v[170:173], v[186:189], v[22:25]
	v_mfma_i32_16x16x64_i8 v[14:17], v[162:165], v[194:197], v[14:17]
	v_mfma_i32_16x16x64_i8 v[10:13], v[170:173], v[194:197], v[10:13]
	v_mfma_i32_16x16x64_i8 v[6:9], v[162:165], v[202:205], v[6:9]
	v_mfma_i32_16x16x64_i8 v[2:5], v[170:173], v[202:205], v[2:5]
	v_mfma_i32_16x16x64_i8 v[46:49], v[166:169], v[182:185], v[46:49]
	v_mfma_i32_16x16x64_i8 v[38:41], v[174:177], v[182:185], v[38:41]
	v_mfma_i32_16x16x64_i8 v[30:33], v[166:169], v[190:193], v[30:33]
	v_mfma_i32_16x16x64_i8 v[22:25], v[174:177], v[190:193], v[22:25]
	v_mfma_i32_16x16x64_i8 v[14:17], v[166:169], v[198:201], v[14:17]
	v_mfma_i32_16x16x64_i8 v[10:13], v[174:177], v[198:201], v[10:13]
	v_mfma_i32_16x16x64_i8 v[6:9], v[166:169], v[206:209], v[6:9]
	v_mfma_i32_16x16x64_i8 v[2:5], v[174:177], v[206:209], v[2:5]
	s_setprio 0
	s_barrier
	s_add_i32 s89, 0, 0x18000
	s_add_i32 s90, 0, 0x1c000
	v_add_u32_e32 v158, s89, v229
	v_add_u32_e32 v174, s90, v229
	ds_read_b128 v[146:149], v158
	ds_read_b128 v[150:153], v158 offset:1024
	ds_read_b128 v[154:157], v158 offset:2048
	ds_read_b128 v[158:161], v158 offset:3072
	ds_read_b128 v[162:165], v174
	ds_read_b128 v[166:169], v174 offset:1024
	ds_read_b128 v[170:173], v174 offset:2048
	ds_read_b128 v[174:177], v174 offset:3072
	s_add_u32 s44, s44, s8
	s_addc_u32 s45, s45, s9
	s_mov_b32 m0, s57
	v_lshl_add_u64 v[222:223], s[44:45], 0, v[130:131]
	ds_read_b128 v[178:181], v231 offset:32768
	ds_read_b128 v[182:185], v231 offset:33792
	ds_read_b128 v[186:189], v231 offset:34816
	ds_read_b128 v[190:193], v231 offset:35840
	ds_read_b128 v[194:197], v231 offset:36864
	ds_read_b128 v[198:201], v231 offset:37888
	ds_read_b128 v[202:205], v231 offset:38912
	ds_read_b128 v[206:209], v231 offset:39936
	global_load_lds_dwordx4 v[222:223], off
	v_lshl_add_u64 v[222:223], s[44:45], 0, v[134:135]
	s_mov_b32 m0, s58
	s_nop 0
	global_load_lds_dwordx4 v[222:223], off
	s_waitcnt vmcnt(8)
	s_waitcnt lgkmcnt(0)
	s_setprio 1
	s_waitcnt lgkmcnt(0)
	v_mfma_i32_16x16x64_i8 v[126:129], v[146:149], v[178:181], v[126:129]
	v_mfma_i32_16x16x64_i8 v[122:125], v[154:157], v[178:181], v[122:125]
	v_mfma_i32_16x16x64_i8 v[118:121], v[146:149], v[186:189], v[118:121]
	v_mfma_i32_16x16x64_i8 v[114:117], v[154:157], v[186:189], v[114:117]
	v_mfma_i32_16x16x64_i8 v[106:109], v[146:149], v[194:197], v[106:109]
	v_mfma_i32_16x16x64_i8 v[98:101], v[154:157], v[194:197], v[98:101]
	s_barrier
	v_mfma_i32_16x16x64_i8 v[90:93], v[146:149], v[202:205], v[90:93]
	v_mfma_i32_16x16x64_i8 v[82:85], v[154:157], v[202:205], v[82:85]
	v_mfma_i32_16x16x64_i8 v[126:129], v[150:153], v[182:185], v[126:129]
	v_mfma_i32_16x16x64_i8 v[122:125], v[158:161], v[182:185], v[122:125]
	v_mfma_i32_16x16x64_i8 v[118:121], v[150:153], v[190:193], v[118:121]
	v_mfma_i32_16x16x64_i8 v[114:117], v[158:161], v[190:193], v[114:117]
	v_mfma_i32_16x16x64_i8 v[106:109], v[150:153], v[198:201], v[106:109]
	v_mfma_i32_16x16x64_i8 v[98:101], v[158:161], v[198:201], v[98:101]
	v_mfma_i32_16x16x64_i8 v[90:93], v[150:153], v[206:209], v[90:93]
	v_mfma_i32_16x16x64_i8 v[82:85], v[158:161], v[206:209], v[82:85]
	s_setprio 0
	s_setprio 1
	v_mfma_i32_16x16x64_i8 v[110:113], v[162:165], v[178:181], v[110:113]
	v_mfma_i32_16x16x64_i8 v[102:105], v[170:173], v[178:181], v[102:105]
	v_mfma_i32_16x16x64_i8 v[94:97], v[162:165], v[186:189], v[94:97]
	v_mfma_i32_16x16x64_i8 v[86:89], v[170:173], v[186:189], v[86:89]
	v_mfma_i32_16x16x64_i8 v[78:81], v[162:165], v[194:197], v[78:81]
	v_mfma_i32_16x16x64_i8 v[74:77], v[170:173], v[194:197], v[74:77]
	v_mfma_i32_16x16x64_i8 v[70:73], v[162:165], v[202:205], v[70:73]
	v_mfma_i32_16x16x64_i8 v[66:69], v[170:173], v[202:205], v[66:69]
	v_mfma_i32_16x16x64_i8 v[110:113], v[166:169], v[182:185], v[110:113]
	v_mfma_i32_16x16x64_i8 v[102:105], v[174:177], v[182:185], v[102:105]
	v_mfma_i32_16x16x64_i8 v[94:97], v[166:169], v[190:193], v[94:97]
	v_mfma_i32_16x16x64_i8 v[86:89], v[174:177], v[190:193], v[86:89]
	v_mfma_i32_16x16x64_i8 v[78:81], v[166:169], v[198:201], v[78:81]
	v_mfma_i32_16x16x64_i8 v[74:77], v[174:177], v[198:201], v[74:77]
	v_mfma_i32_16x16x64_i8 v[70:73], v[166:169], v[206:209], v[70:73]
	v_mfma_i32_16x16x64_i8 v[66:69], v[174:177], v[206:209], v[66:69]
	s_setprio 0
	s_barrier
	s_add_i32 s44, s89, s54
	v_lshl_add_u64 v[210:211], v[210:211], 0, s[30:31]
	s_mov_b32 m0, s44
	ds_read_b128 v[178:181], v231 offset:49152
	ds_read_b128 v[182:185], v231 offset:50176
	ds_read_b128 v[186:189], v231 offset:51200
	ds_read_b128 v[190:193], v231 offset:52224
	ds_read_b128 v[194:197], v231 offset:53248
	ds_read_b128 v[198:201], v231 offset:54272
	ds_read_b128 v[202:205], v231 offset:55296
	ds_read_b128 v[206:209], v231 offset:56320
	global_load_lds_dwordx4 v[210:211], off
	v_lshl_add_u64 v[210:211], v[212:213], 0, s[30:31]
	s_add_i32 m0, s44, 0x2000
	s_add_i32 s44, s90, s54
	global_load_lds_dwordx4 v[210:211], off
	v_lshl_add_u64 v[210:211], v[214:215], 0, s[30:31]
	s_mov_b32 m0, s44
	s_nop 0
	global_load_lds_dwordx4 v[210:211], off
	v_lshl_add_u64 v[210:211], v[216:217], 0, s[30:31]
	s_add_i32 m0, s44, 0x2000
	s_nop 0
	global_load_lds_dwordx4 v[210:211], off
	v_lshl_add_u64 v[210:211], v[218:219], 0, s[30:31]
	s_mov_b32 m0, s63
	s_nop 0
	global_load_lds_dwordx4 v[210:211], off
	v_lshl_add_u64 v[210:211], v[220:221], 0, s[30:31]
	s_mov_b32 m0, s64
	s_nop 0
	global_load_lds_dwordx4 v[210:211], off
	s_waitcnt vmcnt(8)
	s_waitcnt lgkmcnt(0)
	s_setprio 1
	s_waitcnt lgkmcnt(0)
	v_mfma_i32_16x16x64_i8 v[62:65], v[146:149], v[178:181], v[62:65]
	v_mfma_i32_16x16x64_i8 v[58:61], v[154:157], v[178:181], v[58:61]
	v_mfma_i32_16x16x64_i8 v[54:57], v[146:149], v[186:189], v[54:57]
	v_mfma_i32_16x16x64_i8 v[50:53], v[154:157], v[186:189], v[50:53]
	v_mfma_i32_16x16x64_i8 v[42:45], v[146:149], v[194:197], v[42:45]
	v_mfma_i32_16x16x64_i8 v[34:37], v[154:157], v[194:197], v[34:37]
	s_barrier
	v_mfma_i32_16x16x64_i8 v[26:29], v[146:149], v[202:205], v[26:29]
	v_mfma_i32_16x16x64_i8 v[18:21], v[154:157], v[202:205], v[18:21]
	v_mfma_i32_16x16x64_i8 v[62:65], v[150:153], v[182:185], v[62:65]
	v_mfma_i32_16x16x64_i8 v[58:61], v[158:161], v[182:185], v[58:61]
	v_mfma_i32_16x16x64_i8 v[54:57], v[150:153], v[190:193], v[54:57]
	v_mfma_i32_16x16x64_i8 v[50:53], v[158:161], v[190:193], v[50:53]
	v_mfma_i32_16x16x64_i8 v[42:45], v[150:153], v[198:201], v[42:45]
	v_mfma_i32_16x16x64_i8 v[34:37], v[158:161], v[198:201], v[34:37]
	v_mfma_i32_16x16x64_i8 v[26:29], v[150:153], v[206:209], v[26:29]
	v_mfma_i32_16x16x64_i8 v[18:21], v[158:161], v[206:209], v[18:21]
	s_setprio 0
	s_setprio 1
	v_mfma_i32_16x16x64_i8 v[46:49], v[162:165], v[178:181], v[46:49]
	v_mfma_i32_16x16x64_i8 v[38:41], v[170:173], v[178:181], v[38:41]
	v_mfma_i32_16x16x64_i8 v[30:33], v[162:165], v[186:189], v[30:33]
	v_mfma_i32_16x16x64_i8 v[22:25], v[170:173], v[186:189], v[22:25]
	v_mfma_i32_16x16x64_i8 v[14:17], v[162:165], v[194:197], v[14:17]
	v_mfma_i32_16x16x64_i8 v[10:13], v[170:173], v[194:197], v[10:13]
	v_mfma_i32_16x16x64_i8 v[6:9], v[162:165], v[202:205], v[6:9]
	v_mfma_i32_16x16x64_i8 v[2:5], v[170:173], v[202:205], v[2:5]
	v_mfma_i32_16x16x64_i8 v[46:49], v[166:169], v[182:185], v[46:49]
	v_mfma_i32_16x16x64_i8 v[38:41], v[174:177], v[182:185], v[38:41]
	v_mfma_i32_16x16x64_i8 v[30:33], v[166:169], v[190:193], v[30:33]
	v_mfma_i32_16x16x64_i8 v[22:25], v[174:177], v[190:193], v[22:25]
	v_mfma_i32_16x16x64_i8 v[14:17], v[166:169], v[198:201], v[14:17]
	v_mfma_i32_16x16x64_i8 v[10:13], v[174:177], v[198:201], v[10:13]
	v_mfma_i32_16x16x64_i8 v[6:9], v[166:169], v[206:209], v[6:9]
	v_mfma_i32_16x16x64_i8 v[2:5], v[174:177], v[206:209], v[2:5]
	s_setprio 0
	s_barrier
	s_add_u32 s42, s42, 0x100
	s_addc_u32 s43, s43, 0
	s_add_u32 s86, s86, 0x100
	s_addc_u32 s87, s87, 0
	s_cmp_ge_i32 s88, s66
	s_mov_b32 s44, s88
	s_cbranch_scc0 .LBB0_1754
	v_cvt_f32_i32_e32 v214, v126
	v_cvt_f32_i32_e32 v215, v127
	v_cvt_f32_i32_e32 v212, v128
	v_cvt_f32_i32_e32 v213, v129
	v_cvt_f32_i32_e32 v218, v122
	v_cvt_f32_i32_e32 v219, v123
	v_cvt_f32_i32_e32 v216, v124
	v_cvt_f32_i32_e32 v217, v125
	v_cvt_f32_i32_e32 v222, v110
	v_cvt_f32_i32_e32 v223, v111
	v_cvt_f32_i32_e32 v220, v112
	v_cvt_f32_i32_e32 v221, v113
	v_cvt_f32_i32_e32 v226, v102
	v_cvt_f32_i32_e32 v227, v103
	v_cvt_f32_i32_e32 v224, v104
	v_cvt_f32_i32_e32 v225, v105
	v_cvt_f32_i32_e32 v194, v118
	v_cvt_f32_i32_e32 v195, v119
	v_cvt_f32_i32_e32 v192, v120
	v_cvt_f32_i32_e32 v193, v121
	v_cvt_f32_i32_e32 v200, v114
	v_cvt_f32_i32_e32 v201, v115
	v_cvt_f32_i32_e32 v198, v116
	v_cvt_f32_i32_e32 v199, v117
	v_cvt_f32_i32_e32 v206, v94
	v_cvt_f32_i32_e32 v207, v95
	v_cvt_f32_i32_e32 v202, v96
	v_cvt_f32_i32_e32 v203, v97
	v_cvt_f32_i32_e32 v208, v86
	v_cvt_f32_i32_e32 v209, v87
	v_cvt_f32_i32_e32 v204, v88
	v_cvt_f32_i32_e32 v205, v89
	v_cvt_f32_i32_e32 v178, v106
	v_cvt_f32_i32_e32 v179, v107
	v_cvt_f32_i32_e32 v176, v108
	v_cvt_f32_i32_e32 v177, v109
	v_cvt_f32_i32_e32 v182, v98
	v_cvt_f32_i32_e32 v183, v99
	v_cvt_f32_i32_e32 v180, v100
	v_cvt_f32_i32_e32 v181, v101
	v_cvt_f32_i32_e32 v188, v78
	v_cvt_f32_i32_e32 v189, v79
	v_cvt_f32_i32_e32 v184, v80
	v_cvt_f32_i32_e32 v185, v81
	v_cvt_f32_i32_e32 v190, v74
	v_cvt_f32_i32_e32 v191, v75
	v_cvt_f32_i32_e32 v186, v76
	v_cvt_f32_i32_e32 v187, v77
	v_cvt_f32_i32_e32 v162, v90
	v_cvt_f32_i32_e32 v163, v91
	v_cvt_f32_i32_e32 v160, v92
	v_cvt_f32_i32_e32 v161, v93
	v_cvt_f32_i32_e32 v166, v82
	v_cvt_f32_i32_e32 v167, v83
	v_cvt_f32_i32_e32 v164, v84
	v_cvt_f32_i32_e32 v165, v85
	v_cvt_f32_i32_e32 v172, v70
	v_cvt_f32_i32_e32 v173, v71
	v_cvt_f32_i32_e32 v168, v72
	v_cvt_f32_i32_e32 v169, v73
	v_cvt_f32_i32_e32 v174, v66
	v_cvt_f32_i32_e32 v175, v67
	v_cvt_f32_i32_e32 v170, v68
	v_cvt_f32_i32_e32 v171, v69
	v_cvt_f32_i32_e32 v146, v62
	v_cvt_f32_i32_e32 v147, v63
	v_cvt_f32_i32_e32 v128, v64
	v_cvt_f32_i32_e32 v129, v65
	v_cvt_f32_i32_e32 v150, v58
	v_cvt_f32_i32_e32 v151, v59
	v_cvt_f32_i32_e32 v148, v60
	v_cvt_f32_i32_e32 v149, v61
	v_cvt_f32_i32_e32 v156, v46
	v_cvt_f32_i32_e32 v157, v47
	v_cvt_f32_i32_e32 v152, v48
	v_cvt_f32_i32_e32 v153, v49
	v_cvt_f32_i32_e32 v158, v38
	v_cvt_f32_i32_e32 v159, v39
	v_cvt_f32_i32_e32 v154, v40
	v_cvt_f32_i32_e32 v155, v41
	v_cvt_f32_i32_e32 v114, v54
	v_cvt_f32_i32_e32 v115, v55
	v_cvt_f32_i32_e32 v112, v56
	v_cvt_f32_i32_e32 v113, v57
	v_cvt_f32_i32_e32 v118, v50
	v_cvt_f32_i32_e32 v119, v51
	v_cvt_f32_i32_e32 v116, v52
	v_cvt_f32_i32_e32 v117, v53
	v_cvt_f32_i32_e32 v124, v30
	v_cvt_f32_i32_e32 v125, v31
	v_cvt_f32_i32_e32 v120, v32
	v_cvt_f32_i32_e32 v121, v33
	v_cvt_f32_i32_e32 v126, v22
	v_cvt_f32_i32_e32 v127, v23
	v_cvt_f32_i32_e32 v122, v24
	v_cvt_f32_i32_e32 v123, v25
	v_cvt_f32_i32_e32 v64, v42
	v_cvt_f32_i32_e32 v65, v43
	v_cvt_f32_i32_e32 v62, v44
	v_cvt_f32_i32_e32 v63, v45
	v_cvt_f32_i32_e32 v68, v34
	v_cvt_f32_i32_e32 v69, v35
	v_cvt_f32_i32_e32 v66, v36
	v_cvt_f32_i32_e32 v67, v37
	v_cvt_f32_i32_e32 v74, v14
	v_cvt_f32_i32_e32 v75, v15
	v_cvt_f32_i32_e32 v70, v16
	v_cvt_f32_i32_e32 v71, v17
	v_cvt_f32_i32_e32 v76, v10
	v_cvt_f32_i32_e32 v77, v11
	v_cvt_f32_i32_e32 v72, v12
	v_cvt_f32_i32_e32 v73, v13
	v_cvt_f32_i32_e32 v48, v26
	v_cvt_f32_i32_e32 v49, v27
	v_cvt_f32_i32_e32 v46, v28
	v_cvt_f32_i32_e32 v47, v29
	v_cvt_f32_i32_e32 v52, v18
	v_cvt_f32_i32_e32 v53, v19
	v_cvt_f32_i32_e32 v50, v20
	v_cvt_f32_i32_e32 v51, v21
	v_cvt_f32_i32_e32 v58, v6
	v_cvt_f32_i32_e32 v59, v7
	v_cvt_f32_i32_e32 v54, v8
	v_cvt_f32_i32_e32 v55, v9
	v_cvt_f32_i32_e32 v60, v2
	v_cvt_f32_i32_e32 v61, v3
	v_cvt_f32_i32_e32 v56, v4
	v_cvt_f32_i32_e32 v57, v5

.LBB0_1939:
	v_add_u32_e32 v138, s62, v188
	ds_read_b128 v[148:151], v138
	ds_read_b128 v[152:155], v138 offset:1024
	ds_read_b128 v[156:159], v138 offset:2048
	ds_read_b128 v[160:163], v138 offset:3072
	v_add_u32_e32 v138, s63, v188
	ds_read_b128 v[164:167], v138
	ds_read_b128 v[168:171], v138 offset:1024
	ds_read_b128 v[172:175], v138 offset:2048
	ds_read_b128 v[176:179], v138 offset:3072
	s_add_i32 s66, s28, 2
	s_add_u32 s67, s26, 0x80
	s_addc_u32 s29, s27, 0
	s_cmp_eq_u32 s60, s28
	s_cselect_b32 s28, s2, s67
	s_cselect_b32 s29, s3, s29
	s_cselect_b32 s69, s25, s35
	s_cselect_b32 s68, s24, s34
	v_lshl_add_u64 v[184:185], s[26:27], 0, v[140:141]
	s_add_i32 m0, s44, 0xc000
	ds_read_b128 v[180:183], v189
	ds_read_b128 v[190:193], v189 offset:1024
	ds_read_b128 v[194:197], v189 offset:2048
	ds_read_b128 v[198:201], v189 offset:3072
	ds_read_b128 v[202:205], v189 offset:4096
	ds_read_b128 v[206:209], v189 offset:5120
	ds_read_b128 v[210:213], v189 offset:6144
	ds_read_b128 v[214:217], v189 offset:7168
	global_load_lds_dwordx4 v[184:185], off
	v_lshl_add_u64 v[184:185], s[26:27], 0, v[142:143]
	s_add_i32 m0, s44, 0xe000
	s_nop 0
	global_load_lds_dwordx4 v[184:185], off
	s_waitcnt vmcnt(8)
	s_waitcnt lgkmcnt(0)
	s_setprio 1
	s_waitcnt lgkmcnt(0)
	v_mfma_i32_16x16x64_i8 v[126:129], v[148:151], v[180:183], v[126:129]
	v_mfma_i32_16x16x64_i8 v[122:125], v[156:159], v[180:183], v[122:125]
	v_mfma_i32_16x16x64_i8 v[118:121], v[148:151], v[194:197], v[118:121]
	v_mfma_i32_16x16x64_i8 v[114:117], v[156:159], v[194:197], v[114:117]
	v_mfma_i32_16x16x64_i8 v[106:109], v[148:151], v[202:205], v[106:109]
	v_mfma_i32_16x16x64_i8 v[98:101], v[156:159], v[202:205], v[98:101]
	s_barrier
	v_mfma_i32_16x16x64_i8 v[90:93], v[148:151], v[210:213], v[90:93]
	v_mfma_i32_16x16x64_i8 v[82:85], v[156:159], v[210:213], v[82:85]
	v_mfma_i32_16x16x64_i8 v[126:129], v[152:155], v[190:193], v[126:129]
	v_mfma_i32_16x16x64_i8 v[122:125], v[160:163], v[190:193], v[122:125]
	v_mfma_i32_16x16x64_i8 v[118:121], v[152:155], v[198:201], v[118:121]
	v_mfma_i32_16x16x64_i8 v[114:117], v[160:163], v[198:201], v[114:117]
	v_mfma_i32_16x16x64_i8 v[106:109], v[152:155], v[206:209], v[106:109]
	v_mfma_i32_16x16x64_i8 v[98:101], v[160:163], v[206:209], v[98:101]
	v_mfma_i32_16x16x64_i8 v[90:93], v[152:155], v[214:217], v[90:93]
	v_mfma_i32_16x16x64_i8 v[82:85], v[160:163], v[214:217], v[82:85]
	s_setprio 0
	s_setprio 1
	v_mfma_i32_16x16x64_i8 v[110:113], v[164:167], v[180:183], v[110:113]
	v_mfma_i32_16x16x64_i8 v[102:105], v[172:175], v[180:183], v[102:105]
	v_mfma_i32_16x16x64_i8 v[94:97], v[164:167], v[194:197], v[94:97]
	v_mfma_i32_16x16x64_i8 v[86:89], v[172:175], v[194:197], v[86:89]
	v_mfma_i32_16x16x64_i8 v[78:81], v[164:167], v[202:205], v[78:81]
	v_mfma_i32_16x16x64_i8 v[74:77], v[172:175], v[202:205], v[74:77]
	v_mfma_i32_16x16x64_i8 v[70:73], v[164:167], v[210:213], v[70:73]
	v_mfma_i32_16x16x64_i8 v[66:69], v[172:175], v[210:213], v[66:69]
	v_mfma_i32_16x16x64_i8 v[110:113], v[168:171], v[190:193], v[110:113]
	v_mfma_i32_16x16x64_i8 v[102:105], v[176:179], v[190:193], v[102:105]
	v_mfma_i32_16x16x64_i8 v[94:97], v[168:171], v[198:201], v[94:97]
	v_mfma_i32_16x16x64_i8 v[86:89], v[176:179], v[198:201], v[86:89]
	v_mfma_i32_16x16x64_i8 v[78:81], v[168:171], v[206:209], v[78:81]
	v_mfma_i32_16x16x64_i8 v[74:77], v[176:179], v[206:209], v[74:77]
	v_mfma_i32_16x16x64_i8 v[70:73], v[168:171], v[214:217], v[70:73]
	v_mfma_i32_16x16x64_i8 v[66:69], v[176:179], v[214:217], v[66:69]
	s_setprio 0
	s_barrier
	s_add_i32 s67, s62, s43
	v_lshl_add_u64 v[184:185], s[68:69], 0, v[132:133]
	s_mov_b32 m0, s67
	ds_read_b128 v[180:183], v189 offset:16384
	ds_read_b128 v[190:193], v189 offset:17408
	ds_read_b128 v[194:197], v189 offset:18432
	ds_read_b128 v[198:201], v189 offset:19456
	ds_read_b128 v[202:205], v189 offset:20480
	ds_read_b128 v[206:209], v189 offset:21504
	ds_read_b128 v[210:213], v189 offset:22528
	ds_read_b128 v[214:217], v189 offset:23552
	global_load_lds_dwordx4 v[184:185], off
	s_add_i32 m0, s67, 0x2000
	v_lshl_add_u64 v[218:219], s[68:69], 0, v[136:137]
	s_add_u32 s68, s68, s6
	s_addc_u32 s69, s69, s7
	s_add_i32 s67, s63, s43
	global_load_lds_dwordx4 v[218:219], off
	v_lshl_add_u64 v[220:221], s[68:69], 0, v[132:133]
	s_mov_b32 m0, s67
	v_lshl_add_u64 v[222:223], s[68:69], 0, v[136:137]
	global_load_lds_dwordx4 v[220:221], off
	s_add_i32 m0, s67, 0x2000
	v_lshl_add_u64 v[224:225], s[28:29], 0, v[130:131]
	global_load_lds_dwordx4 v[222:223], off
	s_mov_b32 m0, s44
	v_lshl_add_u64 v[226:227], s[28:29], 0, v[134:135]
	global_load_lds_dwordx4 v[224:225], off
	s_mov_b32 m0, s45
	s_nop 0
	global_load_lds_dwordx4 v[226:227], off
	s_waitcnt vmcnt(8)
	s_waitcnt lgkmcnt(0)
	s_setprio 1
	s_waitcnt lgkmcnt(0)
	v_mfma_i32_16x16x64_i8 v[62:65], v[148:151], v[180:183], v[62:65]
	v_mfma_i32_16x16x64_i8 v[58:61], v[156:159], v[180:183], v[58:61]
	v_mfma_i32_16x16x64_i8 v[54:57], v[148:151], v[194:197], v[54:57]
	v_mfma_i32_16x16x64_i8 v[50:53], v[156:159], v[194:197], v[50:53]
	v_mfma_i32_16x16x64_i8 v[42:45], v[148:151], v[202:205], v[42:45]
	v_mfma_i32_16x16x64_i8 v[34:37], v[156:159], v[202:205], v[34:37]
	s_barrier
	v_mfma_i32_16x16x64_i8 v[26:29], v[148:151], v[210:213], v[26:29]
	v_mfma_i32_16x16x64_i8 v[18:21], v[156:159], v[210:213], v[18:21]
	v_mfma_i32_16x16x64_i8 v[62:65], v[152:155], v[190:193], v[62:65]
	v_mfma_i32_16x16x64_i8 v[58:61], v[160:163], v[190:193], v[58:61]
	v_mfma_i32_16x16x64_i8 v[54:57], v[152:155], v[198:201], v[54:57]
	v_mfma_i32_16x16x64_i8 v[50:53], v[160:163], v[198:201], v[50:53]
	v_mfma_i32_16x16x64_i8 v[42:45], v[152:155], v[206:209], v[42:45]
	v_mfma_i32_16x16x64_i8 v[34:37], v[160:163], v[206:209], v[34:37]
	v_mfma_i32_16x16x64_i8 v[26:29], v[152:155], v[214:217], v[26:29]
	v_mfma_i32_16x16x64_i8 v[18:21], v[160:163], v[214:217], v[18:21]
	s_setprio 0
	s_setprio 1
	v_mfma_i32_16x16x64_i8 v[46:49], v[164:167], v[180:183], v[46:49]
	v_mfma_i32_16x16x64_i8 v[38:41], v[172:175], v[180:183], v[38:41]
	v_mfma_i32_16x16x64_i8 v[30:33], v[164:167], v[194:197], v[30:33]
	v_mfma_i32_16x16x64_i8 v[22:25], v[172:175], v[194:197], v[22:25]
	v_mfma_i32_16x16x64_i8 v[14:17], v[164:167], v[202:205], v[14:17]
	v_mfma_i32_16x16x64_i8 v[10:13], v[172:175], v[202:205], v[10:13]
	v_mfma_i32_16x16x64_i8 v[6:9], v[164:167], v[210:213], v[6:9]
	v_mfma_i32_16x16x64_i8 v[2:5], v[172:175], v[210:213], v[2:5]
	v_mfma_i32_16x16x64_i8 v[46:49], v[168:171], v[190:193], v[46:49]
	v_mfma_i32_16x16x64_i8 v[38:41], v[176:179], v[190:193], v[38:41]
	v_mfma_i32_16x16x64_i8 v[30:33], v[168:171], v[198:201], v[30:33]
	v_mfma_i32_16x16x64_i8 v[22:25], v[176:179], v[198:201], v[22:25]
	v_mfma_i32_16x16x64_i8 v[14:17], v[168:171], v[206:209], v[14:17]
	v_mfma_i32_16x16x64_i8 v[10:13], v[176:179], v[206:209], v[10:13]
	v_mfma_i32_16x16x64_i8 v[6:9], v[168:171], v[214:217], v[6:9]
	v_mfma_i32_16x16x64_i8 v[2:5], v[176:179], v[214:217], v[2:5]
	s_setprio 0
	s_barrier
	s_add_i32 s67, 0, 0x18000
	v_add_u32_e32 v138, s67, v188
	s_add_i32 s68, 0, 0x1c000
	ds_read_b128 v[148:151], v138
	ds_read_b128 v[152:155], v138 offset:1024
	ds_read_b128 v[156:159], v138 offset:2048
	ds_read_b128 v[160:163], v138 offset:3072
	v_add_u32_e32 v138, s68, v188
	ds_read_b128 v[164:167], v138
	ds_read_b128 v[168:171], v138 offset:1024
	ds_read_b128 v[172:175], v138 offset:2048
	ds_read_b128 v[176:179], v138 offset:3072
	s_add_u32 s28, s28, s6
	s_addc_u32 s29, s29, s7
	s_mov_b32 m0, s46
	v_lshl_add_u64 v[228:229], s[28:29], 0, v[130:131]
	ds_read_b128 v[180:183], v189 offset:32768
	ds_read_b128 v[190:193], v189 offset:33792
	ds_read_b128 v[194:197], v189 offset:34816
	ds_read_b128 v[198:201], v189 offset:35840
	ds_read_b128 v[202:205], v189 offset:36864
	ds_read_b128 v[206:209], v189 offset:37888
	ds_read_b128 v[210:213], v189 offset:38912
	ds_read_b128 v[214:217], v189 offset:39936
	global_load_lds_dwordx4 v[228:229], off
	v_lshl_add_u64 v[228:229], s[28:29], 0, v[134:135]
	s_mov_b32 m0, s47
	s_nop 0
	global_load_lds_dwordx4 v[228:229], off
	s_waitcnt vmcnt(8)
	s_waitcnt lgkmcnt(0)
	s_setprio 1
	s_waitcnt lgkmcnt(0)
	v_mfma_i32_16x16x64_i8 v[126:129], v[148:151], v[180:183], v[126:129]
	v_mfma_i32_16x16x64_i8 v[122:125], v[156:159], v[180:183], v[122:125]
	v_mfma_i32_16x16x64_i8 v[118:121], v[148:151], v[194:197], v[118:121]
	v_mfma_i32_16x16x64_i8 v[114:117], v[156:159], v[194:197], v[114:117]
	v_mfma_i32_16x16x64_i8 v[106:109], v[148:151], v[202:205], v[106:109]
	v_mfma_i32_16x16x64_i8 v[98:101], v[156:159], v[202:205], v[98:101]
	s_barrier
	v_mfma_i32_16x16x64_i8 v[90:93], v[148:151], v[210:213], v[90:93]
	v_mfma_i32_16x16x64_i8 v[82:85], v[156:159], v[210:213], v[82:85]
	v_mfma_i32_16x16x64_i8 v[126:129], v[152:155], v[190:193], v[126:129]
	v_mfma_i32_16x16x64_i8 v[122:125], v[160:163], v[190:193], v[122:125]
	v_mfma_i32_16x16x64_i8 v[118:121], v[152:155], v[198:201], v[118:121]
	v_mfma_i32_16x16x64_i8 v[114:117], v[160:163], v[198:201], v[114:117]
	v_mfma_i32_16x16x64_i8 v[106:109], v[152:155], v[206:209], v[106:109]
	v_mfma_i32_16x16x64_i8 v[98:101], v[160:163], v[206:209], v[98:101]
	v_mfma_i32_16x16x64_i8 v[90:93], v[152:155], v[214:217], v[90:93]
	v_mfma_i32_16x16x64_i8 v[82:85], v[160:163], v[214:217], v[82:85]
	s_setprio 0
	s_setprio 1
	v_mfma_i32_16x16x64_i8 v[110:113], v[164:167], v[180:183], v[110:113]
	v_mfma_i32_16x16x64_i8 v[102:105], v[172:175], v[180:183], v[102:105]
	v_mfma_i32_16x16x64_i8 v[94:97], v[164:167], v[194:197], v[94:97]
	v_mfma_i32_16x16x64_i8 v[86:89], v[172:175], v[194:197], v[86:89]
	v_mfma_i32_16x16x64_i8 v[78:81], v[164:167], v[202:205], v[78:81]
	v_mfma_i32_16x16x64_i8 v[74:77], v[172:175], v[202:205], v[74:77]
	v_mfma_i32_16x16x64_i8 v[70:73], v[164:167], v[210:213], v[70:73]
	v_mfma_i32_16x16x64_i8 v[66:69], v[172:175], v[210:213], v[66:69]
	v_mfma_i32_16x16x64_i8 v[110:113], v[168:171], v[190:193], v[110:113]
	v_mfma_i32_16x16x64_i8 v[102:105], v[176:179], v[190:193], v[102:105]
	v_mfma_i32_16x16x64_i8 v[94:97], v[168:171], v[198:201], v[94:97]
	v_mfma_i32_16x16x64_i8 v[86:89], v[176:179], v[198:201], v[86:89]
	v_mfma_i32_16x16x64_i8 v[78:81], v[168:171], v[206:209], v[78:81]
	v_mfma_i32_16x16x64_i8 v[74:77], v[176:179], v[206:209], v[74:77]
	v_mfma_i32_16x16x64_i8 v[70:73], v[168:171], v[214:217], v[70:73]
	v_mfma_i32_16x16x64_i8 v[66:69], v[176:179], v[214:217], v[66:69]
	s_setprio 0
	s_barrier
	s_add_i32 s28, s67, s43
	v_lshl_add_u64 v[184:185], v[184:185], 0, s[18:19]
	s_mov_b32 m0, s28
	ds_read_b128 v[180:183], v189 offset:49152
	ds_read_b128 v[190:193], v189 offset:50176
	ds_read_b128 v[194:197], v189 offset:51200
	ds_read_b128 v[198:201], v189 offset:52224
	ds_read_b128 v[202:205], v189 offset:53248
	ds_read_b128 v[206:209], v189 offset:54272
	ds_read_b128 v[210:213], v189 offset:55296
	ds_read_b128 v[214:217], v189 offset:56320
	global_load_lds_dwordx4 v[184:185], off
	v_lshl_add_u64 v[184:185], v[218:219], 0, s[18:19]
	s_add_i32 m0, s28, 0x2000
	s_add_i32 s28, s68, s43
	global_load_lds_dwordx4 v[184:185], off
	v_lshl_add_u64 v[184:185], v[220:221], 0, s[18:19]
	s_mov_b32 m0, s28
	s_nop 0
	global_load_lds_dwordx4 v[184:185], off
	v_lshl_add_u64 v[184:185], v[222:223], 0, s[18:19]
	s_add_i32 m0, s28, 0x2000
	s_nop 0
	global_load_lds_dwordx4 v[184:185], off
	v_lshl_add_u64 v[184:185], v[224:225], 0, s[18:19]
	s_mov_b32 m0, s55
	s_nop 0
	global_load_lds_dwordx4 v[184:185], off
	v_lshl_add_u64 v[184:185], v[226:227], 0, s[18:19]
	s_mov_b32 m0, s56
	s_nop 0
	global_load_lds_dwordx4 v[184:185], off
	s_waitcnt vmcnt(8)
	s_waitcnt lgkmcnt(0)
	s_setprio 1
	s_waitcnt lgkmcnt(0)
	v_mfma_i32_16x16x64_i8 v[62:65], v[148:151], v[180:183], v[62:65]
	v_mfma_i32_16x16x64_i8 v[58:61], v[156:159], v[180:183], v[58:61]
	v_mfma_i32_16x16x64_i8 v[54:57], v[148:151], v[194:197], v[54:57]
	v_mfma_i32_16x16x64_i8 v[50:53], v[156:159], v[194:197], v[50:53]
	v_mfma_i32_16x16x64_i8 v[42:45], v[148:151], v[202:205], v[42:45]
	v_mfma_i32_16x16x64_i8 v[34:37], v[156:159], v[202:205], v[34:37]
	s_barrier
	v_mfma_i32_16x16x64_i8 v[26:29], v[148:151], v[210:213], v[26:29]
	v_mfma_i32_16x16x64_i8 v[18:21], v[156:159], v[210:213], v[18:21]
	v_mfma_i32_16x16x64_i8 v[62:65], v[152:155], v[190:193], v[62:65]
	v_mfma_i32_16x16x64_i8 v[58:61], v[160:163], v[190:193], v[58:61]
	v_mfma_i32_16x16x64_i8 v[54:57], v[152:155], v[198:201], v[54:57]
	v_mfma_i32_16x16x64_i8 v[50:53], v[160:163], v[198:201], v[50:53]
	v_mfma_i32_16x16x64_i8 v[42:45], v[152:155], v[206:209], v[42:45]
	v_mfma_i32_16x16x64_i8 v[34:37], v[160:163], v[206:209], v[34:37]
	v_mfma_i32_16x16x64_i8 v[26:29], v[152:155], v[214:217], v[26:29]
	v_mfma_i32_16x16x64_i8 v[18:21], v[160:163], v[214:217], v[18:21]
	s_setprio 0
	s_setprio 1
	v_mfma_i32_16x16x64_i8 v[46:49], v[164:167], v[180:183], v[46:49]
	v_mfma_i32_16x16x64_i8 v[38:41], v[172:175], v[180:183], v[38:41]
	v_mfma_i32_16x16x64_i8 v[30:33], v[164:167], v[194:197], v[30:33]
	v_mfma_i32_16x16x64_i8 v[22:25], v[172:175], v[194:197], v[22:25]
	v_mfma_i32_16x16x64_i8 v[14:17], v[164:167], v[202:205], v[14:17]
	v_mfma_i32_16x16x64_i8 v[10:13], v[172:175], v[202:205], v[10:13]
	v_mfma_i32_16x16x64_i8 v[6:9], v[164:167], v[210:213], v[6:9]
	v_mfma_i32_16x16x64_i8 v[2:5], v[172:175], v[210:213], v[2:5]
	v_mfma_i32_16x16x64_i8 v[46:49], v[168:171], v[190:193], v[46:49]
	v_mfma_i32_16x16x64_i8 v[38:41], v[176:179], v[190:193], v[38:41]
	v_mfma_i32_16x16x64_i8 v[30:33], v[168:171], v[198:201], v[30:33]
	v_mfma_i32_16x16x64_i8 v[22:25], v[176:179], v[198:201], v[22:25]
	v_mfma_i32_16x16x64_i8 v[14:17], v[168:171], v[206:209], v[14:17]
	v_mfma_i32_16x16x64_i8 v[10:13], v[176:179], v[206:209], v[10:13]
	v_mfma_i32_16x16x64_i8 v[6:9], v[168:171], v[214:217], v[6:9]
	v_mfma_i32_16x16x64_i8 v[2:5], v[176:179], v[214:217], v[2:5]
	s_setprio 0
	s_barrier
	s_add_u32 s26, s26, 0x100
	s_addc_u32 s27, s27, 0
	s_add_u32 s34, s34, 0x100
	s_addc_u32 s35, s35, 0
	s_cmp_ge_i32 s66, s57
	s_mov_b32 s28, s66
	s_cbranch_scc0 .LBB0_1939
	v_cvt_f32_i32_e32 v172, v126
	v_cvt_f32_i32_e32 v173, v127
	v_cvt_f32_i32_e32 v170, v128
	v_cvt_f32_i32_e32 v171, v129
	v_cvt_f32_i32_e32 v174, v122
	v_cvt_f32_i32_e32 v175, v123
	v_cvt_f32_i32_e32 v176, v124
	v_cvt_f32_i32_e32 v177, v125
	v_cvt_f32_i32_e32 v180, v110
	v_cvt_f32_i32_e32 v181, v111
	v_cvt_f32_i32_e32 v182, v112
	v_cvt_f32_i32_e32 v183, v113
	v_cvt_f32_i32_e32 v178, v102
	v_cvt_f32_i32_e32 v179, v103
	v_cvt_f32_i32_e32 v184, v104
	v_cvt_f32_i32_e32 v185, v105
	v_cvt_f32_i32_e32 v152, v118
	v_cvt_f32_i32_e32 v153, v119
	v_cvt_f32_i32_e32 v154, v120
	v_cvt_f32_i32_e32 v155, v121
	v_cvt_f32_i32_e32 v156, v114
	v_cvt_f32_i32_e32 v157, v115
	v_cvt_f32_i32_e32 v158, v116
	v_cvt_f32_i32_e32 v159, v117
	v_cvt_f32_i32_e32 v160, v94
	v_cvt_f32_i32_e32 v161, v95
	v_cvt_f32_i32_e32 v162, v96
	v_cvt_f32_i32_e32 v163, v97
	v_cvt_f32_i32_e32 v164, v86
	v_cvt_f32_i32_e32 v165, v87
	v_cvt_f32_i32_e32 v166, v88
	v_cvt_f32_i32_e32 v167, v89
	v_cvt_f32_i32_e32 v118, v106
	v_cvt_f32_i32_e32 v119, v107
	v_cvt_f32_i32_e32 v120, v108
	v_cvt_f32_i32_e32 v121, v109
	v_cvt_f32_i32_e32 v122, v98
	v_cvt_f32_i32_e32 v123, v99
	v_cvt_f32_i32_e32 v124, v100
	v_cvt_f32_i32_e32 v125, v101
	v_cvt_f32_i32_e32 v126, v78
	v_cvt_f32_i32_e32 v127, v79
	v_cvt_f32_i32_e32 v128, v80
	v_cvt_f32_i32_e32 v129, v81
	v_cvt_f32_i32_e32 v148, v74
	v_cvt_f32_i32_e32 v149, v75
	v_cvt_f32_i32_e32 v150, v76
	v_cvt_f32_i32_e32 v151, v77
	v_cvt_f32_i32_e32 v102, v90
	v_cvt_f32_i32_e32 v103, v91
	v_cvt_f32_i32_e32 v104, v92
	v_cvt_f32_i32_e32 v105, v93
	v_cvt_f32_i32_e32 v106, v82
	v_cvt_f32_i32_e32 v107, v83
	v_cvt_f32_i32_e32 v108, v84
	v_cvt_f32_i32_e32 v109, v85
	v_cvt_f32_i32_e32 v110, v70
	v_cvt_f32_i32_e32 v111, v71
	v_cvt_f32_i32_e32 v112, v72
	v_cvt_f32_i32_e32 v113, v73
	v_cvt_f32_i32_e32 v114, v66
	v_cvt_f32_i32_e32 v115, v67
	v_cvt_f32_i32_e32 v116, v68
	v_cvt_f32_i32_e32 v117, v69
	v_cvt_f32_i32_e32 v82, v62
	v_cvt_f32_i32_e32 v83, v63
	v_cvt_f32_i32_e32 v84, v64
	v_cvt_f32_i32_e32 v85, v65
	v_cvt_f32_i32_e32 v86, v58
	v_cvt_f32_i32_e32 v87, v59
	v_cvt_f32_i32_e32 v88, v60
	v_cvt_f32_i32_e32 v89, v61
	v_cvt_f32_i32_e32 v92, v46
	v_cvt_f32_i32_e32 v93, v47
	v_cvt_f32_i32_e32 v94, v48
	v_cvt_f32_i32_e32 v95, v49
	v_cvt_f32_i32_e32 v96, v38
	v_cvt_f32_i32_e32 v97, v39
	v_cvt_f32_i32_e32 v98, v40
	v_cvt_f32_i32_e32 v99, v41
	v_cvt_f32_i32_e32 v66, v54
	v_cvt_f32_i32_e32 v67, v55
	v_cvt_f32_i32_e32 v68, v56
	v_cvt_f32_i32_e32 v69, v57
	v_cvt_f32_i32_e32 v70, v50
	v_cvt_f32_i32_e32 v71, v51
	v_cvt_f32_i32_e32 v72, v52
	v_cvt_f32_i32_e32 v73, v53
	v_cvt_f32_i32_e32 v74, v30
	v_cvt_f32_i32_e32 v75, v31
	v_cvt_f32_i32_e32 v76, v32
	v_cvt_f32_i32_e32 v77, v33
	v_cvt_f32_i32_e32 v78, v22
	v_cvt_f32_i32_e32 v79, v23
	v_cvt_f32_i32_e32 v80, v24
	v_cvt_f32_i32_e32 v81, v25
	v_cvt_f32_i32_e32 v50, v42
	v_cvt_f32_i32_e32 v51, v43
	v_cvt_f32_i32_e32 v52, v44
	v_cvt_f32_i32_e32 v53, v45
	v_cvt_f32_i32_e32 v54, v34
	v_cvt_f32_i32_e32 v55, v35
	v_cvt_f32_i32_e32 v56, v36
	v_cvt_f32_i32_e32 v57, v37
	v_cvt_f32_i32_e32 v58, v14
	v_cvt_f32_i32_e32 v59, v15
	v_cvt_f32_i32_e32 v60, v16
	v_cvt_f32_i32_e32 v61, v17
	v_cvt_f32_i32_e32 v62, v10
	v_cvt_f32_i32_e32 v63, v11
	v_cvt_f32_i32_e32 v64, v12
	v_cvt_f32_i32_e32 v65, v13
	v_cvt_f32_i32_e32 v34, v26
	v_cvt_f32_i32_e32 v35, v27
	v_cvt_f32_i32_e32 v36, v28
	v_cvt_f32_i32_e32 v37, v29
	v_cvt_f32_i32_e32 v38, v18
	v_cvt_f32_i32_e32 v39, v19
	v_cvt_f32_i32_e32 v40, v20
	v_cvt_f32_i32_e32 v41, v21
	v_cvt_f32_i32_e32 v42, v6
	v_cvt_f32_i32_e32 v43, v7
	v_cvt_f32_i32_e32 v44, v8
	v_cvt_f32_i32_e32 v45, v9
	v_cvt_f32_i32_e32 v46, v2
	v_cvt_f32_i32_e32 v47, v3
	v_cvt_f32_i32_e32 v48, v4
	v_cvt_f32_i32_e32 v49, v5

.LBB0_2022:
	ds_read_b128 v[114:117], v209
	ds_read_b128 v[118:121], v209 offset:1024
	ds_read_b128 v[122:125], v209 offset:2048
	ds_read_b128 v[126:129], v209 offset:3072
	ds_read_b128 v[146:149], v210
	ds_read_b128 v[150:153], v210 offset:1024
	ds_read_b128 v[154:157], v210 offset:2048
	ds_read_b128 v[158:161], v210 offset:3072
	s_add_i32 s84, s36, 2
	s_add_u32 s37, s34, 0x4000
	s_addc_u32 s38, s35, 0
	s_cmp_eq_u32 s63, s36
	s_cselect_b32 s39, s5, s38
	s_cselect_b32 s38, s4, s37
	s_cselect_b32 s86, s30, s82
	s_cselect_b32 s87, s31, s83
	s_add_u32 s36, s38, 0x8000
	s_addc_u32 s37, s39, 0
	v_lshl_add_u64 v[218:219], s[34:35], 0, v[170:171]
	s_add_i32 m0, s47, 0xc000
	ds_read_b128 v[178:181], v211
	ds_read_b128 v[182:185], v211 offset:1024
	ds_read_b128 v[186:189], v211 offset:2048
	ds_read_b128 v[190:193], v211 offset:3072
	ds_read_b128 v[194:197], v211 offset:4096
	ds_read_b128 v[198:201], v211 offset:5120
	ds_read_b128 v[202:205], v211 offset:6144
	ds_read_b128 v[214:217], v211 offset:7168
	global_load_lds_dwordx4 v[218:219], off
	v_lshl_add_u64 v[218:219], s[34:35], 0, v[172:173]
	s_add_i32 m0, s47, 0xe000
	s_nop 0
	global_load_lds_dwordx4 v[218:219], off
	s_waitcnt vmcnt(8)
	s_waitcnt lgkmcnt(0)
	s_setprio 1
	s_waitcnt lgkmcnt(0)
	v_mfma_f32_16x16x32_bf16 v[142:145], v[114:117], v[178:181], v[142:145]
	v_mfma_f32_16x16x32_bf16 v[138:141], v[122:125], v[178:181], v[138:141]
	v_mfma_f32_16x16x32_bf16 v[110:113], v[114:117], v[186:189], v[110:113]
	v_mfma_f32_16x16x32_bf16 v[106:109], v[122:125], v[186:189], v[106:109]
	v_mfma_f32_16x16x32_bf16 v[94:97], v[114:117], v[194:197], v[94:97]
	v_mfma_f32_16x16x32_bf16 v[90:93], v[122:125], v[194:197], v[90:93]
	s_barrier
	v_mfma_f32_16x16x32_bf16 v[78:81], v[114:117], v[202:205], v[78:81]
	v_mfma_f32_16x16x32_bf16 v[74:77], v[122:125], v[202:205], v[74:77]
	v_mfma_f32_16x16x32_bf16 v[142:145], v[118:121], v[182:185], v[142:145]
	v_mfma_f32_16x16x32_bf16 v[138:141], v[126:129], v[182:185], v[138:141]
	v_mfma_f32_16x16x32_bf16 v[110:113], v[118:121], v[190:193], v[110:113]
	v_mfma_f32_16x16x32_bf16 v[106:109], v[126:129], v[190:193], v[106:109]
	v_mfma_f32_16x16x32_bf16 v[94:97], v[118:121], v[198:201], v[94:97]
	v_mfma_f32_16x16x32_bf16 v[90:93], v[126:129], v[198:201], v[90:93]
	v_mfma_f32_16x16x32_bf16 v[78:81], v[118:121], v[214:217], v[78:81]
	v_mfma_f32_16x16x32_bf16 v[74:77], v[126:129], v[214:217], v[74:77]
	s_setprio 0
	s_setprio 1
	v_mfma_f32_16x16x32_bf16 v[134:137], v[146:149], v[178:181], v[134:137]
	v_mfma_f32_16x16x32_bf16 v[130:133], v[154:157], v[178:181], v[130:133]
	v_mfma_f32_16x16x32_bf16 v[102:105], v[146:149], v[186:189], v[102:105]
	v_mfma_f32_16x16x32_bf16 v[98:101], v[154:157], v[186:189], v[98:101]
	v_mfma_f32_16x16x32_bf16 v[86:89], v[146:149], v[194:197], v[86:89]
	v_mfma_f32_16x16x32_bf16 v[82:85], v[154:157], v[194:197], v[82:85]
	v_mfma_f32_16x16x32_bf16 v[70:73], v[146:149], v[202:205], v[70:73]
	v_mfma_f32_16x16x32_bf16 v[66:69], v[154:157], v[202:205], v[66:69]
	v_mfma_f32_16x16x32_bf16 v[134:137], v[150:153], v[182:185], v[134:137]
	v_mfma_f32_16x16x32_bf16 v[130:133], v[158:161], v[182:185], v[130:133]
	v_mfma_f32_16x16x32_bf16 v[102:105], v[150:153], v[190:193], v[102:105]
	v_mfma_f32_16x16x32_bf16 v[98:101], v[158:161], v[190:193], v[98:101]
	v_mfma_f32_16x16x32_bf16 v[86:89], v[150:153], v[198:201], v[86:89]
	v_mfma_f32_16x16x32_bf16 v[82:85], v[158:161], v[198:201], v[82:85]
	v_mfma_f32_16x16x32_bf16 v[70:73], v[150:153], v[214:217], v[70:73]
	v_mfma_f32_16x16x32_bf16 v[66:69], v[158:161], v[214:217], v[66:69]
	s_setprio 0
	s_barrier
	s_add_i32 s85, s66, s46
	v_lshl_add_u64 v[218:219], s[86:87], 0, v[164:165]
	s_mov_b32 m0, s85
	ds_read_b128 v[178:181], v211 offset:16384
	ds_read_b128 v[182:185], v211 offset:17408
	ds_read_b128 v[186:189], v211 offset:18432
	ds_read_b128 v[190:193], v211 offset:19456
	ds_read_b128 v[194:197], v211 offset:20480
	ds_read_b128 v[198:201], v211 offset:21504
	ds_read_b128 v[202:205], v211 offset:22528
	ds_read_b128 v[214:217], v211 offset:23552
	global_load_lds_dwordx4 v[218:219], off
	s_add_i32 m0, s85, 0x2000
	v_lshl_add_u64 v[220:221], s[86:87], 0, v[168:169]
	s_add_u32 s86, s86, s8
	s_addc_u32 s87, s87, s9
	s_add_i32 s85, s67, s46
	global_load_lds_dwordx4 v[220:221], off
	v_lshl_add_u64 v[222:223], s[86:87], 0, v[164:165]
	s_mov_b32 m0, s85
	v_lshl_add_u64 v[224:225], s[86:87], 0, v[168:169]
	global_load_lds_dwordx4 v[222:223], off
	s_add_i32 m0, s85, 0x2000
	v_lshl_add_u64 v[226:227], s[38:39], 0, v[162:163]
	global_load_lds_dwordx4 v[224:225], off
	s_mov_b32 m0, s47
	s_nop 0
	global_load_lds_dwordx4 v[226:227], off
	v_lshl_add_u64 v[226:227], s[38:39], 0, v[166:167]
	s_mov_b32 m0, s50
	s_nop 0
	global_load_lds_dwordx4 v[226:227], off
	s_waitcnt vmcnt(8)
	s_waitcnt lgkmcnt(0)
	s_setprio 1
	s_waitcnt lgkmcnt(0)
	v_mfma_f32_16x16x32_bf16 v[62:65], v[114:117], v[178:181], v[62:65]
	v_mfma_f32_16x16x32_bf16 v[58:61], v[122:125], v[178:181], v[58:61]
	v_mfma_f32_16x16x32_bf16 v[46:49], v[114:117], v[186:189], v[46:49]
	v_mfma_f32_16x16x32_bf16 v[42:45], v[122:125], v[186:189], v[42:45]
	v_mfma_f32_16x16x32_bf16 v[30:33], v[114:117], v[194:197], v[30:33]
	v_mfma_f32_16x16x32_bf16 v[26:29], v[122:125], v[194:197], v[26:29]
	s_barrier
	v_mfma_f32_16x16x32_bf16 v[14:17], v[114:117], v[202:205], v[14:17]
	v_mfma_f32_16x16x32_bf16 v[10:13], v[122:125], v[202:205], v[10:13]
	v_mfma_f32_16x16x32_bf16 v[62:65], v[118:121], v[182:185], v[62:65]
	v_mfma_f32_16x16x32_bf16 v[58:61], v[126:129], v[182:185], v[58:61]
	v_mfma_f32_16x16x32_bf16 v[46:49], v[118:121], v[190:193], v[46:49]
	v_mfma_f32_16x16x32_bf16 v[42:45], v[126:129], v[190:193], v[42:45]
	v_mfma_f32_16x16x32_bf16 v[30:33], v[118:121], v[198:201], v[30:33]
	v_mfma_f32_16x16x32_bf16 v[26:29], v[126:129], v[198:201], v[26:29]
	v_mfma_f32_16x16x32_bf16 v[14:17], v[118:121], v[214:217], v[14:17]
	v_mfma_f32_16x16x32_bf16 v[10:13], v[126:129], v[214:217], v[10:13]
	s_setprio 0
	s_setprio 1
	v_mfma_f32_16x16x32_bf16 v[54:57], v[146:149], v[178:181], v[54:57]
	v_mfma_f32_16x16x32_bf16 v[50:53], v[154:157], v[178:181], v[50:53]
	v_mfma_f32_16x16x32_bf16 v[38:41], v[146:149], v[186:189], v[38:41]
	v_mfma_f32_16x16x32_bf16 v[34:37], v[154:157], v[186:189], v[34:37]
	v_mfma_f32_16x16x32_bf16 v[22:25], v[146:149], v[194:197], v[22:25]
	v_mfma_f32_16x16x32_bf16 v[18:21], v[154:157], v[194:197], v[18:21]
	v_mfma_f32_16x16x32_bf16 v[6:9], v[146:149], v[202:205], v[6:9]
	v_mfma_f32_16x16x32_bf16 v[2:5], v[154:157], v[202:205], v[2:5]
	v_mfma_f32_16x16x32_bf16 v[54:57], v[150:153], v[182:185], v[54:57]
	v_mfma_f32_16x16x32_bf16 v[50:53], v[158:161], v[182:185], v[50:53]
	v_mfma_f32_16x16x32_bf16 v[38:41], v[150:153], v[190:193], v[38:41]
	v_mfma_f32_16x16x32_bf16 v[34:37], v[158:161], v[190:193], v[34:37]
	v_mfma_f32_16x16x32_bf16 v[22:25], v[150:153], v[198:201], v[22:25]
	v_mfma_f32_16x16x32_bf16 v[18:21], v[158:161], v[198:201], v[18:21]
	v_mfma_f32_16x16x32_bf16 v[6:9], v[150:153], v[214:217], v[6:9]
	v_mfma_f32_16x16x32_bf16 v[2:5], v[158:161], v[214:217], v[2:5]
	s_setprio 0
	s_barrier
	s_add_i32 s85, 0, 0x18000
	s_add_i32 s86, 0, 0x1c000
	v_add_u32_e32 v126, s85, v207
	v_add_u32_e32 v158, s86, v207
	ds_read_b128 v[114:117], v126
	ds_read_b128 v[118:121], v126 offset:1024
	ds_read_b128 v[122:125], v126 offset:2048
	ds_read_b128 v[126:129], v126 offset:3072
	ds_read_b128 v[146:149], v158
	ds_read_b128 v[150:153], v158 offset:1024
	ds_read_b128 v[154:157], v158 offset:2048
	ds_read_b128 v[158:161], v158 offset:3072
	s_add_u32 s38, s38, 0x4000
	s_addc_u32 s39, s39, 0
	s_mov_b32 m0, s51
	v_lshl_add_u64 v[226:227], s[38:39], 0, v[162:163]
	ds_read_b128 v[178:181], v211 offset:32768
	ds_read_b128 v[182:185], v211 offset:33792
	ds_read_b128 v[186:189], v211 offset:34816
	ds_read_b128 v[190:193], v211 offset:35840
	ds_read_b128 v[194:197], v211 offset:36864
	ds_read_b128 v[198:201], v211 offset:37888
	ds_read_b128 v[202:205], v211 offset:38912
	ds_read_b128 v[214:217], v211 offset:39936
	global_load_lds_dwordx4 v[226:227], off
	v_lshl_add_u64 v[226:227], s[38:39], 0, v[166:167]
	s_mov_b32 m0, s54
	s_nop 0
	global_load_lds_dwordx4 v[226:227], off
	s_waitcnt vmcnt(8)
	s_waitcnt lgkmcnt(0)
	s_setprio 1
	s_waitcnt lgkmcnt(0)
	v_mfma_f32_16x16x32_bf16 v[142:145], v[114:117], v[178:181], v[142:145]
	v_mfma_f32_16x16x32_bf16 v[138:141], v[122:125], v[178:181], v[138:141]
	v_mfma_f32_16x16x32_bf16 v[110:113], v[114:117], v[186:189], v[110:113]
	v_mfma_f32_16x16x32_bf16 v[106:109], v[122:125], v[186:189], v[106:109]
	v_mfma_f32_16x16x32_bf16 v[94:97], v[114:117], v[194:197], v[94:97]
	v_mfma_f32_16x16x32_bf16 v[90:93], v[122:125], v[194:197], v[90:93]
	s_barrier
	v_mfma_f32_16x16x32_bf16 v[78:81], v[114:117], v[202:205], v[78:81]
	v_mfma_f32_16x16x32_bf16 v[74:77], v[122:125], v[202:205], v[74:77]
	v_mfma_f32_16x16x32_bf16 v[142:145], v[118:121], v[182:185], v[142:145]
	v_mfma_f32_16x16x32_bf16 v[138:141], v[126:129], v[182:185], v[138:141]
	v_mfma_f32_16x16x32_bf16 v[110:113], v[118:121], v[190:193], v[110:113]
	v_mfma_f32_16x16x32_bf16 v[106:109], v[126:129], v[190:193], v[106:109]
	v_mfma_f32_16x16x32_bf16 v[94:97], v[118:121], v[198:201], v[94:97]
	v_mfma_f32_16x16x32_bf16 v[90:93], v[126:129], v[198:201], v[90:93]
	v_mfma_f32_16x16x32_bf16 v[78:81], v[118:121], v[214:217], v[78:81]
	v_mfma_f32_16x16x32_bf16 v[74:77], v[126:129], v[214:217], v[74:77]
	s_setprio 0
	s_setprio 1
	v_mfma_f32_16x16x32_bf16 v[134:137], v[146:149], v[178:181], v[134:137]
	v_mfma_f32_16x16x32_bf16 v[130:133], v[154:157], v[178:181], v[130:133]
	v_mfma_f32_16x16x32_bf16 v[102:105], v[146:149], v[186:189], v[102:105]
	v_mfma_f32_16x16x32_bf16 v[98:101], v[154:157], v[186:189], v[98:101]
	v_mfma_f32_16x16x32_bf16 v[86:89], v[146:149], v[194:197], v[86:89]
	v_mfma_f32_16x16x32_bf16 v[82:85], v[154:157], v[194:197], v[82:85]
	v_mfma_f32_16x16x32_bf16 v[70:73], v[146:149], v[202:205], v[70:73]
	v_mfma_f32_16x16x32_bf16 v[66:69], v[154:157], v[202:205], v[66:69]
	v_mfma_f32_16x16x32_bf16 v[134:137], v[150:153], v[182:185], v[134:137]
	v_mfma_f32_16x16x32_bf16 v[130:133], v[158:161], v[182:185], v[130:133]
	v_mfma_f32_16x16x32_bf16 v[102:105], v[150:153], v[190:193], v[102:105]
	v_mfma_f32_16x16x32_bf16 v[98:101], v[158:161], v[190:193], v[98:101]
	v_mfma_f32_16x16x32_bf16 v[86:89], v[150:153], v[198:201], v[86:89]
	v_mfma_f32_16x16x32_bf16 v[82:85], v[158:161], v[198:201], v[82:85]
	v_mfma_f32_16x16x32_bf16 v[70:73], v[150:153], v[214:217], v[70:73]
	v_mfma_f32_16x16x32_bf16 v[66:69], v[158:161], v[214:217], v[66:69]
	s_setprio 0
	s_barrier
	s_add_i32 s38, s85, s46
	v_lshl_add_u64 v[218:219], v[218:219], 0, s[24:25]
	s_mov_b32 m0, s38
	ds_read_b128 v[178:181], v211 offset:49152
	ds_read_b128 v[182:185], v211 offset:50176
	ds_read_b128 v[186:189], v211 offset:51200
	ds_read_b128 v[190:193], v211 offset:52224
	ds_read_b128 v[194:197], v211 offset:53248
	ds_read_b128 v[198:201], v211 offset:54272
	ds_read_b128 v[202:205], v211 offset:55296
	ds_read_b128 v[214:217], v211 offset:56320
	global_load_lds_dwordx4 v[218:219], off
	v_lshl_add_u64 v[218:219], v[220:221], 0, s[24:25]
	s_add_i32 m0, s38, 0x2000
	s_add_i32 s38, s86, s46
	global_load_lds_dwordx4 v[218:219], off
	v_lshl_add_u64 v[218:219], v[222:223], 0, s[24:25]
	s_mov_b32 m0, s38
	s_nop 0
	global_load_lds_dwordx4 v[218:219], off
	v_lshl_add_u64 v[218:219], v[224:225], 0, s[24:25]
	s_add_i32 m0, s38, 0x2000
	s_nop 0
	global_load_lds_dwordx4 v[218:219], off
	v_lshl_add_u64 v[218:219], s[36:37], 0, v[162:163]
	s_mov_b32 m0, s61
	s_nop 0
	global_load_lds_dwordx4 v[218:219], off
	v_lshl_add_u64 v[218:219], s[36:37], 0, v[166:167]
	s_mov_b32 m0, s62
	s_nop 0
	global_load_lds_dwordx4 v[218:219], off
	s_waitcnt vmcnt(8)
	s_waitcnt lgkmcnt(0)
	s_setprio 1
	s_waitcnt lgkmcnt(0)
	v_mfma_f32_16x16x32_bf16 v[62:65], v[114:117], v[178:181], v[62:65]
	v_mfma_f32_16x16x32_bf16 v[58:61], v[122:125], v[178:181], v[58:61]
	v_mfma_f32_16x16x32_bf16 v[46:49], v[114:117], v[186:189], v[46:49]
	v_mfma_f32_16x16x32_bf16 v[42:45], v[122:125], v[186:189], v[42:45]
	v_mfma_f32_16x16x32_bf16 v[30:33], v[114:117], v[194:197], v[30:33]
	v_mfma_f32_16x16x32_bf16 v[26:29], v[122:125], v[194:197], v[26:29]
	s_barrier
	v_mfma_f32_16x16x32_bf16 v[14:17], v[114:117], v[202:205], v[14:17]
	v_mfma_f32_16x16x32_bf16 v[10:13], v[122:125], v[202:205], v[10:13]
	v_mfma_f32_16x16x32_bf16 v[62:65], v[118:121], v[182:185], v[62:65]
	v_mfma_f32_16x16x32_bf16 v[58:61], v[126:129], v[182:185], v[58:61]
	v_mfma_f32_16x16x32_bf16 v[46:49], v[118:121], v[190:193], v[46:49]
	v_mfma_f32_16x16x32_bf16 v[42:45], v[126:129], v[190:193], v[42:45]
	v_mfma_f32_16x16x32_bf16 v[30:33], v[118:121], v[198:201], v[30:33]
	v_mfma_f32_16x16x32_bf16 v[26:29], v[126:129], v[198:201], v[26:29]
	v_mfma_f32_16x16x32_bf16 v[14:17], v[118:121], v[214:217], v[14:17]
	v_mfma_f32_16x16x32_bf16 v[10:13], v[126:129], v[214:217], v[10:13]
	s_setprio 0
	s_setprio 1
	v_mfma_f32_16x16x32_bf16 v[54:57], v[146:149], v[178:181], v[54:57]
	v_mfma_f32_16x16x32_bf16 v[50:53], v[154:157], v[178:181], v[50:53]
	v_mfma_f32_16x16x32_bf16 v[38:41], v[146:149], v[186:189], v[38:41]
	v_mfma_f32_16x16x32_bf16 v[34:37], v[154:157], v[186:189], v[34:37]
	v_mfma_f32_16x16x32_bf16 v[22:25], v[146:149], v[194:197], v[22:25]
	v_mfma_f32_16x16x32_bf16 v[18:21], v[154:157], v[194:197], v[18:21]
	v_mfma_f32_16x16x32_bf16 v[6:9], v[146:149], v[202:205], v[6:9]
	v_mfma_f32_16x16x32_bf16 v[2:5], v[154:157], v[202:205], v[2:5]
	v_mfma_f32_16x16x32_bf16 v[54:57], v[150:153], v[182:185], v[54:57]
	v_mfma_f32_16x16x32_bf16 v[50:53], v[158:161], v[182:185], v[50:53]
	v_mfma_f32_16x16x32_bf16 v[38:41], v[150:153], v[190:193], v[38:41]
	v_mfma_f32_16x16x32_bf16 v[34:37], v[158:161], v[190:193], v[34:37]
	v_mfma_f32_16x16x32_bf16 v[22:25], v[150:153], v[198:201], v[22:25]
	v_mfma_f32_16x16x32_bf16 v[18:21], v[158:161], v[198:201], v[18:21]
	v_mfma_f32_16x16x32_bf16 v[6:9], v[150:153], v[214:217], v[6:9]
	v_mfma_f32_16x16x32_bf16 v[2:5], v[158:161], v[214:217], v[2:5]
	s_setprio 0
	s_barrier
	s_add_u32 s82, s82, 0x100
	s_addc_u32 s83, s83, 0
	s_add_u32 s34, s34, 0x10000
	s_addc_u32 s35, s35, 0
	s_cmp_ge_i32 s84, s60
	s_mov_b32 s36, s84
	s_cbranch_scc0 .LBB0_2022

.LBB0_2116:
	ds_read_b128 v[34:37], v186
	ds_read_b128 v[38:41], v186 offset:1024
	ds_read_b128 v[50:53], v186 offset:2048
	ds_read_b128 v[54:57], v186 offset:3072
	ds_read_b128 v[168:171], v187
	ds_read_b128 v[172:175], v187 offset:1024
	ds_read_b128 v[176:179], v187 offset:2048
	ds_read_b128 v[192:195], v187 offset:3072
	s_add_i32 s47, s4, 2
	s_add_u32 s50, s2, 0x80
	s_addc_u32 s5, s3, 0
	s_cmp_eq_u32 s85, s4
	s_cselect_b32 s4, s42, s50
	s_cselect_b32 s5, s43, s5
	s_cselect_b32 s51, s45, s7
	s_cselect_b32 s50, s44, s6
	v_lshl_add_u64 v[228:229], s[2:3], 0, v[160:161]
	s_add_i32 m0, s65, 0xc000
	ds_read_b128 v[196:199], v188
	ds_read_b128 v[200:203], v188 offset:1024
	ds_read_b128 v[204:207], v188 offset:2048
	ds_read_b128 v[208:211], v188 offset:3072
	ds_read_b128 v[212:215], v188 offset:4096
	ds_read_b128 v[216:219], v188 offset:5120
	ds_read_b128 v[220:223], v188 offset:6144
	ds_read_b128 v[224:227], v188 offset:7168
	global_load_lds_dwordx4 v[228:229], off
	v_lshl_add_u64 v[228:229], s[2:3], 0, v[162:163]
	s_add_i32 m0, s65, 0xe000
	s_nop 0
	global_load_lds_dwordx4 v[228:229], off
	s_waitcnt vmcnt(8)
	s_waitcnt lgkmcnt(0)
	s_setprio 1
	s_waitcnt lgkmcnt(0)
	v_mfma_f32_16x16x32_bf16 v[142:145], v[34:37], v[196:199], v[142:145]
	v_mfma_f32_16x16x32_bf16 v[138:141], v[50:53], v[196:199], v[138:141]
	v_mfma_f32_16x16x32_bf16 v[126:129], v[34:37], v[204:207], v[126:129]
	v_mfma_f32_16x16x32_bf16 v[122:125], v[50:53], v[204:207], v[122:125]
	v_mfma_f32_16x16x32_bf16 v[110:113], v[34:37], v[212:215], v[110:113]
	v_mfma_f32_16x16x32_bf16 v[106:109], v[50:53], v[212:215], v[106:109]
	s_barrier
	v_mfma_f32_16x16x32_bf16 v[94:97], v[34:37], v[220:223], v[94:97]
	v_mfma_f32_16x16x32_bf16 v[90:93], v[50:53], v[220:223], v[90:93]
	v_mfma_f32_16x16x32_bf16 v[142:145], v[38:41], v[200:203], v[142:145]
	v_mfma_f32_16x16x32_bf16 v[138:141], v[54:57], v[200:203], v[138:141]
	v_mfma_f32_16x16x32_bf16 v[126:129], v[38:41], v[208:211], v[126:129]
	v_mfma_f32_16x16x32_bf16 v[122:125], v[54:57], v[208:211], v[122:125]
	v_mfma_f32_16x16x32_bf16 v[110:113], v[38:41], v[216:219], v[110:113]
	v_mfma_f32_16x16x32_bf16 v[106:109], v[54:57], v[216:219], v[106:109]
	v_mfma_f32_16x16x32_bf16 v[94:97], v[38:41], v[224:227], v[94:97]
	v_mfma_f32_16x16x32_bf16 v[90:93], v[54:57], v[224:227], v[90:93]
	s_setprio 0
	s_setprio 1
	v_mfma_f32_16x16x32_bf16 v[134:137], v[168:171], v[196:199], v[134:137]
	v_mfma_f32_16x16x32_bf16 v[130:133], v[176:179], v[196:199], v[130:133]
	v_mfma_f32_16x16x32_bf16 v[118:121], v[168:171], v[204:207], v[118:121]
	v_mfma_f32_16x16x32_bf16 v[114:117], v[176:179], v[204:207], v[114:117]
	v_mfma_f32_16x16x32_bf16 v[102:105], v[168:171], v[212:215], v[102:105]
	v_mfma_f32_16x16x32_bf16 v[98:101], v[176:179], v[212:215], v[98:101]
	v_mfma_f32_16x16x32_bf16 v[86:89], v[168:171], v[220:223], v[86:89]
	v_mfma_f32_16x16x32_bf16 v[82:85], v[176:179], v[220:223], v[82:85]
	v_mfma_f32_16x16x32_bf16 v[134:137], v[172:175], v[200:203], v[134:137]
	v_mfma_f32_16x16x32_bf16 v[130:133], v[192:195], v[200:203], v[130:133]
	v_mfma_f32_16x16x32_bf16 v[118:121], v[172:175], v[208:211], v[118:121]
	v_mfma_f32_16x16x32_bf16 v[114:117], v[192:195], v[208:211], v[114:117]
	v_mfma_f32_16x16x32_bf16 v[102:105], v[172:175], v[216:219], v[102:105]
	v_mfma_f32_16x16x32_bf16 v[98:101], v[192:195], v[216:219], v[98:101]
	v_mfma_f32_16x16x32_bf16 v[86:89], v[172:175], v[224:227], v[86:89]
	v_mfma_f32_16x16x32_bf16 v[82:85], v[192:195], v[224:227], v[82:85]
	s_setprio 0
	s_barrier
	s_add_i32 s55, s88, s62
	v_lshl_add_u64 v[228:229], s[50:51], 0, v[148:149]
	s_mov_b32 m0, s55
	ds_read_b128 v[196:199], v188 offset:16384
	ds_read_b128 v[200:203], v188 offset:17408
	ds_read_b128 v[204:207], v188 offset:18432
	ds_read_b128 v[208:211], v188 offset:19456
	ds_read_b128 v[212:215], v188 offset:20480
	ds_read_b128 v[216:219], v188 offset:21504
	ds_read_b128 v[220:223], v188 offset:22528
	ds_read_b128 v[224:227], v188 offset:23552
	global_load_lds_dwordx4 v[228:229], off
	s_add_i32 m0, s55, 0x2000
	v_lshl_add_u64 v[230:231], s[50:51], 0, v[152:153]
	s_add_u32 s50, s50, s14
	s_addc_u32 s51, s51, s15
	s_add_i32 s55, s89, s62
	global_load_lds_dwordx4 v[230:231], off
	v_lshl_add_u64 v[232:233], s[50:51], 0, v[148:149]
	s_mov_b32 m0, s55
	v_lshl_add_u64 v[234:235], s[50:51], 0, v[152:153]
	global_load_lds_dwordx4 v[232:233], off
	s_add_i32 m0, s55, 0x2000
	v_lshl_add_u64 v[236:237], s[4:5], 0, v[146:147]
	global_load_lds_dwordx4 v[234:235], off
	s_mov_b32 m0, s65
	v_lshl_add_u64 v[238:239], s[4:5], 0, v[150:151]
	global_load_lds_dwordx4 v[236:237], off
	s_mov_b32 m0, s66
	s_nop 0
	global_load_lds_dwordx4 v[238:239], off
	s_waitcnt vmcnt(8)
	s_waitcnt lgkmcnt(0)
	s_setprio 1
	s_waitcnt lgkmcnt(0)
	v_mfma_f32_16x16x32_bf16 v[78:81], v[34:37], v[196:199], v[78:81]
	v_mfma_f32_16x16x32_bf16 v[74:77], v[50:53], v[196:199], v[74:77]
	v_mfma_f32_16x16x32_bf16 v[62:65], v[34:37], v[204:207], v[62:65]
	v_mfma_f32_16x16x32_bf16 v[58:61], v[50:53], v[204:207], v[58:61]
	v_mfma_f32_16x16x32_bf16 v[30:33], v[34:37], v[212:215], v[30:33]
	v_mfma_f32_16x16x32_bf16 v[26:29], v[50:53], v[212:215], v[26:29]
	s_barrier
	v_mfma_f32_16x16x32_bf16 v[14:17], v[34:37], v[220:223], v[14:17]
	v_mfma_f32_16x16x32_bf16 v[10:13], v[50:53], v[220:223], v[10:13]
	v_mfma_f32_16x16x32_bf16 v[78:81], v[38:41], v[200:203], v[78:81]
	v_mfma_f32_16x16x32_bf16 v[74:77], v[54:57], v[200:203], v[74:77]
	v_mfma_f32_16x16x32_bf16 v[62:65], v[38:41], v[208:211], v[62:65]
	v_mfma_f32_16x16x32_bf16 v[58:61], v[54:57], v[208:211], v[58:61]
	v_mfma_f32_16x16x32_bf16 v[30:33], v[38:41], v[216:219], v[30:33]
	v_mfma_f32_16x16x32_bf16 v[26:29], v[54:57], v[216:219], v[26:29]
	v_mfma_f32_16x16x32_bf16 v[14:17], v[38:41], v[224:227], v[14:17]
	v_mfma_f32_16x16x32_bf16 v[10:13], v[54:57], v[224:227], v[10:13]
	s_setprio 0
	s_setprio 1
	v_mfma_f32_16x16x32_bf16 v[46:49], v[168:171], v[204:207], v[46:49]
	v_mfma_f32_16x16x32_bf16 v[42:45], v[176:179], v[204:207], v[42:45]
	v_mfma_f32_16x16x32_bf16 v[22:25], v[168:171], v[212:215], v[22:25]
	v_mfma_f32_16x16x32_bf16 v[18:21], v[176:179], v[212:215], v[18:21]
	v_mfma_f32_16x16x32_bf16 v[6:9], v[168:171], v[220:223], v[6:9]
	v_mfma_f32_16x16x32_bf16 v[2:5], v[176:179], v[220:223], v[2:5]
	v_mfma_f32_16x16x32_bf16 v[34:37], v[168:171], v[196:199], v[70:73]
	v_mfma_f32_16x16x32_bf16 v[38:41], v[176:179], v[196:199], v[66:69]
	v_mfma_f32_16x16x32_bf16 v[46:49], v[172:175], v[208:211], v[46:49]
	v_mfma_f32_16x16x32_bf16 v[42:45], v[192:195], v[208:211], v[42:45]
	v_mfma_f32_16x16x32_bf16 v[22:25], v[172:175], v[216:219], v[22:25]
	v_mfma_f32_16x16x32_bf16 v[18:21], v[192:195], v[216:219], v[18:21]
	v_mfma_f32_16x16x32_bf16 v[6:9], v[172:175], v[224:227], v[6:9]
	v_mfma_f32_16x16x32_bf16 v[2:5], v[192:195], v[224:227], v[2:5]
	v_mfma_f32_16x16x32_bf16 v[34:37], v[172:175], v[200:203], v[34:37]
	v_mfma_f32_16x16x32_bf16 v[38:41], v[192:195], v[200:203], v[38:41]
	s_setprio 0
	s_barrier
	s_add_i32 s50, 0, 0x18000
	s_add_i32 s51, 0, 0x1c000
	v_add_u32_e32 v70, s50, v184
	v_add_u32_e32 v154, s51, v184
	ds_read_b128 v[50:53], v70
	ds_read_b128 v[54:57], v70 offset:1024
	ds_read_b128 v[66:69], v70 offset:2048
	ds_read_b128 v[70:73], v70 offset:3072
	ds_read_b128 v[168:171], v154
	ds_read_b128 v[172:175], v154 offset:1024
	ds_read_b128 v[176:179], v154 offset:2048
	ds_read_b128 v[192:195], v154 offset:3072
	s_add_u32 s4, s4, s14
	s_addc_u32 s5, s5, s15
	s_mov_b32 m0, s67
	v_lshl_add_u64 v[240:241], s[4:5], 0, v[146:147]
	ds_read_b128 v[196:199], v188 offset:32768
	ds_read_b128 v[200:203], v188 offset:33792
	ds_read_b128 v[204:207], v188 offset:34816
	ds_read_b128 v[208:211], v188 offset:35840
	ds_read_b128 v[212:215], v188 offset:36864
	ds_read_b128 v[216:219], v188 offset:37888
	ds_read_b128 v[220:223], v188 offset:38912
	ds_read_b128 v[224:227], v188 offset:39936
	global_load_lds_dwordx4 v[240:241], off
	v_lshl_add_u64 v[240:241], s[4:5], 0, v[150:151]
	s_mov_b32 m0, s68
	s_nop 0
	global_load_lds_dwordx4 v[240:241], off
	s_waitcnt vmcnt(8)
	s_waitcnt lgkmcnt(0)
	s_setprio 1
	s_waitcnt lgkmcnt(0)
	v_mfma_f32_16x16x32_bf16 v[142:145], v[50:53], v[196:199], v[142:145]
	v_mfma_f32_16x16x32_bf16 v[138:141], v[66:69], v[196:199], v[138:141]
	v_mfma_f32_16x16x32_bf16 v[126:129], v[50:53], v[204:207], v[126:129]
	v_mfma_f32_16x16x32_bf16 v[122:125], v[66:69], v[204:207], v[122:125]
	v_mfma_f32_16x16x32_bf16 v[110:113], v[50:53], v[212:215], v[110:113]
	v_mfma_f32_16x16x32_bf16 v[106:109], v[66:69], v[212:215], v[106:109]
	s_barrier
	v_mfma_f32_16x16x32_bf16 v[94:97], v[50:53], v[220:223], v[94:97]
	v_mfma_f32_16x16x32_bf16 v[90:93], v[66:69], v[220:223], v[90:93]
	v_mfma_f32_16x16x32_bf16 v[142:145], v[54:57], v[200:203], v[142:145]
	v_mfma_f32_16x16x32_bf16 v[138:141], v[70:73], v[200:203], v[138:141]
	v_mfma_f32_16x16x32_bf16 v[126:129], v[54:57], v[208:211], v[126:129]
	v_mfma_f32_16x16x32_bf16 v[122:125], v[70:73], v[208:211], v[122:125]
	v_mfma_f32_16x16x32_bf16 v[110:113], v[54:57], v[216:219], v[110:113]
	v_mfma_f32_16x16x32_bf16 v[106:109], v[70:73], v[216:219], v[106:109]
	v_mfma_f32_16x16x32_bf16 v[94:97], v[54:57], v[224:227], v[94:97]
	v_mfma_f32_16x16x32_bf16 v[90:93], v[70:73], v[224:227], v[90:93]
	s_setprio 0
	s_setprio 1
	v_mfma_f32_16x16x32_bf16 v[134:137], v[168:171], v[196:199], v[134:137]
	v_mfma_f32_16x16x32_bf16 v[130:133], v[176:179], v[196:199], v[130:133]
	v_mfma_f32_16x16x32_bf16 v[118:121], v[168:171], v[204:207], v[118:121]
	v_mfma_f32_16x16x32_bf16 v[114:117], v[176:179], v[204:207], v[114:117]
	v_mfma_f32_16x16x32_bf16 v[102:105], v[168:171], v[212:215], v[102:105]
	v_mfma_f32_16x16x32_bf16 v[98:101], v[176:179], v[212:215], v[98:101]
	v_mfma_f32_16x16x32_bf16 v[86:89], v[168:171], v[220:223], v[86:89]
	v_mfma_f32_16x16x32_bf16 v[82:85], v[176:179], v[220:223], v[82:85]
	v_mfma_f32_16x16x32_bf16 v[134:137], v[172:175], v[200:203], v[134:137]
	v_mfma_f32_16x16x32_bf16 v[130:133], v[192:195], v[200:203], v[130:133]
	v_mfma_f32_16x16x32_bf16 v[118:121], v[172:175], v[208:211], v[118:121]
	v_mfma_f32_16x16x32_bf16 v[114:117], v[192:195], v[208:211], v[114:117]
	v_mfma_f32_16x16x32_bf16 v[102:105], v[172:175], v[216:219], v[102:105]
	v_mfma_f32_16x16x32_bf16 v[98:101], v[192:195], v[216:219], v[98:101]
	v_mfma_f32_16x16x32_bf16 v[86:89], v[172:175], v[224:227], v[86:89]
	v_mfma_f32_16x16x32_bf16 v[82:85], v[192:195], v[224:227], v[82:85]
	s_setprio 0
	s_barrier
	s_add_i32 s4, s50, s62
	v_lshl_add_u64 v[228:229], v[228:229], 0, s[28:29]
	s_mov_b32 m0, s4
	ds_read_b128 v[196:199], v188 offset:49152
	ds_read_b128 v[200:203], v188 offset:50176
	ds_read_b128 v[204:207], v188 offset:51200
	ds_read_b128 v[208:211], v188 offset:52224
	ds_read_b128 v[212:215], v188 offset:53248
	ds_read_b128 v[216:219], v188 offset:54272
	ds_read_b128 v[220:223], v188 offset:55296
	ds_read_b128 v[224:227], v188 offset:56320
	global_load_lds_dwordx4 v[228:229], off
	v_lshl_add_u64 v[228:229], v[230:231], 0, s[28:29]
	s_add_i32 m0, s4, 0x2000
	s_add_i32 s4, s51, s62
	global_load_lds_dwordx4 v[228:229], off
	v_lshl_add_u64 v[228:229], v[232:233], 0, s[28:29]
	s_mov_b32 m0, s4
	s_nop 0
	global_load_lds_dwordx4 v[228:229], off
	v_lshl_add_u64 v[228:229], v[234:235], 0, s[28:29]
	s_add_i32 m0, s4, 0x2000
	s_nop 0
	global_load_lds_dwordx4 v[228:229], off
	v_lshl_add_u64 v[228:229], v[236:237], 0, s[28:29]
	s_mov_b32 m0, s82
	s_nop 0
	global_load_lds_dwordx4 v[228:229], off
	v_lshl_add_u64 v[228:229], v[238:239], 0, s[28:29]
	s_mov_b32 m0, s83
	s_nop 0
	global_load_lds_dwordx4 v[228:229], off
	s_waitcnt vmcnt(8)
	s_waitcnt lgkmcnt(0)
	s_setprio 1
	s_waitcnt lgkmcnt(0)
	v_mfma_f32_16x16x32_bf16 v[78:81], v[50:53], v[196:199], v[78:81]
	v_mfma_f32_16x16x32_bf16 v[74:77], v[66:69], v[196:199], v[74:77]
	v_mfma_f32_16x16x32_bf16 v[62:65], v[50:53], v[204:207], v[62:65]
	v_mfma_f32_16x16x32_bf16 v[58:61], v[66:69], v[204:207], v[58:61]
	v_mfma_f32_16x16x32_bf16 v[30:33], v[50:53], v[212:215], v[30:33]
	v_mfma_f32_16x16x32_bf16 v[26:29], v[66:69], v[212:215], v[26:29]
	s_barrier
	v_mfma_f32_16x16x32_bf16 v[14:17], v[50:53], v[220:223], v[14:17]
	v_mfma_f32_16x16x32_bf16 v[10:13], v[66:69], v[220:223], v[10:13]
	v_mfma_f32_16x16x32_bf16 v[78:81], v[54:57], v[200:203], v[78:81]
	v_mfma_f32_16x16x32_bf16 v[74:77], v[70:73], v[200:203], v[74:77]
	v_mfma_f32_16x16x32_bf16 v[62:65], v[54:57], v[208:211], v[62:65]
	v_mfma_f32_16x16x32_bf16 v[58:61], v[70:73], v[208:211], v[58:61]
	v_mfma_f32_16x16x32_bf16 v[30:33], v[54:57], v[216:219], v[30:33]
	v_mfma_f32_16x16x32_bf16 v[26:29], v[70:73], v[216:219], v[26:29]
	v_mfma_f32_16x16x32_bf16 v[14:17], v[54:57], v[224:227], v[14:17]
	v_mfma_f32_16x16x32_bf16 v[10:13], v[70:73], v[224:227], v[10:13]
	s_setprio 0
	s_setprio 1
	v_mfma_f32_16x16x32_bf16 v[34:37], v[168:171], v[196:199], v[34:37]
	v_mfma_f32_16x16x32_bf16 v[70:73], v[172:175], v[200:203], v[34:37]
	v_mfma_f32_16x16x32_bf16 v[34:37], v[176:179], v[196:199], v[38:41]
	v_mfma_f32_16x16x32_bf16 v[66:69], v[192:195], v[200:203], v[34:37]
	v_mfma_f32_16x16x32_bf16 v[34:37], v[168:171], v[204:207], v[46:49]
	v_mfma_f32_16x16x32_bf16 v[46:49], v[172:175], v[208:211], v[34:37]
	v_mfma_f32_16x16x32_bf16 v[34:37], v[176:179], v[204:207], v[42:45]
	v_mfma_f32_16x16x32_bf16 v[22:25], v[168:171], v[212:215], v[22:25]
	v_mfma_f32_16x16x32_bf16 v[18:21], v[176:179], v[212:215], v[18:21]
	v_mfma_f32_16x16x32_bf16 v[6:9], v[168:171], v[220:223], v[6:9]
	v_mfma_f32_16x16x32_bf16 v[2:5], v[176:179], v[220:223], v[2:5]
	v_mfma_f32_16x16x32_bf16 v[42:45], v[192:195], v[208:211], v[34:37]
	v_mfma_f32_16x16x32_bf16 v[22:25], v[172:175], v[216:219], v[22:25]
	v_mfma_f32_16x16x32_bf16 v[18:21], v[192:195], v[216:219], v[18:21]
	v_mfma_f32_16x16x32_bf16 v[6:9], v[172:175], v[224:227], v[6:9]
	v_mfma_f32_16x16x32_bf16 v[2:5], v[192:195], v[224:227], v[2:5]
	s_setprio 0
	s_barrier
	s_add_u32 s2, s2, 0x100
	s_addc_u32 s3, s3, 0
	s_add_u32 s6, s6, 0x100
	s_addc_u32 s7, s7, 0
	s_cmp_ge_i32 s47, s84
	s_mov_b32 s4, s47
	s_cbranch_scc0 .LBB0_2116

.LBB0_2764:
	v_add_u32_e32 v158, s68, v229
	v_add_u32_e32 v174, s69, v229
	ds_read_b128 v[146:149], v158
	ds_read_b128 v[150:153], v158 offset:1024
	ds_read_b128 v[154:157], v158 offset:2048
	ds_read_b128 v[158:161], v158 offset:3072
	ds_read_b128 v[162:165], v174
	ds_read_b128 v[166:169], v174 offset:1024
	ds_read_b128 v[170:173], v174 offset:2048
	ds_read_b128 v[174:177], v174 offset:3072
	s_add_i32 s84, s42, 2
	s_add_u32 s85, s40, 0x80
	s_addc_u32 s43, s41, 0
	s_cmp_eq_u32 s65, s42
	s_cselect_b32 s42, s4, s85
	s_cselect_b32 s43, s5, s43
	s_cselect_b32 s87, s39, s83
	s_cselect_b32 s86, s38, s82
	v_lshl_add_u64 v[210:211], s[40:41], 0, v[138:139]
	s_add_i32 m0, s51, 0xc000
	ds_read_b128 v[178:181], v231
	ds_read_b128 v[182:185], v231 offset:1024
	ds_read_b128 v[186:189], v231 offset:2048
	ds_read_b128 v[190:193], v231 offset:3072
	ds_read_b128 v[194:197], v231 offset:4096
	ds_read_b128 v[198:201], v231 offset:5120
	ds_read_b128 v[202:205], v231 offset:6144
	ds_read_b128 v[206:209], v231 offset:7168
	global_load_lds_dwordx4 v[210:211], off
	v_lshl_add_u64 v[210:211], s[40:41], 0, v[140:141]
	s_add_i32 m0, s51, 0xe000
	s_nop 0
	global_load_lds_dwordx4 v[210:211], off
	s_waitcnt vmcnt(8)
	s_waitcnt lgkmcnt(0)
	s_setprio 1
	s_waitcnt lgkmcnt(0)
	v_mfma_i32_16x16x64_i8 v[126:129], v[146:149], v[178:181], v[126:129]
	v_mfma_i32_16x16x64_i8 v[122:125], v[154:157], v[178:181], v[122:125]
	v_mfma_i32_16x16x64_i8 v[118:121], v[146:149], v[186:189], v[118:121]
	v_mfma_i32_16x16x64_i8 v[114:117], v[154:157], v[186:189], v[114:117]
	v_mfma_i32_16x16x64_i8 v[106:109], v[146:149], v[194:197], v[106:109]
	v_mfma_i32_16x16x64_i8 v[98:101], v[154:157], v[194:197], v[98:101]
	s_barrier
	v_mfma_i32_16x16x64_i8 v[90:93], v[146:149], v[202:205], v[90:93]
	v_mfma_i32_16x16x64_i8 v[82:85], v[154:157], v[202:205], v[82:85]
	v_mfma_i32_16x16x64_i8 v[126:129], v[150:153], v[182:185], v[126:129]
	v_mfma_i32_16x16x64_i8 v[122:125], v[158:161], v[182:185], v[122:125]
	v_mfma_i32_16x16x64_i8 v[118:121], v[150:153], v[190:193], v[118:121]
	v_mfma_i32_16x16x64_i8 v[114:117], v[158:161], v[190:193], v[114:117]
	v_mfma_i32_16x16x64_i8 v[106:109], v[150:153], v[198:201], v[106:109]
	v_mfma_i32_16x16x64_i8 v[98:101], v[158:161], v[198:201], v[98:101]
	v_mfma_i32_16x16x64_i8 v[90:93], v[150:153], v[206:209], v[90:93]
	v_mfma_i32_16x16x64_i8 v[82:85], v[158:161], v[206:209], v[82:85]
	s_setprio 0
	s_setprio 1
	v_mfma_i32_16x16x64_i8 v[110:113], v[162:165], v[178:181], v[110:113]
	v_mfma_i32_16x16x64_i8 v[102:105], v[170:173], v[178:181], v[102:105]
	v_mfma_i32_16x16x64_i8 v[94:97], v[162:165], v[186:189], v[94:97]
	v_mfma_i32_16x16x64_i8 v[86:89], v[170:173], v[186:189], v[86:89]
	v_mfma_i32_16x16x64_i8 v[78:81], v[162:165], v[194:197], v[78:81]
	v_mfma_i32_16x16x64_i8 v[74:77], v[170:173], v[194:197], v[74:77]
	v_mfma_i32_16x16x64_i8 v[70:73], v[162:165], v[202:205], v[70:73]
	v_mfma_i32_16x16x64_i8 v[66:69], v[170:173], v[202:205], v[66:69]
	v_mfma_i32_16x16x64_i8 v[110:113], v[166:169], v[182:185], v[110:113]
	v_mfma_i32_16x16x64_i8 v[102:105], v[174:177], v[182:185], v[102:105]
	v_mfma_i32_16x16x64_i8 v[94:97], v[166:169], v[190:193], v[94:97]
	v_mfma_i32_16x16x64_i8 v[86:89], v[174:177], v[190:193], v[86:89]
	v_mfma_i32_16x16x64_i8 v[78:81], v[166:169], v[198:201], v[78:81]
	v_mfma_i32_16x16x64_i8 v[74:77], v[174:177], v[198:201], v[74:77]
	v_mfma_i32_16x16x64_i8 v[70:73], v[166:169], v[206:209], v[70:73]
	v_mfma_i32_16x16x64_i8 v[66:69], v[174:177], v[206:209], v[66:69]
	s_setprio 0
	s_barrier
	s_add_i32 s85, s68, s50
	v_lshl_add_u64 v[210:211], s[86:87], 0, v[132:133]
	s_mov_b32 m0, s85
	ds_read_b128 v[178:181], v231 offset:16384
	ds_read_b128 v[182:185], v231 offset:17408
	ds_read_b128 v[186:189], v231 offset:18432
	ds_read_b128 v[190:193], v231 offset:19456
	ds_read_b128 v[194:197], v231 offset:20480
	ds_read_b128 v[198:201], v231 offset:21504
	ds_read_b128 v[202:205], v231 offset:22528
	ds_read_b128 v[206:209], v231 offset:23552
	global_load_lds_dwordx4 v[210:211], off
	s_add_i32 m0, s85, 0x2000
	v_lshl_add_u64 v[212:213], s[86:87], 0, v[136:137]
	s_add_u32 s86, s86, s8
	s_addc_u32 s87, s87, s9
	s_add_i32 s85, s69, s50
	global_load_lds_dwordx4 v[212:213], off
	v_lshl_add_u64 v[214:215], s[86:87], 0, v[132:133]
	s_mov_b32 m0, s85
	v_lshl_add_u64 v[216:217], s[86:87], 0, v[136:137]
	global_load_lds_dwordx4 v[214:215], off
	s_add_i32 m0, s85, 0x2000
	v_lshl_add_u64 v[218:219], s[42:43], 0, v[130:131]
	global_load_lds_dwordx4 v[216:217], off
	s_mov_b32 m0, s51
	v_lshl_add_u64 v[220:221], s[42:43], 0, v[134:135]
	global_load_lds_dwordx4 v[218:219], off
	s_mov_b32 m0, s54
	s_nop 0
	global_load_lds_dwordx4 v[220:221], off
	s_waitcnt vmcnt(8)
	s_waitcnt lgkmcnt(0)
	s_setprio 1
	s_waitcnt lgkmcnt(0)
	v_mfma_i32_16x16x64_i8 v[62:65], v[146:149], v[178:181], v[62:65]
	v_mfma_i32_16x16x64_i8 v[58:61], v[154:157], v[178:181], v[58:61]
	v_mfma_i32_16x16x64_i8 v[54:57], v[146:149], v[186:189], v[54:57]
	v_mfma_i32_16x16x64_i8 v[50:53], v[154:157], v[186:189], v[50:53]
	v_mfma_i32_16x16x64_i8 v[42:45], v[146:149], v[194:197], v[42:45]
	v_mfma_i32_16x16x64_i8 v[34:37], v[154:157], v[194:197], v[34:37]
	s_barrier
	v_mfma_i32_16x16x64_i8 v[26:29], v[146:149], v[202:205], v[26:29]
	v_mfma_i32_16x16x64_i8 v[18:21], v[154:157], v[202:205], v[18:21]
	v_mfma_i32_16x16x64_i8 v[62:65], v[150:153], v[182:185], v[62:65]
	v_mfma_i32_16x16x64_i8 v[58:61], v[158:161], v[182:185], v[58:61]
	v_mfma_i32_16x16x64_i8 v[54:57], v[150:153], v[190:193], v[54:57]
	v_mfma_i32_16x16x64_i8 v[50:53], v[158:161], v[190:193], v[50:53]
	v_mfma_i32_16x16x64_i8 v[42:45], v[150:153], v[198:201], v[42:45]
	v_mfma_i32_16x16x64_i8 v[34:37], v[158:161], v[198:201], v[34:37]
	v_mfma_i32_16x16x64_i8 v[26:29], v[150:153], v[206:209], v[26:29]
	v_mfma_i32_16x16x64_i8 v[18:21], v[158:161], v[206:209], v[18:21]
	s_setprio 0
	s_setprio 1
	v_mfma_i32_16x16x64_i8 v[46:49], v[162:165], v[178:181], v[46:49]
	v_mfma_i32_16x16x64_i8 v[38:41], v[170:173], v[178:181], v[38:41]
	v_mfma_i32_16x16x64_i8 v[30:33], v[162:165], v[186:189], v[30:33]
	v_mfma_i32_16x16x64_i8 v[22:25], v[170:173], v[186:189], v[22:25]
	v_mfma_i32_16x16x64_i8 v[14:17], v[162:165], v[194:197], v[14:17]
	v_mfma_i32_16x16x64_i8 v[10:13], v[170:173], v[194:197], v[10:13]
	v_mfma_i32_16x16x64_i8 v[6:9], v[162:165], v[202:205], v[6:9]
	v_mfma_i32_16x16x64_i8 v[2:5], v[170:173], v[202:205], v[2:5]
	v_mfma_i32_16x16x64_i8 v[46:49], v[166:169], v[182:185], v[46:49]
	v_mfma_i32_16x16x64_i8 v[38:41], v[174:177], v[182:185], v[38:41]
	v_mfma_i32_16x16x64_i8 v[30:33], v[166:169], v[190:193], v[30:33]
	v_mfma_i32_16x16x64_i8 v[22:25], v[174:177], v[190:193], v[22:25]
	v_mfma_i32_16x16x64_i8 v[14:17], v[166:169], v[198:201], v[14:17]
	v_mfma_i32_16x16x64_i8 v[10:13], v[174:177], v[198:201], v[10:13]
	v_mfma_i32_16x16x64_i8 v[6:9], v[166:169], v[206:209], v[6:9]
	v_mfma_i32_16x16x64_i8 v[2:5], v[174:177], v[206:209], v[2:5]
	s_setprio 0
	s_barrier
	s_add_i32 s85, 0, 0x18000
	s_add_i32 s86, 0, 0x1c000
	v_add_u32_e32 v158, s85, v229
	v_add_u32_e32 v174, s86, v229
	ds_read_b128 v[146:149], v158
	ds_read_b128 v[150:153], v158 offset:1024
	ds_read_b128 v[154:157], v158 offset:2048
	ds_read_b128 v[158:161], v158 offset:3072
	ds_read_b128 v[162:165], v174
	ds_read_b128 v[166:169], v174 offset:1024
	ds_read_b128 v[170:173], v174 offset:2048
	ds_read_b128 v[174:177], v174 offset:3072
	s_add_u32 s42, s42, s8
	s_addc_u32 s43, s43, s9
	s_mov_b32 m0, s55
	v_lshl_add_u64 v[222:223], s[42:43], 0, v[130:131]
	ds_read_b128 v[178:181], v231 offset:32768
	ds_read_b128 v[182:185], v231 offset:33792
	ds_read_b128 v[186:189], v231 offset:34816
	ds_read_b128 v[190:193], v231 offset:35840
	ds_read_b128 v[194:197], v231 offset:36864
	ds_read_b128 v[198:201], v231 offset:37888
	ds_read_b128 v[202:205], v231 offset:38912
	ds_read_b128 v[206:209], v231 offset:39936
	global_load_lds_dwordx4 v[222:223], off
	v_lshl_add_u64 v[222:223], s[42:43], 0, v[134:135]
	s_mov_b32 m0, s56
	s_nop 0
	global_load_lds_dwordx4 v[222:223], off
	s_waitcnt vmcnt(8)
	s_waitcnt lgkmcnt(0)
	s_setprio 1
	s_waitcnt lgkmcnt(0)
	v_mfma_i32_16x16x64_i8 v[126:129], v[146:149], v[178:181], v[126:129]
	v_mfma_i32_16x16x64_i8 v[122:125], v[154:157], v[178:181], v[122:125]
	v_mfma_i32_16x16x64_i8 v[118:121], v[146:149], v[186:189], v[118:121]
	v_mfma_i32_16x16x64_i8 v[114:117], v[154:157], v[186:189], v[114:117]
	v_mfma_i32_16x16x64_i8 v[106:109], v[146:149], v[194:197], v[106:109]
	v_mfma_i32_16x16x64_i8 v[98:101], v[154:157], v[194:197], v[98:101]
	s_barrier
	v_mfma_i32_16x16x64_i8 v[90:93], v[146:149], v[202:205], v[90:93]
	v_mfma_i32_16x16x64_i8 v[82:85], v[154:157], v[202:205], v[82:85]
	v_mfma_i32_16x16x64_i8 v[126:129], v[150:153], v[182:185], v[126:129]
	v_mfma_i32_16x16x64_i8 v[122:125], v[158:161], v[182:185], v[122:125]
	v_mfma_i32_16x16x64_i8 v[118:121], v[150:153], v[190:193], v[118:121]
	v_mfma_i32_16x16x64_i8 v[114:117], v[158:161], v[190:193], v[114:117]
	v_mfma_i32_16x16x64_i8 v[106:109], v[150:153], v[198:201], v[106:109]
	v_mfma_i32_16x16x64_i8 v[98:101], v[158:161], v[198:201], v[98:101]
	v_mfma_i32_16x16x64_i8 v[90:93], v[150:153], v[206:209], v[90:93]
	v_mfma_i32_16x16x64_i8 v[82:85], v[158:161], v[206:209], v[82:85]
	s_setprio 0
	s_setprio 1
	v_mfma_i32_16x16x64_i8 v[110:113], v[162:165], v[178:181], v[110:113]
	v_mfma_i32_16x16x64_i8 v[102:105], v[170:173], v[178:181], v[102:105]
	v_mfma_i32_16x16x64_i8 v[94:97], v[162:165], v[186:189], v[94:97]
	v_mfma_i32_16x16x64_i8 v[86:89], v[170:173], v[186:189], v[86:89]
	v_mfma_i32_16x16x64_i8 v[78:81], v[162:165], v[194:197], v[78:81]
	v_mfma_i32_16x16x64_i8 v[74:77], v[170:173], v[194:197], v[74:77]
	v_mfma_i32_16x16x64_i8 v[70:73], v[162:165], v[202:205], v[70:73]
	v_mfma_i32_16x16x64_i8 v[66:69], v[170:173], v[202:205], v[66:69]
	v_mfma_i32_16x16x64_i8 v[110:113], v[166:169], v[182:185], v[110:113]
	v_mfma_i32_16x16x64_i8 v[102:105], v[174:177], v[182:185], v[102:105]
	v_mfma_i32_16x16x64_i8 v[94:97], v[166:169], v[190:193], v[94:97]
	v_mfma_i32_16x16x64_i8 v[86:89], v[174:177], v[190:193], v[86:89]
	v_mfma_i32_16x16x64_i8 v[78:81], v[166:169], v[198:201], v[78:81]
	v_mfma_i32_16x16x64_i8 v[74:77], v[174:177], v[198:201], v[74:77]
	v_mfma_i32_16x16x64_i8 v[70:73], v[166:169], v[206:209], v[70:73]
	v_mfma_i32_16x16x64_i8 v[66:69], v[174:177], v[206:209], v[66:69]
	s_setprio 0
	s_barrier
	s_add_i32 s42, s85, s50
	v_lshl_add_u64 v[210:211], v[210:211], 0, s[30:31]
	s_mov_b32 m0, s42
	ds_read_b128 v[178:181], v231 offset:49152
	ds_read_b128 v[182:185], v231 offset:50176
	ds_read_b128 v[186:189], v231 offset:51200
	ds_read_b128 v[190:193], v231 offset:52224
	ds_read_b128 v[194:197], v231 offset:53248
	ds_read_b128 v[198:201], v231 offset:54272
	ds_read_b128 v[202:205], v231 offset:55296
	ds_read_b128 v[206:209], v231 offset:56320
	global_load_lds_dwordx4 v[210:211], off
	v_lshl_add_u64 v[210:211], v[212:213], 0, s[30:31]
	s_add_i32 m0, s42, 0x2000
	s_add_i32 s42, s86, s50
	global_load_lds_dwordx4 v[210:211], off
	v_lshl_add_u64 v[210:211], v[214:215], 0, s[30:31]
	s_mov_b32 m0, s42
	s_nop 0
	global_load_lds_dwordx4 v[210:211], off
	v_lshl_add_u64 v[210:211], v[216:217], 0, s[30:31]
	s_add_i32 m0, s42, 0x2000
	s_nop 0
	global_load_lds_dwordx4 v[210:211], off
	v_lshl_add_u64 v[210:211], v[218:219], 0, s[30:31]
	s_mov_b32 m0, s61
	s_nop 0
	global_load_lds_dwordx4 v[210:211], off
	v_lshl_add_u64 v[210:211], v[220:221], 0, s[30:31]
	s_mov_b32 m0, s62
	s_nop 0
	global_load_lds_dwordx4 v[210:211], off
	s_waitcnt vmcnt(8)
	s_waitcnt lgkmcnt(0)
	s_setprio 1
	s_waitcnt lgkmcnt(0)
	v_mfma_i32_16x16x64_i8 v[62:65], v[146:149], v[178:181], v[62:65]
	v_mfma_i32_16x16x64_i8 v[58:61], v[154:157], v[178:181], v[58:61]
	v_mfma_i32_16x16x64_i8 v[54:57], v[146:149], v[186:189], v[54:57]
	v_mfma_i32_16x16x64_i8 v[50:53], v[154:157], v[186:189], v[50:53]
	v_mfma_i32_16x16x64_i8 v[42:45], v[146:149], v[194:197], v[42:45]
	v_mfma_i32_16x16x64_i8 v[34:37], v[154:157], v[194:197], v[34:37]
	s_barrier
	v_mfma_i32_16x16x64_i8 v[26:29], v[146:149], v[202:205], v[26:29]
	v_mfma_i32_16x16x64_i8 v[18:21], v[154:157], v[202:205], v[18:21]
	v_mfma_i32_16x16x64_i8 v[62:65], v[150:153], v[182:185], v[62:65]
	v_mfma_i32_16x16x64_i8 v[58:61], v[158:161], v[182:185], v[58:61]
	v_mfma_i32_16x16x64_i8 v[54:57], v[150:153], v[190:193], v[54:57]
	v_mfma_i32_16x16x64_i8 v[50:53], v[158:161], v[190:193], v[50:53]
	v_mfma_i32_16x16x64_i8 v[42:45], v[150:153], v[198:201], v[42:45]
	v_mfma_i32_16x16x64_i8 v[34:37], v[158:161], v[198:201], v[34:37]
	v_mfma_i32_16x16x64_i8 v[26:29], v[150:153], v[206:209], v[26:29]
	v_mfma_i32_16x16x64_i8 v[18:21], v[158:161], v[206:209], v[18:21]
	s_setprio 0
	s_setprio 1
	v_mfma_i32_16x16x64_i8 v[46:49], v[162:165], v[178:181], v[46:49]
	v_mfma_i32_16x16x64_i8 v[38:41], v[170:173], v[178:181], v[38:41]
	v_mfma_i32_16x16x64_i8 v[30:33], v[162:165], v[186:189], v[30:33]
	v_mfma_i32_16x16x64_i8 v[22:25], v[170:173], v[186:189], v[22:25]
	v_mfma_i32_16x16x64_i8 v[14:17], v[162:165], v[194:197], v[14:17]
	v_mfma_i32_16x16x64_i8 v[10:13], v[170:173], v[194:197], v[10:13]
	v_mfma_i32_16x16x64_i8 v[6:9], v[162:165], v[202:205], v[6:9]
	v_mfma_i32_16x16x64_i8 v[2:5], v[170:173], v[202:205], v[2:5]
	v_mfma_i32_16x16x64_i8 v[46:49], v[166:169], v[182:185], v[46:49]
	v_mfma_i32_16x16x64_i8 v[38:41], v[174:177], v[182:185], v[38:41]
	v_mfma_i32_16x16x64_i8 v[30:33], v[166:169], v[190:193], v[30:33]
	v_mfma_i32_16x16x64_i8 v[22:25], v[174:177], v[190:193], v[22:25]
	v_mfma_i32_16x16x64_i8 v[14:17], v[166:169], v[198:201], v[14:17]
	v_mfma_i32_16x16x64_i8 v[10:13], v[174:177], v[198:201], v[10:13]
	v_mfma_i32_16x16x64_i8 v[6:9], v[166:169], v[206:209], v[6:9]
	v_mfma_i32_16x16x64_i8 v[2:5], v[174:177], v[206:209], v[2:5]
	s_setprio 0
	s_barrier
	s_add_u32 s40, s40, 0x100
	s_addc_u32 s41, s41, 0
	s_add_u32 s82, s82, 0x100
	s_addc_u32 s83, s83, 0
	s_cmp_ge_i32 s84, s64
	s_mov_b32 s42, s84
	s_cbranch_scc0 .LBB0_2764
	v_cvt_f32_i32_e32 v214, v126
	v_cvt_f32_i32_e32 v215, v127
	v_cvt_f32_i32_e32 v212, v128
	v_cvt_f32_i32_e32 v213, v129
	v_cvt_f32_i32_e32 v218, v122
	v_cvt_f32_i32_e32 v219, v123
	v_cvt_f32_i32_e32 v216, v124
	v_cvt_f32_i32_e32 v217, v125
	v_cvt_f32_i32_e32 v222, v110
	v_cvt_f32_i32_e32 v223, v111
	v_cvt_f32_i32_e32 v220, v112
	v_cvt_f32_i32_e32 v221, v113
	v_cvt_f32_i32_e32 v226, v102
	v_cvt_f32_i32_e32 v227, v103
	v_cvt_f32_i32_e32 v224, v104
	v_cvt_f32_i32_e32 v225, v105
	v_cvt_f32_i32_e32 v194, v118
	v_cvt_f32_i32_e32 v195, v119
	v_cvt_f32_i32_e32 v192, v120
	v_cvt_f32_i32_e32 v193, v121
	v_cvt_f32_i32_e32 v200, v114
	v_cvt_f32_i32_e32 v201, v115
	v_cvt_f32_i32_e32 v198, v116
	v_cvt_f32_i32_e32 v199, v117
	v_cvt_f32_i32_e32 v206, v94
	v_cvt_f32_i32_e32 v207, v95
	v_cvt_f32_i32_e32 v202, v96
	v_cvt_f32_i32_e32 v203, v97
	v_cvt_f32_i32_e32 v208, v86
	v_cvt_f32_i32_e32 v209, v87
	v_cvt_f32_i32_e32 v204, v88
	v_cvt_f32_i32_e32 v205, v89
	v_cvt_f32_i32_e32 v178, v106
	v_cvt_f32_i32_e32 v179, v107
	v_cvt_f32_i32_e32 v176, v108
	v_cvt_f32_i32_e32 v177, v109
	v_cvt_f32_i32_e32 v182, v98
	v_cvt_f32_i32_e32 v183, v99
	v_cvt_f32_i32_e32 v180, v100
	v_cvt_f32_i32_e32 v181, v101
	v_cvt_f32_i32_e32 v188, v78
	v_cvt_f32_i32_e32 v189, v79
	v_cvt_f32_i32_e32 v184, v80
	v_cvt_f32_i32_e32 v185, v81
	v_cvt_f32_i32_e32 v190, v74
	v_cvt_f32_i32_e32 v191, v75
	v_cvt_f32_i32_e32 v186, v76
	v_cvt_f32_i32_e32 v187, v77
	v_cvt_f32_i32_e32 v162, v90
	v_cvt_f32_i32_e32 v163, v91
	v_cvt_f32_i32_e32 v160, v92
	v_cvt_f32_i32_e32 v161, v93
	v_cvt_f32_i32_e32 v166, v82
	v_cvt_f32_i32_e32 v167, v83
	v_cvt_f32_i32_e32 v164, v84
	v_cvt_f32_i32_e32 v165, v85
	v_cvt_f32_i32_e32 v172, v70
	v_cvt_f32_i32_e32 v173, v71
	v_cvt_f32_i32_e32 v168, v72
	v_cvt_f32_i32_e32 v169, v73
	v_cvt_f32_i32_e32 v174, v66
	v_cvt_f32_i32_e32 v175, v67
	v_cvt_f32_i32_e32 v170, v68
	v_cvt_f32_i32_e32 v171, v69
	v_cvt_f32_i32_e32 v146, v62
	v_cvt_f32_i32_e32 v147, v63
	v_cvt_f32_i32_e32 v128, v64
	v_cvt_f32_i32_e32 v129, v65
	v_cvt_f32_i32_e32 v150, v58
	v_cvt_f32_i32_e32 v151, v59
	v_cvt_f32_i32_e32 v148, v60
	v_cvt_f32_i32_e32 v149, v61
	v_cvt_f32_i32_e32 v156, v46
	v_cvt_f32_i32_e32 v157, v47
	v_cvt_f32_i32_e32 v152, v48
	v_cvt_f32_i32_e32 v153, v49
	v_cvt_f32_i32_e32 v158, v38
	v_cvt_f32_i32_e32 v159, v39
	v_cvt_f32_i32_e32 v154, v40
	v_cvt_f32_i32_e32 v155, v41
	v_cvt_f32_i32_e32 v114, v54
	v_cvt_f32_i32_e32 v115, v55
	v_cvt_f32_i32_e32 v112, v56
	v_cvt_f32_i32_e32 v113, v57
	v_cvt_f32_i32_e32 v118, v50
	v_cvt_f32_i32_e32 v119, v51
	v_cvt_f32_i32_e32 v116, v52
	v_cvt_f32_i32_e32 v117, v53
	v_cvt_f32_i32_e32 v124, v30
	v_cvt_f32_i32_e32 v125, v31
	v_cvt_f32_i32_e32 v120, v32
	v_cvt_f32_i32_e32 v121, v33
	v_cvt_f32_i32_e32 v126, v22
	v_cvt_f32_i32_e32 v127, v23
	v_cvt_f32_i32_e32 v122, v24
	v_cvt_f32_i32_e32 v123, v25
	v_cvt_f32_i32_e32 v64, v42
	v_cvt_f32_i32_e32 v65, v43
	v_cvt_f32_i32_e32 v62, v44
	v_cvt_f32_i32_e32 v63, v45
	v_cvt_f32_i32_e32 v68, v34
	v_cvt_f32_i32_e32 v69, v35
	v_cvt_f32_i32_e32 v66, v36
	v_cvt_f32_i32_e32 v67, v37
	v_cvt_f32_i32_e32 v74, v14
	v_cvt_f32_i32_e32 v75, v15
	v_cvt_f32_i32_e32 v70, v16
	v_cvt_f32_i32_e32 v71, v17
	v_cvt_f32_i32_e32 v76, v10
	v_cvt_f32_i32_e32 v77, v11
	v_cvt_f32_i32_e32 v72, v12
	v_cvt_f32_i32_e32 v73, v13
	v_cvt_f32_i32_e32 v48, v26
	v_cvt_f32_i32_e32 v49, v27
	v_cvt_f32_i32_e32 v46, v28
	v_cvt_f32_i32_e32 v47, v29
	v_cvt_f32_i32_e32 v52, v18
	v_cvt_f32_i32_e32 v53, v19
	v_cvt_f32_i32_e32 v50, v20
	v_cvt_f32_i32_e32 v51, v21
	v_cvt_f32_i32_e32 v58, v6
	v_cvt_f32_i32_e32 v59, v7
	v_cvt_f32_i32_e32 v54, v8
	v_cvt_f32_i32_e32 v55, v9
	v_cvt_f32_i32_e32 v60, v2
	v_cvt_f32_i32_e32 v61, v3
	v_cvt_f32_i32_e32 v56, v4
	v_cvt_f32_i32_e32 v57, v5

.LBB0_2949:
	v_add_u32_e32 v138, s60, v188
	ds_read_b128 v[148:151], v138
	ds_read_b128 v[152:155], v138 offset:1024
	ds_read_b128 v[156:159], v138 offset:2048
	ds_read_b128 v[160:163], v138 offset:3072
	v_add_u32_e32 v138, s61, v188
	ds_read_b128 v[164:167], v138
	ds_read_b128 v[168:171], v138 offset:1024
	ds_read_b128 v[172:175], v138 offset:2048
	ds_read_b128 v[176:179], v138 offset:3072
	s_add_i32 s64, s28, 2
	s_add_u32 s65, s26, 0x80
	s_addc_u32 s29, s27, 0
	s_cmp_eq_u32 s58, s28
	s_cselect_b32 s28, s2, s65
	s_cselect_b32 s29, s3, s29
	s_cselect_b32 s67, s25, s35
	s_cselect_b32 s66, s24, s34
	v_lshl_add_u64 v[184:185], s[26:27], 0, v[140:141]
	s_add_i32 m0, s42, 0xc000
	ds_read_b128 v[180:183], v189
	ds_read_b128 v[190:193], v189 offset:1024
	ds_read_b128 v[194:197], v189 offset:2048
	ds_read_b128 v[198:201], v189 offset:3072
	ds_read_b128 v[202:205], v189 offset:4096
	ds_read_b128 v[206:209], v189 offset:5120
	ds_read_b128 v[210:213], v189 offset:6144
	ds_read_b128 v[214:217], v189 offset:7168
	global_load_lds_dwordx4 v[184:185], off
	v_lshl_add_u64 v[184:185], s[26:27], 0, v[142:143]
	s_add_i32 m0, s42, 0xe000
	s_nop 0
	global_load_lds_dwordx4 v[184:185], off
	s_waitcnt vmcnt(8)
	s_waitcnt lgkmcnt(0)
	s_setprio 1
	s_waitcnt lgkmcnt(0)
	v_mfma_i32_16x16x64_i8 v[126:129], v[148:151], v[180:183], v[126:129]
	v_mfma_i32_16x16x64_i8 v[122:125], v[156:159], v[180:183], v[122:125]
	v_mfma_i32_16x16x64_i8 v[118:121], v[148:151], v[194:197], v[118:121]
	v_mfma_i32_16x16x64_i8 v[114:117], v[156:159], v[194:197], v[114:117]
	v_mfma_i32_16x16x64_i8 v[106:109], v[148:151], v[202:205], v[106:109]
	v_mfma_i32_16x16x64_i8 v[98:101], v[156:159], v[202:205], v[98:101]
	s_barrier
	v_mfma_i32_16x16x64_i8 v[90:93], v[148:151], v[210:213], v[90:93]
	v_mfma_i32_16x16x64_i8 v[82:85], v[156:159], v[210:213], v[82:85]
	v_mfma_i32_16x16x64_i8 v[126:129], v[152:155], v[190:193], v[126:129]
	v_mfma_i32_16x16x64_i8 v[122:125], v[160:163], v[190:193], v[122:125]
	v_mfma_i32_16x16x64_i8 v[118:121], v[152:155], v[198:201], v[118:121]
	v_mfma_i32_16x16x64_i8 v[114:117], v[160:163], v[198:201], v[114:117]
	v_mfma_i32_16x16x64_i8 v[106:109], v[152:155], v[206:209], v[106:109]
	v_mfma_i32_16x16x64_i8 v[98:101], v[160:163], v[206:209], v[98:101]
	v_mfma_i32_16x16x64_i8 v[90:93], v[152:155], v[214:217], v[90:93]
	v_mfma_i32_16x16x64_i8 v[82:85], v[160:163], v[214:217], v[82:85]
	s_setprio 0
	s_setprio 1
	v_mfma_i32_16x16x64_i8 v[110:113], v[164:167], v[180:183], v[110:113]
	v_mfma_i32_16x16x64_i8 v[102:105], v[172:175], v[180:183], v[102:105]
	v_mfma_i32_16x16x64_i8 v[94:97], v[164:167], v[194:197], v[94:97]
	v_mfma_i32_16x16x64_i8 v[86:89], v[172:175], v[194:197], v[86:89]
	v_mfma_i32_16x16x64_i8 v[78:81], v[164:167], v[202:205], v[78:81]
	v_mfma_i32_16x16x64_i8 v[74:77], v[172:175], v[202:205], v[74:77]
	v_mfma_i32_16x16x64_i8 v[70:73], v[164:167], v[210:213], v[70:73]
	v_mfma_i32_16x16x64_i8 v[66:69], v[172:175], v[210:213], v[66:69]
	v_mfma_i32_16x16x64_i8 v[110:113], v[168:171], v[190:193], v[110:113]
	v_mfma_i32_16x16x64_i8 v[102:105], v[176:179], v[190:193], v[102:105]
	v_mfma_i32_16x16x64_i8 v[94:97], v[168:171], v[198:201], v[94:97]
	v_mfma_i32_16x16x64_i8 v[86:89], v[176:179], v[198:201], v[86:89]
	v_mfma_i32_16x16x64_i8 v[78:81], v[168:171], v[206:209], v[78:81]
	v_mfma_i32_16x16x64_i8 v[74:77], v[176:179], v[206:209], v[74:77]
	v_mfma_i32_16x16x64_i8 v[70:73], v[168:171], v[214:217], v[70:73]
	v_mfma_i32_16x16x64_i8 v[66:69], v[176:179], v[214:217], v[66:69]
	s_setprio 0
	s_barrier
	s_add_i32 s65, s60, s41
	v_lshl_add_u64 v[184:185], s[66:67], 0, v[132:133]
	s_mov_b32 m0, s65
	ds_read_b128 v[180:183], v189 offset:16384
	ds_read_b128 v[190:193], v189 offset:17408
	ds_read_b128 v[194:197], v189 offset:18432
	ds_read_b128 v[198:201], v189 offset:19456
	ds_read_b128 v[202:205], v189 offset:20480
	ds_read_b128 v[206:209], v189 offset:21504
	ds_read_b128 v[210:213], v189 offset:22528
	ds_read_b128 v[214:217], v189 offset:23552
	global_load_lds_dwordx4 v[184:185], off
	s_add_i32 m0, s65, 0x2000
	v_lshl_add_u64 v[218:219], s[66:67], 0, v[136:137]
	s_add_u32 s66, s66, s6
	s_addc_u32 s67, s67, s7
	s_add_i32 s65, s61, s41
	global_load_lds_dwordx4 v[218:219], off
	v_lshl_add_u64 v[220:221], s[66:67], 0, v[132:133]
	s_mov_b32 m0, s65
	v_lshl_add_u64 v[222:223], s[66:67], 0, v[136:137]
	global_load_lds_dwordx4 v[220:221], off
	s_add_i32 m0, s65, 0x2000
	v_lshl_add_u64 v[224:225], s[28:29], 0, v[130:131]
	global_load_lds_dwordx4 v[222:223], off
	s_mov_b32 m0, s42
	v_lshl_add_u64 v[226:227], s[28:29], 0, v[134:135]
	global_load_lds_dwordx4 v[224:225], off
	s_mov_b32 m0, s43
	s_nop 0
	global_load_lds_dwordx4 v[226:227], off
	s_waitcnt vmcnt(8)
	s_waitcnt lgkmcnt(0)
	s_setprio 1
	s_waitcnt lgkmcnt(0)
	v_mfma_i32_16x16x64_i8 v[62:65], v[148:151], v[180:183], v[62:65]
	v_mfma_i32_16x16x64_i8 v[58:61], v[156:159], v[180:183], v[58:61]
	v_mfma_i32_16x16x64_i8 v[54:57], v[148:151], v[194:197], v[54:57]
	v_mfma_i32_16x16x64_i8 v[50:53], v[156:159], v[194:197], v[50:53]
	v_mfma_i32_16x16x64_i8 v[42:45], v[148:151], v[202:205], v[42:45]
	v_mfma_i32_16x16x64_i8 v[34:37], v[156:159], v[202:205], v[34:37]
	s_barrier
	v_mfma_i32_16x16x64_i8 v[26:29], v[148:151], v[210:213], v[26:29]
	v_mfma_i32_16x16x64_i8 v[18:21], v[156:159], v[210:213], v[18:21]
	v_mfma_i32_16x16x64_i8 v[62:65], v[152:155], v[190:193], v[62:65]
	v_mfma_i32_16x16x64_i8 v[58:61], v[160:163], v[190:193], v[58:61]
	v_mfma_i32_16x16x64_i8 v[54:57], v[152:155], v[198:201], v[54:57]
	v_mfma_i32_16x16x64_i8 v[50:53], v[160:163], v[198:201], v[50:53]
	v_mfma_i32_16x16x64_i8 v[42:45], v[152:155], v[206:209], v[42:45]
	v_mfma_i32_16x16x64_i8 v[34:37], v[160:163], v[206:209], v[34:37]
	v_mfma_i32_16x16x64_i8 v[26:29], v[152:155], v[214:217], v[26:29]
	v_mfma_i32_16x16x64_i8 v[18:21], v[160:163], v[214:217], v[18:21]
	s_setprio 0
	s_setprio 1
	v_mfma_i32_16x16x64_i8 v[46:49], v[164:167], v[180:183], v[46:49]
	v_mfma_i32_16x16x64_i8 v[38:41], v[172:175], v[180:183], v[38:41]
	v_mfma_i32_16x16x64_i8 v[30:33], v[164:167], v[194:197], v[30:33]
	v_mfma_i32_16x16x64_i8 v[22:25], v[172:175], v[194:197], v[22:25]
	v_mfma_i32_16x16x64_i8 v[14:17], v[164:167], v[202:205], v[14:17]
	v_mfma_i32_16x16x64_i8 v[10:13], v[172:175], v[202:205], v[10:13]
	v_mfma_i32_16x16x64_i8 v[6:9], v[164:167], v[210:213], v[6:9]
	v_mfma_i32_16x16x64_i8 v[2:5], v[172:175], v[210:213], v[2:5]
	v_mfma_i32_16x16x64_i8 v[46:49], v[168:171], v[190:193], v[46:49]
	v_mfma_i32_16x16x64_i8 v[38:41], v[176:179], v[190:193], v[38:41]
	v_mfma_i32_16x16x64_i8 v[30:33], v[168:171], v[198:201], v[30:33]
	v_mfma_i32_16x16x64_i8 v[22:25], v[176:179], v[198:201], v[22:25]
	v_mfma_i32_16x16x64_i8 v[14:17], v[168:171], v[206:209], v[14:17]
	v_mfma_i32_16x16x64_i8 v[10:13], v[176:179], v[206:209], v[10:13]
	v_mfma_i32_16x16x64_i8 v[6:9], v[168:171], v[214:217], v[6:9]
	v_mfma_i32_16x16x64_i8 v[2:5], v[176:179], v[214:217], v[2:5]
	s_setprio 0
	s_barrier
	s_add_i32 s65, 0, 0x18000
	v_add_u32_e32 v138, s65, v188
	s_add_i32 s66, 0, 0x1c000
	ds_read_b128 v[148:151], v138
	ds_read_b128 v[152:155], v138 offset:1024
	ds_read_b128 v[156:159], v138 offset:2048
	ds_read_b128 v[160:163], v138 offset:3072
	v_add_u32_e32 v138, s66, v188
	ds_read_b128 v[164:167], v138
	ds_read_b128 v[168:171], v138 offset:1024
	ds_read_b128 v[172:175], v138 offset:2048
	ds_read_b128 v[176:179], v138 offset:3072
	s_add_u32 s28, s28, s6
	s_addc_u32 s29, s29, s7
	s_mov_b32 m0, s44
	v_lshl_add_u64 v[228:229], s[28:29], 0, v[130:131]
	ds_read_b128 v[180:183], v189 offset:32768
	ds_read_b128 v[190:193], v189 offset:33792
	ds_read_b128 v[194:197], v189 offset:34816
	ds_read_b128 v[198:201], v189 offset:35840
	ds_read_b128 v[202:205], v189 offset:36864
	ds_read_b128 v[206:209], v189 offset:37888
	ds_read_b128 v[210:213], v189 offset:38912
	ds_read_b128 v[214:217], v189 offset:39936
	global_load_lds_dwordx4 v[228:229], off
	v_lshl_add_u64 v[228:229], s[28:29], 0, v[134:135]
	s_mov_b32 m0, s45
	s_nop 0
	global_load_lds_dwordx4 v[228:229], off
	s_waitcnt vmcnt(8)
	s_waitcnt lgkmcnt(0)
	s_setprio 1
	s_waitcnt lgkmcnt(0)
	v_mfma_i32_16x16x64_i8 v[126:129], v[148:151], v[180:183], v[126:129]
	v_mfma_i32_16x16x64_i8 v[122:125], v[156:159], v[180:183], v[122:125]
	v_mfma_i32_16x16x64_i8 v[118:121], v[148:151], v[194:197], v[118:121]
	v_mfma_i32_16x16x64_i8 v[114:117], v[156:159], v[194:197], v[114:117]
	v_mfma_i32_16x16x64_i8 v[106:109], v[148:151], v[202:205], v[106:109]
	v_mfma_i32_16x16x64_i8 v[98:101], v[156:159], v[202:205], v[98:101]
	s_barrier
	v_mfma_i32_16x16x64_i8 v[90:93], v[148:151], v[210:213], v[90:93]
	v_mfma_i32_16x16x64_i8 v[82:85], v[156:159], v[210:213], v[82:85]
	v_mfma_i32_16x16x64_i8 v[126:129], v[152:155], v[190:193], v[126:129]
	v_mfma_i32_16x16x64_i8 v[122:125], v[160:163], v[190:193], v[122:125]
	v_mfma_i32_16x16x64_i8 v[118:121], v[152:155], v[198:201], v[118:121]
	v_mfma_i32_16x16x64_i8 v[114:117], v[160:163], v[198:201], v[114:117]
	v_mfma_i32_16x16x64_i8 v[106:109], v[152:155], v[206:209], v[106:109]
	v_mfma_i32_16x16x64_i8 v[98:101], v[160:163], v[206:209], v[98:101]
	v_mfma_i32_16x16x64_i8 v[90:93], v[152:155], v[214:217], v[90:93]
	v_mfma_i32_16x16x64_i8 v[82:85], v[160:163], v[214:217], v[82:85]
	s_setprio 0
	s_setprio 1
	v_mfma_i32_16x16x64_i8 v[110:113], v[164:167], v[180:183], v[110:113]
	v_mfma_i32_16x16x64_i8 v[102:105], v[172:175], v[180:183], v[102:105]
	v_mfma_i32_16x16x64_i8 v[94:97], v[164:167], v[194:197], v[94:97]
	v_mfma_i32_16x16x64_i8 v[86:89], v[172:175], v[194:197], v[86:89]
	v_mfma_i32_16x16x64_i8 v[78:81], v[164:167], v[202:205], v[78:81]
	v_mfma_i32_16x16x64_i8 v[74:77], v[172:175], v[202:205], v[74:77]
	v_mfma_i32_16x16x64_i8 v[70:73], v[164:167], v[210:213], v[70:73]
	v_mfma_i32_16x16x64_i8 v[66:69], v[172:175], v[210:213], v[66:69]
	v_mfma_i32_16x16x64_i8 v[110:113], v[168:171], v[190:193], v[110:113]
	v_mfma_i32_16x16x64_i8 v[102:105], v[176:179], v[190:193], v[102:105]
	v_mfma_i32_16x16x64_i8 v[94:97], v[168:171], v[198:201], v[94:97]
	v_mfma_i32_16x16x64_i8 v[86:89], v[176:179], v[198:201], v[86:89]
	v_mfma_i32_16x16x64_i8 v[78:81], v[168:171], v[206:209], v[78:81]
	v_mfma_i32_16x16x64_i8 v[74:77], v[176:179], v[206:209], v[74:77]
	v_mfma_i32_16x16x64_i8 v[70:73], v[168:171], v[214:217], v[70:73]
	v_mfma_i32_16x16x64_i8 v[66:69], v[176:179], v[214:217], v[66:69]
	s_setprio 0
	s_barrier
	s_add_i32 s28, s65, s41
	v_lshl_add_u64 v[184:185], v[184:185], 0, s[18:19]
	s_mov_b32 m0, s28
	ds_read_b128 v[180:183], v189 offset:49152
	ds_read_b128 v[190:193], v189 offset:50176
	ds_read_b128 v[194:197], v189 offset:51200
	ds_read_b128 v[198:201], v189 offset:52224
	ds_read_b128 v[202:205], v189 offset:53248
	ds_read_b128 v[206:209], v189 offset:54272
	ds_read_b128 v[210:213], v189 offset:55296
	ds_read_b128 v[214:217], v189 offset:56320
	global_load_lds_dwordx4 v[184:185], off
	v_lshl_add_u64 v[184:185], v[218:219], 0, s[18:19]
	s_add_i32 m0, s28, 0x2000
	s_add_i32 s28, s66, s41
	global_load_lds_dwordx4 v[184:185], off
	v_lshl_add_u64 v[184:185], v[220:221], 0, s[18:19]
	s_mov_b32 m0, s28
	s_nop 0
	global_load_lds_dwordx4 v[184:185], off
	v_lshl_add_u64 v[184:185], v[222:223], 0, s[18:19]
	s_add_i32 m0, s28, 0x2000
	s_nop 0
	global_load_lds_dwordx4 v[184:185], off
	v_lshl_add_u64 v[184:185], v[224:225], 0, s[18:19]
	s_mov_b32 m0, s51
	s_nop 0
	global_load_lds_dwordx4 v[184:185], off
	v_lshl_add_u64 v[184:185], v[226:227], 0, s[18:19]
	s_mov_b32 m0, s54
	s_nop 0
	global_load_lds_dwordx4 v[184:185], off
	s_waitcnt vmcnt(8)
	s_waitcnt lgkmcnt(0)
	s_setprio 1
	s_waitcnt lgkmcnt(0)
	v_mfma_i32_16x16x64_i8 v[62:65], v[148:151], v[180:183], v[62:65]
	v_mfma_i32_16x16x64_i8 v[58:61], v[156:159], v[180:183], v[58:61]
	v_mfma_i32_16x16x64_i8 v[54:57], v[148:151], v[194:197], v[54:57]
	v_mfma_i32_16x16x64_i8 v[50:53], v[156:159], v[194:197], v[50:53]
	v_mfma_i32_16x16x64_i8 v[42:45], v[148:151], v[202:205], v[42:45]
	v_mfma_i32_16x16x64_i8 v[34:37], v[156:159], v[202:205], v[34:37]
	s_barrier
	v_mfma_i32_16x16x64_i8 v[26:29], v[148:151], v[210:213], v[26:29]
	v_mfma_i32_16x16x64_i8 v[18:21], v[156:159], v[210:213], v[18:21]
	v_mfma_i32_16x16x64_i8 v[62:65], v[152:155], v[190:193], v[62:65]
	v_mfma_i32_16x16x64_i8 v[58:61], v[160:163], v[190:193], v[58:61]
	v_mfma_i32_16x16x64_i8 v[54:57], v[152:155], v[198:201], v[54:57]
	v_mfma_i32_16x16x64_i8 v[50:53], v[160:163], v[198:201], v[50:53]
	v_mfma_i32_16x16x64_i8 v[42:45], v[152:155], v[206:209], v[42:45]
	v_mfma_i32_16x16x64_i8 v[34:37], v[160:163], v[206:209], v[34:37]
	v_mfma_i32_16x16x64_i8 v[26:29], v[152:155], v[214:217], v[26:29]
	v_mfma_i32_16x16x64_i8 v[18:21], v[160:163], v[214:217], v[18:21]
	s_setprio 0
	s_setprio 1
	v_mfma_i32_16x16x64_i8 v[46:49], v[164:167], v[180:183], v[46:49]
	v_mfma_i32_16x16x64_i8 v[38:41], v[172:175], v[180:183], v[38:41]
	v_mfma_i32_16x16x64_i8 v[30:33], v[164:167], v[194:197], v[30:33]
	v_mfma_i32_16x16x64_i8 v[22:25], v[172:175], v[194:197], v[22:25]
	v_mfma_i32_16x16x64_i8 v[14:17], v[164:167], v[202:205], v[14:17]
	v_mfma_i32_16x16x64_i8 v[10:13], v[172:175], v[202:205], v[10:13]
	v_mfma_i32_16x16x64_i8 v[6:9], v[164:167], v[210:213], v[6:9]
	v_mfma_i32_16x16x64_i8 v[2:5], v[172:175], v[210:213], v[2:5]
	v_mfma_i32_16x16x64_i8 v[46:49], v[168:171], v[190:193], v[46:49]
	v_mfma_i32_16x16x64_i8 v[38:41], v[176:179], v[190:193], v[38:41]
	v_mfma_i32_16x16x64_i8 v[30:33], v[168:171], v[198:201], v[30:33]
	v_mfma_i32_16x16x64_i8 v[22:25], v[176:179], v[198:201], v[22:25]
	v_mfma_i32_16x16x64_i8 v[14:17], v[168:171], v[206:209], v[14:17]
	v_mfma_i32_16x16x64_i8 v[10:13], v[176:179], v[206:209], v[10:13]
	v_mfma_i32_16x16x64_i8 v[6:9], v[168:171], v[214:217], v[6:9]
	v_mfma_i32_16x16x64_i8 v[2:5], v[176:179], v[214:217], v[2:5]
	s_setprio 0
	s_barrier
	s_add_u32 s26, s26, 0x100
	s_addc_u32 s27, s27, 0
	s_add_u32 s34, s34, 0x100
	s_addc_u32 s35, s35, 0
	s_cmp_ge_i32 s64, s55
	s_mov_b32 s28, s64
	s_cbranch_scc0 .LBB0_2949
	v_cvt_f32_i32_e32 v172, v126
	v_cvt_f32_i32_e32 v173, v127
	v_cvt_f32_i32_e32 v170, v128
	v_cvt_f32_i32_e32 v171, v129
	v_cvt_f32_i32_e32 v174, v122
	v_cvt_f32_i32_e32 v175, v123
	v_cvt_f32_i32_e32 v176, v124
	v_cvt_f32_i32_e32 v177, v125
	v_cvt_f32_i32_e32 v180, v110
	v_cvt_f32_i32_e32 v181, v111
	v_cvt_f32_i32_e32 v182, v112
	v_cvt_f32_i32_e32 v183, v113
	v_cvt_f32_i32_e32 v178, v102
	v_cvt_f32_i32_e32 v179, v103
	v_cvt_f32_i32_e32 v184, v104
	v_cvt_f32_i32_e32 v185, v105
	v_cvt_f32_i32_e32 v152, v118
	v_cvt_f32_i32_e32 v153, v119
	v_cvt_f32_i32_e32 v154, v120
	v_cvt_f32_i32_e32 v155, v121
	v_cvt_f32_i32_e32 v156, v114
	v_cvt_f32_i32_e32 v157, v115
	v_cvt_f32_i32_e32 v158, v116
	v_cvt_f32_i32_e32 v159, v117
	v_cvt_f32_i32_e32 v160, v94
	v_cvt_f32_i32_e32 v161, v95
	v_cvt_f32_i32_e32 v162, v96
	v_cvt_f32_i32_e32 v163, v97
	v_cvt_f32_i32_e32 v164, v86
	v_cvt_f32_i32_e32 v165, v87
	v_cvt_f32_i32_e32 v166, v88
	v_cvt_f32_i32_e32 v167, v89
	v_cvt_f32_i32_e32 v118, v106
	v_cvt_f32_i32_e32 v119, v107
	v_cvt_f32_i32_e32 v120, v108
	v_cvt_f32_i32_e32 v121, v109
	v_cvt_f32_i32_e32 v122, v98
	v_cvt_f32_i32_e32 v123, v99
	v_cvt_f32_i32_e32 v124, v100
	v_cvt_f32_i32_e32 v125, v101
	v_cvt_f32_i32_e32 v126, v78
	v_cvt_f32_i32_e32 v127, v79
	v_cvt_f32_i32_e32 v128, v80
	v_cvt_f32_i32_e32 v129, v81
	v_cvt_f32_i32_e32 v148, v74
	v_cvt_f32_i32_e32 v149, v75
	v_cvt_f32_i32_e32 v150, v76
	v_cvt_f32_i32_e32 v151, v77
	v_cvt_f32_i32_e32 v102, v90
	v_cvt_f32_i32_e32 v103, v91
	v_cvt_f32_i32_e32 v104, v92
	v_cvt_f32_i32_e32 v105, v93
	v_cvt_f32_i32_e32 v106, v82
	v_cvt_f32_i32_e32 v107, v83
	v_cvt_f32_i32_e32 v108, v84
	v_cvt_f32_i32_e32 v109, v85
	v_cvt_f32_i32_e32 v110, v70
	v_cvt_f32_i32_e32 v111, v71
	v_cvt_f32_i32_e32 v112, v72
	v_cvt_f32_i32_e32 v113, v73
	v_cvt_f32_i32_e32 v114, v66
	v_cvt_f32_i32_e32 v115, v67
	v_cvt_f32_i32_e32 v116, v68
	v_cvt_f32_i32_e32 v117, v69
	v_cvt_f32_i32_e32 v82, v62
	v_cvt_f32_i32_e32 v83, v63
	v_cvt_f32_i32_e32 v84, v64
	v_cvt_f32_i32_e32 v85, v65
	v_cvt_f32_i32_e32 v86, v58
	v_cvt_f32_i32_e32 v87, v59
	v_cvt_f32_i32_e32 v88, v60
	v_cvt_f32_i32_e32 v89, v61
	v_cvt_f32_i32_e32 v92, v46
	v_cvt_f32_i32_e32 v93, v47
	v_cvt_f32_i32_e32 v94, v48
	v_cvt_f32_i32_e32 v95, v49
	v_cvt_f32_i32_e32 v96, v38
	v_cvt_f32_i32_e32 v97, v39
	v_cvt_f32_i32_e32 v98, v40
	v_cvt_f32_i32_e32 v99, v41
	v_cvt_f32_i32_e32 v66, v54
	v_cvt_f32_i32_e32 v67, v55
	v_cvt_f32_i32_e32 v68, v56
	v_cvt_f32_i32_e32 v69, v57
	v_cvt_f32_i32_e32 v70, v50
	v_cvt_f32_i32_e32 v71, v51
	v_cvt_f32_i32_e32 v72, v52
	v_cvt_f32_i32_e32 v73, v53
	v_cvt_f32_i32_e32 v74, v30
	v_cvt_f32_i32_e32 v75, v31
	v_cvt_f32_i32_e32 v76, v32
	v_cvt_f32_i32_e32 v77, v33
	v_cvt_f32_i32_e32 v78, v22
	v_cvt_f32_i32_e32 v79, v23
	v_cvt_f32_i32_e32 v80, v24
	v_cvt_f32_i32_e32 v81, v25
	v_cvt_f32_i32_e32 v50, v42
	v_cvt_f32_i32_e32 v51, v43
	v_cvt_f32_i32_e32 v52, v44
	v_cvt_f32_i32_e32 v53, v45
	v_cvt_f32_i32_e32 v54, v34
	v_cvt_f32_i32_e32 v55, v35
	v_cvt_f32_i32_e32 v56, v36
	v_cvt_f32_i32_e32 v57, v37
	v_cvt_f32_i32_e32 v58, v14
	v_cvt_f32_i32_e32 v59, v15
	v_cvt_f32_i32_e32 v60, v16
	v_cvt_f32_i32_e32 v61, v17
	v_cvt_f32_i32_e32 v62, v10
	v_cvt_f32_i32_e32 v63, v11
	v_cvt_f32_i32_e32 v64, v12
	v_cvt_f32_i32_e32 v65, v13
	v_cvt_f32_i32_e32 v34, v26
	v_cvt_f32_i32_e32 v35, v27
	v_cvt_f32_i32_e32 v36, v28
	v_cvt_f32_i32_e32 v37, v29
	v_cvt_f32_i32_e32 v38, v18
	v_cvt_f32_i32_e32 v39, v19
	v_cvt_f32_i32_e32 v40, v20
	v_cvt_f32_i32_e32 v41, v21
	v_cvt_f32_i32_e32 v42, v6
	v_cvt_f32_i32_e32 v43, v7
	v_cvt_f32_i32_e32 v44, v8
	v_cvt_f32_i32_e32 v45, v9
	v_cvt_f32_i32_e32 v46, v2
	v_cvt_f32_i32_e32 v47, v3
	v_cvt_f32_i32_e32 v48, v4
	v_cvt_f32_i32_e32 v49, v5

.LBB0_3032:
	ds_read_b128 v[114:117], v209
	ds_read_b128 v[118:121], v209 offset:1024
	ds_read_b128 v[122:125], v209 offset:2048
	ds_read_b128 v[126:129], v209 offset:3072
	ds_read_b128 v[146:149], v210
	ds_read_b128 v[150:153], v210 offset:1024
	ds_read_b128 v[154:157], v210 offset:2048
	ds_read_b128 v[158:161], v210 offset:3072
	s_add_i32 s80, s36, 2
	s_add_u32 s37, s34, 0x4000
	s_addc_u32 s38, s35, 0
	s_cmp_eq_u32 s61, s36
	s_cselect_b32 s39, s5, s38
	s_cselect_b32 s38, s4, s37
	s_cselect_b32 s82, s30, s70
	s_cselect_b32 s83, s31, s71
	s_add_u32 s36, s38, 0x8000
	s_addc_u32 s37, s39, 0
	v_lshl_add_u64 v[218:219], s[34:35], 0, v[170:171]
	s_add_i32 m0, s45, 0xc000
	ds_read_b128 v[178:181], v211
	ds_read_b128 v[182:185], v211 offset:1024
	ds_read_b128 v[186:189], v211 offset:2048
	ds_read_b128 v[190:193], v211 offset:3072
	ds_read_b128 v[194:197], v211 offset:4096
	ds_read_b128 v[198:201], v211 offset:5120
	ds_read_b128 v[202:205], v211 offset:6144
	ds_read_b128 v[214:217], v211 offset:7168
	global_load_lds_dwordx4 v[218:219], off
	v_lshl_add_u64 v[218:219], s[34:35], 0, v[172:173]
	s_add_i32 m0, s45, 0xe000
	s_nop 0
	global_load_lds_dwordx4 v[218:219], off
	s_waitcnt vmcnt(8)
	s_waitcnt lgkmcnt(0)
	s_setprio 1
	s_waitcnt lgkmcnt(0)
	v_mfma_f32_16x16x32_bf16 v[142:145], v[114:117], v[178:181], v[142:145]
	v_mfma_f32_16x16x32_bf16 v[138:141], v[122:125], v[178:181], v[138:141]
	v_mfma_f32_16x16x32_bf16 v[110:113], v[114:117], v[186:189], v[110:113]
	v_mfma_f32_16x16x32_bf16 v[106:109], v[122:125], v[186:189], v[106:109]
	v_mfma_f32_16x16x32_bf16 v[94:97], v[114:117], v[194:197], v[94:97]
	v_mfma_f32_16x16x32_bf16 v[90:93], v[122:125], v[194:197], v[90:93]
	s_barrier
	v_mfma_f32_16x16x32_bf16 v[78:81], v[114:117], v[202:205], v[78:81]
	v_mfma_f32_16x16x32_bf16 v[74:77], v[122:125], v[202:205], v[74:77]
	v_mfma_f32_16x16x32_bf16 v[142:145], v[118:121], v[182:185], v[142:145]
	v_mfma_f32_16x16x32_bf16 v[138:141], v[126:129], v[182:185], v[138:141]
	v_mfma_f32_16x16x32_bf16 v[110:113], v[118:121], v[190:193], v[110:113]
	v_mfma_f32_16x16x32_bf16 v[106:109], v[126:129], v[190:193], v[106:109]
	v_mfma_f32_16x16x32_bf16 v[94:97], v[118:121], v[198:201], v[94:97]
	v_mfma_f32_16x16x32_bf16 v[90:93], v[126:129], v[198:201], v[90:93]
	v_mfma_f32_16x16x32_bf16 v[78:81], v[118:121], v[214:217], v[78:81]
	v_mfma_f32_16x16x32_bf16 v[74:77], v[126:129], v[214:217], v[74:77]
	s_setprio 0
	s_setprio 1
	v_mfma_f32_16x16x32_bf16 v[134:137], v[146:149], v[178:181], v[134:137]
	v_mfma_f32_16x16x32_bf16 v[130:133], v[154:157], v[178:181], v[130:133]
	v_mfma_f32_16x16x32_bf16 v[102:105], v[146:149], v[186:189], v[102:105]
	v_mfma_f32_16x16x32_bf16 v[98:101], v[154:157], v[186:189], v[98:101]
	v_mfma_f32_16x16x32_bf16 v[86:89], v[146:149], v[194:197], v[86:89]
	v_mfma_f32_16x16x32_bf16 v[82:85], v[154:157], v[194:197], v[82:85]
	v_mfma_f32_16x16x32_bf16 v[70:73], v[146:149], v[202:205], v[70:73]
	v_mfma_f32_16x16x32_bf16 v[66:69], v[154:157], v[202:205], v[66:69]
	v_mfma_f32_16x16x32_bf16 v[134:137], v[150:153], v[182:185], v[134:137]
	v_mfma_f32_16x16x32_bf16 v[130:133], v[158:161], v[182:185], v[130:133]
	v_mfma_f32_16x16x32_bf16 v[102:105], v[150:153], v[190:193], v[102:105]
	v_mfma_f32_16x16x32_bf16 v[98:101], v[158:161], v[190:193], v[98:101]
	v_mfma_f32_16x16x32_bf16 v[86:89], v[150:153], v[198:201], v[86:89]
	v_mfma_f32_16x16x32_bf16 v[82:85], v[158:161], v[198:201], v[82:85]
	v_mfma_f32_16x16x32_bf16 v[70:73], v[150:153], v[214:217], v[70:73]
	v_mfma_f32_16x16x32_bf16 v[66:69], v[158:161], v[214:217], v[66:69]
	s_setprio 0
	s_barrier
	s_add_i32 s81, s64, s44
	v_lshl_add_u64 v[218:219], s[82:83], 0, v[164:165]
	s_mov_b32 m0, s81
	ds_read_b128 v[178:181], v211 offset:16384
	ds_read_b128 v[182:185], v211 offset:17408
	ds_read_b128 v[186:189], v211 offset:18432
	ds_read_b128 v[190:193], v211 offset:19456
	ds_read_b128 v[194:197], v211 offset:20480
	ds_read_b128 v[198:201], v211 offset:21504
	ds_read_b128 v[202:205], v211 offset:22528
	ds_read_b128 v[214:217], v211 offset:23552
	global_load_lds_dwordx4 v[218:219], off
	s_add_i32 m0, s81, 0x2000
	v_lshl_add_u64 v[220:221], s[82:83], 0, v[168:169]
	s_add_u32 s82, s82, s8
	s_addc_u32 s83, s83, s9
	s_add_i32 s81, s65, s44
	global_load_lds_dwordx4 v[220:221], off
	v_lshl_add_u64 v[222:223], s[82:83], 0, v[164:165]
	s_mov_b32 m0, s81
	v_lshl_add_u64 v[224:225], s[82:83], 0, v[168:169]
	global_load_lds_dwordx4 v[222:223], off
	s_add_i32 m0, s81, 0x2000
	v_lshl_add_u64 v[226:227], s[38:39], 0, v[162:163]
	global_load_lds_dwordx4 v[224:225], off
	s_mov_b32 m0, s45
	s_nop 0
	global_load_lds_dwordx4 v[226:227], off
	v_lshl_add_u64 v[226:227], s[38:39], 0, v[166:167]
	s_mov_b32 m0, s46
	s_nop 0
	global_load_lds_dwordx4 v[226:227], off
	s_waitcnt vmcnt(8)
	s_waitcnt lgkmcnt(0)
	s_setprio 1
	s_waitcnt lgkmcnt(0)
	v_mfma_f32_16x16x32_bf16 v[62:65], v[114:117], v[178:181], v[62:65]
	v_mfma_f32_16x16x32_bf16 v[58:61], v[122:125], v[178:181], v[58:61]
	v_mfma_f32_16x16x32_bf16 v[46:49], v[114:117], v[186:189], v[46:49]
	v_mfma_f32_16x16x32_bf16 v[42:45], v[122:125], v[186:189], v[42:45]
	v_mfma_f32_16x16x32_bf16 v[30:33], v[114:117], v[194:197], v[30:33]
	v_mfma_f32_16x16x32_bf16 v[26:29], v[122:125], v[194:197], v[26:29]
	s_barrier
	v_mfma_f32_16x16x32_bf16 v[14:17], v[114:117], v[202:205], v[14:17]
	v_mfma_f32_16x16x32_bf16 v[10:13], v[122:125], v[202:205], v[10:13]
	v_mfma_f32_16x16x32_bf16 v[62:65], v[118:121], v[182:185], v[62:65]
	v_mfma_f32_16x16x32_bf16 v[58:61], v[126:129], v[182:185], v[58:61]
	v_mfma_f32_16x16x32_bf16 v[46:49], v[118:121], v[190:193], v[46:49]
	v_mfma_f32_16x16x32_bf16 v[42:45], v[126:129], v[190:193], v[42:45]
	v_mfma_f32_16x16x32_bf16 v[30:33], v[118:121], v[198:201], v[30:33]
	v_mfma_f32_16x16x32_bf16 v[26:29], v[126:129], v[198:201], v[26:29]
	v_mfma_f32_16x16x32_bf16 v[14:17], v[118:121], v[214:217], v[14:17]
	v_mfma_f32_16x16x32_bf16 v[10:13], v[126:129], v[214:217], v[10:13]
	s_setprio 0
	s_setprio 1
	v_mfma_f32_16x16x32_bf16 v[54:57], v[146:149], v[178:181], v[54:57]
	v_mfma_f32_16x16x32_bf16 v[50:53], v[154:157], v[178:181], v[50:53]
	v_mfma_f32_16x16x32_bf16 v[38:41], v[146:149], v[186:189], v[38:41]
	v_mfma_f32_16x16x32_bf16 v[34:37], v[154:157], v[186:189], v[34:37]
	v_mfma_f32_16x16x32_bf16 v[22:25], v[146:149], v[194:197], v[22:25]
	v_mfma_f32_16x16x32_bf16 v[18:21], v[154:157], v[194:197], v[18:21]
	v_mfma_f32_16x16x32_bf16 v[6:9], v[146:149], v[202:205], v[6:9]
	v_mfma_f32_16x16x32_bf16 v[2:5], v[154:157], v[202:205], v[2:5]
	v_mfma_f32_16x16x32_bf16 v[54:57], v[150:153], v[182:185], v[54:57]
	v_mfma_f32_16x16x32_bf16 v[50:53], v[158:161], v[182:185], v[50:53]
	v_mfma_f32_16x16x32_bf16 v[38:41], v[150:153], v[190:193], v[38:41]
	v_mfma_f32_16x16x32_bf16 v[34:37], v[158:161], v[190:193], v[34:37]
	v_mfma_f32_16x16x32_bf16 v[22:25], v[150:153], v[198:201], v[22:25]
	v_mfma_f32_16x16x32_bf16 v[18:21], v[158:161], v[198:201], v[18:21]
	v_mfma_f32_16x16x32_bf16 v[6:9], v[150:153], v[214:217], v[6:9]
	v_mfma_f32_16x16x32_bf16 v[2:5], v[158:161], v[214:217], v[2:5]
	s_setprio 0
	s_barrier
	s_add_i32 s81, 0, 0x18000
	s_add_i32 s82, 0, 0x1c000
	v_add_u32_e32 v126, s81, v207
	v_add_u32_e32 v158, s82, v207
	ds_read_b128 v[114:117], v126
	ds_read_b128 v[118:121], v126 offset:1024
	ds_read_b128 v[122:125], v126 offset:2048
	ds_read_b128 v[126:129], v126 offset:3072
	ds_read_b128 v[146:149], v158
	ds_read_b128 v[150:153], v158 offset:1024
	ds_read_b128 v[154:157], v158 offset:2048
	ds_read_b128 v[158:161], v158 offset:3072
	s_add_u32 s38, s38, 0x4000
	s_addc_u32 s39, s39, 0
	s_mov_b32 m0, s47
	v_lshl_add_u64 v[226:227], s[38:39], 0, v[162:163]
	ds_read_b128 v[178:181], v211 offset:32768
	ds_read_b128 v[182:185], v211 offset:33792
	ds_read_b128 v[186:189], v211 offset:34816
	ds_read_b128 v[190:193], v211 offset:35840
	ds_read_b128 v[194:197], v211 offset:36864
	ds_read_b128 v[198:201], v211 offset:37888
	ds_read_b128 v[202:205], v211 offset:38912
	ds_read_b128 v[214:217], v211 offset:39936
	global_load_lds_dwordx4 v[226:227], off
	v_lshl_add_u64 v[226:227], s[38:39], 0, v[166:167]
	s_mov_b32 m0, s50
	s_nop 0
	global_load_lds_dwordx4 v[226:227], off
	s_waitcnt vmcnt(8)
	s_waitcnt lgkmcnt(0)
	s_setprio 1
	s_waitcnt lgkmcnt(0)
	v_mfma_f32_16x16x32_bf16 v[142:145], v[114:117], v[178:181], v[142:145]
	v_mfma_f32_16x16x32_bf16 v[138:141], v[122:125], v[178:181], v[138:141]
	v_mfma_f32_16x16x32_bf16 v[110:113], v[114:117], v[186:189], v[110:113]
	v_mfma_f32_16x16x32_bf16 v[106:109], v[122:125], v[186:189], v[106:109]
	v_mfma_f32_16x16x32_bf16 v[94:97], v[114:117], v[194:197], v[94:97]
	v_mfma_f32_16x16x32_bf16 v[90:93], v[122:125], v[194:197], v[90:93]
	s_barrier
	v_mfma_f32_16x16x32_bf16 v[78:81], v[114:117], v[202:205], v[78:81]
	v_mfma_f32_16x16x32_bf16 v[74:77], v[122:125], v[202:205], v[74:77]
	v_mfma_f32_16x16x32_bf16 v[142:145], v[118:121], v[182:185], v[142:145]
	v_mfma_f32_16x16x32_bf16 v[138:141], v[126:129], v[182:185], v[138:141]
	v_mfma_f32_16x16x32_bf16 v[110:113], v[118:121], v[190:193], v[110:113]
	v_mfma_f32_16x16x32_bf16 v[106:109], v[126:129], v[190:193], v[106:109]
	v_mfma_f32_16x16x32_bf16 v[94:97], v[118:121], v[198:201], v[94:97]
	v_mfma_f32_16x16x32_bf16 v[90:93], v[126:129], v[198:201], v[90:93]
	v_mfma_f32_16x16x32_bf16 v[78:81], v[118:121], v[214:217], v[78:81]
	v_mfma_f32_16x16x32_bf16 v[74:77], v[126:129], v[214:217], v[74:77]
	s_setprio 0
	s_setprio 1
	v_mfma_f32_16x16x32_bf16 v[134:137], v[146:149], v[178:181], v[134:137]
	v_mfma_f32_16x16x32_bf16 v[130:133], v[154:157], v[178:181], v[130:133]
	v_mfma_f32_16x16x32_bf16 v[102:105], v[146:149], v[186:189], v[102:105]
	v_mfma_f32_16x16x32_bf16 v[98:101], v[154:157], v[186:189], v[98:101]
	v_mfma_f32_16x16x32_bf16 v[86:89], v[146:149], v[194:197], v[86:89]
	v_mfma_f32_16x16x32_bf16 v[82:85], v[154:157], v[194:197], v[82:85]
	v_mfma_f32_16x16x32_bf16 v[70:73], v[146:149], v[202:205], v[70:73]
	v_mfma_f32_16x16x32_bf16 v[66:69], v[154:157], v[202:205], v[66:69]
	v_mfma_f32_16x16x32_bf16 v[134:137], v[150:153], v[182:185], v[134:137]
	v_mfma_f32_16x16x32_bf16 v[130:133], v[158:161], v[182:185], v[130:133]
	v_mfma_f32_16x16x32_bf16 v[102:105], v[150:153], v[190:193], v[102:105]
	v_mfma_f32_16x16x32_bf16 v[98:101], v[158:161], v[190:193], v[98:101]
	v_mfma_f32_16x16x32_bf16 v[86:89], v[150:153], v[198:201], v[86:89]
	v_mfma_f32_16x16x32_bf16 v[82:85], v[158:161], v[198:201], v[82:85]
	v_mfma_f32_16x16x32_bf16 v[70:73], v[150:153], v[214:217], v[70:73]
	v_mfma_f32_16x16x32_bf16 v[66:69], v[158:161], v[214:217], v[66:69]
	s_setprio 0
	s_barrier
	s_add_i32 s38, s81, s44
	v_lshl_add_u64 v[218:219], v[218:219], 0, s[24:25]
	s_mov_b32 m0, s38
	ds_read_b128 v[178:181], v211 offset:49152
	ds_read_b128 v[182:185], v211 offset:50176
	ds_read_b128 v[186:189], v211 offset:51200
	ds_read_b128 v[190:193], v211 offset:52224
	ds_read_b128 v[194:197], v211 offset:53248
	ds_read_b128 v[198:201], v211 offset:54272
	ds_read_b128 v[202:205], v211 offset:55296
	ds_read_b128 v[214:217], v211 offset:56320
	global_load_lds_dwordx4 v[218:219], off
	v_lshl_add_u64 v[218:219], v[220:221], 0, s[24:25]
	s_add_i32 m0, s38, 0x2000
	s_add_i32 s38, s82, s44
	global_load_lds_dwordx4 v[218:219], off
	v_lshl_add_u64 v[218:219], v[222:223], 0, s[24:25]
	s_mov_b32 m0, s38
	s_nop 0
	global_load_lds_dwordx4 v[218:219], off
	v_lshl_add_u64 v[218:219], v[224:225], 0, s[24:25]
	s_add_i32 m0, s38, 0x2000
	s_nop 0
	global_load_lds_dwordx4 v[218:219], off
	v_lshl_add_u64 v[218:219], s[36:37], 0, v[162:163]
	s_mov_b32 m0, s59
	s_nop 0
	global_load_lds_dwordx4 v[218:219], off
	v_lshl_add_u64 v[218:219], s[36:37], 0, v[166:167]
	s_mov_b32 m0, s60
	s_nop 0
	global_load_lds_dwordx4 v[218:219], off
	s_waitcnt vmcnt(8)
	s_waitcnt lgkmcnt(0)
	s_setprio 1
	s_waitcnt lgkmcnt(0)
	v_mfma_f32_16x16x32_bf16 v[62:65], v[114:117], v[178:181], v[62:65]
	v_mfma_f32_16x16x32_bf16 v[58:61], v[122:125], v[178:181], v[58:61]
	v_mfma_f32_16x16x32_bf16 v[46:49], v[114:117], v[186:189], v[46:49]
	v_mfma_f32_16x16x32_bf16 v[42:45], v[122:125], v[186:189], v[42:45]
	v_mfma_f32_16x16x32_bf16 v[30:33], v[114:117], v[194:197], v[30:33]
	v_mfma_f32_16x16x32_bf16 v[26:29], v[122:125], v[194:197], v[26:29]
	s_barrier
	v_mfma_f32_16x16x32_bf16 v[14:17], v[114:117], v[202:205], v[14:17]
	v_mfma_f32_16x16x32_bf16 v[10:13], v[122:125], v[202:205], v[10:13]
	v_mfma_f32_16x16x32_bf16 v[62:65], v[118:121], v[182:185], v[62:65]
	v_mfma_f32_16x16x32_bf16 v[58:61], v[126:129], v[182:185], v[58:61]
	v_mfma_f32_16x16x32_bf16 v[46:49], v[118:121], v[190:193], v[46:49]
	v_mfma_f32_16x16x32_bf16 v[42:45], v[126:129], v[190:193], v[42:45]
	v_mfma_f32_16x16x32_bf16 v[30:33], v[118:121], v[198:201], v[30:33]
	v_mfma_f32_16x16x32_bf16 v[26:29], v[126:129], v[198:201], v[26:29]
	v_mfma_f32_16x16x32_bf16 v[14:17], v[118:121], v[214:217], v[14:17]
	v_mfma_f32_16x16x32_bf16 v[10:13], v[126:129], v[214:217], v[10:13]
	s_setprio 0
	s_setprio 1
	v_mfma_f32_16x16x32_bf16 v[54:57], v[146:149], v[178:181], v[54:57]
	v_mfma_f32_16x16x32_bf16 v[50:53], v[154:157], v[178:181], v[50:53]
	v_mfma_f32_16x16x32_bf16 v[38:41], v[146:149], v[186:189], v[38:41]
	v_mfma_f32_16x16x32_bf16 v[34:37], v[154:157], v[186:189], v[34:37]
	v_mfma_f32_16x16x32_bf16 v[22:25], v[146:149], v[194:197], v[22:25]
	v_mfma_f32_16x16x32_bf16 v[18:21], v[154:157], v[194:197], v[18:21]
	v_mfma_f32_16x16x32_bf16 v[6:9], v[146:149], v[202:205], v[6:9]
	v_mfma_f32_16x16x32_bf16 v[2:5], v[154:157], v[202:205], v[2:5]
	v_mfma_f32_16x16x32_bf16 v[54:57], v[150:153], v[182:185], v[54:57]
	v_mfma_f32_16x16x32_bf16 v[50:53], v[158:161], v[182:185], v[50:53]
	v_mfma_f32_16x16x32_bf16 v[38:41], v[150:153], v[190:193], v[38:41]
	v_mfma_f32_16x16x32_bf16 v[34:37], v[158:161], v[190:193], v[34:37]
	v_mfma_f32_16x16x32_bf16 v[22:25], v[150:153], v[198:201], v[22:25]
	v_mfma_f32_16x16x32_bf16 v[18:21], v[158:161], v[198:201], v[18:21]
	v_mfma_f32_16x16x32_bf16 v[6:9], v[150:153], v[214:217], v[6:9]
	v_mfma_f32_16x16x32_bf16 v[2:5], v[158:161], v[214:217], v[2:5]
	s_setprio 0
	s_barrier
	s_add_u32 s70, s70, 0x100
	s_addc_u32 s71, s71, 0
	s_add_u32 s34, s34, 0x10000
	s_addc_u32 s35, s35, 0
	s_cmp_ge_i32 s80, s58
	s_mov_b32 s36, s80
	s_cbranch_scc0 .LBB0_3032

.LBB0_3126:
	ds_read_b128 v[34:37], v196
	ds_read_b128 v[38:41], v196 offset:1024
	ds_read_b128 v[50:53], v196 offset:2048
	ds_read_b128 v[54:57], v196 offset:3072
	ds_read_b128 v[146:149], v197
	ds_read_b128 v[150:153], v197 offset:1024
	ds_read_b128 v[184:187], v197 offset:2048
	ds_read_b128 v[188:191], v197 offset:3072
	s_add_i32 s11, s6, 2
	s_add_u32 s12, s4, 0x80
	s_addc_u32 s7, s5, 0
	s_cmp_eq_u32 s84, s6
	s_cselect_b32 s6, s44, s12
	s_cselect_b32 s7, s45, s7
	s_cselect_b32 s13, s47, s9
	s_cselect_b32 s12, s46, s8
	v_lshl_add_u64 v[192:193], s[4:5], 0, v[174:175]
	s_add_i32 m0, s66, 0xc000
	ds_read_b128 v[200:203], v198
	ds_read_b128 v[204:207], v198 offset:1024
	ds_read_b128 v[208:211], v198 offset:2048
	ds_read_b128 v[212:215], v198 offset:3072
	ds_read_b128 v[216:219], v198 offset:4096
	ds_read_b128 v[220:223], v198 offset:5120
	ds_read_b128 v[224:227], v198 offset:6144
	ds_read_b128 v[228:231], v198 offset:7168
	global_load_lds_dwordx4 v[192:193], off
	v_lshl_add_u64 v[192:193], s[4:5], 0, v[176:177]
	s_add_i32 m0, s66, 0xe000
	s_nop 0
	global_load_lds_dwordx4 v[192:193], off
	s_waitcnt vmcnt(8)
	s_waitcnt lgkmcnt(0)
	s_setprio 1
	s_waitcnt lgkmcnt(0)
	v_mfma_f32_16x16x32_bf16 v[142:145], v[34:37], v[200:203], v[142:145]
	v_mfma_f32_16x16x32_bf16 v[138:141], v[50:53], v[200:203], v[138:141]
	v_mfma_f32_16x16x32_bf16 v[126:129], v[34:37], v[208:211], v[126:129]
	v_mfma_f32_16x16x32_bf16 v[122:125], v[50:53], v[208:211], v[122:125]
	v_mfma_f32_16x16x32_bf16 v[110:113], v[34:37], v[216:219], v[110:113]
	v_mfma_f32_16x16x32_bf16 v[106:109], v[50:53], v[216:219], v[106:109]
	s_barrier
	v_mfma_f32_16x16x32_bf16 v[94:97], v[34:37], v[224:227], v[94:97]
	v_mfma_f32_16x16x32_bf16 v[90:93], v[50:53], v[224:227], v[90:93]
	v_mfma_f32_16x16x32_bf16 v[142:145], v[38:41], v[204:207], v[142:145]
	v_mfma_f32_16x16x32_bf16 v[138:141], v[54:57], v[204:207], v[138:141]
	v_mfma_f32_16x16x32_bf16 v[126:129], v[38:41], v[212:215], v[126:129]
	v_mfma_f32_16x16x32_bf16 v[122:125], v[54:57], v[212:215], v[122:125]
	v_mfma_f32_16x16x32_bf16 v[110:113], v[38:41], v[220:223], v[110:113]
	v_mfma_f32_16x16x32_bf16 v[106:109], v[54:57], v[220:223], v[106:109]
	v_mfma_f32_16x16x32_bf16 v[94:97], v[38:41], v[228:231], v[94:97]
	v_mfma_f32_16x16x32_bf16 v[90:93], v[54:57], v[228:231], v[90:93]
	s_setprio 0
	s_setprio 1
	v_mfma_f32_16x16x32_bf16 v[134:137], v[146:149], v[200:203], v[134:137]
	v_mfma_f32_16x16x32_bf16 v[130:133], v[184:187], v[200:203], v[130:133]
	v_mfma_f32_16x16x32_bf16 v[118:121], v[146:149], v[208:211], v[118:121]
	v_mfma_f32_16x16x32_bf16 v[114:117], v[184:187], v[208:211], v[114:117]
	v_mfma_f32_16x16x32_bf16 v[102:105], v[146:149], v[216:219], v[102:105]
	v_mfma_f32_16x16x32_bf16 v[98:101], v[184:187], v[216:219], v[98:101]
	v_mfma_f32_16x16x32_bf16 v[86:89], v[146:149], v[224:227], v[86:89]
	v_mfma_f32_16x16x32_bf16 v[82:85], v[184:187], v[224:227], v[82:85]
	v_mfma_f32_16x16x32_bf16 v[134:137], v[150:153], v[204:207], v[134:137]
	v_mfma_f32_16x16x32_bf16 v[130:133], v[188:191], v[204:207], v[130:133]
	v_mfma_f32_16x16x32_bf16 v[118:121], v[150:153], v[212:215], v[118:121]
	v_mfma_f32_16x16x32_bf16 v[114:117], v[188:191], v[212:215], v[114:117]
	v_mfma_f32_16x16x32_bf16 v[102:105], v[150:153], v[220:223], v[102:105]
	v_mfma_f32_16x16x32_bf16 v[98:101], v[188:191], v[220:223], v[98:101]
	v_mfma_f32_16x16x32_bf16 v[86:89], v[150:153], v[228:231], v[86:89]
	v_mfma_f32_16x16x32_bf16 v[82:85], v[188:191], v[228:231], v[82:85]
	s_setprio 0
	s_barrier
	s_add_i32 s20, s88, s61
	v_lshl_add_u64 v[192:193], s[12:13], 0, v[156:157]
	s_mov_b32 m0, s20
	ds_read_b128 v[200:203], v198 offset:16384
	ds_read_b128 v[204:207], v198 offset:17408
	ds_read_b128 v[208:211], v198 offset:18432
	ds_read_b128 v[212:215], v198 offset:19456
	ds_read_b128 v[216:219], v198 offset:20480
	ds_read_b128 v[220:223], v198 offset:21504
	ds_read_b128 v[224:227], v198 offset:22528
	ds_read_b128 v[228:231], v198 offset:23552
	global_load_lds_dwordx4 v[192:193], off
	s_add_i32 m0, s20, 0x2000
	v_lshl_add_u64 v[232:233], s[12:13], 0, v[160:161]
	s_add_u32 s12, s12, s16
	s_addc_u32 s13, s13, s17
	s_add_i32 s20, s89, s61
	global_load_lds_dwordx4 v[232:233], off
	v_lshl_add_u64 v[234:235], s[12:13], 0, v[156:157]
	s_mov_b32 m0, s20
	v_lshl_add_u64 v[236:237], s[12:13], 0, v[160:161]
	global_load_lds_dwordx4 v[234:235], off
	s_add_i32 m0, s20, 0x2000
	v_lshl_add_u64 v[238:239], s[6:7], 0, v[154:155]
	global_load_lds_dwordx4 v[236:237], off
	s_mov_b32 m0, s66
	v_lshl_add_u64 v[240:241], s[6:7], 0, v[158:159]
	global_load_lds_dwordx4 v[238:239], off
	s_mov_b32 m0, s68
	s_nop 0
	global_load_lds_dwordx4 v[240:241], off
	s_waitcnt vmcnt(8)
	s_waitcnt lgkmcnt(0)
	s_setprio 1
	s_waitcnt lgkmcnt(0)
	v_mfma_f32_16x16x32_bf16 v[78:81], v[34:37], v[200:203], v[78:81]
	v_mfma_f32_16x16x32_bf16 v[74:77], v[50:53], v[200:203], v[74:77]
	v_mfma_f32_16x16x32_bf16 v[62:65], v[34:37], v[208:211], v[62:65]
	v_mfma_f32_16x16x32_bf16 v[58:61], v[50:53], v[208:211], v[58:61]
	v_mfma_f32_16x16x32_bf16 v[30:33], v[34:37], v[216:219], v[30:33]
	v_mfma_f32_16x16x32_bf16 v[26:29], v[50:53], v[216:219], v[26:29]
	s_barrier
	v_mfma_f32_16x16x32_bf16 v[14:17], v[34:37], v[224:227], v[14:17]
	v_mfma_f32_16x16x32_bf16 v[10:13], v[50:53], v[224:227], v[10:13]
	v_mfma_f32_16x16x32_bf16 v[78:81], v[38:41], v[204:207], v[78:81]
	v_mfma_f32_16x16x32_bf16 v[74:77], v[54:57], v[204:207], v[74:77]
	v_mfma_f32_16x16x32_bf16 v[62:65], v[38:41], v[212:215], v[62:65]
	v_mfma_f32_16x16x32_bf16 v[58:61], v[54:57], v[212:215], v[58:61]
	v_mfma_f32_16x16x32_bf16 v[30:33], v[38:41], v[220:223], v[30:33]
	v_mfma_f32_16x16x32_bf16 v[26:29], v[54:57], v[220:223], v[26:29]
	v_mfma_f32_16x16x32_bf16 v[14:17], v[38:41], v[228:231], v[14:17]
	v_mfma_f32_16x16x32_bf16 v[10:13], v[54:57], v[228:231], v[10:13]
	s_setprio 0
	s_setprio 1
	v_mfma_f32_16x16x32_bf16 v[46:49], v[146:149], v[208:211], v[46:49]
	v_mfma_f32_16x16x32_bf16 v[42:45], v[184:187], v[208:211], v[42:45]
	v_mfma_f32_16x16x32_bf16 v[22:25], v[146:149], v[216:219], v[22:25]
	v_mfma_f32_16x16x32_bf16 v[18:21], v[184:187], v[216:219], v[18:21]
	v_mfma_f32_16x16x32_bf16 v[6:9], v[146:149], v[224:227], v[6:9]
	v_mfma_f32_16x16x32_bf16 v[2:5], v[184:187], v[224:227], v[2:5]
	v_mfma_f32_16x16x32_bf16 v[34:37], v[146:149], v[200:203], v[70:73]
	v_mfma_f32_16x16x32_bf16 v[38:41], v[184:187], v[200:203], v[66:69]
	v_mfma_f32_16x16x32_bf16 v[46:49], v[150:153], v[212:215], v[46:49]
	v_mfma_f32_16x16x32_bf16 v[42:45], v[188:191], v[212:215], v[42:45]
	v_mfma_f32_16x16x32_bf16 v[22:25], v[150:153], v[220:223], v[22:25]
	v_mfma_f32_16x16x32_bf16 v[18:21], v[188:191], v[220:223], v[18:21]
	v_mfma_f32_16x16x32_bf16 v[6:9], v[150:153], v[228:231], v[6:9]
	v_mfma_f32_16x16x32_bf16 v[2:5], v[188:191], v[228:231], v[2:5]
	v_mfma_f32_16x16x32_bf16 v[34:37], v[150:153], v[204:207], v[34:37]
	v_mfma_f32_16x16x32_bf16 v[38:41], v[188:191], v[204:207], v[38:41]
	s_setprio 0
	s_barrier
	s_add_i32 s12, 0, 0x18000
	s_add_i32 s13, 0, 0x1c000
	v_add_u32_e32 v70, s12, v194
	v_add_u32_e32 v162, s13, v194
	ds_read_b128 v[50:53], v70
	ds_read_b128 v[54:57], v70 offset:1024
	ds_read_b128 v[66:69], v70 offset:2048
	ds_read_b128 v[70:73], v70 offset:3072
	ds_read_b128 v[146:149], v162
	ds_read_b128 v[150:153], v162 offset:1024
	ds_read_b128 v[184:187], v162 offset:2048
	ds_read_b128 v[188:191], v162 offset:3072
	s_add_u32 s6, s6, s16
	s_addc_u32 s7, s7, s17
	s_mov_b32 m0, s69
	v_lshl_add_u64 v[242:243], s[6:7], 0, v[154:155]
	ds_read_b128 v[200:203], v198 offset:32768
	ds_read_b128 v[204:207], v198 offset:33792
	ds_read_b128 v[208:211], v198 offset:34816
	ds_read_b128 v[212:215], v198 offset:35840
	ds_read_b128 v[216:219], v198 offset:36864
	ds_read_b128 v[220:223], v198 offset:37888
	ds_read_b128 v[224:227], v198 offset:38912
	ds_read_b128 v[228:231], v198 offset:39936
	global_load_lds_dwordx4 v[242:243], off
	v_lshl_add_u64 v[242:243], s[6:7], 0, v[158:159]
	s_mov_b32 m0, s70
	s_nop 0
	global_load_lds_dwordx4 v[242:243], off
	s_waitcnt vmcnt(8)
	s_waitcnt lgkmcnt(0)
	s_setprio 1
	s_waitcnt lgkmcnt(0)
	v_mfma_f32_16x16x32_bf16 v[142:145], v[50:53], v[200:203], v[142:145]
	v_mfma_f32_16x16x32_bf16 v[138:141], v[66:69], v[200:203], v[138:141]
	v_mfma_f32_16x16x32_bf16 v[126:129], v[50:53], v[208:211], v[126:129]
	v_mfma_f32_16x16x32_bf16 v[122:125], v[66:69], v[208:211], v[122:125]
	v_mfma_f32_16x16x32_bf16 v[110:113], v[50:53], v[216:219], v[110:113]
	v_mfma_f32_16x16x32_bf16 v[106:109], v[66:69], v[216:219], v[106:109]
	s_barrier
	v_mfma_f32_16x16x32_bf16 v[94:97], v[50:53], v[224:227], v[94:97]
	v_mfma_f32_16x16x32_bf16 v[90:93], v[66:69], v[224:227], v[90:93]
	v_mfma_f32_16x16x32_bf16 v[142:145], v[54:57], v[204:207], v[142:145]
	v_mfma_f32_16x16x32_bf16 v[138:141], v[70:73], v[204:207], v[138:141]
	v_mfma_f32_16x16x32_bf16 v[126:129], v[54:57], v[212:215], v[126:129]
	v_mfma_f32_16x16x32_bf16 v[122:125], v[70:73], v[212:215], v[122:125]
	v_mfma_f32_16x16x32_bf16 v[110:113], v[54:57], v[220:223], v[110:113]
	v_mfma_f32_16x16x32_bf16 v[106:109], v[70:73], v[220:223], v[106:109]
	v_mfma_f32_16x16x32_bf16 v[94:97], v[54:57], v[228:231], v[94:97]
	v_mfma_f32_16x16x32_bf16 v[90:93], v[70:73], v[228:231], v[90:93]
	s_setprio 0
	s_setprio 1
	v_mfma_f32_16x16x32_bf16 v[134:137], v[146:149], v[200:203], v[134:137]
	v_mfma_f32_16x16x32_bf16 v[130:133], v[184:187], v[200:203], v[130:133]
	v_mfma_f32_16x16x32_bf16 v[118:121], v[146:149], v[208:211], v[118:121]
	v_mfma_f32_16x16x32_bf16 v[114:117], v[184:187], v[208:211], v[114:117]
	v_mfma_f32_16x16x32_bf16 v[102:105], v[146:149], v[216:219], v[102:105]
	v_mfma_f32_16x16x32_bf16 v[98:101], v[184:187], v[216:219], v[98:101]
	v_mfma_f32_16x16x32_bf16 v[86:89], v[146:149], v[224:227], v[86:89]
	v_mfma_f32_16x16x32_bf16 v[82:85], v[184:187], v[224:227], v[82:85]
	v_mfma_f32_16x16x32_bf16 v[134:137], v[150:153], v[204:207], v[134:137]
	v_mfma_f32_16x16x32_bf16 v[130:133], v[188:191], v[204:207], v[130:133]
	v_mfma_f32_16x16x32_bf16 v[118:121], v[150:153], v[212:215], v[118:121]
	v_mfma_f32_16x16x32_bf16 v[114:117], v[188:191], v[212:215], v[114:117]
	v_mfma_f32_16x16x32_bf16 v[102:105], v[150:153], v[220:223], v[102:105]
	v_mfma_f32_16x16x32_bf16 v[98:101], v[188:191], v[220:223], v[98:101]
	v_mfma_f32_16x16x32_bf16 v[86:89], v[150:153], v[228:231], v[86:89]
	v_mfma_f32_16x16x32_bf16 v[82:85], v[188:191], v[228:231], v[82:85]
	s_setprio 0
	s_barrier
	s_add_i32 s6, s12, s61
	v_lshl_add_u64 v[192:193], v[192:193], 0, s[38:39]
	s_mov_b32 m0, s6
	ds_read_b128 v[200:203], v198 offset:49152
	ds_read_b128 v[204:207], v198 offset:50176
	ds_read_b128 v[208:211], v198 offset:51200
	ds_read_b128 v[212:215], v198 offset:52224
	ds_read_b128 v[216:219], v198 offset:53248
	ds_read_b128 v[220:223], v198 offset:54272
	ds_read_b128 v[224:227], v198 offset:55296
	ds_read_b128 v[228:231], v198 offset:56320
	global_load_lds_dwordx4 v[192:193], off
	v_lshl_add_u64 v[192:193], v[232:233], 0, s[38:39]
	s_add_i32 m0, s6, 0x2000
	s_add_i32 s6, s13, s61
	global_load_lds_dwordx4 v[192:193], off
	v_lshl_add_u64 v[192:193], v[234:235], 0, s[38:39]
	s_mov_b32 m0, s6
	s_nop 0
	global_load_lds_dwordx4 v[192:193], off
	v_lshl_add_u64 v[192:193], v[236:237], 0, s[38:39]
	s_add_i32 m0, s6, 0x2000
	s_nop 0
	global_load_lds_dwordx4 v[192:193], off
	v_lshl_add_u64 v[192:193], v[238:239], 0, s[38:39]
	s_mov_b32 m0, s81
	s_nop 0
	global_load_lds_dwordx4 v[192:193], off
	v_lshl_add_u64 v[192:193], v[240:241], 0, s[38:39]
	s_mov_b32 m0, s82
	s_nop 0
	global_load_lds_dwordx4 v[192:193], off
	s_waitcnt vmcnt(8)
	s_waitcnt lgkmcnt(0)
	s_setprio 1
	s_waitcnt lgkmcnt(0)
	v_mfma_f32_16x16x32_bf16 v[78:81], v[50:53], v[200:203], v[78:81]
	v_mfma_f32_16x16x32_bf16 v[74:77], v[66:69], v[200:203], v[74:77]
	v_mfma_f32_16x16x32_bf16 v[62:65], v[50:53], v[208:211], v[62:65]
	v_mfma_f32_16x16x32_bf16 v[58:61], v[66:69], v[208:211], v[58:61]
	v_mfma_f32_16x16x32_bf16 v[30:33], v[50:53], v[216:219], v[30:33]
	v_mfma_f32_16x16x32_bf16 v[26:29], v[66:69], v[216:219], v[26:29]
	s_barrier
	v_mfma_f32_16x16x32_bf16 v[14:17], v[50:53], v[224:227], v[14:17]
	v_mfma_f32_16x16x32_bf16 v[10:13], v[66:69], v[224:227], v[10:13]
	v_mfma_f32_16x16x32_bf16 v[78:81], v[54:57], v[204:207], v[78:81]
	v_mfma_f32_16x16x32_bf16 v[74:77], v[70:73], v[204:207], v[74:77]
	v_mfma_f32_16x16x32_bf16 v[62:65], v[54:57], v[212:215], v[62:65]
	v_mfma_f32_16x16x32_bf16 v[58:61], v[70:73], v[212:215], v[58:61]
	v_mfma_f32_16x16x32_bf16 v[30:33], v[54:57], v[220:223], v[30:33]
	v_mfma_f32_16x16x32_bf16 v[26:29], v[70:73], v[220:223], v[26:29]
	v_mfma_f32_16x16x32_bf16 v[14:17], v[54:57], v[228:231], v[14:17]
	v_mfma_f32_16x16x32_bf16 v[10:13], v[70:73], v[228:231], v[10:13]
	s_setprio 0
	s_setprio 1
	v_mfma_f32_16x16x32_bf16 v[34:37], v[146:149], v[200:203], v[34:37]
	v_mfma_f32_16x16x32_bf16 v[70:73], v[150:153], v[204:207], v[34:37]
	v_mfma_f32_16x16x32_bf16 v[34:37], v[184:187], v[200:203], v[38:41]
	v_mfma_f32_16x16x32_bf16 v[66:69], v[188:191], v[204:207], v[34:37]
	v_mfma_f32_16x16x32_bf16 v[34:37], v[146:149], v[208:211], v[46:49]
	v_mfma_f32_16x16x32_bf16 v[46:49], v[150:153], v[212:215], v[34:37]
	v_mfma_f32_16x16x32_bf16 v[34:37], v[184:187], v[208:211], v[42:45]
	v_mfma_f32_16x16x32_bf16 v[22:25], v[146:149], v[216:219], v[22:25]
	v_mfma_f32_16x16x32_bf16 v[18:21], v[184:187], v[216:219], v[18:21]
	v_mfma_f32_16x16x32_bf16 v[6:9], v[146:149], v[224:227], v[6:9]
	v_mfma_f32_16x16x32_bf16 v[2:5], v[184:187], v[224:227], v[2:5]
	v_mfma_f32_16x16x32_bf16 v[42:45], v[188:191], v[212:215], v[34:37]
	v_mfma_f32_16x16x32_bf16 v[22:25], v[150:153], v[220:223], v[22:25]
	v_mfma_f32_16x16x32_bf16 v[18:21], v[188:191], v[220:223], v[18:21]
	v_mfma_f32_16x16x32_bf16 v[6:9], v[150:153], v[228:231], v[6:9]
	v_mfma_f32_16x16x32_bf16 v[2:5], v[188:191], v[228:231], v[2:5]
	s_setprio 0
	s_barrier
	s_add_u32 s4, s4, 0x100
	s_addc_u32 s5, s5, 0
	s_add_u32 s8, s8, 0x100
	s_addc_u32 s9, s9, 0
	s_cmp_ge_i32 s11, s83
	s_mov_b32 s6, s11
	s_cbranch_scc0 .LBB0_3126

.LBB0_3613:
	v_add_u32_e32 v158, s64, v229
	v_add_u32_e32 v174, s65, v229
	ds_read_b128 v[146:149], v158
	ds_read_b128 v[150:153], v158 offset:1024
	ds_read_b128 v[154:157], v158 offset:2048
	ds_read_b128 v[158:161], v158 offset:3072
	ds_read_b128 v[162:165], v174
	ds_read_b128 v[166:169], v174 offset:1024
	ds_read_b128 v[170:173], v174 offset:2048
	ds_read_b128 v[174:177], v174 offset:3072
	s_add_i32 s80, s42, 2
	s_add_u32 s81, s40, 0x80
	s_addc_u32 s43, s41, 0
	s_cmp_eq_u32 s61, s42
	s_cselect_b32 s42, s4, s81
	s_cselect_b32 s43, s5, s43
	s_cselect_b32 s83, s39, s71
	s_cselect_b32 s82, s38, s70
	v_lshl_add_u64 v[210:211], s[40:41], 0, v[138:139]
	s_add_i32 m0, s51, 0xc000
	ds_read_b128 v[178:181], v231
	ds_read_b128 v[182:185], v231 offset:1024
	ds_read_b128 v[186:189], v231 offset:2048
	ds_read_b128 v[190:193], v231 offset:3072
	ds_read_b128 v[194:197], v231 offset:4096
	ds_read_b128 v[198:201], v231 offset:5120
	ds_read_b128 v[202:205], v231 offset:6144
	ds_read_b128 v[206:209], v231 offset:7168
	global_load_lds_dwordx4 v[210:211], off
	v_lshl_add_u64 v[210:211], s[40:41], 0, v[140:141]
	s_add_i32 m0, s51, 0xe000
	s_nop 0
	global_load_lds_dwordx4 v[210:211], off
	s_waitcnt vmcnt(8)
	s_waitcnt lgkmcnt(0)
	s_setprio 1
	s_waitcnt lgkmcnt(0)
	v_mfma_i32_16x16x64_i8 v[126:129], v[146:149], v[178:181], v[126:129]
	v_mfma_i32_16x16x64_i8 v[122:125], v[154:157], v[178:181], v[122:125]
	v_mfma_i32_16x16x64_i8 v[118:121], v[146:149], v[186:189], v[118:121]
	v_mfma_i32_16x16x64_i8 v[114:117], v[154:157], v[186:189], v[114:117]
	v_mfma_i32_16x16x64_i8 v[106:109], v[146:149], v[194:197], v[106:109]
	v_mfma_i32_16x16x64_i8 v[98:101], v[154:157], v[194:197], v[98:101]
	s_barrier
	v_mfma_i32_16x16x64_i8 v[90:93], v[146:149], v[202:205], v[90:93]
	v_mfma_i32_16x16x64_i8 v[82:85], v[154:157], v[202:205], v[82:85]
	v_mfma_i32_16x16x64_i8 v[126:129], v[150:153], v[182:185], v[126:129]
	v_mfma_i32_16x16x64_i8 v[122:125], v[158:161], v[182:185], v[122:125]
	v_mfma_i32_16x16x64_i8 v[118:121], v[150:153], v[190:193], v[118:121]
	v_mfma_i32_16x16x64_i8 v[114:117], v[158:161], v[190:193], v[114:117]
	v_mfma_i32_16x16x64_i8 v[106:109], v[150:153], v[198:201], v[106:109]
	v_mfma_i32_16x16x64_i8 v[98:101], v[158:161], v[198:201], v[98:101]
	v_mfma_i32_16x16x64_i8 v[90:93], v[150:153], v[206:209], v[90:93]
	v_mfma_i32_16x16x64_i8 v[82:85], v[158:161], v[206:209], v[82:85]
	s_setprio 0
	s_setprio 1
	v_mfma_i32_16x16x64_i8 v[110:113], v[162:165], v[178:181], v[110:113]
	v_mfma_i32_16x16x64_i8 v[102:105], v[170:173], v[178:181], v[102:105]
	v_mfma_i32_16x16x64_i8 v[94:97], v[162:165], v[186:189], v[94:97]
	v_mfma_i32_16x16x64_i8 v[86:89], v[170:173], v[186:189], v[86:89]
	v_mfma_i32_16x16x64_i8 v[78:81], v[162:165], v[194:197], v[78:81]
	v_mfma_i32_16x16x64_i8 v[74:77], v[170:173], v[194:197], v[74:77]
	v_mfma_i32_16x16x64_i8 v[70:73], v[162:165], v[202:205], v[70:73]
	v_mfma_i32_16x16x64_i8 v[66:69], v[170:173], v[202:205], v[66:69]
	v_mfma_i32_16x16x64_i8 v[110:113], v[166:169], v[182:185], v[110:113]
	v_mfma_i32_16x16x64_i8 v[102:105], v[174:177], v[182:185], v[102:105]
	v_mfma_i32_16x16x64_i8 v[94:97], v[166:169], v[190:193], v[94:97]
	v_mfma_i32_16x16x64_i8 v[86:89], v[174:177], v[190:193], v[86:89]
	v_mfma_i32_16x16x64_i8 v[78:81], v[166:169], v[198:201], v[78:81]
	v_mfma_i32_16x16x64_i8 v[74:77], v[174:177], v[198:201], v[74:77]
	v_mfma_i32_16x16x64_i8 v[70:73], v[166:169], v[206:209], v[70:73]
	v_mfma_i32_16x16x64_i8 v[66:69], v[174:177], v[206:209], v[66:69]
	s_setprio 0
	s_barrier
	s_add_i32 s81, s64, s50
	v_lshl_add_u64 v[210:211], s[82:83], 0, v[132:133]
	s_mov_b32 m0, s81
	ds_read_b128 v[178:181], v231 offset:16384
	ds_read_b128 v[182:185], v231 offset:17408
	ds_read_b128 v[186:189], v231 offset:18432
	ds_read_b128 v[190:193], v231 offset:19456
	ds_read_b128 v[194:197], v231 offset:20480
	ds_read_b128 v[198:201], v231 offset:21504
	ds_read_b128 v[202:205], v231 offset:22528
	ds_read_b128 v[206:209], v231 offset:23552
	global_load_lds_dwordx4 v[210:211], off
	s_add_i32 m0, s81, 0x2000
	v_lshl_add_u64 v[212:213], s[82:83], 0, v[136:137]
	s_add_u32 s82, s82, s8
	s_addc_u32 s83, s83, s9
	s_add_i32 s81, s65, s50
	global_load_lds_dwordx4 v[212:213], off
	v_lshl_add_u64 v[214:215], s[82:83], 0, v[132:133]
	s_mov_b32 m0, s81
	v_lshl_add_u64 v[216:217], s[82:83], 0, v[136:137]
	global_load_lds_dwordx4 v[214:215], off
	s_add_i32 m0, s81, 0x2000
	v_lshl_add_u64 v[218:219], s[42:43], 0, v[130:131]
	global_load_lds_dwordx4 v[216:217], off
	s_mov_b32 m0, s51
	v_lshl_add_u64 v[220:221], s[42:43], 0, v[134:135]
	global_load_lds_dwordx4 v[218:219], off
	s_mov_b32 m0, s52
	s_nop 0
	global_load_lds_dwordx4 v[220:221], off
	s_waitcnt vmcnt(8)
	s_waitcnt lgkmcnt(0)
	s_setprio 1
	s_waitcnt lgkmcnt(0)
	v_mfma_i32_16x16x64_i8 v[62:65], v[146:149], v[178:181], v[62:65]
	v_mfma_i32_16x16x64_i8 v[58:61], v[154:157], v[178:181], v[58:61]
	v_mfma_i32_16x16x64_i8 v[54:57], v[146:149], v[186:189], v[54:57]
	v_mfma_i32_16x16x64_i8 v[50:53], v[154:157], v[186:189], v[50:53]
	v_mfma_i32_16x16x64_i8 v[42:45], v[146:149], v[194:197], v[42:45]
	v_mfma_i32_16x16x64_i8 v[34:37], v[154:157], v[194:197], v[34:37]
	s_barrier
	v_mfma_i32_16x16x64_i8 v[26:29], v[146:149], v[202:205], v[26:29]
	v_mfma_i32_16x16x64_i8 v[18:21], v[154:157], v[202:205], v[18:21]
	v_mfma_i32_16x16x64_i8 v[62:65], v[150:153], v[182:185], v[62:65]
	v_mfma_i32_16x16x64_i8 v[58:61], v[158:161], v[182:185], v[58:61]
	v_mfma_i32_16x16x64_i8 v[54:57], v[150:153], v[190:193], v[54:57]
	v_mfma_i32_16x16x64_i8 v[50:53], v[158:161], v[190:193], v[50:53]
	v_mfma_i32_16x16x64_i8 v[42:45], v[150:153], v[198:201], v[42:45]
	v_mfma_i32_16x16x64_i8 v[34:37], v[158:161], v[198:201], v[34:37]
	v_mfma_i32_16x16x64_i8 v[26:29], v[150:153], v[206:209], v[26:29]
	v_mfma_i32_16x16x64_i8 v[18:21], v[158:161], v[206:209], v[18:21]
	s_setprio 0
	s_setprio 1
	v_mfma_i32_16x16x64_i8 v[46:49], v[162:165], v[178:181], v[46:49]
	v_mfma_i32_16x16x64_i8 v[38:41], v[170:173], v[178:181], v[38:41]
	v_mfma_i32_16x16x64_i8 v[30:33], v[162:165], v[186:189], v[30:33]
	v_mfma_i32_16x16x64_i8 v[22:25], v[170:173], v[186:189], v[22:25]
	v_mfma_i32_16x16x64_i8 v[14:17], v[162:165], v[194:197], v[14:17]
	v_mfma_i32_16x16x64_i8 v[10:13], v[170:173], v[194:197], v[10:13]
	v_mfma_i32_16x16x64_i8 v[6:9], v[162:165], v[202:205], v[6:9]
	v_mfma_i32_16x16x64_i8 v[2:5], v[170:173], v[202:205], v[2:5]
	v_mfma_i32_16x16x64_i8 v[46:49], v[166:169], v[182:185], v[46:49]
	v_mfma_i32_16x16x64_i8 v[38:41], v[174:177], v[182:185], v[38:41]
	v_mfma_i32_16x16x64_i8 v[30:33], v[166:169], v[190:193], v[30:33]
	v_mfma_i32_16x16x64_i8 v[22:25], v[174:177], v[190:193], v[22:25]
	v_mfma_i32_16x16x64_i8 v[14:17], v[166:169], v[198:201], v[14:17]
	v_mfma_i32_16x16x64_i8 v[10:13], v[174:177], v[198:201], v[10:13]
	v_mfma_i32_16x16x64_i8 v[6:9], v[166:169], v[206:209], v[6:9]
	v_mfma_i32_16x16x64_i8 v[2:5], v[174:177], v[206:209], v[2:5]
	s_setprio 0
	s_barrier
	s_add_i32 s81, 0, 0x18000
	s_add_i32 s82, 0, 0x1c000
	v_add_u32_e32 v158, s81, v229
	v_add_u32_e32 v174, s82, v229
	ds_read_b128 v[146:149], v158
	ds_read_b128 v[150:153], v158 offset:1024
	ds_read_b128 v[154:157], v158 offset:2048
	ds_read_b128 v[158:161], v158 offset:3072
	ds_read_b128 v[162:165], v174
	ds_read_b128 v[166:169], v174 offset:1024
	ds_read_b128 v[170:173], v174 offset:2048
	ds_read_b128 v[174:177], v174 offset:3072
	s_add_u32 s42, s42, s8
	s_addc_u32 s43, s43, s9
	s_mov_b32 m0, s53
	v_lshl_add_u64 v[222:223], s[42:43], 0, v[130:131]
	ds_read_b128 v[178:181], v231 offset:32768
	ds_read_b128 v[182:185], v231 offset:33792
	ds_read_b128 v[186:189], v231 offset:34816
	ds_read_b128 v[190:193], v231 offset:35840
	ds_read_b128 v[194:197], v231 offset:36864
	ds_read_b128 v[198:201], v231 offset:37888
	ds_read_b128 v[202:205], v231 offset:38912
	ds_read_b128 v[206:209], v231 offset:39936
	global_load_lds_dwordx4 v[222:223], off
	v_lshl_add_u64 v[222:223], s[42:43], 0, v[134:135]
	s_mov_b32 m0, s54
	s_nop 0
	global_load_lds_dwordx4 v[222:223], off
	s_waitcnt vmcnt(8)
	s_waitcnt lgkmcnt(0)
	s_setprio 1
	s_waitcnt lgkmcnt(0)
	v_mfma_i32_16x16x64_i8 v[126:129], v[146:149], v[178:181], v[126:129]
	v_mfma_i32_16x16x64_i8 v[122:125], v[154:157], v[178:181], v[122:125]
	v_mfma_i32_16x16x64_i8 v[118:121], v[146:149], v[186:189], v[118:121]
	v_mfma_i32_16x16x64_i8 v[114:117], v[154:157], v[186:189], v[114:117]
	v_mfma_i32_16x16x64_i8 v[106:109], v[146:149], v[194:197], v[106:109]
	v_mfma_i32_16x16x64_i8 v[98:101], v[154:157], v[194:197], v[98:101]
	s_barrier
	v_mfma_i32_16x16x64_i8 v[90:93], v[146:149], v[202:205], v[90:93]
	v_mfma_i32_16x16x64_i8 v[82:85], v[154:157], v[202:205], v[82:85]
	v_mfma_i32_16x16x64_i8 v[126:129], v[150:153], v[182:185], v[126:129]
	v_mfma_i32_16x16x64_i8 v[122:125], v[158:161], v[182:185], v[122:125]
	v_mfma_i32_16x16x64_i8 v[118:121], v[150:153], v[190:193], v[118:121]
	v_mfma_i32_16x16x64_i8 v[114:117], v[158:161], v[190:193], v[114:117]
	v_mfma_i32_16x16x64_i8 v[106:109], v[150:153], v[198:201], v[106:109]
	v_mfma_i32_16x16x64_i8 v[98:101], v[158:161], v[198:201], v[98:101]
	v_mfma_i32_16x16x64_i8 v[90:93], v[150:153], v[206:209], v[90:93]
	v_mfma_i32_16x16x64_i8 v[82:85], v[158:161], v[206:209], v[82:85]
	s_setprio 0
	s_setprio 1
	v_mfma_i32_16x16x64_i8 v[110:113], v[162:165], v[178:181], v[110:113]
	v_mfma_i32_16x16x64_i8 v[102:105], v[170:173], v[178:181], v[102:105]
	v_mfma_i32_16x16x64_i8 v[94:97], v[162:165], v[186:189], v[94:97]
	v_mfma_i32_16x16x64_i8 v[86:89], v[170:173], v[186:189], v[86:89]
	v_mfma_i32_16x16x64_i8 v[78:81], v[162:165], v[194:197], v[78:81]
	v_mfma_i32_16x16x64_i8 v[74:77], v[170:173], v[194:197], v[74:77]
	v_mfma_i32_16x16x64_i8 v[70:73], v[162:165], v[202:205], v[70:73]
	v_mfma_i32_16x16x64_i8 v[66:69], v[170:173], v[202:205], v[66:69]
	v_mfma_i32_16x16x64_i8 v[110:113], v[166:169], v[182:185], v[110:113]
	v_mfma_i32_16x16x64_i8 v[102:105], v[174:177], v[182:185], v[102:105]
	v_mfma_i32_16x16x64_i8 v[94:97], v[166:169], v[190:193], v[94:97]
	v_mfma_i32_16x16x64_i8 v[86:89], v[174:177], v[190:193], v[86:89]
	v_mfma_i32_16x16x64_i8 v[78:81], v[166:169], v[198:201], v[78:81]
	v_mfma_i32_16x16x64_i8 v[74:77], v[174:177], v[198:201], v[74:77]
	v_mfma_i32_16x16x64_i8 v[70:73], v[166:169], v[206:209], v[70:73]
	v_mfma_i32_16x16x64_i8 v[66:69], v[174:177], v[206:209], v[66:69]
	s_setprio 0
	s_barrier
	s_add_i32 s42, s81, s50
	v_lshl_add_u64 v[210:211], v[210:211], 0, s[30:31]
	s_mov_b32 m0, s42
	ds_read_b128 v[178:181], v231 offset:49152
	ds_read_b128 v[182:185], v231 offset:50176
	ds_read_b128 v[186:189], v231 offset:51200
	ds_read_b128 v[190:193], v231 offset:52224
	ds_read_b128 v[194:197], v231 offset:53248
	ds_read_b128 v[198:201], v231 offset:54272
	ds_read_b128 v[202:205], v231 offset:55296
	ds_read_b128 v[206:209], v231 offset:56320
	global_load_lds_dwordx4 v[210:211], off
	v_lshl_add_u64 v[210:211], v[212:213], 0, s[30:31]
	s_add_i32 m0, s42, 0x2000
	s_add_i32 s42, s82, s50
	global_load_lds_dwordx4 v[210:211], off
	v_lshl_add_u64 v[210:211], v[214:215], 0, s[30:31]
	s_mov_b32 m0, s42
	s_nop 0
	global_load_lds_dwordx4 v[210:211], off
	v_lshl_add_u64 v[210:211], v[216:217], 0, s[30:31]
	s_add_i32 m0, s42, 0x2000
	s_nop 0
	global_load_lds_dwordx4 v[210:211], off
	v_lshl_add_u64 v[210:211], v[218:219], 0, s[30:31]
	s_mov_b32 m0, s57
	s_nop 0
	global_load_lds_dwordx4 v[210:211], off
	v_lshl_add_u64 v[210:211], v[220:221], 0, s[30:31]
	s_mov_b32 m0, s58
	s_nop 0
	global_load_lds_dwordx4 v[210:211], off
	s_waitcnt vmcnt(8)
	s_waitcnt lgkmcnt(0)
	s_setprio 1
	s_waitcnt lgkmcnt(0)
	v_mfma_i32_16x16x64_i8 v[62:65], v[146:149], v[178:181], v[62:65]
	v_mfma_i32_16x16x64_i8 v[58:61], v[154:157], v[178:181], v[58:61]
	v_mfma_i32_16x16x64_i8 v[54:57], v[146:149], v[186:189], v[54:57]
	v_mfma_i32_16x16x64_i8 v[50:53], v[154:157], v[186:189], v[50:53]
	v_mfma_i32_16x16x64_i8 v[42:45], v[146:149], v[194:197], v[42:45]
	v_mfma_i32_16x16x64_i8 v[34:37], v[154:157], v[194:197], v[34:37]
	s_barrier
	v_mfma_i32_16x16x64_i8 v[26:29], v[146:149], v[202:205], v[26:29]
	v_mfma_i32_16x16x64_i8 v[18:21], v[154:157], v[202:205], v[18:21]
	v_mfma_i32_16x16x64_i8 v[62:65], v[150:153], v[182:185], v[62:65]
	v_mfma_i32_16x16x64_i8 v[58:61], v[158:161], v[182:185], v[58:61]
	v_mfma_i32_16x16x64_i8 v[54:57], v[150:153], v[190:193], v[54:57]
	v_mfma_i32_16x16x64_i8 v[50:53], v[158:161], v[190:193], v[50:53]
	v_mfma_i32_16x16x64_i8 v[42:45], v[150:153], v[198:201], v[42:45]
	v_mfma_i32_16x16x64_i8 v[34:37], v[158:161], v[198:201], v[34:37]
	v_mfma_i32_16x16x64_i8 v[26:29], v[150:153], v[206:209], v[26:29]
	v_mfma_i32_16x16x64_i8 v[18:21], v[158:161], v[206:209], v[18:21]
	s_setprio 0
	s_setprio 1
	v_mfma_i32_16x16x64_i8 v[46:49], v[162:165], v[178:181], v[46:49]
	v_mfma_i32_16x16x64_i8 v[38:41], v[170:173], v[178:181], v[38:41]
	v_mfma_i32_16x16x64_i8 v[30:33], v[162:165], v[186:189], v[30:33]
	v_mfma_i32_16x16x64_i8 v[22:25], v[170:173], v[186:189], v[22:25]
	v_mfma_i32_16x16x64_i8 v[14:17], v[162:165], v[194:197], v[14:17]
	v_mfma_i32_16x16x64_i8 v[10:13], v[170:173], v[194:197], v[10:13]
	v_mfma_i32_16x16x64_i8 v[6:9], v[162:165], v[202:205], v[6:9]
	v_mfma_i32_16x16x64_i8 v[2:5], v[170:173], v[202:205], v[2:5]
	v_mfma_i32_16x16x64_i8 v[46:49], v[166:169], v[182:185], v[46:49]
	v_mfma_i32_16x16x64_i8 v[38:41], v[174:177], v[182:185], v[38:41]
	v_mfma_i32_16x16x64_i8 v[30:33], v[166:169], v[190:193], v[30:33]
	v_mfma_i32_16x16x64_i8 v[22:25], v[174:177], v[190:193], v[22:25]
	v_mfma_i32_16x16x64_i8 v[14:17], v[166:169], v[198:201], v[14:17]
	v_mfma_i32_16x16x64_i8 v[10:13], v[174:177], v[198:201], v[10:13]
	v_mfma_i32_16x16x64_i8 v[6:9], v[166:169], v[206:209], v[6:9]
	v_mfma_i32_16x16x64_i8 v[2:5], v[174:177], v[206:209], v[2:5]
	s_setprio 0
	s_barrier
	s_add_u32 s40, s40, 0x100
	s_addc_u32 s41, s41, 0
	s_add_u32 s70, s70, 0x100
	s_addc_u32 s71, s71, 0
	s_cmp_ge_i32 s80, s60
	s_mov_b32 s42, s80
	s_cbranch_scc0 .LBB0_3613
	v_cvt_f32_i32_e32 v214, v126
	v_cvt_f32_i32_e32 v215, v127
	v_cvt_f32_i32_e32 v212, v128
	v_cvt_f32_i32_e32 v213, v129
	v_cvt_f32_i32_e32 v218, v122
	v_cvt_f32_i32_e32 v219, v123
	v_cvt_f32_i32_e32 v216, v124
	v_cvt_f32_i32_e32 v217, v125
	v_cvt_f32_i32_e32 v222, v110
	v_cvt_f32_i32_e32 v223, v111
	v_cvt_f32_i32_e32 v220, v112
	v_cvt_f32_i32_e32 v221, v113
	v_cvt_f32_i32_e32 v226, v102
	v_cvt_f32_i32_e32 v227, v103
	v_cvt_f32_i32_e32 v224, v104
	v_cvt_f32_i32_e32 v225, v105
	v_cvt_f32_i32_e32 v194, v118
	v_cvt_f32_i32_e32 v195, v119
	v_cvt_f32_i32_e32 v192, v120
	v_cvt_f32_i32_e32 v193, v121
	v_cvt_f32_i32_e32 v200, v114
	v_cvt_f32_i32_e32 v201, v115
	v_cvt_f32_i32_e32 v198, v116
	v_cvt_f32_i32_e32 v199, v117
	v_cvt_f32_i32_e32 v206, v94
	v_cvt_f32_i32_e32 v207, v95
	v_cvt_f32_i32_e32 v202, v96
	v_cvt_f32_i32_e32 v203, v97
	v_cvt_f32_i32_e32 v208, v86
	v_cvt_f32_i32_e32 v209, v87
	v_cvt_f32_i32_e32 v204, v88
	v_cvt_f32_i32_e32 v205, v89
	v_cvt_f32_i32_e32 v178, v106
	v_cvt_f32_i32_e32 v179, v107
	v_cvt_f32_i32_e32 v176, v108
	v_cvt_f32_i32_e32 v177, v109
	v_cvt_f32_i32_e32 v182, v98
	v_cvt_f32_i32_e32 v183, v99
	v_cvt_f32_i32_e32 v180, v100
	v_cvt_f32_i32_e32 v181, v101
	v_cvt_f32_i32_e32 v188, v78
	v_cvt_f32_i32_e32 v189, v79
	v_cvt_f32_i32_e32 v184, v80
	v_cvt_f32_i32_e32 v185, v81
	v_cvt_f32_i32_e32 v190, v74
	v_cvt_f32_i32_e32 v191, v75
	v_cvt_f32_i32_e32 v186, v76
	v_cvt_f32_i32_e32 v187, v77
	v_cvt_f32_i32_e32 v162, v90
	v_cvt_f32_i32_e32 v163, v91
	v_cvt_f32_i32_e32 v160, v92
	v_cvt_f32_i32_e32 v161, v93
	v_cvt_f32_i32_e32 v166, v82
	v_cvt_f32_i32_e32 v167, v83
	v_cvt_f32_i32_e32 v164, v84
	v_cvt_f32_i32_e32 v165, v85
	v_cvt_f32_i32_e32 v172, v70
	v_cvt_f32_i32_e32 v173, v71
	v_cvt_f32_i32_e32 v168, v72
	v_cvt_f32_i32_e32 v169, v73
	v_cvt_f32_i32_e32 v174, v66
	v_cvt_f32_i32_e32 v175, v67
	v_cvt_f32_i32_e32 v170, v68
	v_cvt_f32_i32_e32 v171, v69
	v_cvt_f32_i32_e32 v146, v62
	v_cvt_f32_i32_e32 v147, v63
	v_cvt_f32_i32_e32 v128, v64
	v_cvt_f32_i32_e32 v129, v65
	v_cvt_f32_i32_e32 v150, v58
	v_cvt_f32_i32_e32 v151, v59
	v_cvt_f32_i32_e32 v148, v60
	v_cvt_f32_i32_e32 v149, v61
	v_cvt_f32_i32_e32 v156, v46
	v_cvt_f32_i32_e32 v157, v47
	v_cvt_f32_i32_e32 v152, v48
	v_cvt_f32_i32_e32 v153, v49
	v_cvt_f32_i32_e32 v158, v38
	v_cvt_f32_i32_e32 v159, v39
	v_cvt_f32_i32_e32 v154, v40
	v_cvt_f32_i32_e32 v155, v41
	v_cvt_f32_i32_e32 v114, v54
	v_cvt_f32_i32_e32 v115, v55
	v_cvt_f32_i32_e32 v112, v56
	v_cvt_f32_i32_e32 v113, v57
	v_cvt_f32_i32_e32 v118, v50
	v_cvt_f32_i32_e32 v119, v51
	v_cvt_f32_i32_e32 v116, v52
	v_cvt_f32_i32_e32 v117, v53
	v_cvt_f32_i32_e32 v124, v30
	v_cvt_f32_i32_e32 v125, v31
	v_cvt_f32_i32_e32 v120, v32
	v_cvt_f32_i32_e32 v121, v33
	v_cvt_f32_i32_e32 v126, v22
	v_cvt_f32_i32_e32 v127, v23
	v_cvt_f32_i32_e32 v122, v24
	v_cvt_f32_i32_e32 v123, v25
	v_cvt_f32_i32_e32 v64, v42
	v_cvt_f32_i32_e32 v65, v43
	v_cvt_f32_i32_e32 v62, v44
	v_cvt_f32_i32_e32 v63, v45
	v_cvt_f32_i32_e32 v68, v34
	v_cvt_f32_i32_e32 v69, v35
	v_cvt_f32_i32_e32 v66, v36
	v_cvt_f32_i32_e32 v67, v37
	v_cvt_f32_i32_e32 v74, v14
	v_cvt_f32_i32_e32 v75, v15
	v_cvt_f32_i32_e32 v70, v16
	v_cvt_f32_i32_e32 v71, v17
	v_cvt_f32_i32_e32 v76, v10
	v_cvt_f32_i32_e32 v77, v11
	v_cvt_f32_i32_e32 v72, v12
	v_cvt_f32_i32_e32 v73, v13
	v_cvt_f32_i32_e32 v48, v26
	v_cvt_f32_i32_e32 v49, v27
	v_cvt_f32_i32_e32 v46, v28
	v_cvt_f32_i32_e32 v47, v29
	v_cvt_f32_i32_e32 v52, v18
	v_cvt_f32_i32_e32 v53, v19
	v_cvt_f32_i32_e32 v50, v20
	v_cvt_f32_i32_e32 v51, v21
	v_cvt_f32_i32_e32 v58, v6
	v_cvt_f32_i32_e32 v59, v7
	v_cvt_f32_i32_e32 v54, v8
	v_cvt_f32_i32_e32 v55, v9
	v_cvt_f32_i32_e32 v60, v2
	v_cvt_f32_i32_e32 v61, v3
	v_cvt_f32_i32_e32 v56, v4
	v_cvt_f32_i32_e32 v57, v5

.LBB0_3798:
	v_add_u32_e32 v138, s56, v188
	ds_read_b128 v[148:151], v138
	ds_read_b128 v[152:155], v138 offset:1024
	ds_read_b128 v[156:159], v138 offset:2048
	ds_read_b128 v[160:163], v138 offset:3072
	v_add_u32_e32 v138, s57, v188
	ds_read_b128 v[164:167], v138
	ds_read_b128 v[168:171], v138 offset:1024
	ds_read_b128 v[172:175], v138 offset:2048
	ds_read_b128 v[176:179], v138 offset:3072
	s_add_i32 s60, s28, 2
	s_add_u32 s61, s26, 0x80
	s_addc_u32 s29, s27, 0
	s_cmp_eq_u32 s54, s28
	s_cselect_b32 s28, s2, s61
	s_cselect_b32 s29, s3, s29
	s_cselect_b32 s63, s25, s35
	s_cselect_b32 s62, s24, s34
	v_lshl_add_u64 v[184:185], s[26:27], 0, v[140:141]
	s_add_i32 m0, s42, 0xc000
	ds_read_b128 v[180:183], v189
	ds_read_b128 v[190:193], v189 offset:1024
	ds_read_b128 v[194:197], v189 offset:2048
	ds_read_b128 v[198:201], v189 offset:3072
	ds_read_b128 v[202:205], v189 offset:4096
	ds_read_b128 v[206:209], v189 offset:5120
	ds_read_b128 v[210:213], v189 offset:6144
	ds_read_b128 v[214:217], v189 offset:7168
	global_load_lds_dwordx4 v[184:185], off
	v_lshl_add_u64 v[184:185], s[26:27], 0, v[142:143]
	s_add_i32 m0, s42, 0xe000
	s_nop 0
	global_load_lds_dwordx4 v[184:185], off
	s_waitcnt vmcnt(8)
	s_waitcnt lgkmcnt(0)
	s_setprio 1
	s_waitcnt lgkmcnt(0)
	v_mfma_i32_16x16x64_i8 v[126:129], v[148:151], v[180:183], v[126:129]
	v_mfma_i32_16x16x64_i8 v[122:125], v[156:159], v[180:183], v[122:125]
	v_mfma_i32_16x16x64_i8 v[118:121], v[148:151], v[194:197], v[118:121]
	v_mfma_i32_16x16x64_i8 v[114:117], v[156:159], v[194:197], v[114:117]
	v_mfma_i32_16x16x64_i8 v[106:109], v[148:151], v[202:205], v[106:109]
	v_mfma_i32_16x16x64_i8 v[98:101], v[156:159], v[202:205], v[98:101]
	s_barrier
	v_mfma_i32_16x16x64_i8 v[90:93], v[148:151], v[210:213], v[90:93]
	v_mfma_i32_16x16x64_i8 v[82:85], v[156:159], v[210:213], v[82:85]
	v_mfma_i32_16x16x64_i8 v[126:129], v[152:155], v[190:193], v[126:129]
	v_mfma_i32_16x16x64_i8 v[122:125], v[160:163], v[190:193], v[122:125]
	v_mfma_i32_16x16x64_i8 v[118:121], v[152:155], v[198:201], v[118:121]
	v_mfma_i32_16x16x64_i8 v[114:117], v[160:163], v[198:201], v[114:117]
	v_mfma_i32_16x16x64_i8 v[106:109], v[152:155], v[206:209], v[106:109]
	v_mfma_i32_16x16x64_i8 v[98:101], v[160:163], v[206:209], v[98:101]
	v_mfma_i32_16x16x64_i8 v[90:93], v[152:155], v[214:217], v[90:93]
	v_mfma_i32_16x16x64_i8 v[82:85], v[160:163], v[214:217], v[82:85]
	s_setprio 0
	s_setprio 1
	v_mfma_i32_16x16x64_i8 v[110:113], v[164:167], v[180:183], v[110:113]
	v_mfma_i32_16x16x64_i8 v[102:105], v[172:175], v[180:183], v[102:105]
	v_mfma_i32_16x16x64_i8 v[94:97], v[164:167], v[194:197], v[94:97]
	v_mfma_i32_16x16x64_i8 v[86:89], v[172:175], v[194:197], v[86:89]
	v_mfma_i32_16x16x64_i8 v[78:81], v[164:167], v[202:205], v[78:81]
	v_mfma_i32_16x16x64_i8 v[74:77], v[172:175], v[202:205], v[74:77]
	v_mfma_i32_16x16x64_i8 v[70:73], v[164:167], v[210:213], v[70:73]
	v_mfma_i32_16x16x64_i8 v[66:69], v[172:175], v[210:213], v[66:69]
	v_mfma_i32_16x16x64_i8 v[110:113], v[168:171], v[190:193], v[110:113]
	v_mfma_i32_16x16x64_i8 v[102:105], v[176:179], v[190:193], v[102:105]
	v_mfma_i32_16x16x64_i8 v[94:97], v[168:171], v[198:201], v[94:97]
	v_mfma_i32_16x16x64_i8 v[86:89], v[176:179], v[198:201], v[86:89]
	v_mfma_i32_16x16x64_i8 v[78:81], v[168:171], v[206:209], v[78:81]
	v_mfma_i32_16x16x64_i8 v[74:77], v[176:179], v[206:209], v[74:77]
	v_mfma_i32_16x16x64_i8 v[70:73], v[168:171], v[214:217], v[70:73]
	v_mfma_i32_16x16x64_i8 v[66:69], v[176:179], v[214:217], v[66:69]
	s_setprio 0
	s_barrier
	s_add_i32 s61, s56, s41
	v_lshl_add_u64 v[184:185], s[62:63], 0, v[132:133]
	s_mov_b32 m0, s61
	ds_read_b128 v[180:183], v189 offset:16384
	ds_read_b128 v[190:193], v189 offset:17408
	ds_read_b128 v[194:197], v189 offset:18432
	ds_read_b128 v[198:201], v189 offset:19456
	ds_read_b128 v[202:205], v189 offset:20480
	ds_read_b128 v[206:209], v189 offset:21504
	ds_read_b128 v[210:213], v189 offset:22528
	ds_read_b128 v[214:217], v189 offset:23552
	global_load_lds_dwordx4 v[184:185], off
	s_add_i32 m0, s61, 0x2000
	v_lshl_add_u64 v[218:219], s[62:63], 0, v[136:137]
	s_add_u32 s62, s62, s6
	s_addc_u32 s63, s63, s7
	s_add_i32 s61, s57, s41
	global_load_lds_dwordx4 v[218:219], off
	v_lshl_add_u64 v[220:221], s[62:63], 0, v[132:133]
	s_mov_b32 m0, s61
	v_lshl_add_u64 v[222:223], s[62:63], 0, v[136:137]
	global_load_lds_dwordx4 v[220:221], off
	s_add_i32 m0, s61, 0x2000
	v_lshl_add_u64 v[224:225], s[28:29], 0, v[130:131]
	global_load_lds_dwordx4 v[222:223], off
	s_mov_b32 m0, s42
	v_lshl_add_u64 v[226:227], s[28:29], 0, v[134:135]
	global_load_lds_dwordx4 v[224:225], off
	s_mov_b32 m0, s43
	s_nop 0
	global_load_lds_dwordx4 v[226:227], off
	s_waitcnt vmcnt(8)
	s_waitcnt lgkmcnt(0)
	s_setprio 1
	s_waitcnt lgkmcnt(0)
	v_mfma_i32_16x16x64_i8 v[62:65], v[148:151], v[180:183], v[62:65]
	v_mfma_i32_16x16x64_i8 v[58:61], v[156:159], v[180:183], v[58:61]
	v_mfma_i32_16x16x64_i8 v[54:57], v[148:151], v[194:197], v[54:57]
	v_mfma_i32_16x16x64_i8 v[50:53], v[156:159], v[194:197], v[50:53]
	v_mfma_i32_16x16x64_i8 v[42:45], v[148:151], v[202:205], v[42:45]
	v_mfma_i32_16x16x64_i8 v[34:37], v[156:159], v[202:205], v[34:37]
	s_barrier
	v_mfma_i32_16x16x64_i8 v[26:29], v[148:151], v[210:213], v[26:29]
	v_mfma_i32_16x16x64_i8 v[18:21], v[156:159], v[210:213], v[18:21]
	v_mfma_i32_16x16x64_i8 v[62:65], v[152:155], v[190:193], v[62:65]
	v_mfma_i32_16x16x64_i8 v[58:61], v[160:163], v[190:193], v[58:61]
	v_mfma_i32_16x16x64_i8 v[54:57], v[152:155], v[198:201], v[54:57]
	v_mfma_i32_16x16x64_i8 v[50:53], v[160:163], v[198:201], v[50:53]
	v_mfma_i32_16x16x64_i8 v[42:45], v[152:155], v[206:209], v[42:45]
	v_mfma_i32_16x16x64_i8 v[34:37], v[160:163], v[206:209], v[34:37]
	v_mfma_i32_16x16x64_i8 v[26:29], v[152:155], v[214:217], v[26:29]
	v_mfma_i32_16x16x64_i8 v[18:21], v[160:163], v[214:217], v[18:21]
	s_setprio 0
	s_setprio 1
	v_mfma_i32_16x16x64_i8 v[46:49], v[164:167], v[180:183], v[46:49]
	v_mfma_i32_16x16x64_i8 v[38:41], v[172:175], v[180:183], v[38:41]
	v_mfma_i32_16x16x64_i8 v[30:33], v[164:167], v[194:197], v[30:33]
	v_mfma_i32_16x16x64_i8 v[22:25], v[172:175], v[194:197], v[22:25]
	v_mfma_i32_16x16x64_i8 v[14:17], v[164:167], v[202:205], v[14:17]
	v_mfma_i32_16x16x64_i8 v[10:13], v[172:175], v[202:205], v[10:13]
	v_mfma_i32_16x16x64_i8 v[6:9], v[164:167], v[210:213], v[6:9]
	v_mfma_i32_16x16x64_i8 v[2:5], v[172:175], v[210:213], v[2:5]
	v_mfma_i32_16x16x64_i8 v[46:49], v[168:171], v[190:193], v[46:49]
	v_mfma_i32_16x16x64_i8 v[38:41], v[176:179], v[190:193], v[38:41]
	v_mfma_i32_16x16x64_i8 v[30:33], v[168:171], v[198:201], v[30:33]
	v_mfma_i32_16x16x64_i8 v[22:25], v[176:179], v[198:201], v[22:25]
	v_mfma_i32_16x16x64_i8 v[14:17], v[168:171], v[206:209], v[14:17]
	v_mfma_i32_16x16x64_i8 v[10:13], v[176:179], v[206:209], v[10:13]
	v_mfma_i32_16x16x64_i8 v[6:9], v[168:171], v[214:217], v[6:9]
	v_mfma_i32_16x16x64_i8 v[2:5], v[176:179], v[214:217], v[2:5]
	s_setprio 0
	s_barrier
	s_add_i32 s61, 0, 0x18000
	v_add_u32_e32 v138, s61, v188
	s_add_i32 s62, 0, 0x1c000
	ds_read_b128 v[148:151], v138
	ds_read_b128 v[152:155], v138 offset:1024
	ds_read_b128 v[156:159], v138 offset:2048
	ds_read_b128 v[160:163], v138 offset:3072
	v_add_u32_e32 v138, s62, v188
	ds_read_b128 v[164:167], v138
	ds_read_b128 v[168:171], v138 offset:1024
	ds_read_b128 v[172:175], v138 offset:2048
	ds_read_b128 v[176:179], v138 offset:3072
	s_add_u32 s28, s28, s6
	s_addc_u32 s29, s29, s7
	s_mov_b32 m0, s44
	v_lshl_add_u64 v[228:229], s[28:29], 0, v[130:131]
	ds_read_b128 v[180:183], v189 offset:32768
	ds_read_b128 v[190:193], v189 offset:33792
	ds_read_b128 v[194:197], v189 offset:34816
	ds_read_b128 v[198:201], v189 offset:35840
	ds_read_b128 v[202:205], v189 offset:36864
	ds_read_b128 v[206:209], v189 offset:37888
	ds_read_b128 v[210:213], v189 offset:38912
	ds_read_b128 v[214:217], v189 offset:39936
	global_load_lds_dwordx4 v[228:229], off
	v_lshl_add_u64 v[228:229], s[28:29], 0, v[134:135]
	s_mov_b32 m0, s45
	s_nop 0
	global_load_lds_dwordx4 v[228:229], off
	s_waitcnt vmcnt(8)
	s_waitcnt lgkmcnt(0)
	s_setprio 1
	s_waitcnt lgkmcnt(0)
	v_mfma_i32_16x16x64_i8 v[126:129], v[148:151], v[180:183], v[126:129]
	v_mfma_i32_16x16x64_i8 v[122:125], v[156:159], v[180:183], v[122:125]
	v_mfma_i32_16x16x64_i8 v[118:121], v[148:151], v[194:197], v[118:121]
	v_mfma_i32_16x16x64_i8 v[114:117], v[156:159], v[194:197], v[114:117]
	v_mfma_i32_16x16x64_i8 v[106:109], v[148:151], v[202:205], v[106:109]
	v_mfma_i32_16x16x64_i8 v[98:101], v[156:159], v[202:205], v[98:101]
	s_barrier
	v_mfma_i32_16x16x64_i8 v[90:93], v[148:151], v[210:213], v[90:93]
	v_mfma_i32_16x16x64_i8 v[82:85], v[156:159], v[210:213], v[82:85]
	v_mfma_i32_16x16x64_i8 v[126:129], v[152:155], v[190:193], v[126:129]
	v_mfma_i32_16x16x64_i8 v[122:125], v[160:163], v[190:193], v[122:125]
	v_mfma_i32_16x16x64_i8 v[118:121], v[152:155], v[198:201], v[118:121]
	v_mfma_i32_16x16x64_i8 v[114:117], v[160:163], v[198:201], v[114:117]
	v_mfma_i32_16x16x64_i8 v[106:109], v[152:155], v[206:209], v[106:109]
	v_mfma_i32_16x16x64_i8 v[98:101], v[160:163], v[206:209], v[98:101]
	v_mfma_i32_16x16x64_i8 v[90:93], v[152:155], v[214:217], v[90:93]
	v_mfma_i32_16x16x64_i8 v[82:85], v[160:163], v[214:217], v[82:85]
	s_setprio 0
	s_setprio 1
	v_mfma_i32_16x16x64_i8 v[110:113], v[164:167], v[180:183], v[110:113]
	v_mfma_i32_16x16x64_i8 v[102:105], v[172:175], v[180:183], v[102:105]
	v_mfma_i32_16x16x64_i8 v[94:97], v[164:167], v[194:197], v[94:97]
	v_mfma_i32_16x16x64_i8 v[86:89], v[172:175], v[194:197], v[86:89]
	v_mfma_i32_16x16x64_i8 v[78:81], v[164:167], v[202:205], v[78:81]
	v_mfma_i32_16x16x64_i8 v[74:77], v[172:175], v[202:205], v[74:77]
	v_mfma_i32_16x16x64_i8 v[70:73], v[164:167], v[210:213], v[70:73]
	v_mfma_i32_16x16x64_i8 v[66:69], v[172:175], v[210:213], v[66:69]
	v_mfma_i32_16x16x64_i8 v[110:113], v[168:171], v[190:193], v[110:113]
	v_mfma_i32_16x16x64_i8 v[102:105], v[176:179], v[190:193], v[102:105]
	v_mfma_i32_16x16x64_i8 v[94:97], v[168:171], v[198:201], v[94:97]
	v_mfma_i32_16x16x64_i8 v[86:89], v[176:179], v[198:201], v[86:89]
	v_mfma_i32_16x16x64_i8 v[78:81], v[168:171], v[206:209], v[78:81]
	v_mfma_i32_16x16x64_i8 v[74:77], v[176:179], v[206:209], v[74:77]
	v_mfma_i32_16x16x64_i8 v[70:73], v[168:171], v[214:217], v[70:73]
	v_mfma_i32_16x16x64_i8 v[66:69], v[176:179], v[214:217], v[66:69]
	s_setprio 0
	s_barrier
	s_add_i32 s28, s61, s41
	v_lshl_add_u64 v[184:185], v[184:185], 0, s[18:19]
	s_mov_b32 m0, s28
	ds_read_b128 v[180:183], v189 offset:49152
	ds_read_b128 v[190:193], v189 offset:50176
	ds_read_b128 v[194:197], v189 offset:51200
	ds_read_b128 v[198:201], v189 offset:52224
	ds_read_b128 v[202:205], v189 offset:53248
	ds_read_b128 v[206:209], v189 offset:54272
	ds_read_b128 v[210:213], v189 offset:55296
	ds_read_b128 v[214:217], v189 offset:56320
	global_load_lds_dwordx4 v[184:185], off
	v_lshl_add_u64 v[184:185], v[218:219], 0, s[18:19]
	s_add_i32 m0, s28, 0x2000
	s_add_i32 s28, s62, s41
	global_load_lds_dwordx4 v[184:185], off
	v_lshl_add_u64 v[184:185], v[220:221], 0, s[18:19]
	s_mov_b32 m0, s28
	s_nop 0
	global_load_lds_dwordx4 v[184:185], off
	v_lshl_add_u64 v[184:185], v[222:223], 0, s[18:19]
	s_add_i32 m0, s28, 0x2000
	s_nop 0
	global_load_lds_dwordx4 v[184:185], off
	v_lshl_add_u64 v[184:185], v[224:225], 0, s[18:19]
	s_mov_b32 m0, s49
	s_nop 0
	global_load_lds_dwordx4 v[184:185], off
	v_lshl_add_u64 v[184:185], v[226:227], 0, s[18:19]
	s_mov_b32 m0, s50
	s_nop 0
	global_load_lds_dwordx4 v[184:185], off
	s_waitcnt vmcnt(8)
	s_waitcnt lgkmcnt(0)
	s_setprio 1
	s_waitcnt lgkmcnt(0)
	v_mfma_i32_16x16x64_i8 v[62:65], v[148:151], v[180:183], v[62:65]
	v_mfma_i32_16x16x64_i8 v[58:61], v[156:159], v[180:183], v[58:61]
	v_mfma_i32_16x16x64_i8 v[54:57], v[148:151], v[194:197], v[54:57]
	v_mfma_i32_16x16x64_i8 v[50:53], v[156:159], v[194:197], v[50:53]
	v_mfma_i32_16x16x64_i8 v[42:45], v[148:151], v[202:205], v[42:45]
	v_mfma_i32_16x16x64_i8 v[34:37], v[156:159], v[202:205], v[34:37]
	s_barrier
	v_mfma_i32_16x16x64_i8 v[26:29], v[148:151], v[210:213], v[26:29]
	v_mfma_i32_16x16x64_i8 v[18:21], v[156:159], v[210:213], v[18:21]
	v_mfma_i32_16x16x64_i8 v[62:65], v[152:155], v[190:193], v[62:65]
	v_mfma_i32_16x16x64_i8 v[58:61], v[160:163], v[190:193], v[58:61]
	v_mfma_i32_16x16x64_i8 v[54:57], v[152:155], v[198:201], v[54:57]
	v_mfma_i32_16x16x64_i8 v[50:53], v[160:163], v[198:201], v[50:53]
	v_mfma_i32_16x16x64_i8 v[42:45], v[152:155], v[206:209], v[42:45]
	v_mfma_i32_16x16x64_i8 v[34:37], v[160:163], v[206:209], v[34:37]
	v_mfma_i32_16x16x64_i8 v[26:29], v[152:155], v[214:217], v[26:29]
	v_mfma_i32_16x16x64_i8 v[18:21], v[160:163], v[214:217], v[18:21]
	s_setprio 0
	s_setprio 1
	v_mfma_i32_16x16x64_i8 v[46:49], v[164:167], v[180:183], v[46:49]
	v_mfma_i32_16x16x64_i8 v[38:41], v[172:175], v[180:183], v[38:41]
	v_mfma_i32_16x16x64_i8 v[30:33], v[164:167], v[194:197], v[30:33]
	v_mfma_i32_16x16x64_i8 v[22:25], v[172:175], v[194:197], v[22:25]
	v_mfma_i32_16x16x64_i8 v[14:17], v[164:167], v[202:205], v[14:17]
	v_mfma_i32_16x16x64_i8 v[10:13], v[172:175], v[202:205], v[10:13]
	v_mfma_i32_16x16x64_i8 v[6:9], v[164:167], v[210:213], v[6:9]
	v_mfma_i32_16x16x64_i8 v[2:5], v[172:175], v[210:213], v[2:5]
	v_mfma_i32_16x16x64_i8 v[46:49], v[168:171], v[190:193], v[46:49]
	v_mfma_i32_16x16x64_i8 v[38:41], v[176:179], v[190:193], v[38:41]
	v_mfma_i32_16x16x64_i8 v[30:33], v[168:171], v[198:201], v[30:33]
	v_mfma_i32_16x16x64_i8 v[22:25], v[176:179], v[198:201], v[22:25]
	v_mfma_i32_16x16x64_i8 v[14:17], v[168:171], v[206:209], v[14:17]
	v_mfma_i32_16x16x64_i8 v[10:13], v[176:179], v[206:209], v[10:13]
	v_mfma_i32_16x16x64_i8 v[6:9], v[168:171], v[214:217], v[6:9]
	v_mfma_i32_16x16x64_i8 v[2:5], v[176:179], v[214:217], v[2:5]
	s_setprio 0
	s_barrier
	s_add_u32 s26, s26, 0x100
	s_addc_u32 s27, s27, 0
	s_add_u32 s34, s34, 0x100
	s_addc_u32 s35, s35, 0
	s_cmp_ge_i32 s60, s51
	s_mov_b32 s28, s60
	s_cbranch_scc0 .LBB0_3798
	v_cvt_f32_i32_e32 v172, v126
	v_cvt_f32_i32_e32 v173, v127
	v_cvt_f32_i32_e32 v170, v128
	v_cvt_f32_i32_e32 v171, v129
	v_cvt_f32_i32_e32 v174, v122
	v_cvt_f32_i32_e32 v175, v123
	v_cvt_f32_i32_e32 v176, v124
	v_cvt_f32_i32_e32 v177, v125
	v_cvt_f32_i32_e32 v180, v110
	v_cvt_f32_i32_e32 v181, v111
	v_cvt_f32_i32_e32 v182, v112
	v_cvt_f32_i32_e32 v183, v113
	v_cvt_f32_i32_e32 v178, v102
	v_cvt_f32_i32_e32 v179, v103
	v_cvt_f32_i32_e32 v184, v104
	v_cvt_f32_i32_e32 v185, v105
	v_cvt_f32_i32_e32 v152, v118
	v_cvt_f32_i32_e32 v153, v119
	v_cvt_f32_i32_e32 v154, v120
	v_cvt_f32_i32_e32 v155, v121
	v_cvt_f32_i32_e32 v156, v114
	v_cvt_f32_i32_e32 v157, v115
	v_cvt_f32_i32_e32 v158, v116
	v_cvt_f32_i32_e32 v159, v117
	v_cvt_f32_i32_e32 v160, v94
	v_cvt_f32_i32_e32 v161, v95
	v_cvt_f32_i32_e32 v162, v96
	v_cvt_f32_i32_e32 v163, v97
	v_cvt_f32_i32_e32 v164, v86
	v_cvt_f32_i32_e32 v165, v87
	v_cvt_f32_i32_e32 v166, v88
	v_cvt_f32_i32_e32 v167, v89
	v_cvt_f32_i32_e32 v118, v106
	v_cvt_f32_i32_e32 v119, v107
	v_cvt_f32_i32_e32 v120, v108
	v_cvt_f32_i32_e32 v121, v109
	v_cvt_f32_i32_e32 v122, v98
	v_cvt_f32_i32_e32 v123, v99
	v_cvt_f32_i32_e32 v124, v100
	v_cvt_f32_i32_e32 v125, v101
	v_cvt_f32_i32_e32 v126, v78
	v_cvt_f32_i32_e32 v127, v79
	v_cvt_f32_i32_e32 v128, v80
	v_cvt_f32_i32_e32 v129, v81
	v_cvt_f32_i32_e32 v148, v74
	v_cvt_f32_i32_e32 v149, v75
	v_cvt_f32_i32_e32 v150, v76
	v_cvt_f32_i32_e32 v151, v77
	v_cvt_f32_i32_e32 v102, v90
	v_cvt_f32_i32_e32 v103, v91
	v_cvt_f32_i32_e32 v104, v92
	v_cvt_f32_i32_e32 v105, v93
	v_cvt_f32_i32_e32 v106, v82
	v_cvt_f32_i32_e32 v107, v83
	v_cvt_f32_i32_e32 v108, v84
	v_cvt_f32_i32_e32 v109, v85
	v_cvt_f32_i32_e32 v110, v70
	v_cvt_f32_i32_e32 v111, v71
	v_cvt_f32_i32_e32 v112, v72
	v_cvt_f32_i32_e32 v113, v73
	v_cvt_f32_i32_e32 v114, v66
	v_cvt_f32_i32_e32 v115, v67
	v_cvt_f32_i32_e32 v116, v68
	v_cvt_f32_i32_e32 v117, v69
	v_cvt_f32_i32_e32 v82, v62
	v_cvt_f32_i32_e32 v83, v63
	v_cvt_f32_i32_e32 v84, v64
	v_cvt_f32_i32_e32 v85, v65
	v_cvt_f32_i32_e32 v86, v58
	v_cvt_f32_i32_e32 v87, v59
	v_cvt_f32_i32_e32 v88, v60
	v_cvt_f32_i32_e32 v89, v61
	v_cvt_f32_i32_e32 v92, v46
	v_cvt_f32_i32_e32 v93, v47
	v_cvt_f32_i32_e32 v94, v48
	v_cvt_f32_i32_e32 v95, v49
	v_cvt_f32_i32_e32 v96, v38
	v_cvt_f32_i32_e32 v97, v39
	v_cvt_f32_i32_e32 v98, v40
	v_cvt_f32_i32_e32 v99, v41
	v_cvt_f32_i32_e32 v66, v54
	v_cvt_f32_i32_e32 v67, v55
	v_cvt_f32_i32_e32 v68, v56
	v_cvt_f32_i32_e32 v69, v57
	v_cvt_f32_i32_e32 v70, v50
	v_cvt_f32_i32_e32 v71, v51
	v_cvt_f32_i32_e32 v72, v52
	v_cvt_f32_i32_e32 v73, v53
	v_cvt_f32_i32_e32 v74, v30
	v_cvt_f32_i32_e32 v75, v31
	v_cvt_f32_i32_e32 v76, v32
	v_cvt_f32_i32_e32 v77, v33
	v_cvt_f32_i32_e32 v78, v22
	v_cvt_f32_i32_e32 v79, v23
	v_cvt_f32_i32_e32 v80, v24
	v_cvt_f32_i32_e32 v81, v25
	v_cvt_f32_i32_e32 v50, v42
	v_cvt_f32_i32_e32 v51, v43
	v_cvt_f32_i32_e32 v52, v44
	v_cvt_f32_i32_e32 v53, v45
	v_cvt_f32_i32_e32 v54, v34
	v_cvt_f32_i32_e32 v55, v35
	v_cvt_f32_i32_e32 v56, v36
	v_cvt_f32_i32_e32 v57, v37
	v_cvt_f32_i32_e32 v58, v14
	v_cvt_f32_i32_e32 v59, v15
	v_cvt_f32_i32_e32 v60, v16
	v_cvt_f32_i32_e32 v61, v17
	v_cvt_f32_i32_e32 v62, v10
	v_cvt_f32_i32_e32 v63, v11
	v_cvt_f32_i32_e32 v64, v12
	v_cvt_f32_i32_e32 v65, v13
	v_cvt_f32_i32_e32 v34, v26
	v_cvt_f32_i32_e32 v35, v27
	v_cvt_f32_i32_e32 v36, v28
	v_cvt_f32_i32_e32 v37, v29
	v_cvt_f32_i32_e32 v38, v18
	v_cvt_f32_i32_e32 v39, v19
	v_cvt_f32_i32_e32 v40, v20
	v_cvt_f32_i32_e32 v41, v21
	v_cvt_f32_i32_e32 v42, v6
	v_cvt_f32_i32_e32 v43, v7
	v_cvt_f32_i32_e32 v44, v8
	v_cvt_f32_i32_e32 v45, v9
	v_cvt_f32_i32_e32 v46, v2
	v_cvt_f32_i32_e32 v47, v3
	v_cvt_f32_i32_e32 v48, v4
	v_cvt_f32_i32_e32 v49, v5

.LBB0_3879:
	ds_read_b128 v[130:133], v169
	ds_read_b128 v[134:137], v169 offset:1024
	ds_read_b128 v[138:141], v169 offset:2048
	ds_read_b128 v[142:145], v169 offset:3072
	ds_read_b128 v[162:165], v170
	ds_read_b128 v[172:175], v170 offset:1024
	ds_read_b128 v[176:179], v170 offset:2048
	ds_read_b128 v[180:183], v170 offset:3072
	s_add_i32 s59, s26, 2
	s_add_u32 s27, s24, 0x4000
	s_addc_u32 s28, s25, 0
	s_cmp_eq_u32 s48, s26
	s_cselect_b32 s29, s3, s28
	s_cselect_b32 s28, s2, s27
	s_cselect_b32 s60, s22, s57
	s_cselect_b32 s61, s23, s58
	s_add_u32 s26, s28, 0x8000
	s_addc_u32 s27, s29, 0
	v_lshl_add_u64 v[216:217], s[24:25], 0, v[154:155]
	s_add_i32 m0, s38, 0xc000
	ds_read_b128 v[184:187], v171
	ds_read_b128 v[188:191], v171 offset:1024
	ds_read_b128 v[192:195], v171 offset:2048
	ds_read_b128 v[196:199], v171 offset:3072
	ds_read_b128 v[200:203], v171 offset:4096
	ds_read_b128 v[204:207], v171 offset:5120
	ds_read_b128 v[208:211], v171 offset:6144
	ds_read_b128 v[212:215], v171 offset:7168
	global_load_lds_dwordx4 v[216:217], off
	v_lshl_add_u64 v[216:217], s[24:25], 0, v[156:157]
	s_add_i32 m0, s38, 0xe000
	s_nop 0
	global_load_lds_dwordx4 v[216:217], off
	s_waitcnt vmcnt(8)
	s_waitcnt lgkmcnt(0)
	s_setprio 1
	s_waitcnt lgkmcnt(0)
	v_mfma_f32_16x16x32_bf16 v[126:129], v[130:133], v[184:187], v[126:129]
	v_mfma_f32_16x16x32_bf16 v[122:125], v[138:141], v[184:187], v[122:125]
	v_mfma_f32_16x16x32_bf16 v[110:113], v[130:133], v[192:195], v[110:113]
	v_mfma_f32_16x16x32_bf16 v[106:109], v[138:141], v[192:195], v[106:109]
	v_mfma_f32_16x16x32_bf16 v[94:97], v[130:133], v[200:203], v[94:97]
	v_mfma_f32_16x16x32_bf16 v[90:93], v[138:141], v[200:203], v[90:93]
	s_barrier
	v_mfma_f32_16x16x32_bf16 v[78:81], v[130:133], v[208:211], v[78:81]
	v_mfma_f32_16x16x32_bf16 v[74:77], v[138:141], v[208:211], v[74:77]
	v_mfma_f32_16x16x32_bf16 v[126:129], v[134:137], v[188:191], v[126:129]
	v_mfma_f32_16x16x32_bf16 v[122:125], v[142:145], v[188:191], v[122:125]
	v_mfma_f32_16x16x32_bf16 v[110:113], v[134:137], v[196:199], v[110:113]
	v_mfma_f32_16x16x32_bf16 v[106:109], v[142:145], v[196:199], v[106:109]
	v_mfma_f32_16x16x32_bf16 v[94:97], v[134:137], v[204:207], v[94:97]
	v_mfma_f32_16x16x32_bf16 v[90:93], v[142:145], v[204:207], v[90:93]
	v_mfma_f32_16x16x32_bf16 v[78:81], v[134:137], v[212:215], v[78:81]
	v_mfma_f32_16x16x32_bf16 v[74:77], v[142:145], v[212:215], v[74:77]
	s_setprio 0
	s_setprio 1
	v_mfma_f32_16x16x32_bf16 v[118:121], v[162:165], v[184:187], v[118:121]
	v_mfma_f32_16x16x32_bf16 v[114:117], v[176:179], v[184:187], v[114:117]
	v_mfma_f32_16x16x32_bf16 v[102:105], v[162:165], v[192:195], v[102:105]
	v_mfma_f32_16x16x32_bf16 v[98:101], v[176:179], v[192:195], v[98:101]
	v_mfma_f32_16x16x32_bf16 v[86:89], v[162:165], v[200:203], v[86:89]
	v_mfma_f32_16x16x32_bf16 v[82:85], v[176:179], v[200:203], v[82:85]
	v_mfma_f32_16x16x32_bf16 v[70:73], v[162:165], v[208:211], v[70:73]
	v_mfma_f32_16x16x32_bf16 v[66:69], v[176:179], v[208:211], v[66:69]
	v_mfma_f32_16x16x32_bf16 v[118:121], v[172:175], v[188:191], v[118:121]
	v_mfma_f32_16x16x32_bf16 v[114:117], v[180:183], v[188:191], v[114:117]
	v_mfma_f32_16x16x32_bf16 v[102:105], v[172:175], v[196:199], v[102:105]
	v_mfma_f32_16x16x32_bf16 v[98:101], v[180:183], v[196:199], v[98:101]
	v_mfma_f32_16x16x32_bf16 v[86:89], v[172:175], v[204:207], v[86:89]
	v_mfma_f32_16x16x32_bf16 v[82:85], v[180:183], v[204:207], v[82:85]
	v_mfma_f32_16x16x32_bf16 v[70:73], v[172:175], v[212:215], v[70:73]
	v_mfma_f32_16x16x32_bf16 v[66:69], v[180:183], v[212:215], v[66:69]
	s_setprio 0
	s_barrier
	s_add_i32 s62, s50, s37
	v_lshl_add_u64 v[216:217], s[60:61], 0, v[148:149]
	s_mov_b32 m0, s62
	ds_read_b128 v[184:187], v171 offset:16384
	ds_read_b128 v[188:191], v171 offset:17408
	ds_read_b128 v[192:195], v171 offset:18432
	ds_read_b128 v[196:199], v171 offset:19456
	ds_read_b128 v[200:203], v171 offset:20480
	ds_read_b128 v[204:207], v171 offset:21504
	ds_read_b128 v[208:211], v171 offset:22528
	ds_read_b128 v[212:215], v171 offset:23552
	global_load_lds_dwordx4 v[216:217], off
	s_add_i32 m0, s62, 0x2000
	v_lshl_add_u64 v[218:219], s[60:61], 0, v[152:153]
	s_add_u32 s60, s60, s6
	s_addc_u32 s61, s61, s7
	s_add_i32 s62, s51, s37
	global_load_lds_dwordx4 v[218:219], off
	v_lshl_add_u64 v[220:221], s[60:61], 0, v[148:149]
	s_mov_b32 m0, s62
	v_lshl_add_u64 v[222:223], s[60:61], 0, v[152:153]
	global_load_lds_dwordx4 v[220:221], off
	s_add_i32 m0, s62, 0x2000
	v_lshl_add_u64 v[224:225], s[28:29], 0, v[146:147]
	global_load_lds_dwordx4 v[222:223], off
	s_mov_b32 m0, s38
	s_nop 0
	global_load_lds_dwordx4 v[224:225], off
	v_lshl_add_u64 v[224:225], s[28:29], 0, v[150:151]
	s_mov_b32 m0, s39
	s_nop 0
	global_load_lds_dwordx4 v[224:225], off
	s_waitcnt vmcnt(8)
	s_waitcnt lgkmcnt(0)
	s_setprio 1
	s_waitcnt lgkmcnt(0)
	v_mfma_f32_16x16x32_bf16 v[62:65], v[130:133], v[184:187], v[62:65]
	v_mfma_f32_16x16x32_bf16 v[58:61], v[138:141], v[184:187], v[58:61]
	v_mfma_f32_16x16x32_bf16 v[46:49], v[130:133], v[192:195], v[46:49]
	v_mfma_f32_16x16x32_bf16 v[42:45], v[138:141], v[192:195], v[42:45]
	v_mfma_f32_16x16x32_bf16 v[30:33], v[130:133], v[200:203], v[30:33]
	v_mfma_f32_16x16x32_bf16 v[26:29], v[138:141], v[200:203], v[26:29]
	s_barrier
	v_mfma_f32_16x16x32_bf16 v[14:17], v[130:133], v[208:211], v[14:17]
	v_mfma_f32_16x16x32_bf16 v[10:13], v[138:141], v[208:211], v[10:13]
	v_mfma_f32_16x16x32_bf16 v[62:65], v[134:137], v[188:191], v[62:65]
	v_mfma_f32_16x16x32_bf16 v[58:61], v[142:145], v[188:191], v[58:61]
	v_mfma_f32_16x16x32_bf16 v[46:49], v[134:137], v[196:199], v[46:49]
	v_mfma_f32_16x16x32_bf16 v[42:45], v[142:145], v[196:199], v[42:45]
	v_mfma_f32_16x16x32_bf16 v[30:33], v[134:137], v[204:207], v[30:33]
	v_mfma_f32_16x16x32_bf16 v[26:29], v[142:145], v[204:207], v[26:29]
	v_mfma_f32_16x16x32_bf16 v[14:17], v[134:137], v[212:215], v[14:17]
	v_mfma_f32_16x16x32_bf16 v[10:13], v[142:145], v[212:215], v[10:13]
	s_setprio 0
	s_setprio 1
	v_mfma_f32_16x16x32_bf16 v[54:57], v[162:165], v[184:187], v[54:57]
	v_mfma_f32_16x16x32_bf16 v[50:53], v[176:179], v[184:187], v[50:53]
	v_mfma_f32_16x16x32_bf16 v[38:41], v[162:165], v[192:195], v[38:41]
	v_mfma_f32_16x16x32_bf16 v[34:37], v[176:179], v[192:195], v[34:37]
	v_mfma_f32_16x16x32_bf16 v[22:25], v[162:165], v[200:203], v[22:25]
	v_mfma_f32_16x16x32_bf16 v[18:21], v[176:179], v[200:203], v[18:21]
	v_mfma_f32_16x16x32_bf16 v[6:9], v[162:165], v[208:211], v[6:9]
	v_mfma_f32_16x16x32_bf16 v[2:5], v[176:179], v[208:211], v[2:5]
	v_mfma_f32_16x16x32_bf16 v[54:57], v[172:175], v[188:191], v[54:57]
	v_mfma_f32_16x16x32_bf16 v[50:53], v[180:183], v[188:191], v[50:53]
	v_mfma_f32_16x16x32_bf16 v[38:41], v[172:175], v[196:199], v[38:41]
	v_mfma_f32_16x16x32_bf16 v[34:37], v[180:183], v[196:199], v[34:37]
	v_mfma_f32_16x16x32_bf16 v[22:25], v[172:175], v[204:207], v[22:25]
	v_mfma_f32_16x16x32_bf16 v[18:21], v[180:183], v[204:207], v[18:21]
	v_mfma_f32_16x16x32_bf16 v[6:9], v[172:175], v[212:215], v[6:9]
	v_mfma_f32_16x16x32_bf16 v[2:5], v[180:183], v[212:215], v[2:5]
	s_setprio 0
	s_barrier
	s_add_i32 s60, 0, 0x18000
	s_add_i32 s61, 0, 0x1c000
	v_add_u32_e32 v142, s60, v167
	v_add_u32_e32 v180, s61, v167
	ds_read_b128 v[130:133], v142
	ds_read_b128 v[134:137], v142 offset:1024
	ds_read_b128 v[138:141], v142 offset:2048
	ds_read_b128 v[142:145], v142 offset:3072
	ds_read_b128 v[162:165], v180
	ds_read_b128 v[172:175], v180 offset:1024
	ds_read_b128 v[176:179], v180 offset:2048
	ds_read_b128 v[180:183], v180 offset:3072
	s_add_u32 s28, s28, 0x4000
	s_addc_u32 s29, s29, 0
	s_mov_b32 m0, s40
	v_lshl_add_u64 v[224:225], s[28:29], 0, v[146:147]
	ds_read_b128 v[184:187], v171 offset:32768
	ds_read_b128 v[188:191], v171 offset:33792
	ds_read_b128 v[192:195], v171 offset:34816
	ds_read_b128 v[196:199], v171 offset:35840
	ds_read_b128 v[200:203], v171 offset:36864
	ds_read_b128 v[204:207], v171 offset:37888
	ds_read_b128 v[208:211], v171 offset:38912
	ds_read_b128 v[212:215], v171 offset:39936
	global_load_lds_dwordx4 v[224:225], off
	v_lshl_add_u64 v[224:225], s[28:29], 0, v[150:151]
	s_mov_b32 m0, s41
	s_nop 0
	global_load_lds_dwordx4 v[224:225], off
	s_waitcnt vmcnt(8)
	s_waitcnt lgkmcnt(0)
	s_setprio 1
	s_waitcnt lgkmcnt(0)
	v_mfma_f32_16x16x32_bf16 v[126:129], v[130:133], v[184:187], v[126:129]
	v_mfma_f32_16x16x32_bf16 v[122:125], v[138:141], v[184:187], v[122:125]
	v_mfma_f32_16x16x32_bf16 v[110:113], v[130:133], v[192:195], v[110:113]
	v_mfma_f32_16x16x32_bf16 v[106:109], v[138:141], v[192:195], v[106:109]
	v_mfma_f32_16x16x32_bf16 v[94:97], v[130:133], v[200:203], v[94:97]
	v_mfma_f32_16x16x32_bf16 v[90:93], v[138:141], v[200:203], v[90:93]
	s_barrier
	v_mfma_f32_16x16x32_bf16 v[78:81], v[130:133], v[208:211], v[78:81]
	v_mfma_f32_16x16x32_bf16 v[74:77], v[138:141], v[208:211], v[74:77]
	v_mfma_f32_16x16x32_bf16 v[126:129], v[134:137], v[188:191], v[126:129]
	v_mfma_f32_16x16x32_bf16 v[122:125], v[142:145], v[188:191], v[122:125]
	v_mfma_f32_16x16x32_bf16 v[110:113], v[134:137], v[196:199], v[110:113]
	v_mfma_f32_16x16x32_bf16 v[106:109], v[142:145], v[196:199], v[106:109]
	v_mfma_f32_16x16x32_bf16 v[94:97], v[134:137], v[204:207], v[94:97]
	v_mfma_f32_16x16x32_bf16 v[90:93], v[142:145], v[204:207], v[90:93]
	v_mfma_f32_16x16x32_bf16 v[78:81], v[134:137], v[212:215], v[78:81]
	v_mfma_f32_16x16x32_bf16 v[74:77], v[142:145], v[212:215], v[74:77]
	s_setprio 0
	s_setprio 1
	v_mfma_f32_16x16x32_bf16 v[118:121], v[162:165], v[184:187], v[118:121]
	v_mfma_f32_16x16x32_bf16 v[114:117], v[176:179], v[184:187], v[114:117]
	v_mfma_f32_16x16x32_bf16 v[102:105], v[162:165], v[192:195], v[102:105]
	v_mfma_f32_16x16x32_bf16 v[98:101], v[176:179], v[192:195], v[98:101]
	v_mfma_f32_16x16x32_bf16 v[86:89], v[162:165], v[200:203], v[86:89]
	v_mfma_f32_16x16x32_bf16 v[82:85], v[176:179], v[200:203], v[82:85]
	v_mfma_f32_16x16x32_bf16 v[70:73], v[162:165], v[208:211], v[70:73]
	v_mfma_f32_16x16x32_bf16 v[66:69], v[176:179], v[208:211], v[66:69]
	v_mfma_f32_16x16x32_bf16 v[118:121], v[172:175], v[188:191], v[118:121]
	v_mfma_f32_16x16x32_bf16 v[114:117], v[180:183], v[188:191], v[114:117]
	v_mfma_f32_16x16x32_bf16 v[102:105], v[172:175], v[196:199], v[102:105]
	v_mfma_f32_16x16x32_bf16 v[98:101], v[180:183], v[196:199], v[98:101]
	v_mfma_f32_16x16x32_bf16 v[86:89], v[172:175], v[204:207], v[86:89]
	v_mfma_f32_16x16x32_bf16 v[82:85], v[180:183], v[204:207], v[82:85]
	v_mfma_f32_16x16x32_bf16 v[70:73], v[172:175], v[212:215], v[70:73]
	v_mfma_f32_16x16x32_bf16 v[66:69], v[180:183], v[212:215], v[66:69]
	s_setprio 0
	s_barrier
	s_add_i32 s28, s60, s37
	v_lshl_add_u64 v[216:217], v[216:217], 0, s[14:15]
	s_mov_b32 m0, s28
	ds_read_b128 v[184:187], v171 offset:49152
	ds_read_b128 v[188:191], v171 offset:50176
	ds_read_b128 v[192:195], v171 offset:51200
	ds_read_b128 v[196:199], v171 offset:52224
	ds_read_b128 v[200:203], v171 offset:53248
	ds_read_b128 v[204:207], v171 offset:54272
	ds_read_b128 v[208:211], v171 offset:55296
	ds_read_b128 v[212:215], v171 offset:56320
	global_load_lds_dwordx4 v[216:217], off
	v_lshl_add_u64 v[216:217], v[218:219], 0, s[14:15]
	s_add_i32 m0, s28, 0x2000
	s_add_i32 s28, s61, s37
	global_load_lds_dwordx4 v[216:217], off
	v_lshl_add_u64 v[216:217], v[220:221], 0, s[14:15]
	s_mov_b32 m0, s28
	s_nop 0
	global_load_lds_dwordx4 v[216:217], off
	v_lshl_add_u64 v[216:217], v[222:223], 0, s[14:15]
	s_add_i32 m0, s28, 0x2000
	s_nop 0
	global_load_lds_dwordx4 v[216:217], off
	v_lshl_add_u64 v[216:217], s[26:27], 0, v[146:147]
	s_mov_b32 m0, s46
	s_nop 0
	global_load_lds_dwordx4 v[216:217], off
	v_lshl_add_u64 v[216:217], s[26:27], 0, v[150:151]
	s_mov_b32 m0, s47
	s_nop 0
	global_load_lds_dwordx4 v[216:217], off
	s_waitcnt vmcnt(8)
	s_waitcnt lgkmcnt(0)
	s_setprio 1
	s_waitcnt lgkmcnt(0)
	v_mfma_f32_16x16x32_bf16 v[62:65], v[130:133], v[184:187], v[62:65]
	v_mfma_f32_16x16x32_bf16 v[58:61], v[138:141], v[184:187], v[58:61]
	v_mfma_f32_16x16x32_bf16 v[46:49], v[130:133], v[192:195], v[46:49]
	v_mfma_f32_16x16x32_bf16 v[42:45], v[138:141], v[192:195], v[42:45]
	v_mfma_f32_16x16x32_bf16 v[30:33], v[130:133], v[200:203], v[30:33]
	v_mfma_f32_16x16x32_bf16 v[26:29], v[138:141], v[200:203], v[26:29]
	s_barrier
	v_mfma_f32_16x16x32_bf16 v[14:17], v[130:133], v[208:211], v[14:17]
	v_mfma_f32_16x16x32_bf16 v[10:13], v[138:141], v[208:211], v[10:13]
	v_mfma_f32_16x16x32_bf16 v[62:65], v[134:137], v[188:191], v[62:65]
	v_mfma_f32_16x16x32_bf16 v[58:61], v[142:145], v[188:191], v[58:61]
	v_mfma_f32_16x16x32_bf16 v[46:49], v[134:137], v[196:199], v[46:49]
	v_mfma_f32_16x16x32_bf16 v[42:45], v[142:145], v[196:199], v[42:45]
	v_mfma_f32_16x16x32_bf16 v[30:33], v[134:137], v[204:207], v[30:33]
	v_mfma_f32_16x16x32_bf16 v[26:29], v[142:145], v[204:207], v[26:29]
	v_mfma_f32_16x16x32_bf16 v[14:17], v[134:137], v[212:215], v[14:17]
	v_mfma_f32_16x16x32_bf16 v[10:13], v[142:145], v[212:215], v[10:13]
	s_setprio 0
	s_setprio 1
	v_mfma_f32_16x16x32_bf16 v[54:57], v[162:165], v[184:187], v[54:57]
	v_mfma_f32_16x16x32_bf16 v[50:53], v[176:179], v[184:187], v[50:53]
	v_mfma_f32_16x16x32_bf16 v[38:41], v[162:165], v[192:195], v[38:41]
	v_mfma_f32_16x16x32_bf16 v[34:37], v[176:179], v[192:195], v[34:37]
	v_mfma_f32_16x16x32_bf16 v[22:25], v[162:165], v[200:203], v[22:25]
	v_mfma_f32_16x16x32_bf16 v[18:21], v[176:179], v[200:203], v[18:21]
	v_mfma_f32_16x16x32_bf16 v[6:9], v[162:165], v[208:211], v[6:9]
	v_mfma_f32_16x16x32_bf16 v[2:5], v[176:179], v[208:211], v[2:5]
	v_mfma_f32_16x16x32_bf16 v[54:57], v[172:175], v[188:191], v[54:57]
	v_mfma_f32_16x16x32_bf16 v[50:53], v[180:183], v[188:191], v[50:53]
	v_mfma_f32_16x16x32_bf16 v[38:41], v[172:175], v[196:199], v[38:41]
	v_mfma_f32_16x16x32_bf16 v[34:37], v[180:183], v[196:199], v[34:37]
	v_mfma_f32_16x16x32_bf16 v[22:25], v[172:175], v[204:207], v[22:25]
	v_mfma_f32_16x16x32_bf16 v[18:21], v[180:183], v[204:207], v[18:21]
	v_mfma_f32_16x16x32_bf16 v[6:9], v[172:175], v[212:215], v[6:9]
	v_mfma_f32_16x16x32_bf16 v[2:5], v[180:183], v[212:215], v[2:5]
	s_setprio 0
	s_barrier
	s_add_u32 s57, s57, 0x100
	s_addc_u32 s58, s58, 0
	s_add_u32 s24, s24, 0x10000
	s_addc_u32 s25, s25, 0
	s_cmp_ge_i32 s59, s45
	s_mov_b32 s26, s59
	s_cbranch_scc0 .LBB0_3879
